# GEMM mainloops: the priority drop/raise pair in the middle of each 16-MFMA cluster removed; one raise per cluster
# speedup vs baseline: 1.0011x; 1.0011x over previous
; #define PG8_STAGE(bufoff, gbase, voff) do { _Pragma("unroll") for (int _i = 0; _i < 2; ++_i) \
;         __builtin_amdgcn_global_load_lds((const unsigned*)((const char*)(gbase) + (voff)[_i]), (PG8_LAS unsigned*)(lds + (bufoff) + ldsw + _i * 8192), 16, 0, 0); } while (0)
; #define PG8_WAIT_V(n) asm volatile("s_waitcnt vmcnt(" #n ")" ::: "memory")
; #define PG8_WAIT_L(n) asm volatile("s_waitcnt lgkmcnt(" #n ")" ::: "memory")
; #define PG8_BAR __builtin_amdgcn_s_barrier()
; #define PG8_SCHED __builtin_amdgcn_sched_barrier(0)
; template <class Epi, class Sched, bool ALIGN_EPI = false, bool SP2 = false, bool F8 = false>
; __device__ __forceinline__ void gemm_phase(PG8_LAS unsigned char* lds, const Gemm g, const Sched& S, const Epi& E) {
;     ...
;             const char* a1 = cA + (size_t)(t + 1) * kstep;
;             const char* a2 = last ? nA : cA + (size_t)(t + 2) * kstep; const char* b2 = last ? nB : cB + (size_t)(t + 2) * kstep;
;             const char* a3 = a2 + kstep; const char* b3 = b2 + kstep;
;             if (last && has_next) S.a_ready(nxt);
;             if constexpr (SP2) {
;             PG8_LDB(B0, 0, 0); PG8_LDB(B1, 0, 1); PG8_SCHED; PG8_LDA(At, 0, 0); PG8_STAGE(PG8_SA(1, 1), a1 + hstep, voffA);
;             PG8_WAIT_V(8); PG8_WAIT_L(0); PG8_BAR; PG8_MMA(0, 0, At, B0); PG8_MMA(0, 1, At, B1); PG8_BAR; PG8_SCHED;
;             PG8_LDA(At, 0, 1); PG8_STAGE(PG8_SB(0, 0), b2, voffB); PG8_STAGE(PG8_SB(0, 1), b2 + hstep, voffB); PG8_STAGE(PG8_SA(0, 0), a2, voffA);
;             PG8_WAIT_V(8); PG8_WAIT_L(0); PG8_BAR; PG8_MMA(1, 0, At, B0); PG8_MMA(1, 1, At, B1); PG8_BAR; PG8_SCHED;
.LBB0_31:
	s_ashr_i32 s47, s46, 31
	s_lshl_b64 s[16:17], s[46:47], 20
	v_readlane_b32 s28, v251, 7
	v_readlane_b32 s29, v251, 8
	s_add_u32 s48, s28, s16
	s_addc_u32 s49, s29, s17
	s_and_b64 s[16:17], s[38:39], exec
	s_cselect_b32 s19, s49, s1
	s_cselect_b32 s23, s48, s0
	s_ashr_i32 s45, s44, 31
	s_lshl_b64 s[16:17], s[44:45], 20
	s_add_u32 s50, s13, s16
	s_addc_u32 s51, s22, s17
	s_and_b64 s[16:17], s[38:39], exec
	s_cselect_b32 s28, s51, s11
	s_cselect_b32 s29, s50, s10
	s_add_u32 s0, s0, 0x80080
	s_addc_u32 s1, s1, 0
	s_add_u32 s45, s10, 0x100
	s_addc_u32 s47, s11, 0
	s_mov_b32 s52, -2
	s_add_u32 s10, s0, 0xfff80080
	s_addc_u32 s11, s1, -1
	s_add_i32 s53, 0, 0x10000
	s_cmp_eq_u32 s52, 28
	s_cselect_b32 s17, s19, s11
	s_cselect_b32 s16, s23, s10
	v_add_u32_e32 v146, s53, v149
	s_cselect_b32 s11, s28, s47
	s_cselect_b32 s10, s29, s45
	s_add_i32 s56, 0, 0x14000
	ds_read_b128 v[138:141], v146
	ds_read_b128 v[142:145], v146 offset:1024
	ds_read_b128 v[152:155], v146 offset:2048
	ds_read_b128 v[156:159], v146 offset:3072
	v_add_u32_e32 v146, s56, v149
	ds_read_b128 v[184:187], v146
	ds_read_b128 v[188:191], v146 offset:1024
	ds_read_b128 v[192:195], v146 offset:2048
	ds_read_b128 v[196:199], v146 offset:3072
	v_lshl_add_u64 v[146:147], s[0:1], 0, v[134:135]
	s_add_i32 m0, s35, 0xc000
	ds_read_b128 v[200:203], v151
	ds_read_b128 v[214:217], v151 offset:1024
	ds_read_b128 v[218:221], v151 offset:2048
	ds_read_b128 v[222:225], v151 offset:3072
	ds_read_b128 v[226:229], v151 offset:4096
	ds_read_b128 v[230:233], v151 offset:5120
	ds_read_b128 v[234:237], v151 offset:6144
	ds_read_b128 v[238:241], v151 offset:7168
	global_load_lds_dwordx4 v[146:147], off
	v_lshl_add_u64 v[146:147], s[0:1], 0, v[136:137]
	s_add_i32 m0, s35, 0xe000
	s_nop 0
	global_load_lds_dwordx4 v[146:147], off
	s_waitcnt vmcnt(8)
	s_waitcnt lgkmcnt(0)
	s_barrier
	s_setprio 1
	s_waitcnt lgkmcnt(0)
	v_mfma_f32_16x16x32_bf16 v[124:127], v[138:141], v[200:203], 0
	v_mfma_f32_16x16x32_bf16 v[120:123], v[152:155], v[200:203], 0
	v_mfma_f32_16x16x32_bf16 v[108:111], v[138:141], v[218:221], 0
	v_mfma_f32_16x16x32_bf16 v[104:107], v[152:155], v[218:221], 0
	v_mfma_f32_16x16x32_bf16 v[92:95], v[138:141], v[226:229], 0
	v_mfma_f32_16x16x32_bf16 v[88:91], v[152:155], v[226:229], 0
	v_mfma_f32_16x16x32_bf16 v[76:79], v[138:141], v[234:237], 0
	v_mfma_f32_16x16x32_bf16 v[72:75], v[152:155], v[234:237], 0
	v_mfma_f32_16x16x32_bf16 v[124:127], v[142:145], v[214:217], v[124:127]
	v_mfma_f32_16x16x32_bf16 v[120:123], v[156:159], v[214:217], v[120:123]
	v_mfma_f32_16x16x32_bf16 v[108:111], v[142:145], v[222:225], v[108:111]
	v_mfma_f32_16x16x32_bf16 v[104:107], v[156:159], v[222:225], v[104:107]
	v_mfma_f32_16x16x32_bf16 v[92:95], v[142:145], v[230:233], v[92:95]
	v_mfma_f32_16x16x32_bf16 v[88:91], v[156:159], v[230:233], v[88:91]
	v_mfma_f32_16x16x32_bf16 v[76:79], v[142:145], v[238:241], v[76:79]
	v_mfma_f32_16x16x32_bf16 v[72:75], v[156:159], v[238:241], v[72:75]
	v_mfma_f32_16x16x32_bf16 v[116:119], v[184:187], v[200:203], 0
	v_mfma_f32_16x16x32_bf16 v[112:115], v[192:195], v[200:203], 0
	v_mfma_f32_16x16x32_bf16 v[100:103], v[184:187], v[218:221], 0
	v_mfma_f32_16x16x32_bf16 v[96:99], v[192:195], v[218:221], 0
	v_mfma_f32_16x16x32_bf16 v[84:87], v[184:187], v[226:229], 0
	v_mfma_f32_16x16x32_bf16 v[80:83], v[192:195], v[226:229], 0
	v_mfma_f32_16x16x32_bf16 v[68:71], v[184:187], v[234:237], 0
	v_mfma_f32_16x16x32_bf16 v[64:67], v[192:195], v[234:237], 0
	v_mfma_f32_16x16x32_bf16 v[116:119], v[188:191], v[214:217], v[116:119]
	v_mfma_f32_16x16x32_bf16 v[112:115], v[196:199], v[214:217], v[112:115]
	v_mfma_f32_16x16x32_bf16 v[100:103], v[188:191], v[222:225], v[100:103]
	v_mfma_f32_16x16x32_bf16 v[96:99], v[196:199], v[222:225], v[96:99]
	v_mfma_f32_16x16x32_bf16 v[84:87], v[188:191], v[230:233], v[84:87]
	v_mfma_f32_16x16x32_bf16 v[80:83], v[196:199], v[230:233], v[80:83]
	v_mfma_f32_16x16x32_bf16 v[68:71], v[188:191], v[238:241], v[68:71]
	v_mfma_f32_16x16x32_bf16 v[64:67], v[196:199], v[238:241], v[64:67]
	s_setprio 0
	s_barrier
	s_add_i32 s53, s53, s34
	v_lshl_add_u64 v[146:147], s[10:11], 0, v[160:161]
	s_mov_b32 m0, s53
	ds_read_b128 v[200:203], v151 offset:16384
	ds_read_b128 v[214:217], v151 offset:17408
	ds_read_b128 v[218:221], v151 offset:18432
	ds_read_b128 v[222:225], v151 offset:19456
	ds_read_b128 v[226:229], v151 offset:20480
	ds_read_b128 v[230:233], v151 offset:21504
	ds_read_b128 v[234:237], v151 offset:22528
	ds_read_b128 v[238:241], v151 offset:23552
	global_load_lds_dwordx4 v[146:147], off
	s_add_i32 m0, s53, 0x2000
	s_add_u32 s60, s10, 0x80000
	v_lshl_add_u64 v[162:163], s[10:11], 0, v[128:129]
	s_addc_u32 s61, s11, 0
	s_add_i32 s53, s56, s34
	global_load_lds_dwordx4 v[162:163], off
	v_lshl_add_u64 v[242:243], s[60:61], 0, v[160:161]
	s_mov_b32 m0, s53
	v_lshl_add_u64 v[244:245], s[16:17], 0, v[130:131]
	global_load_lds_dwordx4 v[242:243], off
	v_lshl_add_u64 v[242:243], s[60:61], 0, v[128:129]
	s_add_i32 m0, s53, 0x2000
	s_nop 0
	global_load_lds_dwordx4 v[242:243], off
	v_lshl_add_u64 v[242:243], s[16:17], 0, v[132:133]
	s_mov_b32 m0, s35
	s_nop 0
	global_load_lds_dwordx4 v[242:243], off
	s_mov_b32 m0, s36
	s_nop 0
	global_load_lds_dwordx4 v[244:245], off
	s_waitcnt vmcnt(8)
	s_waitcnt lgkmcnt(0)
	s_barrier
; #define PG8_STAGE(bufoff, gbase, voff) do { _Pragma("unroll") for (int _i = 0; _i < 2; ++_i) \
;         __builtin_amdgcn_global_load_lds((const unsigned*)((const char*)(gbase) + (voff)[_i]), (PG8_LAS unsigned*)(lds + (bufoff) + ldsw + _i * 8192), 16, 0, 0); } while (0)
; #define PG8_WAIT_V(n) asm volatile("s_waitcnt vmcnt(" #n ")" ::: "memory")
; #define PG8_WAIT_L(n) asm volatile("s_waitcnt lgkmcnt(" #n ")" ::: "memory")
; #define PG8_BAR __builtin_amdgcn_s_barrier()
; #define PG8_SCHED __builtin_amdgcn_sched_barrier(0)
; template <class Epi, class Sched, bool ALIGN_EPI = false, bool SP2 = false, bool F8 = false>
; __device__ __forceinline__ void gemm_phase(PG8_LAS unsigned char* lds, const Gemm g, const Sched& S, const Epi& E) {
;     ...
;             PG8_LDB(B0, 0, 0); PG8_LDB(B1, 0, 1); PG8_SCHED; PG8_LDA(At, 0, 0); PG8_STAGE(PG8_SA(1, 1), a1 + hstep, voffA);
;             PG8_WAIT_V(8); PG8_WAIT_L(0); PG8_BAR; PG8_MMA(0, 0, At, B0); PG8_MMA(0, 1, At, B1); PG8_BAR; PG8_SCHED;
;             PG8_LDA(At, 0, 1); PG8_STAGE(PG8_SB(0, 0), b2, voffB); PG8_STAGE(PG8_SB(0, 1), b2 + hstep, voffB); PG8_STAGE(PG8_SA(0, 0), a2, voffA);
;             PG8_WAIT_V(8); PG8_WAIT_L(0); PG8_BAR; PG8_MMA(1, 0, At, B0); PG8_MMA(1, 1, At, B1); PG8_BAR; PG8_SCHED;
;             PG8_LDB(B0, 1, 0); PG8_LDB(B1, 1, 1); PG8_SCHED; PG8_LDA(At, 1, 0); PG8_STAGE(PG8_SA(0, 1), a2 + hstep, voffA);
;             PG8_WAIT_V(8); PG8_WAIT_L(0); PG8_BAR; PG8_MMA(0, 0, At, B0); PG8_MMA(0, 1, At, B1); PG8_BAR; PG8_SCHED;
;             PG8_LDA(At, 1, 1); PG8_STAGE(PG8_SB(1, 0), b3, voffB); PG8_STAGE(PG8_SB(1, 1), b3 + hstep, voffB); PG8_STAGE(PG8_SA(1, 0), a3, voffA);
;             PG8_WAIT_V(8); PG8_WAIT_L(0); PG8_BAR; PG8_MMA(1, 0, At, B0); PG8_MMA(1, 1, At, B1); PG8_BAR; PG8_SCHED;
	s_setprio 1
	s_waitcnt lgkmcnt(0)
	v_mfma_f32_16x16x32_bf16 v[60:63], v[138:141], v[200:203], 0
	v_mfma_f32_16x16x32_bf16 v[56:59], v[152:155], v[200:203], 0
	v_mfma_f32_16x16x32_bf16 v[44:47], v[138:141], v[218:221], 0
	v_mfma_f32_16x16x32_bf16 v[40:43], v[152:155], v[218:221], 0
	v_mfma_f32_16x16x32_bf16 v[28:31], v[138:141], v[226:229], 0
	v_mfma_f32_16x16x32_bf16 v[24:27], v[152:155], v[226:229], 0
	v_mfma_f32_16x16x32_bf16 v[12:15], v[138:141], v[234:237], 0
	v_mfma_f32_16x16x32_bf16 v[8:11], v[152:155], v[234:237], 0
	v_mfma_f32_16x16x32_bf16 v[60:63], v[142:145], v[214:217], v[60:63]
	v_mfma_f32_16x16x32_bf16 v[56:59], v[156:159], v[214:217], v[56:59]
	v_mfma_f32_16x16x32_bf16 v[44:47], v[142:145], v[222:225], v[44:47]
	v_mfma_f32_16x16x32_bf16 v[40:43], v[156:159], v[222:225], v[40:43]
	v_mfma_f32_16x16x32_bf16 v[28:31], v[142:145], v[230:233], v[28:31]
	v_mfma_f32_16x16x32_bf16 v[24:27], v[156:159], v[230:233], v[24:27]
	v_mfma_f32_16x16x32_bf16 v[12:15], v[142:145], v[238:241], v[12:15]
	v_mfma_f32_16x16x32_bf16 v[8:11], v[156:159], v[238:241], v[8:11]
	v_mfma_f32_16x16x32_bf16 v[52:55], v[184:187], v[200:203], 0
	v_mfma_f32_16x16x32_bf16 v[48:51], v[192:195], v[200:203], 0
	v_mfma_f32_16x16x32_bf16 v[36:39], v[184:187], v[218:221], 0
	v_mfma_f32_16x16x32_bf16 v[32:35], v[192:195], v[218:221], 0
	v_mfma_f32_16x16x32_bf16 v[20:23], v[184:187], v[226:229], 0
	v_mfma_f32_16x16x32_bf16 v[16:19], v[192:195], v[226:229], 0
	v_mfma_f32_16x16x32_bf16 v[4:7], v[184:187], v[234:237], 0
	v_mfma_f32_16x16x32_bf16 v[0:3], v[192:195], v[234:237], 0
	v_mfma_f32_16x16x32_bf16 v[52:55], v[188:191], v[214:217], v[52:55]
	v_mfma_f32_16x16x32_bf16 v[48:51], v[196:199], v[214:217], v[48:51]
	v_mfma_f32_16x16x32_bf16 v[36:39], v[188:191], v[222:225], v[36:39]
	v_mfma_f32_16x16x32_bf16 v[32:35], v[196:199], v[222:225], v[32:35]
	v_mfma_f32_16x16x32_bf16 v[20:23], v[188:191], v[230:233], v[20:23]
	v_mfma_f32_16x16x32_bf16 v[16:19], v[196:199], v[230:233], v[16:19]
	v_mfma_f32_16x16x32_bf16 v[4:7], v[188:191], v[238:241], v[4:7]
	v_mfma_f32_16x16x32_bf16 v[0:3], v[196:199], v[238:241], v[0:3]
	s_setprio 0
	s_barrier
	s_add_i32 s53, 0, 0x18000
	s_add_i32 s56, 0, 0x1c000
	v_add_u32_e32 v156, s53, v149
	v_add_u32_e32 v196, s56, v149
	ds_read_b128 v[138:141], v156
	ds_read_b128 v[142:145], v156 offset:1024
	ds_read_b128 v[152:155], v156 offset:2048
	ds_read_b128 v[156:159], v156 offset:3072
	ds_read_b128 v[184:187], v196
	ds_read_b128 v[188:191], v196 offset:1024
	ds_read_b128 v[192:195], v196 offset:2048
	ds_read_b128 v[196:199], v196 offset:3072
	s_add_u32 s16, s16, 0x80000
	s_addc_u32 s17, s17, 0
	s_mov_b32 m0, s37
	v_lshl_add_u64 v[246:247], s[16:17], 0, v[132:133]
	ds_read_b128 v[200:203], v151 offset:32768
	ds_read_b128 v[214:217], v151 offset:33792
	ds_read_b128 v[218:221], v151 offset:34816
	ds_read_b128 v[222:225], v151 offset:35840
	ds_read_b128 v[226:229], v151 offset:36864
	ds_read_b128 v[230:233], v151 offset:37888
	ds_read_b128 v[234:237], v151 offset:38912
	ds_read_b128 v[238:241], v151 offset:39936
	global_load_lds_dwordx4 v[246:247], off
	v_lshl_add_u64 v[246:247], s[16:17], 0, v[130:131]
	s_mov_b32 m0, s54
	s_nop 0
	global_load_lds_dwordx4 v[246:247], off
	s_waitcnt vmcnt(8)
	s_waitcnt lgkmcnt(0)
	s_barrier
	s_setprio 1
	s_waitcnt lgkmcnt(0)
	v_mfma_f32_16x16x32_bf16 v[124:127], v[138:141], v[200:203], v[124:127]
	v_mfma_f32_16x16x32_bf16 v[120:123], v[152:155], v[200:203], v[120:123]
	v_mfma_f32_16x16x32_bf16 v[108:111], v[138:141], v[218:221], v[108:111]
	v_mfma_f32_16x16x32_bf16 v[104:107], v[152:155], v[218:221], v[104:107]
	v_mfma_f32_16x16x32_bf16 v[92:95], v[138:141], v[226:229], v[92:95]
	v_mfma_f32_16x16x32_bf16 v[88:91], v[152:155], v[226:229], v[88:91]
	v_mfma_f32_16x16x32_bf16 v[76:79], v[138:141], v[234:237], v[76:79]
	v_mfma_f32_16x16x32_bf16 v[72:75], v[152:155], v[234:237], v[72:75]
	v_mfma_f32_16x16x32_bf16 v[124:127], v[142:145], v[214:217], v[124:127]
	v_mfma_f32_16x16x32_bf16 v[120:123], v[156:159], v[214:217], v[120:123]
	v_mfma_f32_16x16x32_bf16 v[108:111], v[142:145], v[222:225], v[108:111]
	v_mfma_f32_16x16x32_bf16 v[104:107], v[156:159], v[222:225], v[104:107]
	v_mfma_f32_16x16x32_bf16 v[92:95], v[142:145], v[230:233], v[92:95]
	v_mfma_f32_16x16x32_bf16 v[88:91], v[156:159], v[230:233], v[88:91]
	v_mfma_f32_16x16x32_bf16 v[76:79], v[142:145], v[238:241], v[76:79]
	v_mfma_f32_16x16x32_bf16 v[72:75], v[156:159], v[238:241], v[72:75]
	v_mfma_f32_16x16x32_bf16 v[116:119], v[184:187], v[200:203], v[116:119]
	v_mfma_f32_16x16x32_bf16 v[112:115], v[192:195], v[200:203], v[112:115]
	v_mfma_f32_16x16x32_bf16 v[100:103], v[184:187], v[218:221], v[100:103]
	v_mfma_f32_16x16x32_bf16 v[96:99], v[192:195], v[218:221], v[96:99]
	v_mfma_f32_16x16x32_bf16 v[84:87], v[184:187], v[226:229], v[84:87]
	v_mfma_f32_16x16x32_bf16 v[80:83], v[192:195], v[226:229], v[80:83]
	v_mfma_f32_16x16x32_bf16 v[68:71], v[184:187], v[234:237], v[68:71]
	v_mfma_f32_16x16x32_bf16 v[64:67], v[192:195], v[234:237], v[64:67]
	v_mfma_f32_16x16x32_bf16 v[116:119], v[188:191], v[214:217], v[116:119]
	v_mfma_f32_16x16x32_bf16 v[112:115], v[196:199], v[214:217], v[112:115]
	v_mfma_f32_16x16x32_bf16 v[100:103], v[188:191], v[222:225], v[100:103]
	v_mfma_f32_16x16x32_bf16 v[96:99], v[196:199], v[222:225], v[96:99]
	v_mfma_f32_16x16x32_bf16 v[84:87], v[188:191], v[230:233], v[84:87]
	v_mfma_f32_16x16x32_bf16 v[80:83], v[196:199], v[230:233], v[80:83]
	v_mfma_f32_16x16x32_bf16 v[68:71], v[188:191], v[238:241], v[68:71]
	v_mfma_f32_16x16x32_bf16 v[64:67], v[196:199], v[238:241], v[64:67]
	s_setprio 0
	s_barrier
; #define PG8_STAGE(bufoff, gbase, voff) do { _Pragma("unroll") for (int _i = 0; _i < 2; ++_i) \
;         __builtin_amdgcn_global_load_lds((const unsigned*)((const char*)(gbase) + (voff)[_i]), (PG8_LAS unsigned*)(lds + (bufoff) + ldsw + _i * 8192), 16, 0, 0); } while (0)
; #define PG8_WAIT_V(n) asm volatile("s_waitcnt vmcnt(" #n ")" ::: "memory")
; #define PG8_WAIT_L(n) asm volatile("s_waitcnt lgkmcnt(" #n ")" ::: "memory")
; #define PG8_BAR __builtin_amdgcn_s_barrier()
; #define PG8_SCHED __builtin_amdgcn_sched_barrier(0)
; template <class Epi, class Sched, bool ALIGN_EPI = false, bool SP2 = false, bool F8 = false>
; __device__ __forceinline__ void gemm_phase(PG8_LAS unsigned char* lds, const Gemm g, const Sched& S, const Epi& E) {
;     ...
;         for (int t = 0; t < nt; t += 2) {
;             const bool last = (t == nt - 2);
;             const char* a1 = cA + (size_t)(t + 1) * kstep;
;             const char* a2 = last ? nA : cA + (size_t)(t + 2) * kstep; const char* b2 = last ? nB : cB + (size_t)(t + 2) * kstep;
;             const char* a3 = a2 + kstep; const char* b3 = b2 + kstep;
;             if (last && has_next) S.a_ready(nxt);
;             if constexpr (SP2) {
;             PG8_LDB(B0, 0, 0); PG8_LDB(B1, 0, 1); PG8_SCHED; PG8_LDA(At, 0, 0); PG8_STAGE(PG8_SA(1, 1), a1 + hstep, voffA);
;             PG8_WAIT_V(8); PG8_WAIT_L(0); PG8_BAR; PG8_MMA(0, 0, At, B0); PG8_MMA(0, 1, At, B1); PG8_BAR; PG8_SCHED;
;             PG8_LDA(At, 0, 1); PG8_STAGE(PG8_SB(0, 0), b2, voffB); PG8_STAGE(PG8_SB(0, 1), b2 + hstep, voffB); PG8_STAGE(PG8_SA(0, 0), a2, voffA);
;             PG8_WAIT_V(8); PG8_WAIT_L(0); PG8_BAR; PG8_MMA(1, 0, At, B0); PG8_MMA(1, 1, At, B1); PG8_BAR; PG8_SCHED;
;             PG8_LDB(B0, 1, 0); PG8_LDB(B1, 1, 1); PG8_SCHED; PG8_LDA(At, 1, 0); PG8_STAGE(PG8_SA(0, 1), a2 + hstep, voffA);
;             PG8_WAIT_V(8); PG8_WAIT_L(0); PG8_BAR; PG8_MMA(0, 0, At, B0); PG8_MMA(0, 1, At, B1); PG8_BAR; PG8_SCHED;
;             PG8_LDA(At, 1, 1); PG8_STAGE(PG8_SB(1, 0), b3, voffB); PG8_STAGE(PG8_SB(1, 1), b3 + hstep, voffB); PG8_STAGE(PG8_SA(1, 0), a3, voffA);
;             PG8_WAIT_V(8); PG8_WAIT_L(0); PG8_BAR; PG8_MMA(1, 0, At, B0); PG8_MMA(1, 1, At, B1); PG8_BAR; PG8_SCHED;
	s_add_i32 s16, s53, s34
	v_lshl_add_u64 v[146:147], v[146:147], 0, s[14:15]
	s_mov_b32 m0, s16
	ds_read_b128 v[200:203], v151 offset:49152
	ds_read_b128 v[214:217], v151 offset:50176
	ds_read_b128 v[218:221], v151 offset:51200
	ds_read_b128 v[222:225], v151 offset:52224
	ds_read_b128 v[226:229], v151 offset:53248
	ds_read_b128 v[230:233], v151 offset:54272
	ds_read_b128 v[234:237], v151 offset:55296
	ds_read_b128 v[238:241], v151 offset:56320
	global_load_lds_dwordx4 v[146:147], off
	s_add_i32 m0, s16, 0x2000
	s_add_u32 s10, s10, 0x80080
	v_lshl_add_u64 v[146:147], v[162:163], 0, s[14:15]
	s_addc_u32 s11, s11, 0
	s_add_i32 s16, s56, s34
	global_load_lds_dwordx4 v[146:147], off
	v_lshl_add_u64 v[146:147], s[10:11], 0, v[160:161]
	s_mov_b32 m0, s16
	s_nop 0
	global_load_lds_dwordx4 v[146:147], off
	v_lshl_add_u64 v[146:147], s[10:11], 0, v[128:129]
	s_add_i32 m0, s16, 0x2000
	s_nop 0
	global_load_lds_dwordx4 v[146:147], off
	v_lshl_add_u64 v[146:147], v[242:243], 0, s[14:15]
	s_mov_b32 m0, s55
	s_nop 0
	global_load_lds_dwordx4 v[146:147], off
	v_lshl_add_u64 v[146:147], v[244:245], 0, s[14:15]
	s_mov_b32 m0, s58
	s_nop 0
	global_load_lds_dwordx4 v[146:147], off
	s_waitcnt vmcnt(8)
	s_waitcnt lgkmcnt(0)
	s_barrier
	s_setprio 1
	s_waitcnt lgkmcnt(0)
	v_mfma_f32_16x16x32_bf16 v[60:63], v[138:141], v[200:203], v[60:63]
	v_mfma_f32_16x16x32_bf16 v[56:59], v[152:155], v[200:203], v[56:59]
	v_mfma_f32_16x16x32_bf16 v[44:47], v[138:141], v[218:221], v[44:47]
	v_mfma_f32_16x16x32_bf16 v[40:43], v[152:155], v[218:221], v[40:43]
	v_mfma_f32_16x16x32_bf16 v[28:31], v[138:141], v[226:229], v[28:31]
	v_mfma_f32_16x16x32_bf16 v[24:27], v[152:155], v[226:229], v[24:27]
	v_mfma_f32_16x16x32_bf16 v[12:15], v[138:141], v[234:237], v[12:15]
	v_mfma_f32_16x16x32_bf16 v[8:11], v[152:155], v[234:237], v[8:11]
	v_mfma_f32_16x16x32_bf16 v[60:63], v[142:145], v[214:217], v[60:63]
	v_mfma_f32_16x16x32_bf16 v[56:59], v[156:159], v[214:217], v[56:59]
	v_mfma_f32_16x16x32_bf16 v[44:47], v[142:145], v[222:225], v[44:47]
	v_mfma_f32_16x16x32_bf16 v[40:43], v[156:159], v[222:225], v[40:43]
	v_mfma_f32_16x16x32_bf16 v[28:31], v[142:145], v[230:233], v[28:31]
	v_mfma_f32_16x16x32_bf16 v[24:27], v[156:159], v[230:233], v[24:27]
	v_mfma_f32_16x16x32_bf16 v[12:15], v[142:145], v[238:241], v[12:15]
	v_mfma_f32_16x16x32_bf16 v[8:11], v[156:159], v[238:241], v[8:11]
	v_mfma_f32_16x16x32_bf16 v[52:55], v[184:187], v[200:203], v[52:55]
	v_mfma_f32_16x16x32_bf16 v[48:51], v[192:195], v[200:203], v[48:51]
	v_mfma_f32_16x16x32_bf16 v[36:39], v[184:187], v[218:221], v[36:39]
	v_mfma_f32_16x16x32_bf16 v[32:35], v[192:195], v[218:221], v[32:35]
	v_mfma_f32_16x16x32_bf16 v[20:23], v[184:187], v[226:229], v[20:23]
	v_mfma_f32_16x16x32_bf16 v[16:19], v[192:195], v[226:229], v[16:19]
	v_mfma_f32_16x16x32_bf16 v[4:7], v[184:187], v[234:237], v[4:7]
	v_mfma_f32_16x16x32_bf16 v[0:3], v[192:195], v[234:237], v[0:3]
	v_mfma_f32_16x16x32_bf16 v[52:55], v[188:191], v[214:217], v[52:55]
	v_mfma_f32_16x16x32_bf16 v[48:51], v[196:199], v[214:217], v[48:51]
	v_mfma_f32_16x16x32_bf16 v[36:39], v[188:191], v[222:225], v[36:39]
	v_mfma_f32_16x16x32_bf16 v[32:35], v[196:199], v[222:225], v[32:35]
	v_mfma_f32_16x16x32_bf16 v[20:23], v[188:191], v[230:233], v[20:23]
	v_mfma_f32_16x16x32_bf16 v[16:19], v[196:199], v[230:233], v[16:19]
	v_mfma_f32_16x16x32_bf16 v[4:7], v[188:191], v[238:241], v[4:7]
	v_mfma_f32_16x16x32_bf16 v[0:3], v[196:199], v[238:241], v[0:3]
	s_setprio 0
	s_barrier
	s_add_i32 s52, s52, 2
	s_add_u32 s0, s0, 0x100
	s_addc_u32 s1, s1, 0
	s_add_u32 s45, s45, 0x100
	s_addc_u32 s47, s47, 0
	s_cmp_gt_u32 s52, 29
	s_cbranch_scc0 .LBB0_32
	s_branch .Lgk_after_32
.LBB0_32:
	s_add_u32 s10, s0, 0xfff80080
	s_addc_u32 s11, s1, -1
	s_add_i32 s53, 0, 0x10000
	s_cmp_eq_u32 s52, 28
	s_cselect_b32 s17, s19, s11
	s_cselect_b32 s16, s23, s10
	v_add_u32_e32 v146, s53, v149
	s_cselect_b32 s11, s28, s47
	s_cselect_b32 s10, s29, s45
	s_add_i32 s56, 0, 0x14000
	ds_read_b128 v[138:141], v146
	ds_read_b128 v[142:145], v146 offset:1024
	ds_read_b128 v[152:155], v146 offset:2048
	ds_read_b128 v[156:159], v146 offset:3072
	v_add_u32_e32 v146, s56, v149
	ds_read_b128 v[184:187], v146
	ds_read_b128 v[188:191], v146 offset:1024
	ds_read_b128 v[192:195], v146 offset:2048
	ds_read_b128 v[196:199], v146 offset:3072
	v_lshl_add_u64 v[146:147], s[0:1], 0, v[134:135]
	s_add_i32 m0, s35, 0xc000
	ds_read_b128 v[200:203], v151
	ds_read_b128 v[214:217], v151 offset:1024
	ds_read_b128 v[218:221], v151 offset:2048
	ds_read_b128 v[222:225], v151 offset:3072
	ds_read_b128 v[226:229], v151 offset:4096
	ds_read_b128 v[230:233], v151 offset:5120
	ds_read_b128 v[234:237], v151 offset:6144
	ds_read_b128 v[238:241], v151 offset:7168
	global_load_lds_dwordx4 v[146:147], off
	v_lshl_add_u64 v[146:147], s[0:1], 0, v[136:137]
	s_add_i32 m0, s35, 0xe000
	s_nop 0
	global_load_lds_dwordx4 v[146:147], off
	s_waitcnt vmcnt(8)
	s_waitcnt lgkmcnt(0)
	s_barrier
; #define PG8_STAGE(bufoff, gbase, voff) do { _Pragma("unroll") for (int _i = 0; _i < 2; ++_i) \
;         __builtin_amdgcn_global_load_lds((const unsigned*)((const char*)(gbase) + (voff)[_i]), (PG8_LAS unsigned*)(lds + (bufoff) + ldsw + _i * 8192), 16, 0, 0); } while (0)
; #define PG8_WAIT_V(n) asm volatile("s_waitcnt vmcnt(" #n ")" ::: "memory")
; #define PG8_WAIT_L(n) asm volatile("s_waitcnt lgkmcnt(" #n ")" ::: "memory")
; #define PG8_BAR __builtin_amdgcn_s_barrier()
; #define PG8_SCHED __builtin_amdgcn_sched_barrier(0)
; template <class Epi, class Sched, bool ALIGN_EPI = false, bool SP2 = false, bool F8 = false>
; __device__ __forceinline__ void gemm_phase(PG8_LAS unsigned char* lds, const Gemm g, const Sched& S, const Epi& E) {
;     ...
;             PG8_LDB(B0, 0, 0); PG8_LDB(B1, 0, 1); PG8_SCHED; PG8_LDA(At, 0, 0); PG8_STAGE(PG8_SA(1, 1), a1 + hstep, voffA);
;             PG8_WAIT_V(8); PG8_WAIT_L(0); PG8_BAR; PG8_MMA(0, 0, At, B0); PG8_MMA(0, 1, At, B1); PG8_BAR; PG8_SCHED;
;             PG8_LDA(At, 0, 1); PG8_STAGE(PG8_SB(0, 0), b2, voffB); PG8_STAGE(PG8_SB(0, 1), b2 + hstep, voffB); PG8_STAGE(PG8_SA(0, 0), a2, voffA);
;             PG8_WAIT_V(8); PG8_WAIT_L(0); PG8_BAR; PG8_MMA(1, 0, At, B0); PG8_MMA(1, 1, At, B1); PG8_BAR; PG8_SCHED;
;             PG8_LDB(B0, 1, 0); PG8_LDB(B1, 1, 1); PG8_SCHED; PG8_LDA(At, 1, 0); PG8_STAGE(PG8_SA(0, 1), a2 + hstep, voffA);
;             PG8_WAIT_V(8); PG8_WAIT_L(0); PG8_BAR; PG8_MMA(0, 0, At, B0); PG8_MMA(0, 1, At, B1); PG8_BAR; PG8_SCHED;
;             PG8_LDA(At, 1, 1); PG8_STAGE(PG8_SB(1, 0), b3, voffB); PG8_STAGE(PG8_SB(1, 1), b3 + hstep, voffB); PG8_STAGE(PG8_SA(1, 0), a3, voffA);
;             PG8_WAIT_V(8); PG8_WAIT_L(0); PG8_BAR; PG8_MMA(1, 0, At, B0); PG8_MMA(1, 1, At, B1); PG8_BAR; PG8_SCHED;
	s_setprio 1
	s_waitcnt lgkmcnt(0)
	v_mfma_f32_16x16x32_bf16 v[124:127], v[138:141], v[200:203], v[124:127]
	v_mfma_f32_16x16x32_bf16 v[120:123], v[152:155], v[200:203], v[120:123]
	v_mfma_f32_16x16x32_bf16 v[108:111], v[138:141], v[218:221], v[108:111]
	v_mfma_f32_16x16x32_bf16 v[104:107], v[152:155], v[218:221], v[104:107]
	v_mfma_f32_16x16x32_bf16 v[92:95], v[138:141], v[226:229], v[92:95]
	v_mfma_f32_16x16x32_bf16 v[88:91], v[152:155], v[226:229], v[88:91]
	v_mfma_f32_16x16x32_bf16 v[76:79], v[138:141], v[234:237], v[76:79]
	v_mfma_f32_16x16x32_bf16 v[72:75], v[152:155], v[234:237], v[72:75]
	v_mfma_f32_16x16x32_bf16 v[124:127], v[142:145], v[214:217], v[124:127]
	v_mfma_f32_16x16x32_bf16 v[120:123], v[156:159], v[214:217], v[120:123]
	v_mfma_f32_16x16x32_bf16 v[108:111], v[142:145], v[222:225], v[108:111]
	v_mfma_f32_16x16x32_bf16 v[104:107], v[156:159], v[222:225], v[104:107]
	v_mfma_f32_16x16x32_bf16 v[92:95], v[142:145], v[230:233], v[92:95]
	v_mfma_f32_16x16x32_bf16 v[88:91], v[156:159], v[230:233], v[88:91]
	v_mfma_f32_16x16x32_bf16 v[76:79], v[142:145], v[238:241], v[76:79]
	v_mfma_f32_16x16x32_bf16 v[72:75], v[156:159], v[238:241], v[72:75]
	v_mfma_f32_16x16x32_bf16 v[116:119], v[184:187], v[200:203], v[116:119]
	v_mfma_f32_16x16x32_bf16 v[112:115], v[192:195], v[200:203], v[112:115]
	v_mfma_f32_16x16x32_bf16 v[100:103], v[184:187], v[218:221], v[100:103]
	v_mfma_f32_16x16x32_bf16 v[96:99], v[192:195], v[218:221], v[96:99]
	v_mfma_f32_16x16x32_bf16 v[84:87], v[184:187], v[226:229], v[84:87]
	v_mfma_f32_16x16x32_bf16 v[80:83], v[192:195], v[226:229], v[80:83]
	v_mfma_f32_16x16x32_bf16 v[68:71], v[184:187], v[234:237], v[68:71]
	v_mfma_f32_16x16x32_bf16 v[64:67], v[192:195], v[234:237], v[64:67]
	v_mfma_f32_16x16x32_bf16 v[116:119], v[188:191], v[214:217], v[116:119]
	v_mfma_f32_16x16x32_bf16 v[112:115], v[196:199], v[214:217], v[112:115]
	v_mfma_f32_16x16x32_bf16 v[100:103], v[188:191], v[222:225], v[100:103]
	v_mfma_f32_16x16x32_bf16 v[96:99], v[196:199], v[222:225], v[96:99]
	v_mfma_f32_16x16x32_bf16 v[84:87], v[188:191], v[230:233], v[84:87]
	v_mfma_f32_16x16x32_bf16 v[80:83], v[196:199], v[230:233], v[80:83]
	v_mfma_f32_16x16x32_bf16 v[68:71], v[188:191], v[238:241], v[68:71]
	v_mfma_f32_16x16x32_bf16 v[64:67], v[196:199], v[238:241], v[64:67]
	s_setprio 0
	s_barrier
	s_add_i32 s53, s53, s34
	v_lshl_add_u64 v[146:147], s[10:11], 0, v[160:161]
	s_mov_b32 m0, s53
	ds_read_b128 v[200:203], v151 offset:16384
	ds_read_b128 v[214:217], v151 offset:17408
	ds_read_b128 v[218:221], v151 offset:18432
	ds_read_b128 v[222:225], v151 offset:19456
	ds_read_b128 v[226:229], v151 offset:20480
	ds_read_b128 v[230:233], v151 offset:21504
	ds_read_b128 v[234:237], v151 offset:22528
	ds_read_b128 v[238:241], v151 offset:23552
	global_load_lds_dwordx4 v[146:147], off
	s_add_i32 m0, s53, 0x2000
	s_add_u32 s60, s10, 0x80000
	v_lshl_add_u64 v[162:163], s[10:11], 0, v[128:129]
	s_addc_u32 s61, s11, 0
	s_add_i32 s53, s56, s34
	global_load_lds_dwordx4 v[162:163], off
	v_lshl_add_u64 v[242:243], s[60:61], 0, v[160:161]
	s_mov_b32 m0, s53
	v_lshl_add_u64 v[244:245], s[16:17], 0, v[130:131]
	global_load_lds_dwordx4 v[242:243], off
	v_lshl_add_u64 v[242:243], s[60:61], 0, v[128:129]
	s_add_i32 m0, s53, 0x2000
	s_nop 0
	global_load_lds_dwordx4 v[242:243], off
	v_lshl_add_u64 v[242:243], s[16:17], 0, v[132:133]
	s_mov_b32 m0, s35
	s_nop 0
	global_load_lds_dwordx4 v[242:243], off
	s_mov_b32 m0, s36
	s_nop 0
	global_load_lds_dwordx4 v[244:245], off
	s_waitcnt vmcnt(8)
	s_waitcnt lgkmcnt(0)
	s_barrier
	s_setprio 1
	s_waitcnt lgkmcnt(0)
	v_mfma_f32_16x16x32_bf16 v[60:63], v[138:141], v[200:203], v[60:63]
	v_mfma_f32_16x16x32_bf16 v[56:59], v[152:155], v[200:203], v[56:59]
	v_mfma_f32_16x16x32_bf16 v[44:47], v[138:141], v[218:221], v[44:47]
	v_mfma_f32_16x16x32_bf16 v[40:43], v[152:155], v[218:221], v[40:43]
	v_mfma_f32_16x16x32_bf16 v[28:31], v[138:141], v[226:229], v[28:31]
	v_mfma_f32_16x16x32_bf16 v[24:27], v[152:155], v[226:229], v[24:27]
	v_mfma_f32_16x16x32_bf16 v[12:15], v[138:141], v[234:237], v[12:15]
	v_mfma_f32_16x16x32_bf16 v[8:11], v[152:155], v[234:237], v[8:11]
	v_mfma_f32_16x16x32_bf16 v[60:63], v[142:145], v[214:217], v[60:63]
	v_mfma_f32_16x16x32_bf16 v[56:59], v[156:159], v[214:217], v[56:59]
	v_mfma_f32_16x16x32_bf16 v[44:47], v[142:145], v[222:225], v[44:47]
	v_mfma_f32_16x16x32_bf16 v[40:43], v[156:159], v[222:225], v[40:43]
	v_mfma_f32_16x16x32_bf16 v[28:31], v[142:145], v[230:233], v[28:31]
	v_mfma_f32_16x16x32_bf16 v[24:27], v[156:159], v[230:233], v[24:27]
	v_mfma_f32_16x16x32_bf16 v[12:15], v[142:145], v[238:241], v[12:15]
	v_mfma_f32_16x16x32_bf16 v[8:11], v[156:159], v[238:241], v[8:11]
	v_mfma_f32_16x16x32_bf16 v[52:55], v[184:187], v[200:203], v[52:55]
	v_mfma_f32_16x16x32_bf16 v[48:51], v[192:195], v[200:203], v[48:51]
	v_mfma_f32_16x16x32_bf16 v[36:39], v[184:187], v[218:221], v[36:39]
	v_mfma_f32_16x16x32_bf16 v[32:35], v[192:195], v[218:221], v[32:35]
	v_mfma_f32_16x16x32_bf16 v[20:23], v[184:187], v[226:229], v[20:23]
	v_mfma_f32_16x16x32_bf16 v[16:19], v[192:195], v[226:229], v[16:19]
	v_mfma_f32_16x16x32_bf16 v[4:7], v[184:187], v[234:237], v[4:7]
	v_mfma_f32_16x16x32_bf16 v[0:3], v[192:195], v[234:237], v[0:3]
	v_mfma_f32_16x16x32_bf16 v[52:55], v[188:191], v[214:217], v[52:55]
	v_mfma_f32_16x16x32_bf16 v[48:51], v[196:199], v[214:217], v[48:51]
	v_mfma_f32_16x16x32_bf16 v[36:39], v[188:191], v[222:225], v[36:39]
	v_mfma_f32_16x16x32_bf16 v[32:35], v[196:199], v[222:225], v[32:35]
	v_mfma_f32_16x16x32_bf16 v[20:23], v[188:191], v[230:233], v[20:23]
	v_mfma_f32_16x16x32_bf16 v[16:19], v[196:199], v[230:233], v[16:19]
	v_mfma_f32_16x16x32_bf16 v[4:7], v[188:191], v[238:241], v[4:7]
	v_mfma_f32_16x16x32_bf16 v[0:3], v[196:199], v[238:241], v[0:3]
	s_setprio 0
	s_barrier
; #define PG8_STAGE(bufoff, gbase, voff) do { _Pragma("unroll") for (int _i = 0; _i < 2; ++_i) \
;         __builtin_amdgcn_global_load_lds((const unsigned*)((const char*)(gbase) + (voff)[_i]), (PG8_LAS unsigned*)(lds + (bufoff) + ldsw + _i * 8192), 16, 0, 0); } while (0)
; #define PG8_WAIT_V(n) asm volatile("s_waitcnt vmcnt(" #n ")" ::: "memory")
; #define PG8_WAIT_L(n) asm volatile("s_waitcnt lgkmcnt(" #n ")" ::: "memory")
; #define PG8_BAR __builtin_amdgcn_s_barrier()
; #define PG8_SCHED __builtin_amdgcn_sched_barrier(0)
; template <class Epi, class Sched, bool ALIGN_EPI = false, bool SP2 = false, bool F8 = false>
; __device__ __forceinline__ void gemm_phase(PG8_LAS unsigned char* lds, const Gemm g, const Sched& S, const Epi& E) {
;     ...
;             PG8_LDB(B0, 1, 0); PG8_LDB(B1, 1, 1); PG8_SCHED; PG8_LDA(At, 1, 0); PG8_STAGE(PG8_SA(0, 1), a2 + hstep, voffA);
;             PG8_WAIT_V(8); PG8_WAIT_L(0); PG8_BAR; PG8_MMA(0, 0, At, B0); PG8_MMA(0, 1, At, B1); PG8_BAR; PG8_SCHED;
	s_add_i32 s53, 0, 0x18000
	s_add_i32 s56, 0, 0x1c000
	v_add_u32_e32 v156, s53, v149
	v_add_u32_e32 v196, s56, v149
	ds_read_b128 v[138:141], v156
	ds_read_b128 v[142:145], v156 offset:1024
	ds_read_b128 v[152:155], v156 offset:2048
	ds_read_b128 v[156:159], v156 offset:3072
	ds_read_b128 v[184:187], v196
	ds_read_b128 v[188:191], v196 offset:1024
	ds_read_b128 v[192:195], v196 offset:2048
	ds_read_b128 v[196:199], v196 offset:3072
	s_add_u32 s16, s16, 0x80000
	s_addc_u32 s17, s17, 0
	s_mov_b32 m0, s37
	v_lshl_add_u64 v[246:247], s[16:17], 0, v[132:133]
	ds_read_b128 v[200:203], v151 offset:32768
	ds_read_b128 v[214:217], v151 offset:33792
	ds_read_b128 v[218:221], v151 offset:34816
	ds_read_b128 v[222:225], v151 offset:35840
	ds_read_b128 v[226:229], v151 offset:36864
	ds_read_b128 v[230:233], v151 offset:37888
	ds_read_b128 v[234:237], v151 offset:38912
	ds_read_b128 v[238:241], v151 offset:39936
	global_load_lds_dwordx4 v[246:247], off
	v_lshl_add_u64 v[246:247], s[16:17], 0, v[130:131]
	s_mov_b32 m0, s54
	s_nop 0
	global_load_lds_dwordx4 v[246:247], off
	s_waitcnt vmcnt(8)
	s_waitcnt lgkmcnt(0)
	s_barrier
	s_setprio 1
	s_waitcnt lgkmcnt(0)
	v_mfma_f32_16x16x32_bf16 v[124:127], v[138:141], v[200:203], v[124:127]
	v_mfma_f32_16x16x32_bf16 v[120:123], v[152:155], v[200:203], v[120:123]
	v_mfma_f32_16x16x32_bf16 v[108:111], v[138:141], v[218:221], v[108:111]
	v_mfma_f32_16x16x32_bf16 v[104:107], v[152:155], v[218:221], v[104:107]
	v_mfma_f32_16x16x32_bf16 v[92:95], v[138:141], v[226:229], v[92:95]
	v_mfma_f32_16x16x32_bf16 v[88:91], v[152:155], v[226:229], v[88:91]
	v_mfma_f32_16x16x32_bf16 v[76:79], v[138:141], v[234:237], v[76:79]
	v_mfma_f32_16x16x32_bf16 v[72:75], v[152:155], v[234:237], v[72:75]
	v_mfma_f32_16x16x32_bf16 v[124:127], v[142:145], v[214:217], v[124:127]
	v_mfma_f32_16x16x32_bf16 v[120:123], v[156:159], v[214:217], v[120:123]
	v_mfma_f32_16x16x32_bf16 v[108:111], v[142:145], v[222:225], v[108:111]
	v_mfma_f32_16x16x32_bf16 v[104:107], v[156:159], v[222:225], v[104:107]
	v_mfma_f32_16x16x32_bf16 v[92:95], v[142:145], v[230:233], v[92:95]
	v_mfma_f32_16x16x32_bf16 v[88:91], v[156:159], v[230:233], v[88:91]
	v_mfma_f32_16x16x32_bf16 v[76:79], v[142:145], v[238:241], v[76:79]
	v_mfma_f32_16x16x32_bf16 v[72:75], v[156:159], v[238:241], v[72:75]
	v_mfma_f32_16x16x32_bf16 v[116:119], v[184:187], v[200:203], v[116:119]
	v_mfma_f32_16x16x32_bf16 v[112:115], v[192:195], v[200:203], v[112:115]
	v_mfma_f32_16x16x32_bf16 v[100:103], v[184:187], v[218:221], v[100:103]
	v_mfma_f32_16x16x32_bf16 v[96:99], v[192:195], v[218:221], v[96:99]
	v_mfma_f32_16x16x32_bf16 v[84:87], v[184:187], v[226:229], v[84:87]
	v_mfma_f32_16x16x32_bf16 v[80:83], v[192:195], v[226:229], v[80:83]
	v_mfma_f32_16x16x32_bf16 v[68:71], v[184:187], v[234:237], v[68:71]
	v_mfma_f32_16x16x32_bf16 v[64:67], v[192:195], v[234:237], v[64:67]
	v_mfma_f32_16x16x32_bf16 v[116:119], v[188:191], v[214:217], v[116:119]
	v_mfma_f32_16x16x32_bf16 v[112:115], v[196:199], v[214:217], v[112:115]
	v_mfma_f32_16x16x32_bf16 v[100:103], v[188:191], v[222:225], v[100:103]
	v_mfma_f32_16x16x32_bf16 v[96:99], v[196:199], v[222:225], v[96:99]
	v_mfma_f32_16x16x32_bf16 v[84:87], v[188:191], v[230:233], v[84:87]
	v_mfma_f32_16x16x32_bf16 v[80:83], v[196:199], v[230:233], v[80:83]
	v_mfma_f32_16x16x32_bf16 v[68:71], v[188:191], v[238:241], v[68:71]
	v_mfma_f32_16x16x32_bf16 v[64:67], v[196:199], v[238:241], v[64:67]
	s_setprio 0
	s_barrier
; #define PG8_STAGE(bufoff, gbase, voff) do { _Pragma("unroll") for (int _i = 0; _i < 2; ++_i) \
;         __builtin_amdgcn_global_load_lds((const unsigned*)((const char*)(gbase) + (voff)[_i]), (PG8_LAS unsigned*)(lds + (bufoff) + ldsw + _i * 8192), 16, 0, 0); } while (0)
; #define PG8_WAIT_V(n) asm volatile("s_waitcnt vmcnt(" #n ")" ::: "memory")
; #define PG8_WAIT_L(n) asm volatile("s_waitcnt lgkmcnt(" #n ")" ::: "memory")
; #define PG8_BAR __builtin_amdgcn_s_barrier()
; #define PG8_SCHED __builtin_amdgcn_sched_barrier(0)
; template <class Epi, class Sched, bool ALIGN_EPI = false, bool SP2 = false, bool F8 = false>
; __device__ __forceinline__ void gemm_phase(PG8_LAS unsigned char* lds, const Gemm g, const Sched& S, const Epi& E) {
;     ...
;         for (int t = 0; t < nt; t += 2) {
;             const bool last = (t == nt - 2);
;             const char* a1 = cA + (size_t)(t + 1) * kstep;
;             const char* a2 = last ? nA : cA + (size_t)(t + 2) * kstep; const char* b2 = last ? nB : cB + (size_t)(t + 2) * kstep;
;             const char* a3 = a2 + kstep; const char* b3 = b2 + kstep;
;             if (last && has_next) S.a_ready(nxt);
;             if constexpr (SP2) {
;             PG8_LDB(B0, 0, 0); PG8_LDB(B1, 0, 1); PG8_SCHED; PG8_LDA(At, 0, 0); PG8_STAGE(PG8_SA(1, 1), a1 + hstep, voffA);
;             PG8_WAIT_V(8); PG8_WAIT_L(0); PG8_BAR; PG8_MMA(0, 0, At, B0); PG8_MMA(0, 1, At, B1); PG8_BAR; PG8_SCHED;
;             PG8_LDA(At, 0, 1); PG8_STAGE(PG8_SB(0, 0), b2, voffB); PG8_STAGE(PG8_SB(0, 1), b2 + hstep, voffB); PG8_STAGE(PG8_SA(0, 0), a2, voffA);
;             PG8_WAIT_V(8); PG8_WAIT_L(0); PG8_BAR; PG8_MMA(1, 0, At, B0); PG8_MMA(1, 1, At, B1); PG8_BAR; PG8_SCHED;
;             PG8_LDB(B0, 1, 0); PG8_LDB(B1, 1, 1); PG8_SCHED; PG8_LDA(At, 1, 0); PG8_STAGE(PG8_SA(0, 1), a2 + hstep, voffA);
;             PG8_WAIT_V(8); PG8_WAIT_L(0); PG8_BAR; PG8_MMA(0, 0, At, B0); PG8_MMA(0, 1, At, B1); PG8_BAR; PG8_SCHED;
;             PG8_LDA(At, 1, 1); PG8_STAGE(PG8_SB(1, 0), b3, voffB); PG8_STAGE(PG8_SB(1, 1), b3 + hstep, voffB); PG8_STAGE(PG8_SA(1, 0), a3, voffA);
;             PG8_WAIT_V(8); PG8_WAIT_L(0); PG8_BAR; PG8_MMA(1, 0, At, B0); PG8_MMA(1, 1, At, B1); PG8_BAR; PG8_SCHED;
	s_add_i32 s16, s53, s34
	v_lshl_add_u64 v[146:147], v[146:147], 0, s[14:15]
	s_mov_b32 m0, s16
	ds_read_b128 v[200:203], v151 offset:49152
	ds_read_b128 v[214:217], v151 offset:50176
	ds_read_b128 v[218:221], v151 offset:51200
	ds_read_b128 v[222:225], v151 offset:52224
	ds_read_b128 v[226:229], v151 offset:53248
	ds_read_b128 v[230:233], v151 offset:54272
	ds_read_b128 v[234:237], v151 offset:55296
	ds_read_b128 v[238:241], v151 offset:56320
	global_load_lds_dwordx4 v[146:147], off
	s_add_i32 m0, s16, 0x2000
	s_add_u32 s10, s10, 0x80080
	v_lshl_add_u64 v[146:147], v[162:163], 0, s[14:15]
	s_addc_u32 s11, s11, 0
	s_add_i32 s16, s56, s34
	global_load_lds_dwordx4 v[146:147], off
	v_lshl_add_u64 v[146:147], s[10:11], 0, v[160:161]
	s_mov_b32 m0, s16
	s_nop 0
	global_load_lds_dwordx4 v[146:147], off
	v_lshl_add_u64 v[146:147], s[10:11], 0, v[128:129]
	s_add_i32 m0, s16, 0x2000
	s_nop 0
	global_load_lds_dwordx4 v[146:147], off
	v_lshl_add_u64 v[146:147], v[242:243], 0, s[14:15]
	s_mov_b32 m0, s55
	s_nop 0
	global_load_lds_dwordx4 v[146:147], off
	v_lshl_add_u64 v[146:147], v[244:245], 0, s[14:15]
	s_mov_b32 m0, s58
	s_nop 0
	global_load_lds_dwordx4 v[146:147], off
	s_waitcnt vmcnt(8)
	s_waitcnt lgkmcnt(0)
	s_barrier
	s_setprio 1
	s_waitcnt lgkmcnt(0)
	v_mfma_f32_16x16x32_bf16 v[60:63], v[138:141], v[200:203], v[60:63]
	v_mfma_f32_16x16x32_bf16 v[56:59], v[152:155], v[200:203], v[56:59]
	v_mfma_f32_16x16x32_bf16 v[44:47], v[138:141], v[218:221], v[44:47]
	v_mfma_f32_16x16x32_bf16 v[40:43], v[152:155], v[218:221], v[40:43]
	v_mfma_f32_16x16x32_bf16 v[28:31], v[138:141], v[226:229], v[28:31]
	v_mfma_f32_16x16x32_bf16 v[24:27], v[152:155], v[226:229], v[24:27]
	v_mfma_f32_16x16x32_bf16 v[12:15], v[138:141], v[234:237], v[12:15]
	v_mfma_f32_16x16x32_bf16 v[8:11], v[152:155], v[234:237], v[8:11]
	v_mfma_f32_16x16x32_bf16 v[60:63], v[142:145], v[214:217], v[60:63]
	v_mfma_f32_16x16x32_bf16 v[56:59], v[156:159], v[214:217], v[56:59]
	v_mfma_f32_16x16x32_bf16 v[44:47], v[142:145], v[222:225], v[44:47]
	v_mfma_f32_16x16x32_bf16 v[40:43], v[156:159], v[222:225], v[40:43]
	v_mfma_f32_16x16x32_bf16 v[28:31], v[142:145], v[230:233], v[28:31]
	v_mfma_f32_16x16x32_bf16 v[24:27], v[156:159], v[230:233], v[24:27]
	v_mfma_f32_16x16x32_bf16 v[12:15], v[142:145], v[238:241], v[12:15]
	v_mfma_f32_16x16x32_bf16 v[8:11], v[156:159], v[238:241], v[8:11]
	v_mfma_f32_16x16x32_bf16 v[52:55], v[184:187], v[200:203], v[52:55]
	v_mfma_f32_16x16x32_bf16 v[48:51], v[192:195], v[200:203], v[48:51]
	v_mfma_f32_16x16x32_bf16 v[36:39], v[184:187], v[218:221], v[36:39]
	v_mfma_f32_16x16x32_bf16 v[32:35], v[192:195], v[218:221], v[32:35]
	v_mfma_f32_16x16x32_bf16 v[20:23], v[184:187], v[226:229], v[20:23]
	v_mfma_f32_16x16x32_bf16 v[16:19], v[192:195], v[226:229], v[16:19]
	v_mfma_f32_16x16x32_bf16 v[4:7], v[184:187], v[234:237], v[4:7]
	v_mfma_f32_16x16x32_bf16 v[0:3], v[192:195], v[234:237], v[0:3]
	v_mfma_f32_16x16x32_bf16 v[52:55], v[188:191], v[214:217], v[52:55]
	v_mfma_f32_16x16x32_bf16 v[48:51], v[196:199], v[214:217], v[48:51]
	v_mfma_f32_16x16x32_bf16 v[36:39], v[188:191], v[222:225], v[36:39]
	v_mfma_f32_16x16x32_bf16 v[32:35], v[196:199], v[222:225], v[32:35]
	v_mfma_f32_16x16x32_bf16 v[20:23], v[188:191], v[230:233], v[20:23]
	v_mfma_f32_16x16x32_bf16 v[16:19], v[196:199], v[230:233], v[16:19]
	v_mfma_f32_16x16x32_bf16 v[4:7], v[188:191], v[238:241], v[4:7]
	v_mfma_f32_16x16x32_bf16 v[0:3], v[196:199], v[238:241], v[0:3]
	s_setprio 0
	s_barrier
	s_add_i32 s52, s52, 2
	s_add_u32 s0, s0, 0x100
	s_addc_u32 s1, s1, 0
	s_add_u32 s45, s45, 0x100
	s_addc_u32 s47, s47, 0
	s_cmp_gt_u32 s52, 29
	s_cbranch_scc0 .LBB0_32

; #define PG8_STAGE(bufoff, gbase, voff) do { _Pragma("unroll") for (int _i = 0; _i < 2; ++_i) \
;         __builtin_amdgcn_global_load_lds((const unsigned*)((const char*)(gbase) + (voff)[_i]), (PG8_LAS unsigned*)(lds + (bufoff) + ldsw + _i * 8192), 16, 0, 0); } while (0)
; #define PG8_WAIT_V(n) asm volatile("s_waitcnt vmcnt(" #n ")" ::: "memory")
; #define PG8_WAIT_L(n) asm volatile("s_waitcnt lgkmcnt(" #n ")" ::: "memory")
; #define PG8_BAR __builtin_amdgcn_s_barrier()
; template <class Epi, class Sched, bool ALIGN_EPI = false, bool SP2 = false, bool F8 = false>
; __device__ __forceinline__ void gemm_phase(PG8_LAS unsigned char* lds, const Gemm g, const Sched& S, const Epi& E) {
;     ...
;         const bool has_next = S.next(ui + 1, nxt);
;         const char* nA = has_next ? (const char*)g.A + (size_t)nxt.pm * tstep : cA; const char* nB = has_next ? (const char*)g.Bt + (size_t)nxt.pn * tstep : cB;
;         for (int t = 0; t < nt; t += 2) {
;             const bool last = (t == nt - 2);
;             const char* a1 = cA + (size_t)(t + 1) * kstep;
;             const char* a2 = last ? nA : cA + (size_t)(t + 2) * kstep; const char* b2 = last ? nB : cB + (size_t)(t + 2) * kstep;
;             const char* a3 = a2 + kstep; const char* b3 = b2 + kstep;
;             if (last && has_next) S.a_ready(nxt);
;             if constexpr (SP2) {
;             PG8_LDB(B0, 0, 0); PG8_LDB(B1, 0, 1); PG8_SCHED; PG8_LDA(At, 0, 0); PG8_STAGE(PG8_SA(1, 1), a1 + hstep, voffA);
;             PG8_WAIT_V(8); PG8_WAIT_L(0); PG8_BAR; PG8_MMA(0, 0, At, B0); PG8_MMA(0, 1, At, B1); PG8_BAR; PG8_SCHED;
;             PG8_LDA(At, 0, 1); PG8_STAGE(PG8_SB(0, 0), b2, voffB); PG8_STAGE(PG8_SB(0, 1), b2 + hstep, voffB); PG8_STAGE(PG8_SA(0, 0), a2, voffA);
;             PG8_WAIT_V(8); PG8_WAIT_L(0); PG8_BAR; PG8_MMA(1, 0, At, B0); PG8_MMA(1, 1, At, B1); PG8_BAR; PG8_SCHED;
;             PG8_LDB(B0, 1, 0); PG8_LDB(B1, 1, 1); PG8_SCHED; PG8_LDA(At, 1, 0); PG8_STAGE(PG8_SA(0, 1), a2 + hstep, voffA);
;             PG8_WAIT_V(8); PG8_WAIT_L(0); PG8_BAR; PG8_MMA(0, 0, At, B0); PG8_MMA(0, 1, At, B1); PG8_BAR; PG8_SCHED;
;             PG8_LDA(At, 1, 1); PG8_STAGE(PG8_SB(1, 0), b3, voffB); PG8_STAGE(PG8_SB(1, 1), b3 + hstep, voffB); PG8_STAGE(PG8_SA(1, 0), a3, voffA);
;             PG8_WAIT_V(8); PG8_WAIT_L(0); PG8_BAR; PG8_MMA(1, 0, At, B0); PG8_MMA(1, 1, At, B1); PG8_BAR; PG8_SCHED;
.LBB0_58:
	s_ashr_i32 s49, s48, 31
	s_lshl_b64 s[8:9], s[48:49], 20
	s_add_u32 s50, s26, s8
	s_addc_u32 s51, s27, s9
	s_and_b64 s[8:9], s[40:41], exec
	s_cselect_b32 s1, s51, s37
	s_cselect_b32 s8, s50, s36
	s_ashr_i32 s47, s46, 31
	s_lshl_b64 s[28:29], s[46:47], 20
	s_add_u32 s54, s13, s28
	s_addc_u32 s55, s22, s29
	s_and_b64 s[28:29], s[40:41], exec
	s_cselect_b32 s9, s55, s59
	s_cselect_b32 s11, s54, s58
	s_add_u32 s36, s36, 0x80080
	s_addc_u32 s37, s37, 0
	s_add_u32 s19, s58, 0x100
	s_addc_u32 s23, s59, 0
	s_mov_b32 s28, -2
	s_add_u32 s29, s36, 0xfff80080
	s_addc_u32 s34, s37, -1
	s_add_i32 s35, 0, 0x10000
	s_cmp_eq_u32 s28, 28
	s_cselect_b32 s61, s1, s34
	s_cselect_b32 s60, s8, s29
	s_cselect_b32 s59, s9, s23
	s_cselect_b32 s58, s11, s19
	s_add_i32 s29, 0, 0x14000
	v_add_u32_e32 v154, s35, v151
	v_add_u32_e32 v158, s29, v151
	ds_read_b128 v[138:141], v154
	ds_read_b128 v[142:145], v154 offset:1024
	ds_read_b128 v[146:149], v154 offset:2048
	ds_read_b128 v[154:157], v154 offset:3072
	ds_read_b128 v[184:187], v158
	ds_read_b128 v[188:191], v158 offset:1024
	ds_read_b128 v[192:195], v158 offset:2048
	ds_read_b128 v[196:199], v158 offset:3072
	v_lshl_add_u64 v[158:159], s[36:37], 0, v[134:135]
	s_add_i32 m0, s17, 0xc000
	ds_read_b128 v[200:203], v153
	ds_read_b128 v[214:217], v153 offset:1024
	ds_read_b128 v[218:221], v153 offset:2048
	ds_read_b128 v[222:225], v153 offset:3072
	ds_read_b128 v[226:229], v153 offset:4096
	ds_read_b128 v[230:233], v153 offset:5120
	ds_read_b128 v[234:237], v153 offset:6144
	ds_read_b128 v[238:241], v153 offset:7168
	global_load_lds_dwordx4 v[158:159], off
	v_lshl_add_u64 v[158:159], s[36:37], 0, v[136:137]
	s_add_i32 m0, s17, 0xe000
	s_nop 0
	global_load_lds_dwordx4 v[158:159], off
	s_waitcnt vmcnt(8)
	s_waitcnt lgkmcnt(0)
	s_barrier
	s_setprio 1
	s_waitcnt lgkmcnt(0)
	v_mfma_f32_16x16x32_bf16 v[124:127], v[138:141], v[200:203], 0
	v_mfma_f32_16x16x32_bf16 v[120:123], v[146:149], v[200:203], 0
	v_mfma_f32_16x16x32_bf16 v[108:111], v[138:141], v[218:221], 0
	v_mfma_f32_16x16x32_bf16 v[104:107], v[146:149], v[218:221], 0
	v_mfma_f32_16x16x32_bf16 v[92:95], v[138:141], v[226:229], 0
	v_mfma_f32_16x16x32_bf16 v[88:91], v[146:149], v[226:229], 0
	v_mfma_f32_16x16x32_bf16 v[76:79], v[138:141], v[234:237], 0
	v_mfma_f32_16x16x32_bf16 v[72:75], v[146:149], v[234:237], 0
	v_mfma_f32_16x16x32_bf16 v[124:127], v[142:145], v[214:217], v[124:127]
	v_mfma_f32_16x16x32_bf16 v[120:123], v[154:157], v[214:217], v[120:123]
	v_mfma_f32_16x16x32_bf16 v[108:111], v[142:145], v[222:225], v[108:111]
	v_mfma_f32_16x16x32_bf16 v[104:107], v[154:157], v[222:225], v[104:107]
	v_mfma_f32_16x16x32_bf16 v[92:95], v[142:145], v[230:233], v[92:95]
	v_mfma_f32_16x16x32_bf16 v[88:91], v[154:157], v[230:233], v[88:91]
	v_mfma_f32_16x16x32_bf16 v[76:79], v[142:145], v[238:241], v[76:79]
	v_mfma_f32_16x16x32_bf16 v[72:75], v[154:157], v[238:241], v[72:75]
	v_mfma_f32_16x16x32_bf16 v[116:119], v[184:187], v[200:203], 0
	v_mfma_f32_16x16x32_bf16 v[112:115], v[192:195], v[200:203], 0
	v_mfma_f32_16x16x32_bf16 v[100:103], v[184:187], v[218:221], 0
	v_mfma_f32_16x16x32_bf16 v[96:99], v[192:195], v[218:221], 0
	v_mfma_f32_16x16x32_bf16 v[84:87], v[184:187], v[226:229], 0
	v_mfma_f32_16x16x32_bf16 v[80:83], v[192:195], v[226:229], 0
	v_mfma_f32_16x16x32_bf16 v[68:71], v[184:187], v[234:237], 0
	v_mfma_f32_16x16x32_bf16 v[64:67], v[192:195], v[234:237], 0
	v_mfma_f32_16x16x32_bf16 v[116:119], v[188:191], v[214:217], v[116:119]
	v_mfma_f32_16x16x32_bf16 v[112:115], v[196:199], v[214:217], v[112:115]
	v_mfma_f32_16x16x32_bf16 v[100:103], v[188:191], v[222:225], v[100:103]
	v_mfma_f32_16x16x32_bf16 v[96:99], v[196:199], v[222:225], v[96:99]
	v_mfma_f32_16x16x32_bf16 v[84:87], v[188:191], v[230:233], v[84:87]
	v_mfma_f32_16x16x32_bf16 v[80:83], v[196:199], v[230:233], v[80:83]
	v_mfma_f32_16x16x32_bf16 v[68:71], v[188:191], v[238:241], v[68:71]
	v_mfma_f32_16x16x32_bf16 v[64:67], v[196:199], v[238:241], v[64:67]
	s_setprio 0
	s_barrier
	s_add_i32 s34, s35, s64
	v_lshl_add_u64 v[158:159], s[58:59], 0, v[160:161]
	s_mov_b32 m0, s34
	ds_read_b128 v[200:203], v153 offset:16384
	ds_read_b128 v[214:217], v153 offset:17408
	ds_read_b128 v[218:221], v153 offset:18432
	ds_read_b128 v[222:225], v153 offset:19456
	ds_read_b128 v[226:229], v153 offset:20480
	ds_read_b128 v[230:233], v153 offset:21504
	ds_read_b128 v[234:237], v153 offset:22528
	ds_read_b128 v[238:241], v153 offset:23552
	global_load_lds_dwordx4 v[158:159], off
	s_add_i32 m0, s34, 0x2000
	s_add_u32 s34, s58, 0x80000
	v_lshl_add_u64 v[162:163], s[58:59], 0, v[132:133]
	s_addc_u32 s35, s59, 0
	s_add_i32 s29, s29, s64
	global_load_lds_dwordx4 v[162:163], off
	v_lshl_add_u64 v[242:243], s[34:35], 0, v[160:161]
	s_mov_b32 m0, s29
	v_lshl_add_u64 v[244:245], s[60:61], 0, v[130:131]
	global_load_lds_dwordx4 v[242:243], off
	v_lshl_add_u64 v[242:243], s[34:35], 0, v[132:133]
	s_add_i32 m0, s29, 0x2000
	s_nop 0
	global_load_lds_dwordx4 v[242:243], off
	v_lshl_add_u64 v[242:243], s[60:61], 0, v[128:129]
	s_mov_b32 m0, s17
	s_nop 0
	global_load_lds_dwordx4 v[242:243], off
	s_mov_b32 m0, s65
	s_nop 0
	global_load_lds_dwordx4 v[244:245], off
	s_waitcnt vmcnt(8)
	s_waitcnt lgkmcnt(0)
	s_barrier
; #define PG8_STAGE(bufoff, gbase, voff) do { _Pragma("unroll") for (int _i = 0; _i < 2; ++_i) \
;         __builtin_amdgcn_global_load_lds((const unsigned*)((const char*)(gbase) + (voff)[_i]), (PG8_LAS unsigned*)(lds + (bufoff) + ldsw + _i * 8192), 16, 0, 0); } while (0)
; #define PG8_WAIT_V(n) asm volatile("s_waitcnt vmcnt(" #n ")" ::: "memory")
; #define PG8_WAIT_L(n) asm volatile("s_waitcnt lgkmcnt(" #n ")" ::: "memory")
; #define PG8_BAR __builtin_amdgcn_s_barrier()
; #define PG8_SCHED __builtin_amdgcn_sched_barrier(0)
; template <class Epi, class Sched, bool ALIGN_EPI = false, bool SP2 = false, bool F8 = false>
; __device__ __forceinline__ void gemm_phase(PG8_LAS unsigned char* lds, const Gemm g, const Sched& S, const Epi& E) {
;     ...
;             PG8_LDB(B0, 0, 0); PG8_LDB(B1, 0, 1); PG8_SCHED; PG8_LDA(At, 0, 0); PG8_STAGE(PG8_SA(1, 1), a1 + hstep, voffA);
;             PG8_WAIT_V(8); PG8_WAIT_L(0); PG8_BAR; PG8_MMA(0, 0, At, B0); PG8_MMA(0, 1, At, B1); PG8_BAR; PG8_SCHED;
;             PG8_LDA(At, 0, 1); PG8_STAGE(PG8_SB(0, 0), b2, voffB); PG8_STAGE(PG8_SB(0, 1), b2 + hstep, voffB); PG8_STAGE(PG8_SA(0, 0), a2, voffA);
;             PG8_WAIT_V(8); PG8_WAIT_L(0); PG8_BAR; PG8_MMA(1, 0, At, B0); PG8_MMA(1, 1, At, B1); PG8_BAR; PG8_SCHED;
;             PG8_LDB(B0, 1, 0); PG8_LDB(B1, 1, 1); PG8_SCHED; PG8_LDA(At, 1, 0); PG8_STAGE(PG8_SA(0, 1), a2 + hstep, voffA);
;             PG8_WAIT_V(8); PG8_WAIT_L(0); PG8_BAR; PG8_MMA(0, 0, At, B0); PG8_MMA(0, 1, At, B1); PG8_BAR; PG8_SCHED;
;             PG8_LDA(At, 1, 1); PG8_STAGE(PG8_SB(1, 0), b3, voffB); PG8_STAGE(PG8_SB(1, 1), b3 + hstep, voffB); PG8_STAGE(PG8_SA(1, 0), a3, voffA);
;             PG8_WAIT_V(8); PG8_WAIT_L(0); PG8_BAR; PG8_MMA(1, 0, At, B0); PG8_MMA(1, 1, At, B1); PG8_BAR; PG8_SCHED;
	s_setprio 1
	s_waitcnt lgkmcnt(0)
	v_mfma_f32_16x16x32_bf16 v[60:63], v[138:141], v[200:203], 0
	v_mfma_f32_16x16x32_bf16 v[56:59], v[146:149], v[200:203], 0
	v_mfma_f32_16x16x32_bf16 v[44:47], v[138:141], v[218:221], 0
	v_mfma_f32_16x16x32_bf16 v[40:43], v[146:149], v[218:221], 0
	v_mfma_f32_16x16x32_bf16 v[28:31], v[138:141], v[226:229], 0
	v_mfma_f32_16x16x32_bf16 v[24:27], v[146:149], v[226:229], 0
	v_mfma_f32_16x16x32_bf16 v[12:15], v[138:141], v[234:237], 0
	v_mfma_f32_16x16x32_bf16 v[8:11], v[146:149], v[234:237], 0
	v_mfma_f32_16x16x32_bf16 v[60:63], v[142:145], v[214:217], v[60:63]
	v_mfma_f32_16x16x32_bf16 v[56:59], v[154:157], v[214:217], v[56:59]
	v_mfma_f32_16x16x32_bf16 v[44:47], v[142:145], v[222:225], v[44:47]
	v_mfma_f32_16x16x32_bf16 v[40:43], v[154:157], v[222:225], v[40:43]
	v_mfma_f32_16x16x32_bf16 v[28:31], v[142:145], v[230:233], v[28:31]
	v_mfma_f32_16x16x32_bf16 v[24:27], v[154:157], v[230:233], v[24:27]
	v_mfma_f32_16x16x32_bf16 v[12:15], v[142:145], v[238:241], v[12:15]
	v_mfma_f32_16x16x32_bf16 v[8:11], v[154:157], v[238:241], v[8:11]
	v_mfma_f32_16x16x32_bf16 v[52:55], v[184:187], v[200:203], 0
	v_mfma_f32_16x16x32_bf16 v[48:51], v[192:195], v[200:203], 0
	v_mfma_f32_16x16x32_bf16 v[36:39], v[184:187], v[218:221], 0
	v_mfma_f32_16x16x32_bf16 v[32:35], v[192:195], v[218:221], 0
	v_mfma_f32_16x16x32_bf16 v[20:23], v[184:187], v[226:229], 0
	v_mfma_f32_16x16x32_bf16 v[16:19], v[192:195], v[226:229], 0
	v_mfma_f32_16x16x32_bf16 v[4:7], v[184:187], v[234:237], 0
	v_mfma_f32_16x16x32_bf16 v[0:3], v[192:195], v[234:237], 0
	v_mfma_f32_16x16x32_bf16 v[52:55], v[188:191], v[214:217], v[52:55]
	v_mfma_f32_16x16x32_bf16 v[48:51], v[196:199], v[214:217], v[48:51]
	v_mfma_f32_16x16x32_bf16 v[36:39], v[188:191], v[222:225], v[36:39]
	v_mfma_f32_16x16x32_bf16 v[32:35], v[196:199], v[222:225], v[32:35]
	v_mfma_f32_16x16x32_bf16 v[20:23], v[188:191], v[230:233], v[20:23]
	v_mfma_f32_16x16x32_bf16 v[16:19], v[196:199], v[230:233], v[16:19]
	v_mfma_f32_16x16x32_bf16 v[4:7], v[188:191], v[238:241], v[4:7]
	v_mfma_f32_16x16x32_bf16 v[0:3], v[196:199], v[238:241], v[0:3]
	s_setprio 0
	s_barrier
	s_add_i32 s29, 0, 0x18000
	s_add_i32 s47, 0, 0x1c000
	v_add_u32_e32 v154, s29, v151
	v_add_u32_e32 v196, s47, v151
	ds_read_b128 v[138:141], v154
	ds_read_b128 v[142:145], v154 offset:1024
	ds_read_b128 v[146:149], v154 offset:2048
	ds_read_b128 v[154:157], v154 offset:3072
	ds_read_b128 v[184:187], v196
	ds_read_b128 v[188:191], v196 offset:1024
	ds_read_b128 v[192:195], v196 offset:2048
	ds_read_b128 v[196:199], v196 offset:3072
	s_add_u32 s34, s60, 0x80000
	s_addc_u32 s35, s61, 0
	s_mov_b32 m0, s74
	v_lshl_add_u64 v[246:247], s[34:35], 0, v[128:129]
	ds_read_b128 v[200:203], v153 offset:32768
	ds_read_b128 v[214:217], v153 offset:33792
	ds_read_b128 v[218:221], v153 offset:34816
	ds_read_b128 v[222:225], v153 offset:35840
	ds_read_b128 v[226:229], v153 offset:36864
	ds_read_b128 v[230:233], v153 offset:37888
	ds_read_b128 v[234:237], v153 offset:38912
	ds_read_b128 v[238:241], v153 offset:39936
	global_load_lds_dwordx4 v[246:247], off
	v_lshl_add_u64 v[246:247], s[34:35], 0, v[130:131]
	s_mov_b32 m0, s75
	s_nop 0
	global_load_lds_dwordx4 v[246:247], off
	s_waitcnt vmcnt(8)
	s_waitcnt lgkmcnt(0)
	s_barrier
	s_setprio 1
	s_waitcnt lgkmcnt(0)
	v_mfma_f32_16x16x32_bf16 v[124:127], v[138:141], v[200:203], v[124:127]
	v_mfma_f32_16x16x32_bf16 v[120:123], v[146:149], v[200:203], v[120:123]
	v_mfma_f32_16x16x32_bf16 v[108:111], v[138:141], v[218:221], v[108:111]
	v_mfma_f32_16x16x32_bf16 v[104:107], v[146:149], v[218:221], v[104:107]
	v_mfma_f32_16x16x32_bf16 v[92:95], v[138:141], v[226:229], v[92:95]
	v_mfma_f32_16x16x32_bf16 v[88:91], v[146:149], v[226:229], v[88:91]
	v_mfma_f32_16x16x32_bf16 v[76:79], v[138:141], v[234:237], v[76:79]
	v_mfma_f32_16x16x32_bf16 v[72:75], v[146:149], v[234:237], v[72:75]
	v_mfma_f32_16x16x32_bf16 v[124:127], v[142:145], v[214:217], v[124:127]
	v_mfma_f32_16x16x32_bf16 v[120:123], v[154:157], v[214:217], v[120:123]
	v_mfma_f32_16x16x32_bf16 v[108:111], v[142:145], v[222:225], v[108:111]
	v_mfma_f32_16x16x32_bf16 v[104:107], v[154:157], v[222:225], v[104:107]
	v_mfma_f32_16x16x32_bf16 v[92:95], v[142:145], v[230:233], v[92:95]
	v_mfma_f32_16x16x32_bf16 v[88:91], v[154:157], v[230:233], v[88:91]
	v_mfma_f32_16x16x32_bf16 v[76:79], v[142:145], v[238:241], v[76:79]
	v_mfma_f32_16x16x32_bf16 v[72:75], v[154:157], v[238:241], v[72:75]
	v_mfma_f32_16x16x32_bf16 v[116:119], v[184:187], v[200:203], v[116:119]
	v_mfma_f32_16x16x32_bf16 v[112:115], v[192:195], v[200:203], v[112:115]
	v_mfma_f32_16x16x32_bf16 v[100:103], v[184:187], v[218:221], v[100:103]
	v_mfma_f32_16x16x32_bf16 v[96:99], v[192:195], v[218:221], v[96:99]
	v_mfma_f32_16x16x32_bf16 v[84:87], v[184:187], v[226:229], v[84:87]
	v_mfma_f32_16x16x32_bf16 v[80:83], v[192:195], v[226:229], v[80:83]
	v_mfma_f32_16x16x32_bf16 v[68:71], v[184:187], v[234:237], v[68:71]
	v_mfma_f32_16x16x32_bf16 v[64:67], v[192:195], v[234:237], v[64:67]
	v_mfma_f32_16x16x32_bf16 v[116:119], v[188:191], v[214:217], v[116:119]
	v_mfma_f32_16x16x32_bf16 v[112:115], v[196:199], v[214:217], v[112:115]
	v_mfma_f32_16x16x32_bf16 v[100:103], v[188:191], v[222:225], v[100:103]
	v_mfma_f32_16x16x32_bf16 v[96:99], v[196:199], v[222:225], v[96:99]
	v_mfma_f32_16x16x32_bf16 v[84:87], v[188:191], v[230:233], v[84:87]
	v_mfma_f32_16x16x32_bf16 v[80:83], v[196:199], v[230:233], v[80:83]
	v_mfma_f32_16x16x32_bf16 v[68:71], v[188:191], v[238:241], v[68:71]
	v_mfma_f32_16x16x32_bf16 v[64:67], v[196:199], v[238:241], v[64:67]
	s_setprio 0
	s_barrier
; #define PG8_STAGE(bufoff, gbase, voff) do { _Pragma("unroll") for (int _i = 0; _i < 2; ++_i) \
;         __builtin_amdgcn_global_load_lds((const unsigned*)((const char*)(gbase) + (voff)[_i]), (PG8_LAS unsigned*)(lds + (bufoff) + ldsw + _i * 8192), 16, 0, 0); } while (0)
; #define PG8_WAIT_V(n) asm volatile("s_waitcnt vmcnt(" #n ")" ::: "memory")
; #define PG8_WAIT_L(n) asm volatile("s_waitcnt lgkmcnt(" #n ")" ::: "memory")
; #define PG8_BAR __builtin_amdgcn_s_barrier()
; #define PG8_SCHED __builtin_amdgcn_sched_barrier(0)
; template <class Epi, class Sched, bool ALIGN_EPI = false, bool SP2 = false, bool F8 = false>
; __device__ __forceinline__ void gemm_phase(PG8_LAS unsigned char* lds, const Gemm g, const Sched& S, const Epi& E) {
;     ...
;         for (int t = 0; t < nt; t += 2) {
;             const bool last = (t == nt - 2);
;             const char* a1 = cA + (size_t)(t + 1) * kstep;
;             const char* a2 = last ? nA : cA + (size_t)(t + 2) * kstep; const char* b2 = last ? nB : cB + (size_t)(t + 2) * kstep;
;             const char* a3 = a2 + kstep; const char* b3 = b2 + kstep;
;             if (last && has_next) S.a_ready(nxt);
;             if constexpr (SP2) {
;             PG8_LDB(B0, 0, 0); PG8_LDB(B1, 0, 1); PG8_SCHED; PG8_LDA(At, 0, 0); PG8_STAGE(PG8_SA(1, 1), a1 + hstep, voffA);
;             PG8_WAIT_V(8); PG8_WAIT_L(0); PG8_BAR; PG8_MMA(0, 0, At, B0); PG8_MMA(0, 1, At, B1); PG8_BAR; PG8_SCHED;
;             PG8_LDA(At, 0, 1); PG8_STAGE(PG8_SB(0, 0), b2, voffB); PG8_STAGE(PG8_SB(0, 1), b2 + hstep, voffB); PG8_STAGE(PG8_SA(0, 0), a2, voffA);
;             PG8_WAIT_V(8); PG8_WAIT_L(0); PG8_BAR; PG8_MMA(1, 0, At, B0); PG8_MMA(1, 1, At, B1); PG8_BAR; PG8_SCHED;
;             PG8_LDB(B0, 1, 0); PG8_LDB(B1, 1, 1); PG8_SCHED; PG8_LDA(At, 1, 0); PG8_STAGE(PG8_SA(0, 1), a2 + hstep, voffA);
;             PG8_WAIT_V(8); PG8_WAIT_L(0); PG8_BAR; PG8_MMA(0, 0, At, B0); PG8_MMA(0, 1, At, B1); PG8_BAR; PG8_SCHED;
;             PG8_LDA(At, 1, 1); PG8_STAGE(PG8_SB(1, 0), b3, voffB); PG8_STAGE(PG8_SB(1, 1), b3 + hstep, voffB); PG8_STAGE(PG8_SA(1, 0), a3, voffA);
;             PG8_WAIT_V(8); PG8_WAIT_L(0); PG8_BAR; PG8_MMA(1, 0, At, B0); PG8_MMA(1, 1, At, B1); PG8_BAR; PG8_SCHED;
	s_add_i32 s29, s29, s64
	v_lshl_add_u64 v[158:159], v[158:159], 0, s[14:15]
	s_mov_b32 m0, s29
	ds_read_b128 v[200:203], v153 offset:49152
	ds_read_b128 v[214:217], v153 offset:50176
	ds_read_b128 v[218:221], v153 offset:51200
	ds_read_b128 v[222:225], v153 offset:52224
	ds_read_b128 v[226:229], v153 offset:53248
	ds_read_b128 v[230:233], v153 offset:54272
	ds_read_b128 v[234:237], v153 offset:55296
	ds_read_b128 v[238:241], v153 offset:56320
	global_load_lds_dwordx4 v[158:159], off
	s_add_i32 m0, s29, 0x2000
	s_add_u32 s34, s58, 0x80080
	v_lshl_add_u64 v[158:159], v[162:163], 0, s[14:15]
	s_addc_u32 s35, s59, 0
	s_add_i32 s29, s47, s64
	global_load_lds_dwordx4 v[158:159], off
	v_lshl_add_u64 v[158:159], s[34:35], 0, v[160:161]
	s_mov_b32 m0, s29
	s_nop 0
	global_load_lds_dwordx4 v[158:159], off
	v_lshl_add_u64 v[158:159], s[34:35], 0, v[132:133]
	s_add_i32 m0, s29, 0x2000
	s_nop 0
	global_load_lds_dwordx4 v[158:159], off
	v_lshl_add_u64 v[158:159], v[242:243], 0, s[14:15]
	s_mov_b32 m0, s52
	s_nop 0
	global_load_lds_dwordx4 v[158:159], off
	v_lshl_add_u64 v[158:159], v[244:245], 0, s[14:15]
	s_mov_b32 m0, s53
	s_nop 0
	global_load_lds_dwordx4 v[158:159], off
	s_waitcnt vmcnt(8)
	s_waitcnt lgkmcnt(0)
	s_barrier
	s_setprio 1
	s_waitcnt lgkmcnt(0)
	v_mfma_f32_16x16x32_bf16 v[60:63], v[138:141], v[200:203], v[60:63]
	v_mfma_f32_16x16x32_bf16 v[56:59], v[146:149], v[200:203], v[56:59]
	v_mfma_f32_16x16x32_bf16 v[44:47], v[138:141], v[218:221], v[44:47]
	v_mfma_f32_16x16x32_bf16 v[40:43], v[146:149], v[218:221], v[40:43]
	v_mfma_f32_16x16x32_bf16 v[28:31], v[138:141], v[226:229], v[28:31]
	v_mfma_f32_16x16x32_bf16 v[24:27], v[146:149], v[226:229], v[24:27]
	v_mfma_f32_16x16x32_bf16 v[12:15], v[138:141], v[234:237], v[12:15]
	v_mfma_f32_16x16x32_bf16 v[8:11], v[146:149], v[234:237], v[8:11]
	v_mfma_f32_16x16x32_bf16 v[60:63], v[142:145], v[214:217], v[60:63]
	v_mfma_f32_16x16x32_bf16 v[56:59], v[154:157], v[214:217], v[56:59]
	v_mfma_f32_16x16x32_bf16 v[44:47], v[142:145], v[222:225], v[44:47]
	v_mfma_f32_16x16x32_bf16 v[40:43], v[154:157], v[222:225], v[40:43]
	v_mfma_f32_16x16x32_bf16 v[28:31], v[142:145], v[230:233], v[28:31]
	v_mfma_f32_16x16x32_bf16 v[24:27], v[154:157], v[230:233], v[24:27]
	v_mfma_f32_16x16x32_bf16 v[12:15], v[142:145], v[238:241], v[12:15]
	v_mfma_f32_16x16x32_bf16 v[8:11], v[154:157], v[238:241], v[8:11]
	v_mfma_f32_16x16x32_bf16 v[52:55], v[184:187], v[200:203], v[52:55]
	v_mfma_f32_16x16x32_bf16 v[48:51], v[192:195], v[200:203], v[48:51]
	v_mfma_f32_16x16x32_bf16 v[36:39], v[184:187], v[218:221], v[36:39]
	v_mfma_f32_16x16x32_bf16 v[32:35], v[192:195], v[218:221], v[32:35]
	v_mfma_f32_16x16x32_bf16 v[20:23], v[184:187], v[226:229], v[20:23]
	v_mfma_f32_16x16x32_bf16 v[16:19], v[192:195], v[226:229], v[16:19]
	v_mfma_f32_16x16x32_bf16 v[4:7], v[184:187], v[234:237], v[4:7]
	v_mfma_f32_16x16x32_bf16 v[0:3], v[192:195], v[234:237], v[0:3]
	v_mfma_f32_16x16x32_bf16 v[52:55], v[188:191], v[214:217], v[52:55]
	v_mfma_f32_16x16x32_bf16 v[48:51], v[196:199], v[214:217], v[48:51]
	v_mfma_f32_16x16x32_bf16 v[36:39], v[188:191], v[222:225], v[36:39]
	v_mfma_f32_16x16x32_bf16 v[32:35], v[196:199], v[222:225], v[32:35]
	v_mfma_f32_16x16x32_bf16 v[20:23], v[188:191], v[230:233], v[20:23]
	v_mfma_f32_16x16x32_bf16 v[16:19], v[196:199], v[230:233], v[16:19]
	v_mfma_f32_16x16x32_bf16 v[4:7], v[188:191], v[238:241], v[4:7]
	v_mfma_f32_16x16x32_bf16 v[0:3], v[196:199], v[238:241], v[0:3]
	s_setprio 0
	s_barrier
	s_add_i32 s28, s28, 2
	s_add_u32 s36, s36, 0x100
	s_addc_u32 s37, s37, 0
	s_add_u32 s19, s19, 0x100
	s_addc_u32 s23, s23, 0
	s_cmp_gt_u32 s28, 29
	s_cbranch_scc0 .LBB0_59
	s_branch .Lgk_after_59
.LBB0_59:
	s_add_u32 s29, s36, 0xfff80080
	s_addc_u32 s34, s37, -1
	s_add_i32 s35, 0, 0x10000
	s_cmp_eq_u32 s28, 28
	s_cselect_b32 s61, s1, s34
	s_cselect_b32 s60, s8, s29
	s_cselect_b32 s59, s9, s23
	s_cselect_b32 s58, s11, s19
	s_add_i32 s29, 0, 0x14000
	v_add_u32_e32 v154, s35, v151
	v_add_u32_e32 v158, s29, v151
	ds_read_b128 v[138:141], v154
	ds_read_b128 v[142:145], v154 offset:1024
	ds_read_b128 v[146:149], v154 offset:2048
	ds_read_b128 v[154:157], v154 offset:3072
	ds_read_b128 v[184:187], v158
	ds_read_b128 v[188:191], v158 offset:1024
	ds_read_b128 v[192:195], v158 offset:2048
	ds_read_b128 v[196:199], v158 offset:3072
	v_lshl_add_u64 v[158:159], s[36:37], 0, v[134:135]
	s_add_i32 m0, s17, 0xc000
	ds_read_b128 v[200:203], v153
	ds_read_b128 v[214:217], v153 offset:1024
	ds_read_b128 v[218:221], v153 offset:2048
	ds_read_b128 v[222:225], v153 offset:3072
	ds_read_b128 v[226:229], v153 offset:4096
	ds_read_b128 v[230:233], v153 offset:5120
	ds_read_b128 v[234:237], v153 offset:6144
	ds_read_b128 v[238:241], v153 offset:7168
	global_load_lds_dwordx4 v[158:159], off
	v_lshl_add_u64 v[158:159], s[36:37], 0, v[136:137]
	s_add_i32 m0, s17, 0xe000
	s_nop 0
	global_load_lds_dwordx4 v[158:159], off
	s_waitcnt vmcnt(8)
	s_waitcnt lgkmcnt(0)
	s_barrier
; #define PG8_STAGE(bufoff, gbase, voff) do { _Pragma("unroll") for (int _i = 0; _i < 2; ++_i) \
;         __builtin_amdgcn_global_load_lds((const unsigned*)((const char*)(gbase) + (voff)[_i]), (PG8_LAS unsigned*)(lds + (bufoff) + ldsw + _i * 8192), 16, 0, 0); } while (0)
; #define PG8_WAIT_V(n) asm volatile("s_waitcnt vmcnt(" #n ")" ::: "memory")
; #define PG8_WAIT_L(n) asm volatile("s_waitcnt lgkmcnt(" #n ")" ::: "memory")
; #define PG8_BAR __builtin_amdgcn_s_barrier()
; #define PG8_SCHED __builtin_amdgcn_sched_barrier(0)
; template <class Epi, class Sched, bool ALIGN_EPI = false, bool SP2 = false, bool F8 = false>
; __device__ __forceinline__ void gemm_phase(PG8_LAS unsigned char* lds, const Gemm g, const Sched& S, const Epi& E) {
;     ...
;             PG8_LDB(B0, 0, 0); PG8_LDB(B1, 0, 1); PG8_SCHED; PG8_LDA(At, 0, 0); PG8_STAGE(PG8_SA(1, 1), a1 + hstep, voffA);
;             PG8_WAIT_V(8); PG8_WAIT_L(0); PG8_BAR; PG8_MMA(0, 0, At, B0); PG8_MMA(0, 1, At, B1); PG8_BAR; PG8_SCHED;
;             PG8_LDA(At, 0, 1); PG8_STAGE(PG8_SB(0, 0), b2, voffB); PG8_STAGE(PG8_SB(0, 1), b2 + hstep, voffB); PG8_STAGE(PG8_SA(0, 0), a2, voffA);
;             PG8_WAIT_V(8); PG8_WAIT_L(0); PG8_BAR; PG8_MMA(1, 0, At, B0); PG8_MMA(1, 1, At, B1); PG8_BAR; PG8_SCHED;
;             PG8_LDB(B0, 1, 0); PG8_LDB(B1, 1, 1); PG8_SCHED; PG8_LDA(At, 1, 0); PG8_STAGE(PG8_SA(0, 1), a2 + hstep, voffA);
;             PG8_WAIT_V(8); PG8_WAIT_L(0); PG8_BAR; PG8_MMA(0, 0, At, B0); PG8_MMA(0, 1, At, B1); PG8_BAR; PG8_SCHED;
;             PG8_LDA(At, 1, 1); PG8_STAGE(PG8_SB(1, 0), b3, voffB); PG8_STAGE(PG8_SB(1, 1), b3 + hstep, voffB); PG8_STAGE(PG8_SA(1, 0), a3, voffA);
;             PG8_WAIT_V(8); PG8_WAIT_L(0); PG8_BAR; PG8_MMA(1, 0, At, B0); PG8_MMA(1, 1, At, B1); PG8_BAR; PG8_SCHED;
	s_setprio 1
	s_waitcnt lgkmcnt(0)
	v_mfma_f32_16x16x32_bf16 v[124:127], v[138:141], v[200:203], v[124:127]
	v_mfma_f32_16x16x32_bf16 v[120:123], v[146:149], v[200:203], v[120:123]
	v_mfma_f32_16x16x32_bf16 v[108:111], v[138:141], v[218:221], v[108:111]
	v_mfma_f32_16x16x32_bf16 v[104:107], v[146:149], v[218:221], v[104:107]
	v_mfma_f32_16x16x32_bf16 v[92:95], v[138:141], v[226:229], v[92:95]
	v_mfma_f32_16x16x32_bf16 v[88:91], v[146:149], v[226:229], v[88:91]
	v_mfma_f32_16x16x32_bf16 v[76:79], v[138:141], v[234:237], v[76:79]
	v_mfma_f32_16x16x32_bf16 v[72:75], v[146:149], v[234:237], v[72:75]
	v_mfma_f32_16x16x32_bf16 v[124:127], v[142:145], v[214:217], v[124:127]
	v_mfma_f32_16x16x32_bf16 v[120:123], v[154:157], v[214:217], v[120:123]
	v_mfma_f32_16x16x32_bf16 v[108:111], v[142:145], v[222:225], v[108:111]
	v_mfma_f32_16x16x32_bf16 v[104:107], v[154:157], v[222:225], v[104:107]
	v_mfma_f32_16x16x32_bf16 v[92:95], v[142:145], v[230:233], v[92:95]
	v_mfma_f32_16x16x32_bf16 v[88:91], v[154:157], v[230:233], v[88:91]
	v_mfma_f32_16x16x32_bf16 v[76:79], v[142:145], v[238:241], v[76:79]
	v_mfma_f32_16x16x32_bf16 v[72:75], v[154:157], v[238:241], v[72:75]
	v_mfma_f32_16x16x32_bf16 v[116:119], v[184:187], v[200:203], v[116:119]
	v_mfma_f32_16x16x32_bf16 v[112:115], v[192:195], v[200:203], v[112:115]
	v_mfma_f32_16x16x32_bf16 v[100:103], v[184:187], v[218:221], v[100:103]
	v_mfma_f32_16x16x32_bf16 v[96:99], v[192:195], v[218:221], v[96:99]
	v_mfma_f32_16x16x32_bf16 v[84:87], v[184:187], v[226:229], v[84:87]
	v_mfma_f32_16x16x32_bf16 v[80:83], v[192:195], v[226:229], v[80:83]
	v_mfma_f32_16x16x32_bf16 v[68:71], v[184:187], v[234:237], v[68:71]
	v_mfma_f32_16x16x32_bf16 v[64:67], v[192:195], v[234:237], v[64:67]
	v_mfma_f32_16x16x32_bf16 v[116:119], v[188:191], v[214:217], v[116:119]
	v_mfma_f32_16x16x32_bf16 v[112:115], v[196:199], v[214:217], v[112:115]
	v_mfma_f32_16x16x32_bf16 v[100:103], v[188:191], v[222:225], v[100:103]
	v_mfma_f32_16x16x32_bf16 v[96:99], v[196:199], v[222:225], v[96:99]
	v_mfma_f32_16x16x32_bf16 v[84:87], v[188:191], v[230:233], v[84:87]
	v_mfma_f32_16x16x32_bf16 v[80:83], v[196:199], v[230:233], v[80:83]
	v_mfma_f32_16x16x32_bf16 v[68:71], v[188:191], v[238:241], v[68:71]
	v_mfma_f32_16x16x32_bf16 v[64:67], v[196:199], v[238:241], v[64:67]
	s_setprio 0
	s_barrier
	s_add_i32 s34, s35, s64
	v_lshl_add_u64 v[158:159], s[58:59], 0, v[160:161]
	s_mov_b32 m0, s34
	ds_read_b128 v[200:203], v153 offset:16384
	ds_read_b128 v[214:217], v153 offset:17408
	ds_read_b128 v[218:221], v153 offset:18432
	ds_read_b128 v[222:225], v153 offset:19456
	ds_read_b128 v[226:229], v153 offset:20480
	ds_read_b128 v[230:233], v153 offset:21504
	ds_read_b128 v[234:237], v153 offset:22528
	ds_read_b128 v[238:241], v153 offset:23552
	global_load_lds_dwordx4 v[158:159], off
	s_add_i32 m0, s34, 0x2000
	s_add_u32 s34, s58, 0x80000
	v_lshl_add_u64 v[162:163], s[58:59], 0, v[132:133]
	s_addc_u32 s35, s59, 0
	s_add_i32 s29, s29, s64
	global_load_lds_dwordx4 v[162:163], off
	v_lshl_add_u64 v[242:243], s[34:35], 0, v[160:161]
	s_mov_b32 m0, s29
	v_lshl_add_u64 v[244:245], s[60:61], 0, v[130:131]
	global_load_lds_dwordx4 v[242:243], off
	v_lshl_add_u64 v[242:243], s[34:35], 0, v[132:133]
	s_add_i32 m0, s29, 0x2000
	s_nop 0
	global_load_lds_dwordx4 v[242:243], off
	v_lshl_add_u64 v[242:243], s[60:61], 0, v[128:129]
	s_mov_b32 m0, s17
	s_nop 0
	global_load_lds_dwordx4 v[242:243], off
	s_mov_b32 m0, s65
	s_nop 0
	global_load_lds_dwordx4 v[244:245], off
	s_waitcnt vmcnt(8)
	s_waitcnt lgkmcnt(0)
	s_barrier
	s_setprio 1
	s_waitcnt lgkmcnt(0)
	v_mfma_f32_16x16x32_bf16 v[60:63], v[138:141], v[200:203], v[60:63]
	v_mfma_f32_16x16x32_bf16 v[56:59], v[146:149], v[200:203], v[56:59]
	v_mfma_f32_16x16x32_bf16 v[44:47], v[138:141], v[218:221], v[44:47]
	v_mfma_f32_16x16x32_bf16 v[40:43], v[146:149], v[218:221], v[40:43]
	v_mfma_f32_16x16x32_bf16 v[28:31], v[138:141], v[226:229], v[28:31]
	v_mfma_f32_16x16x32_bf16 v[24:27], v[146:149], v[226:229], v[24:27]
	v_mfma_f32_16x16x32_bf16 v[12:15], v[138:141], v[234:237], v[12:15]
	v_mfma_f32_16x16x32_bf16 v[8:11], v[146:149], v[234:237], v[8:11]
	v_mfma_f32_16x16x32_bf16 v[60:63], v[142:145], v[214:217], v[60:63]
	v_mfma_f32_16x16x32_bf16 v[56:59], v[154:157], v[214:217], v[56:59]
	v_mfma_f32_16x16x32_bf16 v[44:47], v[142:145], v[222:225], v[44:47]
	v_mfma_f32_16x16x32_bf16 v[40:43], v[154:157], v[222:225], v[40:43]
	v_mfma_f32_16x16x32_bf16 v[28:31], v[142:145], v[230:233], v[28:31]
	v_mfma_f32_16x16x32_bf16 v[24:27], v[154:157], v[230:233], v[24:27]
	v_mfma_f32_16x16x32_bf16 v[12:15], v[142:145], v[238:241], v[12:15]
	v_mfma_f32_16x16x32_bf16 v[8:11], v[154:157], v[238:241], v[8:11]
	v_mfma_f32_16x16x32_bf16 v[52:55], v[184:187], v[200:203], v[52:55]
	v_mfma_f32_16x16x32_bf16 v[48:51], v[192:195], v[200:203], v[48:51]
	v_mfma_f32_16x16x32_bf16 v[36:39], v[184:187], v[218:221], v[36:39]
	v_mfma_f32_16x16x32_bf16 v[32:35], v[192:195], v[218:221], v[32:35]
	v_mfma_f32_16x16x32_bf16 v[20:23], v[184:187], v[226:229], v[20:23]
	v_mfma_f32_16x16x32_bf16 v[16:19], v[192:195], v[226:229], v[16:19]
	v_mfma_f32_16x16x32_bf16 v[4:7], v[184:187], v[234:237], v[4:7]
	v_mfma_f32_16x16x32_bf16 v[0:3], v[192:195], v[234:237], v[0:3]
	v_mfma_f32_16x16x32_bf16 v[52:55], v[188:191], v[214:217], v[52:55]
	v_mfma_f32_16x16x32_bf16 v[48:51], v[196:199], v[214:217], v[48:51]
	v_mfma_f32_16x16x32_bf16 v[36:39], v[188:191], v[222:225], v[36:39]
	v_mfma_f32_16x16x32_bf16 v[32:35], v[196:199], v[222:225], v[32:35]
	v_mfma_f32_16x16x32_bf16 v[20:23], v[188:191], v[230:233], v[20:23]
	v_mfma_f32_16x16x32_bf16 v[16:19], v[196:199], v[230:233], v[16:19]
	v_mfma_f32_16x16x32_bf16 v[4:7], v[188:191], v[238:241], v[4:7]
	v_mfma_f32_16x16x32_bf16 v[0:3], v[196:199], v[238:241], v[0:3]
	s_setprio 0
	s_barrier
; #define PG8_STAGE(bufoff, gbase, voff) do { _Pragma("unroll") for (int _i = 0; _i < 2; ++_i) \
;         __builtin_amdgcn_global_load_lds((const unsigned*)((const char*)(gbase) + (voff)[_i]), (PG8_LAS unsigned*)(lds + (bufoff) + ldsw + _i * 8192), 16, 0, 0); } while (0)
; #define PG8_WAIT_V(n) asm volatile("s_waitcnt vmcnt(" #n ")" ::: "memory")
; #define PG8_WAIT_L(n) asm volatile("s_waitcnt lgkmcnt(" #n ")" ::: "memory")
; #define PG8_BAR __builtin_amdgcn_s_barrier()
; #define PG8_SCHED __builtin_amdgcn_sched_barrier(0)
; template <class Epi, class Sched, bool ALIGN_EPI = false, bool SP2 = false, bool F8 = false>
; __device__ __forceinline__ void gemm_phase(PG8_LAS unsigned char* lds, const Gemm g, const Sched& S, const Epi& E) {
;     ...
;             PG8_LDB(B0, 1, 0); PG8_LDB(B1, 1, 1); PG8_SCHED; PG8_LDA(At, 1, 0); PG8_STAGE(PG8_SA(0, 1), a2 + hstep, voffA);
;             PG8_WAIT_V(8); PG8_WAIT_L(0); PG8_BAR; PG8_MMA(0, 0, At, B0); PG8_MMA(0, 1, At, B1); PG8_BAR; PG8_SCHED;
	s_add_i32 s29, 0, 0x18000
	s_add_i32 s47, 0, 0x1c000
	v_add_u32_e32 v154, s29, v151
	v_add_u32_e32 v196, s47, v151
	ds_read_b128 v[138:141], v154
	ds_read_b128 v[142:145], v154 offset:1024
	ds_read_b128 v[146:149], v154 offset:2048
	ds_read_b128 v[154:157], v154 offset:3072
	ds_read_b128 v[184:187], v196
	ds_read_b128 v[188:191], v196 offset:1024
	ds_read_b128 v[192:195], v196 offset:2048
	ds_read_b128 v[196:199], v196 offset:3072
	s_add_u32 s34, s60, 0x80000
	s_addc_u32 s35, s61, 0
	s_mov_b32 m0, s74
	v_lshl_add_u64 v[246:247], s[34:35], 0, v[128:129]
	ds_read_b128 v[200:203], v153 offset:32768
	ds_read_b128 v[214:217], v153 offset:33792
	ds_read_b128 v[218:221], v153 offset:34816
	ds_read_b128 v[222:225], v153 offset:35840
	ds_read_b128 v[226:229], v153 offset:36864
	ds_read_b128 v[230:233], v153 offset:37888
	ds_read_b128 v[234:237], v153 offset:38912
	ds_read_b128 v[238:241], v153 offset:39936
	global_load_lds_dwordx4 v[246:247], off
	v_lshl_add_u64 v[246:247], s[34:35], 0, v[130:131]
	s_mov_b32 m0, s75
	s_nop 0
	global_load_lds_dwordx4 v[246:247], off
	s_waitcnt vmcnt(8)
	s_waitcnt lgkmcnt(0)
	s_barrier
	s_setprio 1
	s_waitcnt lgkmcnt(0)
	v_mfma_f32_16x16x32_bf16 v[124:127], v[138:141], v[200:203], v[124:127]
	v_mfma_f32_16x16x32_bf16 v[120:123], v[146:149], v[200:203], v[120:123]
	v_mfma_f32_16x16x32_bf16 v[108:111], v[138:141], v[218:221], v[108:111]
	v_mfma_f32_16x16x32_bf16 v[104:107], v[146:149], v[218:221], v[104:107]
	v_mfma_f32_16x16x32_bf16 v[92:95], v[138:141], v[226:229], v[92:95]
	v_mfma_f32_16x16x32_bf16 v[88:91], v[146:149], v[226:229], v[88:91]
	v_mfma_f32_16x16x32_bf16 v[76:79], v[138:141], v[234:237], v[76:79]
	v_mfma_f32_16x16x32_bf16 v[72:75], v[146:149], v[234:237], v[72:75]
	v_mfma_f32_16x16x32_bf16 v[124:127], v[142:145], v[214:217], v[124:127]
	v_mfma_f32_16x16x32_bf16 v[120:123], v[154:157], v[214:217], v[120:123]
	v_mfma_f32_16x16x32_bf16 v[108:111], v[142:145], v[222:225], v[108:111]
	v_mfma_f32_16x16x32_bf16 v[104:107], v[154:157], v[222:225], v[104:107]
	v_mfma_f32_16x16x32_bf16 v[92:95], v[142:145], v[230:233], v[92:95]
	v_mfma_f32_16x16x32_bf16 v[88:91], v[154:157], v[230:233], v[88:91]
	v_mfma_f32_16x16x32_bf16 v[76:79], v[142:145], v[238:241], v[76:79]
	v_mfma_f32_16x16x32_bf16 v[72:75], v[154:157], v[238:241], v[72:75]
	v_mfma_f32_16x16x32_bf16 v[116:119], v[184:187], v[200:203], v[116:119]
	v_mfma_f32_16x16x32_bf16 v[112:115], v[192:195], v[200:203], v[112:115]
	v_mfma_f32_16x16x32_bf16 v[100:103], v[184:187], v[218:221], v[100:103]
	v_mfma_f32_16x16x32_bf16 v[96:99], v[192:195], v[218:221], v[96:99]
	v_mfma_f32_16x16x32_bf16 v[84:87], v[184:187], v[226:229], v[84:87]
	v_mfma_f32_16x16x32_bf16 v[80:83], v[192:195], v[226:229], v[80:83]
	v_mfma_f32_16x16x32_bf16 v[68:71], v[184:187], v[234:237], v[68:71]
	v_mfma_f32_16x16x32_bf16 v[64:67], v[192:195], v[234:237], v[64:67]
	v_mfma_f32_16x16x32_bf16 v[116:119], v[188:191], v[214:217], v[116:119]
	v_mfma_f32_16x16x32_bf16 v[112:115], v[196:199], v[214:217], v[112:115]
	v_mfma_f32_16x16x32_bf16 v[100:103], v[188:191], v[222:225], v[100:103]
	v_mfma_f32_16x16x32_bf16 v[96:99], v[196:199], v[222:225], v[96:99]
	v_mfma_f32_16x16x32_bf16 v[84:87], v[188:191], v[230:233], v[84:87]
	v_mfma_f32_16x16x32_bf16 v[80:83], v[196:199], v[230:233], v[80:83]
	v_mfma_f32_16x16x32_bf16 v[68:71], v[188:191], v[238:241], v[68:71]
	v_mfma_f32_16x16x32_bf16 v[64:67], v[196:199], v[238:241], v[64:67]
	s_setprio 0
	s_barrier
; #define PG8_STAGE(bufoff, gbase, voff) do { _Pragma("unroll") for (int _i = 0; _i < 2; ++_i) \
;         __builtin_amdgcn_global_load_lds((const unsigned*)((const char*)(gbase) + (voff)[_i]), (PG8_LAS unsigned*)(lds + (bufoff) + ldsw + _i * 8192), 16, 0, 0); } while (0)
; #define PG8_WAIT_V(n) asm volatile("s_waitcnt vmcnt(" #n ")" ::: "memory")
; #define PG8_WAIT_L(n) asm volatile("s_waitcnt lgkmcnt(" #n ")" ::: "memory")
; #define PG8_BAR __builtin_amdgcn_s_barrier()
; #define PG8_SCHED __builtin_amdgcn_sched_barrier(0)
; template <class Epi, class Sched, bool ALIGN_EPI = false, bool SP2 = false, bool F8 = false>
; __device__ __forceinline__ void gemm_phase(PG8_LAS unsigned char* lds, const Gemm g, const Sched& S, const Epi& E) {
;     ...
;         for (int t = 0; t < nt; t += 2) {
;             const bool last = (t == nt - 2);
;             const char* a1 = cA + (size_t)(t + 1) * kstep;
;             const char* a2 = last ? nA : cA + (size_t)(t + 2) * kstep; const char* b2 = last ? nB : cB + (size_t)(t + 2) * kstep;
;             const char* a3 = a2 + kstep; const char* b3 = b2 + kstep;
;             if (last && has_next) S.a_ready(nxt);
;             if constexpr (SP2) {
;             PG8_LDB(B0, 0, 0); PG8_LDB(B1, 0, 1); PG8_SCHED; PG8_LDA(At, 0, 0); PG8_STAGE(PG8_SA(1, 1), a1 + hstep, voffA);
;             PG8_WAIT_V(8); PG8_WAIT_L(0); PG8_BAR; PG8_MMA(0, 0, At, B0); PG8_MMA(0, 1, At, B1); PG8_BAR; PG8_SCHED;
;             PG8_LDA(At, 0, 1); PG8_STAGE(PG8_SB(0, 0), b2, voffB); PG8_STAGE(PG8_SB(0, 1), b2 + hstep, voffB); PG8_STAGE(PG8_SA(0, 0), a2, voffA);
;             PG8_WAIT_V(8); PG8_WAIT_L(0); PG8_BAR; PG8_MMA(1, 0, At, B0); PG8_MMA(1, 1, At, B1); PG8_BAR; PG8_SCHED;
;             PG8_LDB(B0, 1, 0); PG8_LDB(B1, 1, 1); PG8_SCHED; PG8_LDA(At, 1, 0); PG8_STAGE(PG8_SA(0, 1), a2 + hstep, voffA);
;             PG8_WAIT_V(8); PG8_WAIT_L(0); PG8_BAR; PG8_MMA(0, 0, At, B0); PG8_MMA(0, 1, At, B1); PG8_BAR; PG8_SCHED;
;             PG8_LDA(At, 1, 1); PG8_STAGE(PG8_SB(1, 0), b3, voffB); PG8_STAGE(PG8_SB(1, 1), b3 + hstep, voffB); PG8_STAGE(PG8_SA(1, 0), a3, voffA);
;             PG8_WAIT_V(8); PG8_WAIT_L(0); PG8_BAR; PG8_MMA(1, 0, At, B0); PG8_MMA(1, 1, At, B1); PG8_BAR; PG8_SCHED;
	s_add_i32 s29, s29, s64
	v_lshl_add_u64 v[158:159], v[158:159], 0, s[14:15]
	s_mov_b32 m0, s29
	ds_read_b128 v[200:203], v153 offset:49152
	ds_read_b128 v[214:217], v153 offset:50176
	ds_read_b128 v[218:221], v153 offset:51200
	ds_read_b128 v[222:225], v153 offset:52224
	ds_read_b128 v[226:229], v153 offset:53248
	ds_read_b128 v[230:233], v153 offset:54272
	ds_read_b128 v[234:237], v153 offset:55296
	ds_read_b128 v[238:241], v153 offset:56320
	global_load_lds_dwordx4 v[158:159], off
	s_add_i32 m0, s29, 0x2000
	s_add_u32 s34, s58, 0x80080
	v_lshl_add_u64 v[158:159], v[162:163], 0, s[14:15]
	s_addc_u32 s35, s59, 0
	s_add_i32 s29, s47, s64
	global_load_lds_dwordx4 v[158:159], off
	v_lshl_add_u64 v[158:159], s[34:35], 0, v[160:161]
	s_mov_b32 m0, s29
	s_nop 0
	global_load_lds_dwordx4 v[158:159], off
	v_lshl_add_u64 v[158:159], s[34:35], 0, v[132:133]
	s_add_i32 m0, s29, 0x2000
	s_nop 0
	global_load_lds_dwordx4 v[158:159], off
	v_lshl_add_u64 v[158:159], v[242:243], 0, s[14:15]
	s_mov_b32 m0, s52
	s_nop 0
	global_load_lds_dwordx4 v[158:159], off
	v_lshl_add_u64 v[158:159], v[244:245], 0, s[14:15]
	s_mov_b32 m0, s53
	s_nop 0
	global_load_lds_dwordx4 v[158:159], off
	s_waitcnt vmcnt(8)
	s_waitcnt lgkmcnt(0)
	s_barrier
	s_setprio 1
	s_waitcnt lgkmcnt(0)
	v_mfma_f32_16x16x32_bf16 v[60:63], v[138:141], v[200:203], v[60:63]
	v_mfma_f32_16x16x32_bf16 v[56:59], v[146:149], v[200:203], v[56:59]
	v_mfma_f32_16x16x32_bf16 v[44:47], v[138:141], v[218:221], v[44:47]
	v_mfma_f32_16x16x32_bf16 v[40:43], v[146:149], v[218:221], v[40:43]
	v_mfma_f32_16x16x32_bf16 v[28:31], v[138:141], v[226:229], v[28:31]
	v_mfma_f32_16x16x32_bf16 v[24:27], v[146:149], v[226:229], v[24:27]
	v_mfma_f32_16x16x32_bf16 v[12:15], v[138:141], v[234:237], v[12:15]
	v_mfma_f32_16x16x32_bf16 v[8:11], v[146:149], v[234:237], v[8:11]
	v_mfma_f32_16x16x32_bf16 v[60:63], v[142:145], v[214:217], v[60:63]
	v_mfma_f32_16x16x32_bf16 v[56:59], v[154:157], v[214:217], v[56:59]
	v_mfma_f32_16x16x32_bf16 v[44:47], v[142:145], v[222:225], v[44:47]
	v_mfma_f32_16x16x32_bf16 v[40:43], v[154:157], v[222:225], v[40:43]
	v_mfma_f32_16x16x32_bf16 v[28:31], v[142:145], v[230:233], v[28:31]
	v_mfma_f32_16x16x32_bf16 v[24:27], v[154:157], v[230:233], v[24:27]
	v_mfma_f32_16x16x32_bf16 v[12:15], v[142:145], v[238:241], v[12:15]
	v_mfma_f32_16x16x32_bf16 v[8:11], v[154:157], v[238:241], v[8:11]
	v_mfma_f32_16x16x32_bf16 v[52:55], v[184:187], v[200:203], v[52:55]
	v_mfma_f32_16x16x32_bf16 v[48:51], v[192:195], v[200:203], v[48:51]
	v_mfma_f32_16x16x32_bf16 v[36:39], v[184:187], v[218:221], v[36:39]
	v_mfma_f32_16x16x32_bf16 v[32:35], v[192:195], v[218:221], v[32:35]
	v_mfma_f32_16x16x32_bf16 v[20:23], v[184:187], v[226:229], v[20:23]
	v_mfma_f32_16x16x32_bf16 v[16:19], v[192:195], v[226:229], v[16:19]
	v_mfma_f32_16x16x32_bf16 v[4:7], v[184:187], v[234:237], v[4:7]
	v_mfma_f32_16x16x32_bf16 v[0:3], v[192:195], v[234:237], v[0:3]
	v_mfma_f32_16x16x32_bf16 v[52:55], v[188:191], v[214:217], v[52:55]
	v_mfma_f32_16x16x32_bf16 v[48:51], v[196:199], v[214:217], v[48:51]
	v_mfma_f32_16x16x32_bf16 v[36:39], v[188:191], v[222:225], v[36:39]
	v_mfma_f32_16x16x32_bf16 v[32:35], v[196:199], v[222:225], v[32:35]
	v_mfma_f32_16x16x32_bf16 v[20:23], v[188:191], v[230:233], v[20:23]
	v_mfma_f32_16x16x32_bf16 v[16:19], v[196:199], v[230:233], v[16:19]
	v_mfma_f32_16x16x32_bf16 v[4:7], v[188:191], v[238:241], v[4:7]
	v_mfma_f32_16x16x32_bf16 v[0:3], v[196:199], v[238:241], v[0:3]
	s_setprio 0
	s_barrier
	s_add_i32 s28, s28, 2
	s_add_u32 s36, s36, 0x100
	s_addc_u32 s37, s37, 0
	s_add_u32 s19, s19, 0x100
	s_addc_u32 s23, s23, 0
	s_cmp_gt_u32 s28, 29
	s_cbranch_scc0 .LBB0_59

; #define PG8_STAGE(bufoff, gbase, voff) do { _Pragma("unroll") for (int _i = 0; _i < 2; ++_i) \
;         __builtin_amdgcn_global_load_lds((const unsigned*)((const char*)(gbase) + (voff)[_i]), (PG8_LAS unsigned*)(lds + (bufoff) + ldsw + _i * 8192), 16, 0, 0); } while (0)
; #define PG8_WAIT_V(n) asm volatile("s_waitcnt vmcnt(" #n ")" ::: "memory")
; #define PG8_WAIT_L(n) asm volatile("s_waitcnt lgkmcnt(" #n ")" ::: "memory")
; #define PG8_BAR __builtin_amdgcn_s_barrier()
; template <class Epi, class Sched, bool ALIGN_EPI = false, bool SP2 = false, bool F8 = false>
; __device__ __forceinline__ void gemm_phase(PG8_LAS unsigned char* lds, const Gemm g, const Sched& S, const Epi& E) {
;     ...
;         const bool has_next = S.next(ui + 1, nxt);
;         const char* nA = has_next ? (const char*)g.A + (size_t)nxt.pm * tstep : cA; const char* nB = has_next ? (const char*)g.Bt + (size_t)nxt.pn * tstep : cB;
;         for (int t = 0; t < nt; t += 2) {
;             const bool last = (t == nt - 2);
;             const char* a1 = cA + (size_t)(t + 1) * kstep;
;             const char* a2 = last ? nA : cA + (size_t)(t + 2) * kstep; const char* b2 = last ? nB : cB + (size_t)(t + 2) * kstep;
;             const char* a3 = a2 + kstep; const char* b3 = b2 + kstep;
;             if (last && has_next) S.a_ready(nxt);
;             if constexpr (SP2) {
;             PG8_LDB(B0, 0, 0); PG8_LDB(B1, 0, 1); PG8_SCHED; PG8_LDA(At, 0, 0); PG8_STAGE(PG8_SA(1, 1), a1 + hstep, voffA);
;             PG8_WAIT_V(8); PG8_WAIT_L(0); PG8_BAR; PG8_MMA(0, 0, At, B0); PG8_MMA(0, 1, At, B1); PG8_BAR; PG8_SCHED;
;             PG8_LDA(At, 0, 1); PG8_STAGE(PG8_SB(0, 0), b2, voffB); PG8_STAGE(PG8_SB(0, 1), b2 + hstep, voffB); PG8_STAGE(PG8_SA(0, 0), a2, voffA);
;             PG8_WAIT_V(8); PG8_WAIT_L(0); PG8_BAR; PG8_MMA(1, 0, At, B0); PG8_MMA(1, 1, At, B1); PG8_BAR; PG8_SCHED;
;             PG8_LDB(B0, 1, 0); PG8_LDB(B1, 1, 1); PG8_SCHED; PG8_LDA(At, 1, 0); PG8_STAGE(PG8_SA(0, 1), a2 + hstep, voffA);
;             PG8_WAIT_V(8); PG8_WAIT_L(0); PG8_BAR; PG8_MMA(0, 0, At, B0); PG8_MMA(0, 1, At, B1); PG8_BAR; PG8_SCHED;
;             PG8_LDA(At, 1, 1); PG8_STAGE(PG8_SB(1, 0), b3, voffB); PG8_STAGE(PG8_SB(1, 1), b3 + hstep, voffB); PG8_STAGE(PG8_SA(1, 0), a3, voffA);
;             PG8_WAIT_V(8); PG8_WAIT_L(0); PG8_BAR; PG8_MMA(1, 0, At, B0); PG8_MMA(1, 1, At, B1); PG8_BAR; PG8_SCHED;
.LBB0_96:
	s_ashr_i32 s17, s16, 31
	s_lshl_b64 s[28:29], s[16:17], 18
	s_add_u32 s36, s62, s28
	s_addc_u32 s37, s63, s29
	s_and_b64 s[28:29], s[38:39], exec
	s_cselect_b32 s17, s37, s43
	s_cselect_b32 s19, s36, s42
	s_ashr_i32 s11, s10, 31
	s_lshl_b64 s[28:29], s[10:11], 18
	s_add_u32 s40, s13, s28
	s_addc_u32 s41, s22, s29
	s_and_b64 s[28:29], s[38:39], exec
	s_cselect_b32 s11, s41, s45
	s_cselect_b32 s23, s40, s44
	s_add_u32 s42, s42, 0x20080
	s_addc_u32 s43, s43, 0
	s_add_u32 s28, s44, 0x100
	s_addc_u32 s29, s45, 0
	s_mov_b32 s54, -2
	s_add_u32 s44, s42, 0xfffe0080
	s_addc_u32 s45, s43, -1
	s_add_i32 s55, 0, 0x10000
	s_cmp_eq_u32 s54, 4
	s_cselect_b32 s47, s17, s45
	s_cselect_b32 s46, s19, s44
	s_cselect_b32 s45, s11, s29
	s_cselect_b32 s44, s23, s28
	s_add_i32 s56, 0, 0x14000
	v_add_u32_e32 v154, s55, v143
	v_add_u32_e32 v158, s56, v143
	ds_read_b128 v[138:141], v154
	ds_read_b128 v[146:149], v154 offset:1024
	ds_read_b128 v[150:153], v154 offset:2048
	ds_read_b128 v[154:157], v154 offset:3072
	ds_read_b128 v[184:187], v158
	ds_read_b128 v[188:191], v158 offset:1024
	ds_read_b128 v[192:195], v158 offset:2048
	ds_read_b128 v[196:199], v158 offset:3072
	v_lshl_add_u64 v[158:159], s[42:43], 0, v[134:135]
	s_add_i32 m0, s35, 0xc000
	ds_read_b128 v[200:203], v145
	ds_read_b128 v[214:217], v145 offset:1024
	ds_read_b128 v[218:221], v145 offset:2048
	ds_read_b128 v[222:225], v145 offset:3072
	ds_read_b128 v[226:229], v145 offset:4096
	ds_read_b128 v[230:233], v145 offset:5120
	ds_read_b128 v[234:237], v145 offset:6144
	ds_read_b128 v[238:241], v145 offset:7168
	global_load_lds_dwordx4 v[158:159], off
	v_lshl_add_u64 v[158:159], s[42:43], 0, v[136:137]
	s_add_i32 m0, s35, 0xe000
	s_nop 0
	global_load_lds_dwordx4 v[158:159], off
	s_waitcnt vmcnt(8)
	s_waitcnt lgkmcnt(0)
	s_barrier
	s_setprio 1
	s_waitcnt lgkmcnt(0)
	v_mfma_f32_16x16x32_bf16 v[124:127], v[138:141], v[200:203], 0
	v_mfma_f32_16x16x32_bf16 v[120:123], v[150:153], v[200:203], 0
	v_mfma_f32_16x16x32_bf16 v[108:111], v[138:141], v[218:221], 0
	v_mfma_f32_16x16x32_bf16 v[104:107], v[150:153], v[218:221], 0
	v_mfma_f32_16x16x32_bf16 v[92:95], v[138:141], v[226:229], 0
	v_mfma_f32_16x16x32_bf16 v[88:91], v[150:153], v[226:229], 0
	v_mfma_f32_16x16x32_bf16 v[76:79], v[138:141], v[234:237], 0
	v_mfma_f32_16x16x32_bf16 v[72:75], v[150:153], v[234:237], 0
	v_mfma_f32_16x16x32_bf16 v[124:127], v[146:149], v[214:217], v[124:127]
	v_mfma_f32_16x16x32_bf16 v[120:123], v[154:157], v[214:217], v[120:123]
	v_mfma_f32_16x16x32_bf16 v[108:111], v[146:149], v[222:225], v[108:111]
	v_mfma_f32_16x16x32_bf16 v[104:107], v[154:157], v[222:225], v[104:107]
	v_mfma_f32_16x16x32_bf16 v[92:95], v[146:149], v[230:233], v[92:95]
	v_mfma_f32_16x16x32_bf16 v[88:91], v[154:157], v[230:233], v[88:91]
	v_mfma_f32_16x16x32_bf16 v[76:79], v[146:149], v[238:241], v[76:79]
	v_mfma_f32_16x16x32_bf16 v[72:75], v[154:157], v[238:241], v[72:75]
	v_mfma_f32_16x16x32_bf16 v[116:119], v[184:187], v[200:203], 0
	v_mfma_f32_16x16x32_bf16 v[112:115], v[192:195], v[200:203], 0
	v_mfma_f32_16x16x32_bf16 v[100:103], v[184:187], v[218:221], 0
	v_mfma_f32_16x16x32_bf16 v[96:99], v[192:195], v[218:221], 0
	v_mfma_f32_16x16x32_bf16 v[84:87], v[184:187], v[226:229], 0
	v_mfma_f32_16x16x32_bf16 v[80:83], v[192:195], v[226:229], 0
	v_mfma_f32_16x16x32_bf16 v[68:71], v[184:187], v[234:237], 0
	v_mfma_f32_16x16x32_bf16 v[64:67], v[192:195], v[234:237], 0
	v_mfma_f32_16x16x32_bf16 v[116:119], v[188:191], v[214:217], v[116:119]
	v_mfma_f32_16x16x32_bf16 v[112:115], v[196:199], v[214:217], v[112:115]
	v_mfma_f32_16x16x32_bf16 v[100:103], v[188:191], v[222:225], v[100:103]
	v_mfma_f32_16x16x32_bf16 v[96:99], v[196:199], v[222:225], v[96:99]
	v_mfma_f32_16x16x32_bf16 v[84:87], v[188:191], v[230:233], v[84:87]
	v_mfma_f32_16x16x32_bf16 v[80:83], v[196:199], v[230:233], v[80:83]
	v_mfma_f32_16x16x32_bf16 v[68:71], v[188:191], v[238:241], v[68:71]
	v_mfma_f32_16x16x32_bf16 v[64:67], v[196:199], v[238:241], v[64:67]
	s_setprio 0
	s_barrier
	s_add_i32 s55, s55, s34
	v_lshl_add_u64 v[158:159], s[44:45], 0, v[160:161]
	s_mov_b32 m0, s55
	ds_read_b128 v[200:203], v145 offset:16384
	ds_read_b128 v[214:217], v145 offset:17408
	ds_read_b128 v[218:221], v145 offset:18432
	ds_read_b128 v[222:225], v145 offset:19456
	ds_read_b128 v[226:229], v145 offset:20480
	ds_read_b128 v[230:233], v145 offset:21504
	ds_read_b128 v[234:237], v145 offset:22528
	ds_read_b128 v[238:241], v145 offset:23552
	global_load_lds_dwordx4 v[158:159], off
	s_add_i32 m0, s55, 0x2000
	s_add_u32 s58, s44, 0x20000
	v_lshl_add_u64 v[162:163], s[44:45], 0, v[128:129]
	s_addc_u32 s59, s45, 0
	s_add_i32 s55, s56, s34
	global_load_lds_dwordx4 v[162:163], off
	v_lshl_add_u64 v[242:243], s[58:59], 0, v[160:161]
	s_mov_b32 m0, s55
	v_lshl_add_u64 v[244:245], s[46:47], 0, v[130:131]
	global_load_lds_dwordx4 v[242:243], off
	v_lshl_add_u64 v[242:243], s[58:59], 0, v[128:129]
	s_add_i32 m0, s55, 0x2000
	s_nop 0
	global_load_lds_dwordx4 v[242:243], off
	v_lshl_add_u64 v[242:243], s[46:47], 0, v[132:133]
	s_mov_b32 m0, s35
	s_nop 0
	global_load_lds_dwordx4 v[242:243], off
	s_mov_b32 m0, s48
	s_nop 0
	global_load_lds_dwordx4 v[244:245], off
	s_waitcnt vmcnt(8)
	s_waitcnt lgkmcnt(0)
	s_barrier
; #define PG8_STAGE(bufoff, gbase, voff) do { _Pragma("unroll") for (int _i = 0; _i < 2; ++_i) \
;         __builtin_amdgcn_global_load_lds((const unsigned*)((const char*)(gbase) + (voff)[_i]), (PG8_LAS unsigned*)(lds + (bufoff) + ldsw + _i * 8192), 16, 0, 0); } while (0)
; #define PG8_WAIT_V(n) asm volatile("s_waitcnt vmcnt(" #n ")" ::: "memory")
; #define PG8_WAIT_L(n) asm volatile("s_waitcnt lgkmcnt(" #n ")" ::: "memory")
; #define PG8_BAR __builtin_amdgcn_s_barrier()
; #define PG8_SCHED __builtin_amdgcn_sched_barrier(0)
; template <class Epi, class Sched, bool ALIGN_EPI = false, bool SP2 = false, bool F8 = false>
; __device__ __forceinline__ void gemm_phase(PG8_LAS unsigned char* lds, const Gemm g, const Sched& S, const Epi& E) {
;     ...
;             PG8_LDB(B0, 0, 0); PG8_LDB(B1, 0, 1); PG8_SCHED; PG8_LDA(At, 0, 0); PG8_STAGE(PG8_SA(1, 1), a1 + hstep, voffA);
;             PG8_WAIT_V(8); PG8_WAIT_L(0); PG8_BAR; PG8_MMA(0, 0, At, B0); PG8_MMA(0, 1, At, B1); PG8_BAR; PG8_SCHED;
;             PG8_LDA(At, 0, 1); PG8_STAGE(PG8_SB(0, 0), b2, voffB); PG8_STAGE(PG8_SB(0, 1), b2 + hstep, voffB); PG8_STAGE(PG8_SA(0, 0), a2, voffA);
;             PG8_WAIT_V(8); PG8_WAIT_L(0); PG8_BAR; PG8_MMA(1, 0, At, B0); PG8_MMA(1, 1, At, B1); PG8_BAR; PG8_SCHED;
;             PG8_LDB(B0, 1, 0); PG8_LDB(B1, 1, 1); PG8_SCHED; PG8_LDA(At, 1, 0); PG8_STAGE(PG8_SA(0, 1), a2 + hstep, voffA);
;             PG8_WAIT_V(8); PG8_WAIT_L(0); PG8_BAR; PG8_MMA(0, 0, At, B0); PG8_MMA(0, 1, At, B1); PG8_BAR; PG8_SCHED;
;             PG8_LDA(At, 1, 1); PG8_STAGE(PG8_SB(1, 0), b3, voffB); PG8_STAGE(PG8_SB(1, 1), b3 + hstep, voffB); PG8_STAGE(PG8_SA(1, 0), a3, voffA);
;             PG8_WAIT_V(8); PG8_WAIT_L(0); PG8_BAR; PG8_MMA(1, 0, At, B0); PG8_MMA(1, 1, At, B1); PG8_BAR; PG8_SCHED;
	s_setprio 1
	s_waitcnt lgkmcnt(0)
	v_mfma_f32_16x16x32_bf16 v[60:63], v[138:141], v[200:203], 0
	v_mfma_f32_16x16x32_bf16 v[56:59], v[150:153], v[200:203], 0
	v_mfma_f32_16x16x32_bf16 v[44:47], v[138:141], v[218:221], 0
	v_mfma_f32_16x16x32_bf16 v[40:43], v[150:153], v[218:221], 0
	v_mfma_f32_16x16x32_bf16 v[28:31], v[138:141], v[226:229], 0
	v_mfma_f32_16x16x32_bf16 v[24:27], v[150:153], v[226:229], 0
	v_mfma_f32_16x16x32_bf16 v[12:15], v[138:141], v[234:237], 0
	v_mfma_f32_16x16x32_bf16 v[8:11], v[150:153], v[234:237], 0
	v_mfma_f32_16x16x32_bf16 v[60:63], v[146:149], v[214:217], v[60:63]
	v_mfma_f32_16x16x32_bf16 v[56:59], v[154:157], v[214:217], v[56:59]
	v_mfma_f32_16x16x32_bf16 v[44:47], v[146:149], v[222:225], v[44:47]
	v_mfma_f32_16x16x32_bf16 v[40:43], v[154:157], v[222:225], v[40:43]
	v_mfma_f32_16x16x32_bf16 v[28:31], v[146:149], v[230:233], v[28:31]
	v_mfma_f32_16x16x32_bf16 v[24:27], v[154:157], v[230:233], v[24:27]
	v_mfma_f32_16x16x32_bf16 v[12:15], v[146:149], v[238:241], v[12:15]
	v_mfma_f32_16x16x32_bf16 v[8:11], v[154:157], v[238:241], v[8:11]
	v_mfma_f32_16x16x32_bf16 v[52:55], v[184:187], v[200:203], 0
	v_mfma_f32_16x16x32_bf16 v[48:51], v[192:195], v[200:203], 0
	v_mfma_f32_16x16x32_bf16 v[36:39], v[184:187], v[218:221], 0
	v_mfma_f32_16x16x32_bf16 v[32:35], v[192:195], v[218:221], 0
	v_mfma_f32_16x16x32_bf16 v[20:23], v[184:187], v[226:229], 0
	v_mfma_f32_16x16x32_bf16 v[16:19], v[192:195], v[226:229], 0
	v_mfma_f32_16x16x32_bf16 v[4:7], v[184:187], v[234:237], 0
	v_mfma_f32_16x16x32_bf16 v[0:3], v[192:195], v[234:237], 0
	v_mfma_f32_16x16x32_bf16 v[52:55], v[188:191], v[214:217], v[52:55]
	v_mfma_f32_16x16x32_bf16 v[48:51], v[196:199], v[214:217], v[48:51]
	v_mfma_f32_16x16x32_bf16 v[36:39], v[188:191], v[222:225], v[36:39]
	v_mfma_f32_16x16x32_bf16 v[32:35], v[196:199], v[222:225], v[32:35]
	v_mfma_f32_16x16x32_bf16 v[20:23], v[188:191], v[230:233], v[20:23]
	v_mfma_f32_16x16x32_bf16 v[16:19], v[196:199], v[230:233], v[16:19]
	v_mfma_f32_16x16x32_bf16 v[4:7], v[188:191], v[238:241], v[4:7]
	v_mfma_f32_16x16x32_bf16 v[0:3], v[196:199], v[238:241], v[0:3]
	s_setprio 0
	s_barrier
	s_add_i32 s55, 0, 0x18000
	s_add_i32 s56, 0, 0x1c000
	v_add_u32_e32 v154, s55, v143
	v_add_u32_e32 v196, s56, v143
	ds_read_b128 v[138:141], v154
	ds_read_b128 v[146:149], v154 offset:1024
	ds_read_b128 v[150:153], v154 offset:2048
	ds_read_b128 v[154:157], v154 offset:3072
	ds_read_b128 v[184:187], v196
	ds_read_b128 v[188:191], v196 offset:1024
	ds_read_b128 v[192:195], v196 offset:2048
	ds_read_b128 v[196:199], v196 offset:3072
	s_add_u32 s46, s46, 0x20000
	s_addc_u32 s47, s47, 0
	s_mov_b32 m0, s49
	v_lshl_add_u64 v[246:247], s[46:47], 0, v[132:133]
	ds_read_b128 v[200:203], v145 offset:32768
	ds_read_b128 v[214:217], v145 offset:33792
	ds_read_b128 v[218:221], v145 offset:34816
	ds_read_b128 v[222:225], v145 offset:35840
	ds_read_b128 v[226:229], v145 offset:36864
	ds_read_b128 v[230:233], v145 offset:37888
	ds_read_b128 v[234:237], v145 offset:38912
	ds_read_b128 v[238:241], v145 offset:39936
	global_load_lds_dwordx4 v[246:247], off
	v_lshl_add_u64 v[246:247], s[46:47], 0, v[130:131]
	s_mov_b32 m0, s50
	s_nop 0
	global_load_lds_dwordx4 v[246:247], off
	s_waitcnt vmcnt(8)
	s_waitcnt lgkmcnt(0)
	s_barrier
	s_setprio 1
	s_waitcnt lgkmcnt(0)
	v_mfma_f32_16x16x32_bf16 v[124:127], v[138:141], v[200:203], v[124:127]
	v_mfma_f32_16x16x32_bf16 v[120:123], v[150:153], v[200:203], v[120:123]
	v_mfma_f32_16x16x32_bf16 v[108:111], v[138:141], v[218:221], v[108:111]
	v_mfma_f32_16x16x32_bf16 v[104:107], v[150:153], v[218:221], v[104:107]
	v_mfma_f32_16x16x32_bf16 v[92:95], v[138:141], v[226:229], v[92:95]
	v_mfma_f32_16x16x32_bf16 v[88:91], v[150:153], v[226:229], v[88:91]
	v_mfma_f32_16x16x32_bf16 v[76:79], v[138:141], v[234:237], v[76:79]
	v_mfma_f32_16x16x32_bf16 v[72:75], v[150:153], v[234:237], v[72:75]
	v_mfma_f32_16x16x32_bf16 v[124:127], v[146:149], v[214:217], v[124:127]
	v_mfma_f32_16x16x32_bf16 v[120:123], v[154:157], v[214:217], v[120:123]
	v_mfma_f32_16x16x32_bf16 v[108:111], v[146:149], v[222:225], v[108:111]
	v_mfma_f32_16x16x32_bf16 v[104:107], v[154:157], v[222:225], v[104:107]
	v_mfma_f32_16x16x32_bf16 v[92:95], v[146:149], v[230:233], v[92:95]
	v_mfma_f32_16x16x32_bf16 v[88:91], v[154:157], v[230:233], v[88:91]
	v_mfma_f32_16x16x32_bf16 v[76:79], v[146:149], v[238:241], v[76:79]
	v_mfma_f32_16x16x32_bf16 v[72:75], v[154:157], v[238:241], v[72:75]
	v_mfma_f32_16x16x32_bf16 v[116:119], v[184:187], v[200:203], v[116:119]
	v_mfma_f32_16x16x32_bf16 v[112:115], v[192:195], v[200:203], v[112:115]
	v_mfma_f32_16x16x32_bf16 v[100:103], v[184:187], v[218:221], v[100:103]
	v_mfma_f32_16x16x32_bf16 v[96:99], v[192:195], v[218:221], v[96:99]
	v_mfma_f32_16x16x32_bf16 v[84:87], v[184:187], v[226:229], v[84:87]
	v_mfma_f32_16x16x32_bf16 v[80:83], v[192:195], v[226:229], v[80:83]
	v_mfma_f32_16x16x32_bf16 v[68:71], v[184:187], v[234:237], v[68:71]
	v_mfma_f32_16x16x32_bf16 v[64:67], v[192:195], v[234:237], v[64:67]
	v_mfma_f32_16x16x32_bf16 v[116:119], v[188:191], v[214:217], v[116:119]
	v_mfma_f32_16x16x32_bf16 v[112:115], v[196:199], v[214:217], v[112:115]
	v_mfma_f32_16x16x32_bf16 v[100:103], v[188:191], v[222:225], v[100:103]
	v_mfma_f32_16x16x32_bf16 v[96:99], v[196:199], v[222:225], v[96:99]
	v_mfma_f32_16x16x32_bf16 v[84:87], v[188:191], v[230:233], v[84:87]
	v_mfma_f32_16x16x32_bf16 v[80:83], v[196:199], v[230:233], v[80:83]
	v_mfma_f32_16x16x32_bf16 v[68:71], v[188:191], v[238:241], v[68:71]
	v_mfma_f32_16x16x32_bf16 v[64:67], v[196:199], v[238:241], v[64:67]
	s_setprio 0
	s_barrier
; #define PG8_STAGE(bufoff, gbase, voff) do { _Pragma("unroll") for (int _i = 0; _i < 2; ++_i) \
;         __builtin_amdgcn_global_load_lds((const unsigned*)((const char*)(gbase) + (voff)[_i]), (PG8_LAS unsigned*)(lds + (bufoff) + ldsw + _i * 8192), 16, 0, 0); } while (0)
; #define PG8_WAIT_V(n) asm volatile("s_waitcnt vmcnt(" #n ")" ::: "memory")
; #define PG8_WAIT_L(n) asm volatile("s_waitcnt lgkmcnt(" #n ")" ::: "memory")
; #define PG8_BAR __builtin_amdgcn_s_barrier()
; #define PG8_SCHED __builtin_amdgcn_sched_barrier(0)
; template <class Epi, class Sched, bool ALIGN_EPI = false, bool SP2 = false, bool F8 = false>
; __device__ __forceinline__ void gemm_phase(PG8_LAS unsigned char* lds, const Gemm g, const Sched& S, const Epi& E) {
;     ...
;         for (int t = 0; t < nt; t += 2) {
;             const bool last = (t == nt - 2);
;             const char* a1 = cA + (size_t)(t + 1) * kstep;
;             const char* a2 = last ? nA : cA + (size_t)(t + 2) * kstep; const char* b2 = last ? nB : cB + (size_t)(t + 2) * kstep;
;             const char* a3 = a2 + kstep; const char* b3 = b2 + kstep;
;             if (last && has_next) S.a_ready(nxt);
;             if constexpr (SP2) {
;             PG8_LDB(B0, 0, 0); PG8_LDB(B1, 0, 1); PG8_SCHED; PG8_LDA(At, 0, 0); PG8_STAGE(PG8_SA(1, 1), a1 + hstep, voffA);
;             PG8_WAIT_V(8); PG8_WAIT_L(0); PG8_BAR; PG8_MMA(0, 0, At, B0); PG8_MMA(0, 1, At, B1); PG8_BAR; PG8_SCHED;
;             PG8_LDA(At, 0, 1); PG8_STAGE(PG8_SB(0, 0), b2, voffB); PG8_STAGE(PG8_SB(0, 1), b2 + hstep, voffB); PG8_STAGE(PG8_SA(0, 0), a2, voffA);
;             PG8_WAIT_V(8); PG8_WAIT_L(0); PG8_BAR; PG8_MMA(1, 0, At, B0); PG8_MMA(1, 1, At, B1); PG8_BAR; PG8_SCHED;
;             PG8_LDB(B0, 1, 0); PG8_LDB(B1, 1, 1); PG8_SCHED; PG8_LDA(At, 1, 0); PG8_STAGE(PG8_SA(0, 1), a2 + hstep, voffA);
;             PG8_WAIT_V(8); PG8_WAIT_L(0); PG8_BAR; PG8_MMA(0, 0, At, B0); PG8_MMA(0, 1, At, B1); PG8_BAR; PG8_SCHED;
;             PG8_LDA(At, 1, 1); PG8_STAGE(PG8_SB(1, 0), b3, voffB); PG8_STAGE(PG8_SB(1, 1), b3 + hstep, voffB); PG8_STAGE(PG8_SA(1, 0), a3, voffA);
;             PG8_WAIT_V(8); PG8_WAIT_L(0); PG8_BAR; PG8_MMA(1, 0, At, B0); PG8_MMA(1, 1, At, B1); PG8_BAR; PG8_SCHED;
	s_add_i32 s46, s55, s34
	v_lshl_add_u64 v[158:159], v[158:159], 0, s[14:15]
	s_mov_b32 m0, s46
	ds_read_b128 v[200:203], v145 offset:49152
	ds_read_b128 v[214:217], v145 offset:50176
	ds_read_b128 v[218:221], v145 offset:51200
	ds_read_b128 v[222:225], v145 offset:52224
	ds_read_b128 v[226:229], v145 offset:53248
	ds_read_b128 v[230:233], v145 offset:54272
	ds_read_b128 v[234:237], v145 offset:55296
	ds_read_b128 v[238:241], v145 offset:56320
	global_load_lds_dwordx4 v[158:159], off
	s_add_i32 m0, s46, 0x2000
	s_add_u32 s44, s44, 0x20080
	v_lshl_add_u64 v[158:159], v[162:163], 0, s[14:15]
	s_addc_u32 s45, s45, 0
	s_add_i32 s46, s56, s34
	global_load_lds_dwordx4 v[158:159], off
	v_lshl_add_u64 v[158:159], s[44:45], 0, v[160:161]
	s_mov_b32 m0, s46
	s_nop 0
	global_load_lds_dwordx4 v[158:159], off
	v_lshl_add_u64 v[158:159], s[44:45], 0, v[128:129]
	s_add_i32 m0, s46, 0x2000
	s_nop 0
	global_load_lds_dwordx4 v[158:159], off
	v_lshl_add_u64 v[158:159], v[242:243], 0, s[14:15]
	s_mov_b32 m0, s51
	s_nop 0
	global_load_lds_dwordx4 v[158:159], off
	v_lshl_add_u64 v[158:159], v[244:245], 0, s[14:15]
	s_mov_b32 m0, s52
	s_nop 0
	global_load_lds_dwordx4 v[158:159], off
	s_waitcnt vmcnt(8)
	s_waitcnt lgkmcnt(0)
	s_barrier
	s_setprio 1
	s_waitcnt lgkmcnt(0)
	v_mfma_f32_16x16x32_bf16 v[60:63], v[138:141], v[200:203], v[60:63]
	v_mfma_f32_16x16x32_bf16 v[56:59], v[150:153], v[200:203], v[56:59]
	v_mfma_f32_16x16x32_bf16 v[44:47], v[138:141], v[218:221], v[44:47]
	v_mfma_f32_16x16x32_bf16 v[40:43], v[150:153], v[218:221], v[40:43]
	v_mfma_f32_16x16x32_bf16 v[28:31], v[138:141], v[226:229], v[28:31]
	v_mfma_f32_16x16x32_bf16 v[24:27], v[150:153], v[226:229], v[24:27]
	v_mfma_f32_16x16x32_bf16 v[12:15], v[138:141], v[234:237], v[12:15]
	v_mfma_f32_16x16x32_bf16 v[8:11], v[150:153], v[234:237], v[8:11]
	v_mfma_f32_16x16x32_bf16 v[60:63], v[146:149], v[214:217], v[60:63]
	v_mfma_f32_16x16x32_bf16 v[56:59], v[154:157], v[214:217], v[56:59]
	v_mfma_f32_16x16x32_bf16 v[44:47], v[146:149], v[222:225], v[44:47]
	v_mfma_f32_16x16x32_bf16 v[40:43], v[154:157], v[222:225], v[40:43]
	v_mfma_f32_16x16x32_bf16 v[28:31], v[146:149], v[230:233], v[28:31]
	v_mfma_f32_16x16x32_bf16 v[24:27], v[154:157], v[230:233], v[24:27]
	v_mfma_f32_16x16x32_bf16 v[12:15], v[146:149], v[238:241], v[12:15]
	v_mfma_f32_16x16x32_bf16 v[8:11], v[154:157], v[238:241], v[8:11]
	v_mfma_f32_16x16x32_bf16 v[52:55], v[184:187], v[200:203], v[52:55]
	v_mfma_f32_16x16x32_bf16 v[48:51], v[192:195], v[200:203], v[48:51]
	v_mfma_f32_16x16x32_bf16 v[36:39], v[184:187], v[218:221], v[36:39]
	v_mfma_f32_16x16x32_bf16 v[32:35], v[192:195], v[218:221], v[32:35]
	v_mfma_f32_16x16x32_bf16 v[20:23], v[184:187], v[226:229], v[20:23]
	v_mfma_f32_16x16x32_bf16 v[16:19], v[192:195], v[226:229], v[16:19]
	v_mfma_f32_16x16x32_bf16 v[4:7], v[184:187], v[234:237], v[4:7]
	v_mfma_f32_16x16x32_bf16 v[0:3], v[192:195], v[234:237], v[0:3]
	v_mfma_f32_16x16x32_bf16 v[52:55], v[188:191], v[214:217], v[52:55]
	v_mfma_f32_16x16x32_bf16 v[48:51], v[196:199], v[214:217], v[48:51]
	v_mfma_f32_16x16x32_bf16 v[36:39], v[188:191], v[222:225], v[36:39]
	v_mfma_f32_16x16x32_bf16 v[32:35], v[196:199], v[222:225], v[32:35]
	v_mfma_f32_16x16x32_bf16 v[20:23], v[188:191], v[230:233], v[20:23]
	v_mfma_f32_16x16x32_bf16 v[16:19], v[196:199], v[230:233], v[16:19]
	v_mfma_f32_16x16x32_bf16 v[4:7], v[188:191], v[238:241], v[4:7]
	v_mfma_f32_16x16x32_bf16 v[0:3], v[196:199], v[238:241], v[0:3]
	s_setprio 0
	s_barrier
	s_add_i32 s54, s54, 2
	s_add_u32 s42, s42, 0x100
	s_addc_u32 s43, s43, 0
	s_add_u32 s28, s28, 0x100
	s_addc_u32 s29, s29, 0
	s_cmp_gt_u32 s54, 5
	s_cbranch_scc0 .LBB0_97
	s_branch .Lgk_after_97
.LBB0_97:
	s_add_u32 s44, s42, 0xfffe0080
	s_addc_u32 s45, s43, -1
	s_add_i32 s55, 0, 0x10000
	s_cmp_eq_u32 s54, 4
	s_cselect_b32 s47, s17, s45
	s_cselect_b32 s46, s19, s44
	s_cselect_b32 s45, s11, s29
	s_cselect_b32 s44, s23, s28
	s_add_i32 s56, 0, 0x14000
	v_add_u32_e32 v154, s55, v143
	v_add_u32_e32 v158, s56, v143
	ds_read_b128 v[138:141], v154
	ds_read_b128 v[146:149], v154 offset:1024
	ds_read_b128 v[150:153], v154 offset:2048
	ds_read_b128 v[154:157], v154 offset:3072
	ds_read_b128 v[184:187], v158
	ds_read_b128 v[188:191], v158 offset:1024
	ds_read_b128 v[192:195], v158 offset:2048
	ds_read_b128 v[196:199], v158 offset:3072
	v_lshl_add_u64 v[158:159], s[42:43], 0, v[134:135]
	s_add_i32 m0, s35, 0xc000
	ds_read_b128 v[200:203], v145
	ds_read_b128 v[214:217], v145 offset:1024
	ds_read_b128 v[218:221], v145 offset:2048
	ds_read_b128 v[222:225], v145 offset:3072
	ds_read_b128 v[226:229], v145 offset:4096
	ds_read_b128 v[230:233], v145 offset:5120
	ds_read_b128 v[234:237], v145 offset:6144
	ds_read_b128 v[238:241], v145 offset:7168
	global_load_lds_dwordx4 v[158:159], off
	v_lshl_add_u64 v[158:159], s[42:43], 0, v[136:137]
	s_add_i32 m0, s35, 0xe000
	s_nop 0
	global_load_lds_dwordx4 v[158:159], off
	s_waitcnt vmcnt(8)
	s_waitcnt lgkmcnt(0)
	s_barrier
; #define PG8_STAGE(bufoff, gbase, voff) do { _Pragma("unroll") for (int _i = 0; _i < 2; ++_i) \
;         __builtin_amdgcn_global_load_lds((const unsigned*)((const char*)(gbase) + (voff)[_i]), (PG8_LAS unsigned*)(lds + (bufoff) + ldsw + _i * 8192), 16, 0, 0); } while (0)
; #define PG8_WAIT_V(n) asm volatile("s_waitcnt vmcnt(" #n ")" ::: "memory")
; #define PG8_WAIT_L(n) asm volatile("s_waitcnt lgkmcnt(" #n ")" ::: "memory")
; #define PG8_BAR __builtin_amdgcn_s_barrier()
; #define PG8_SCHED __builtin_amdgcn_sched_barrier(0)
; template <class Epi, class Sched, bool ALIGN_EPI = false, bool SP2 = false, bool F8 = false>
; __device__ __forceinline__ void gemm_phase(PG8_LAS unsigned char* lds, const Gemm g, const Sched& S, const Epi& E) {
;     ...
;             PG8_LDB(B0, 0, 0); PG8_LDB(B1, 0, 1); PG8_SCHED; PG8_LDA(At, 0, 0); PG8_STAGE(PG8_SA(1, 1), a1 + hstep, voffA);
;             PG8_WAIT_V(8); PG8_WAIT_L(0); PG8_BAR; PG8_MMA(0, 0, At, B0); PG8_MMA(0, 1, At, B1); PG8_BAR; PG8_SCHED;
;             PG8_LDA(At, 0, 1); PG8_STAGE(PG8_SB(0, 0), b2, voffB); PG8_STAGE(PG8_SB(0, 1), b2 + hstep, voffB); PG8_STAGE(PG8_SA(0, 0), a2, voffA);
;             PG8_WAIT_V(8); PG8_WAIT_L(0); PG8_BAR; PG8_MMA(1, 0, At, B0); PG8_MMA(1, 1, At, B1); PG8_BAR; PG8_SCHED;
;             PG8_LDB(B0, 1, 0); PG8_LDB(B1, 1, 1); PG8_SCHED; PG8_LDA(At, 1, 0); PG8_STAGE(PG8_SA(0, 1), a2 + hstep, voffA);
;             PG8_WAIT_V(8); PG8_WAIT_L(0); PG8_BAR; PG8_MMA(0, 0, At, B0); PG8_MMA(0, 1, At, B1); PG8_BAR; PG8_SCHED;
;             PG8_LDA(At, 1, 1); PG8_STAGE(PG8_SB(1, 0), b3, voffB); PG8_STAGE(PG8_SB(1, 1), b3 + hstep, voffB); PG8_STAGE(PG8_SA(1, 0), a3, voffA);
;             PG8_WAIT_V(8); PG8_WAIT_L(0); PG8_BAR; PG8_MMA(1, 0, At, B0); PG8_MMA(1, 1, At, B1); PG8_BAR; PG8_SCHED;
	s_setprio 1
	s_waitcnt lgkmcnt(0)
	v_mfma_f32_16x16x32_bf16 v[124:127], v[138:141], v[200:203], v[124:127]
	v_mfma_f32_16x16x32_bf16 v[120:123], v[150:153], v[200:203], v[120:123]
	v_mfma_f32_16x16x32_bf16 v[108:111], v[138:141], v[218:221], v[108:111]
	v_mfma_f32_16x16x32_bf16 v[104:107], v[150:153], v[218:221], v[104:107]
	v_mfma_f32_16x16x32_bf16 v[92:95], v[138:141], v[226:229], v[92:95]
	v_mfma_f32_16x16x32_bf16 v[88:91], v[150:153], v[226:229], v[88:91]
	v_mfma_f32_16x16x32_bf16 v[76:79], v[138:141], v[234:237], v[76:79]
	v_mfma_f32_16x16x32_bf16 v[72:75], v[150:153], v[234:237], v[72:75]
	v_mfma_f32_16x16x32_bf16 v[124:127], v[146:149], v[214:217], v[124:127]
	v_mfma_f32_16x16x32_bf16 v[120:123], v[154:157], v[214:217], v[120:123]
	v_mfma_f32_16x16x32_bf16 v[108:111], v[146:149], v[222:225], v[108:111]
	v_mfma_f32_16x16x32_bf16 v[104:107], v[154:157], v[222:225], v[104:107]
	v_mfma_f32_16x16x32_bf16 v[92:95], v[146:149], v[230:233], v[92:95]
	v_mfma_f32_16x16x32_bf16 v[88:91], v[154:157], v[230:233], v[88:91]
	v_mfma_f32_16x16x32_bf16 v[76:79], v[146:149], v[238:241], v[76:79]
	v_mfma_f32_16x16x32_bf16 v[72:75], v[154:157], v[238:241], v[72:75]
	v_mfma_f32_16x16x32_bf16 v[116:119], v[184:187], v[200:203], v[116:119]
	v_mfma_f32_16x16x32_bf16 v[112:115], v[192:195], v[200:203], v[112:115]
	v_mfma_f32_16x16x32_bf16 v[100:103], v[184:187], v[218:221], v[100:103]
	v_mfma_f32_16x16x32_bf16 v[96:99], v[192:195], v[218:221], v[96:99]
	v_mfma_f32_16x16x32_bf16 v[84:87], v[184:187], v[226:229], v[84:87]
	v_mfma_f32_16x16x32_bf16 v[80:83], v[192:195], v[226:229], v[80:83]
	v_mfma_f32_16x16x32_bf16 v[68:71], v[184:187], v[234:237], v[68:71]
	v_mfma_f32_16x16x32_bf16 v[64:67], v[192:195], v[234:237], v[64:67]
	v_mfma_f32_16x16x32_bf16 v[116:119], v[188:191], v[214:217], v[116:119]
	v_mfma_f32_16x16x32_bf16 v[112:115], v[196:199], v[214:217], v[112:115]
	v_mfma_f32_16x16x32_bf16 v[100:103], v[188:191], v[222:225], v[100:103]
	v_mfma_f32_16x16x32_bf16 v[96:99], v[196:199], v[222:225], v[96:99]
	v_mfma_f32_16x16x32_bf16 v[84:87], v[188:191], v[230:233], v[84:87]
	v_mfma_f32_16x16x32_bf16 v[80:83], v[196:199], v[230:233], v[80:83]
	v_mfma_f32_16x16x32_bf16 v[68:71], v[188:191], v[238:241], v[68:71]
	v_mfma_f32_16x16x32_bf16 v[64:67], v[196:199], v[238:241], v[64:67]
	s_setprio 0
	s_barrier
	s_add_i32 s55, s55, s34
	v_lshl_add_u64 v[158:159], s[44:45], 0, v[160:161]
	s_mov_b32 m0, s55
	ds_read_b128 v[200:203], v145 offset:16384
	ds_read_b128 v[214:217], v145 offset:17408
	ds_read_b128 v[218:221], v145 offset:18432
	ds_read_b128 v[222:225], v145 offset:19456
	ds_read_b128 v[226:229], v145 offset:20480
	ds_read_b128 v[230:233], v145 offset:21504
	ds_read_b128 v[234:237], v145 offset:22528
	ds_read_b128 v[238:241], v145 offset:23552
	global_load_lds_dwordx4 v[158:159], off
	s_add_i32 m0, s55, 0x2000
	s_add_u32 s58, s44, 0x20000
	v_lshl_add_u64 v[162:163], s[44:45], 0, v[128:129]
	s_addc_u32 s59, s45, 0
	s_add_i32 s55, s56, s34
	global_load_lds_dwordx4 v[162:163], off
	v_lshl_add_u64 v[242:243], s[58:59], 0, v[160:161]
	s_mov_b32 m0, s55
	v_lshl_add_u64 v[244:245], s[46:47], 0, v[130:131]
	global_load_lds_dwordx4 v[242:243], off
	v_lshl_add_u64 v[242:243], s[58:59], 0, v[128:129]
	s_add_i32 m0, s55, 0x2000
	s_nop 0
	global_load_lds_dwordx4 v[242:243], off
	v_lshl_add_u64 v[242:243], s[46:47], 0, v[132:133]
	s_mov_b32 m0, s35
	s_nop 0
	global_load_lds_dwordx4 v[242:243], off
	s_mov_b32 m0, s48
	s_nop 0
	global_load_lds_dwordx4 v[244:245], off
	s_waitcnt vmcnt(8)
	s_waitcnt lgkmcnt(0)
	s_barrier
	s_setprio 1
	s_waitcnt lgkmcnt(0)
	v_mfma_f32_16x16x32_bf16 v[60:63], v[138:141], v[200:203], v[60:63]
	v_mfma_f32_16x16x32_bf16 v[56:59], v[150:153], v[200:203], v[56:59]
	v_mfma_f32_16x16x32_bf16 v[44:47], v[138:141], v[218:221], v[44:47]
	v_mfma_f32_16x16x32_bf16 v[40:43], v[150:153], v[218:221], v[40:43]
	v_mfma_f32_16x16x32_bf16 v[28:31], v[138:141], v[226:229], v[28:31]
	v_mfma_f32_16x16x32_bf16 v[24:27], v[150:153], v[226:229], v[24:27]
	v_mfma_f32_16x16x32_bf16 v[12:15], v[138:141], v[234:237], v[12:15]
	v_mfma_f32_16x16x32_bf16 v[8:11], v[150:153], v[234:237], v[8:11]
	v_mfma_f32_16x16x32_bf16 v[60:63], v[146:149], v[214:217], v[60:63]
	v_mfma_f32_16x16x32_bf16 v[56:59], v[154:157], v[214:217], v[56:59]
	v_mfma_f32_16x16x32_bf16 v[44:47], v[146:149], v[222:225], v[44:47]
	v_mfma_f32_16x16x32_bf16 v[40:43], v[154:157], v[222:225], v[40:43]
	v_mfma_f32_16x16x32_bf16 v[28:31], v[146:149], v[230:233], v[28:31]
	v_mfma_f32_16x16x32_bf16 v[24:27], v[154:157], v[230:233], v[24:27]
	v_mfma_f32_16x16x32_bf16 v[12:15], v[146:149], v[238:241], v[12:15]
	v_mfma_f32_16x16x32_bf16 v[8:11], v[154:157], v[238:241], v[8:11]
	v_mfma_f32_16x16x32_bf16 v[52:55], v[184:187], v[200:203], v[52:55]
	v_mfma_f32_16x16x32_bf16 v[48:51], v[192:195], v[200:203], v[48:51]
	v_mfma_f32_16x16x32_bf16 v[36:39], v[184:187], v[218:221], v[36:39]
	v_mfma_f32_16x16x32_bf16 v[32:35], v[192:195], v[218:221], v[32:35]
	v_mfma_f32_16x16x32_bf16 v[20:23], v[184:187], v[226:229], v[20:23]
	v_mfma_f32_16x16x32_bf16 v[16:19], v[192:195], v[226:229], v[16:19]
	v_mfma_f32_16x16x32_bf16 v[4:7], v[184:187], v[234:237], v[4:7]
	v_mfma_f32_16x16x32_bf16 v[0:3], v[192:195], v[234:237], v[0:3]
	v_mfma_f32_16x16x32_bf16 v[52:55], v[188:191], v[214:217], v[52:55]
	v_mfma_f32_16x16x32_bf16 v[48:51], v[196:199], v[214:217], v[48:51]
	v_mfma_f32_16x16x32_bf16 v[36:39], v[188:191], v[222:225], v[36:39]
	v_mfma_f32_16x16x32_bf16 v[32:35], v[196:199], v[222:225], v[32:35]
	v_mfma_f32_16x16x32_bf16 v[20:23], v[188:191], v[230:233], v[20:23]
	v_mfma_f32_16x16x32_bf16 v[16:19], v[196:199], v[230:233], v[16:19]
	v_mfma_f32_16x16x32_bf16 v[4:7], v[188:191], v[238:241], v[4:7]
	v_mfma_f32_16x16x32_bf16 v[0:3], v[196:199], v[238:241], v[0:3]
	s_setprio 0
	s_barrier
; #define PG8_STAGE(bufoff, gbase, voff) do { _Pragma("unroll") for (int _i = 0; _i < 2; ++_i) \
;         __builtin_amdgcn_global_load_lds((const unsigned*)((const char*)(gbase) + (voff)[_i]), (PG8_LAS unsigned*)(lds + (bufoff) + ldsw + _i * 8192), 16, 0, 0); } while (0)
; #define PG8_WAIT_V(n) asm volatile("s_waitcnt vmcnt(" #n ")" ::: "memory")
; #define PG8_WAIT_L(n) asm volatile("s_waitcnt lgkmcnt(" #n ")" ::: "memory")
; #define PG8_BAR __builtin_amdgcn_s_barrier()
; #define PG8_SCHED __builtin_amdgcn_sched_barrier(0)
; template <class Epi, class Sched, bool ALIGN_EPI = false, bool SP2 = false, bool F8 = false>
; __device__ __forceinline__ void gemm_phase(PG8_LAS unsigned char* lds, const Gemm g, const Sched& S, const Epi& E) {
;     ...
;             PG8_LDB(B0, 1, 0); PG8_LDB(B1, 1, 1); PG8_SCHED; PG8_LDA(At, 1, 0); PG8_STAGE(PG8_SA(0, 1), a2 + hstep, voffA);
;             PG8_WAIT_V(8); PG8_WAIT_L(0); PG8_BAR; PG8_MMA(0, 0, At, B0); PG8_MMA(0, 1, At, B1); PG8_BAR; PG8_SCHED;
	s_add_i32 s55, 0, 0x18000
	s_add_i32 s56, 0, 0x1c000
	v_add_u32_e32 v154, s55, v143
	v_add_u32_e32 v196, s56, v143
	ds_read_b128 v[138:141], v154
	ds_read_b128 v[146:149], v154 offset:1024
	ds_read_b128 v[150:153], v154 offset:2048
	ds_read_b128 v[154:157], v154 offset:3072
	ds_read_b128 v[184:187], v196
	ds_read_b128 v[188:191], v196 offset:1024
	ds_read_b128 v[192:195], v196 offset:2048
	ds_read_b128 v[196:199], v196 offset:3072
	s_add_u32 s46, s46, 0x20000
	s_addc_u32 s47, s47, 0
	s_mov_b32 m0, s49
	v_lshl_add_u64 v[246:247], s[46:47], 0, v[132:133]
	ds_read_b128 v[200:203], v145 offset:32768
	ds_read_b128 v[214:217], v145 offset:33792
	ds_read_b128 v[218:221], v145 offset:34816
	ds_read_b128 v[222:225], v145 offset:35840
	ds_read_b128 v[226:229], v145 offset:36864
	ds_read_b128 v[230:233], v145 offset:37888
	ds_read_b128 v[234:237], v145 offset:38912
	ds_read_b128 v[238:241], v145 offset:39936
	global_load_lds_dwordx4 v[246:247], off
	v_lshl_add_u64 v[246:247], s[46:47], 0, v[130:131]
	s_mov_b32 m0, s50
	s_nop 0
	global_load_lds_dwordx4 v[246:247], off
	s_waitcnt vmcnt(8)
	s_waitcnt lgkmcnt(0)
	s_barrier
	s_setprio 1
	s_waitcnt lgkmcnt(0)
	v_mfma_f32_16x16x32_bf16 v[124:127], v[138:141], v[200:203], v[124:127]
	v_mfma_f32_16x16x32_bf16 v[120:123], v[150:153], v[200:203], v[120:123]
	v_mfma_f32_16x16x32_bf16 v[108:111], v[138:141], v[218:221], v[108:111]
	v_mfma_f32_16x16x32_bf16 v[104:107], v[150:153], v[218:221], v[104:107]
	v_mfma_f32_16x16x32_bf16 v[92:95], v[138:141], v[226:229], v[92:95]
	v_mfma_f32_16x16x32_bf16 v[88:91], v[150:153], v[226:229], v[88:91]
	v_mfma_f32_16x16x32_bf16 v[76:79], v[138:141], v[234:237], v[76:79]
	v_mfma_f32_16x16x32_bf16 v[72:75], v[150:153], v[234:237], v[72:75]
	v_mfma_f32_16x16x32_bf16 v[124:127], v[146:149], v[214:217], v[124:127]
	v_mfma_f32_16x16x32_bf16 v[120:123], v[154:157], v[214:217], v[120:123]
	v_mfma_f32_16x16x32_bf16 v[108:111], v[146:149], v[222:225], v[108:111]
	v_mfma_f32_16x16x32_bf16 v[104:107], v[154:157], v[222:225], v[104:107]
	v_mfma_f32_16x16x32_bf16 v[92:95], v[146:149], v[230:233], v[92:95]
	v_mfma_f32_16x16x32_bf16 v[88:91], v[154:157], v[230:233], v[88:91]
	v_mfma_f32_16x16x32_bf16 v[76:79], v[146:149], v[238:241], v[76:79]
	v_mfma_f32_16x16x32_bf16 v[72:75], v[154:157], v[238:241], v[72:75]
	v_mfma_f32_16x16x32_bf16 v[116:119], v[184:187], v[200:203], v[116:119]
	v_mfma_f32_16x16x32_bf16 v[112:115], v[192:195], v[200:203], v[112:115]
	v_mfma_f32_16x16x32_bf16 v[100:103], v[184:187], v[218:221], v[100:103]
	v_mfma_f32_16x16x32_bf16 v[96:99], v[192:195], v[218:221], v[96:99]
	v_mfma_f32_16x16x32_bf16 v[84:87], v[184:187], v[226:229], v[84:87]
	v_mfma_f32_16x16x32_bf16 v[80:83], v[192:195], v[226:229], v[80:83]
	v_mfma_f32_16x16x32_bf16 v[68:71], v[184:187], v[234:237], v[68:71]
	v_mfma_f32_16x16x32_bf16 v[64:67], v[192:195], v[234:237], v[64:67]
	v_mfma_f32_16x16x32_bf16 v[116:119], v[188:191], v[214:217], v[116:119]
	v_mfma_f32_16x16x32_bf16 v[112:115], v[196:199], v[214:217], v[112:115]
	v_mfma_f32_16x16x32_bf16 v[100:103], v[188:191], v[222:225], v[100:103]
	v_mfma_f32_16x16x32_bf16 v[96:99], v[196:199], v[222:225], v[96:99]
	v_mfma_f32_16x16x32_bf16 v[84:87], v[188:191], v[230:233], v[84:87]
	v_mfma_f32_16x16x32_bf16 v[80:83], v[196:199], v[230:233], v[80:83]
	v_mfma_f32_16x16x32_bf16 v[68:71], v[188:191], v[238:241], v[68:71]
	v_mfma_f32_16x16x32_bf16 v[64:67], v[196:199], v[238:241], v[64:67]
	s_setprio 0
	s_barrier
; #define PG8_STAGE(bufoff, gbase, voff) do { _Pragma("unroll") for (int _i = 0; _i < 2; ++_i) \
;         __builtin_amdgcn_global_load_lds((const unsigned*)((const char*)(gbase) + (voff)[_i]), (PG8_LAS unsigned*)(lds + (bufoff) + ldsw + _i * 8192), 16, 0, 0); } while (0)
; #define PG8_WAIT_V(n) asm volatile("s_waitcnt vmcnt(" #n ")" ::: "memory")
; #define PG8_WAIT_L(n) asm volatile("s_waitcnt lgkmcnt(" #n ")" ::: "memory")
; #define PG8_BAR __builtin_amdgcn_s_barrier()
; #define PG8_SCHED __builtin_amdgcn_sched_barrier(0)
; template <class Epi, class Sched, bool ALIGN_EPI = false, bool SP2 = false, bool F8 = false>
; __device__ __forceinline__ void gemm_phase(PG8_LAS unsigned char* lds, const Gemm g, const Sched& S, const Epi& E) {
;     ...
;         for (int t = 0; t < nt; t += 2) {
;             const bool last = (t == nt - 2);
;             const char* a1 = cA + (size_t)(t + 1) * kstep;
;             const char* a2 = last ? nA : cA + (size_t)(t + 2) * kstep; const char* b2 = last ? nB : cB + (size_t)(t + 2) * kstep;
;             const char* a3 = a2 + kstep; const char* b3 = b2 + kstep;
;             if (last && has_next) S.a_ready(nxt);
;             if constexpr (SP2) {
;             PG8_LDB(B0, 0, 0); PG8_LDB(B1, 0, 1); PG8_SCHED; PG8_LDA(At, 0, 0); PG8_STAGE(PG8_SA(1, 1), a1 + hstep, voffA);
;             PG8_WAIT_V(8); PG8_WAIT_L(0); PG8_BAR; PG8_MMA(0, 0, At, B0); PG8_MMA(0, 1, At, B1); PG8_BAR; PG8_SCHED;
;             PG8_LDA(At, 0, 1); PG8_STAGE(PG8_SB(0, 0), b2, voffB); PG8_STAGE(PG8_SB(0, 1), b2 + hstep, voffB); PG8_STAGE(PG8_SA(0, 0), a2, voffA);
;             PG8_WAIT_V(8); PG8_WAIT_L(0); PG8_BAR; PG8_MMA(1, 0, At, B0); PG8_MMA(1, 1, At, B1); PG8_BAR; PG8_SCHED;
;             PG8_LDB(B0, 1, 0); PG8_LDB(B1, 1, 1); PG8_SCHED; PG8_LDA(At, 1, 0); PG8_STAGE(PG8_SA(0, 1), a2 + hstep, voffA);
;             PG8_WAIT_V(8); PG8_WAIT_L(0); PG8_BAR; PG8_MMA(0, 0, At, B0); PG8_MMA(0, 1, At, B1); PG8_BAR; PG8_SCHED;
;             PG8_LDA(At, 1, 1); PG8_STAGE(PG8_SB(1, 0), b3, voffB); PG8_STAGE(PG8_SB(1, 1), b3 + hstep, voffB); PG8_STAGE(PG8_SA(1, 0), a3, voffA);
;             PG8_WAIT_V(8); PG8_WAIT_L(0); PG8_BAR; PG8_MMA(1, 0, At, B0); PG8_MMA(1, 1, At, B1); PG8_BAR; PG8_SCHED;
	s_add_i32 s46, s55, s34
	v_lshl_add_u64 v[158:159], v[158:159], 0, s[14:15]
	s_mov_b32 m0, s46
	ds_read_b128 v[200:203], v145 offset:49152
	ds_read_b128 v[214:217], v145 offset:50176
	ds_read_b128 v[218:221], v145 offset:51200
	ds_read_b128 v[222:225], v145 offset:52224
	ds_read_b128 v[226:229], v145 offset:53248
	ds_read_b128 v[230:233], v145 offset:54272
	ds_read_b128 v[234:237], v145 offset:55296
	ds_read_b128 v[238:241], v145 offset:56320
	global_load_lds_dwordx4 v[158:159], off
	s_add_i32 m0, s46, 0x2000
	s_add_u32 s44, s44, 0x20080
	v_lshl_add_u64 v[158:159], v[162:163], 0, s[14:15]
	s_addc_u32 s45, s45, 0
	s_add_i32 s46, s56, s34
	global_load_lds_dwordx4 v[158:159], off
	v_lshl_add_u64 v[158:159], s[44:45], 0, v[160:161]
	s_mov_b32 m0, s46
	s_nop 0
	global_load_lds_dwordx4 v[158:159], off
	v_lshl_add_u64 v[158:159], s[44:45], 0, v[128:129]
	s_add_i32 m0, s46, 0x2000
	s_nop 0
	global_load_lds_dwordx4 v[158:159], off
	v_lshl_add_u64 v[158:159], v[242:243], 0, s[14:15]
	s_mov_b32 m0, s51
	s_nop 0
	global_load_lds_dwordx4 v[158:159], off
	v_lshl_add_u64 v[158:159], v[244:245], 0, s[14:15]
	s_mov_b32 m0, s52
	s_nop 0
	global_load_lds_dwordx4 v[158:159], off
	s_waitcnt vmcnt(8)
	s_waitcnt lgkmcnt(0)
	s_barrier
	s_setprio 1
	s_waitcnt lgkmcnt(0)
	v_mfma_f32_16x16x32_bf16 v[60:63], v[138:141], v[200:203], v[60:63]
	v_mfma_f32_16x16x32_bf16 v[56:59], v[150:153], v[200:203], v[56:59]
	v_mfma_f32_16x16x32_bf16 v[44:47], v[138:141], v[218:221], v[44:47]
	v_mfma_f32_16x16x32_bf16 v[40:43], v[150:153], v[218:221], v[40:43]
	v_mfma_f32_16x16x32_bf16 v[28:31], v[138:141], v[226:229], v[28:31]
	v_mfma_f32_16x16x32_bf16 v[24:27], v[150:153], v[226:229], v[24:27]
	v_mfma_f32_16x16x32_bf16 v[12:15], v[138:141], v[234:237], v[12:15]
	v_mfma_f32_16x16x32_bf16 v[8:11], v[150:153], v[234:237], v[8:11]
	v_mfma_f32_16x16x32_bf16 v[60:63], v[146:149], v[214:217], v[60:63]
	v_mfma_f32_16x16x32_bf16 v[56:59], v[154:157], v[214:217], v[56:59]
	v_mfma_f32_16x16x32_bf16 v[44:47], v[146:149], v[222:225], v[44:47]
	v_mfma_f32_16x16x32_bf16 v[40:43], v[154:157], v[222:225], v[40:43]
	v_mfma_f32_16x16x32_bf16 v[28:31], v[146:149], v[230:233], v[28:31]
	v_mfma_f32_16x16x32_bf16 v[24:27], v[154:157], v[230:233], v[24:27]
	v_mfma_f32_16x16x32_bf16 v[12:15], v[146:149], v[238:241], v[12:15]
	v_mfma_f32_16x16x32_bf16 v[8:11], v[154:157], v[238:241], v[8:11]
	v_mfma_f32_16x16x32_bf16 v[52:55], v[184:187], v[200:203], v[52:55]
	v_mfma_f32_16x16x32_bf16 v[48:51], v[192:195], v[200:203], v[48:51]
	v_mfma_f32_16x16x32_bf16 v[36:39], v[184:187], v[218:221], v[36:39]
	v_mfma_f32_16x16x32_bf16 v[32:35], v[192:195], v[218:221], v[32:35]
	v_mfma_f32_16x16x32_bf16 v[20:23], v[184:187], v[226:229], v[20:23]
	v_mfma_f32_16x16x32_bf16 v[16:19], v[192:195], v[226:229], v[16:19]
	v_mfma_f32_16x16x32_bf16 v[4:7], v[184:187], v[234:237], v[4:7]
	v_mfma_f32_16x16x32_bf16 v[0:3], v[192:195], v[234:237], v[0:3]
	v_mfma_f32_16x16x32_bf16 v[52:55], v[188:191], v[214:217], v[52:55]
	v_mfma_f32_16x16x32_bf16 v[48:51], v[196:199], v[214:217], v[48:51]
	v_mfma_f32_16x16x32_bf16 v[36:39], v[188:191], v[222:225], v[36:39]
	v_mfma_f32_16x16x32_bf16 v[32:35], v[196:199], v[222:225], v[32:35]
	v_mfma_f32_16x16x32_bf16 v[20:23], v[188:191], v[230:233], v[20:23]
	v_mfma_f32_16x16x32_bf16 v[16:19], v[196:199], v[230:233], v[16:19]
	v_mfma_f32_16x16x32_bf16 v[4:7], v[188:191], v[238:241], v[4:7]
	v_mfma_f32_16x16x32_bf16 v[0:3], v[196:199], v[238:241], v[0:3]
	s_setprio 0
	s_barrier
	s_add_i32 s54, s54, 2
	s_add_u32 s42, s42, 0x100
	s_addc_u32 s43, s43, 0
	s_add_u32 s28, s28, 0x100
	s_addc_u32 s29, s29, 0
	s_cmp_gt_u32 s54, 5
	s_cbranch_scc0 .LBB0_97

; #define PG8_STAGE(bufoff, gbase, voff) do { _Pragma("unroll") for (int _i = 0; _i < 2; ++_i) \
;         __builtin_amdgcn_global_load_lds((const unsigned*)((const char*)(gbase) + (voff)[_i]), (PG8_LAS unsigned*)(lds + (bufoff) + ldsw + _i * 8192), 16, 0, 0); } while (0)
; #define PG8_WAIT_V(n) asm volatile("s_waitcnt vmcnt(" #n ")" ::: "memory")
; #define PG8_WAIT_L(n) asm volatile("s_waitcnt lgkmcnt(" #n ")" ::: "memory")
; #define PG8_BAR __builtin_amdgcn_s_barrier()
; template <class Epi, class Sched, bool ALIGN_EPI = false, bool SP2 = false, bool F8 = false>
; __device__ __forceinline__ void gemm_phase(PG8_LAS unsigned char* lds, const Gemm g, const Sched& S, const Epi& E) {
;     ...
;         const bool has_next = S.next(ui + 1, nxt);
;         const char* nA = has_next ? (const char*)g.A + (size_t)nxt.pm * tstep : cA; const char* nB = has_next ? (const char*)g.Bt + (size_t)nxt.pn * tstep : cB;
;         for (int t = 0; t < nt; t += 2) {
;             const bool last = (t == nt - 2);
;             const char* a1 = cA + (size_t)(t + 1) * kstep;
;             const char* a2 = last ? nA : cA + (size_t)(t + 2) * kstep; const char* b2 = last ? nB : cB + (size_t)(t + 2) * kstep;
;             const char* a3 = a2 + kstep; const char* b3 = b2 + kstep;
;             if (last && has_next) S.a_ready(nxt);
;             if constexpr (SP2) {
;             PG8_LDB(B0, 0, 0); PG8_LDB(B1, 0, 1); PG8_SCHED; PG8_LDA(At, 0, 0); PG8_STAGE(PG8_SA(1, 1), a1 + hstep, voffA);
;             PG8_WAIT_V(8); PG8_WAIT_L(0); PG8_BAR; PG8_MMA(0, 0, At, B0); PG8_MMA(0, 1, At, B1); PG8_BAR; PG8_SCHED;
;             PG8_LDA(At, 0, 1); PG8_STAGE(PG8_SB(0, 0), b2, voffB); PG8_STAGE(PG8_SB(0, 1), b2 + hstep, voffB); PG8_STAGE(PG8_SA(0, 0), a2, voffA);
;             PG8_WAIT_V(8); PG8_WAIT_L(0); PG8_BAR; PG8_MMA(1, 0, At, B0); PG8_MMA(1, 1, At, B1); PG8_BAR; PG8_SCHED;
;             PG8_LDB(B0, 1, 0); PG8_LDB(B1, 1, 1); PG8_SCHED; PG8_LDA(At, 1, 0); PG8_STAGE(PG8_SA(0, 1), a2 + hstep, voffA);
;             PG8_WAIT_V(8); PG8_WAIT_L(0); PG8_BAR; PG8_MMA(0, 0, At, B0); PG8_MMA(0, 1, At, B1); PG8_BAR; PG8_SCHED;
;             PG8_LDA(At, 1, 1); PG8_STAGE(PG8_SB(1, 0), b3, voffB); PG8_STAGE(PG8_SB(1, 1), b3 + hstep, voffB); PG8_STAGE(PG8_SA(1, 0), a3, voffA);
;             PG8_WAIT_V(8); PG8_WAIT_L(0); PG8_BAR; PG8_MMA(1, 0, At, B0); PG8_MMA(1, 1, At, B1); PG8_BAR; PG8_SCHED;
.LBB0_116:
	s_ashr_i32 s41, s40, 31
	s_lshl_b64 s[28:29], s[40:41], 19
	s_add_u32 s42, s96, s28
	v_readlane_b32 s17, v253, 22
	s_addc_u32 s43, s17, s29
	s_and_b64 s[28:29], s[38:39], exec
	s_cselect_b32 s19, s43, s11
	s_cselect_b32 s23, s42, s10
	s_ashr_i32 s17, s16, 31
	s_lshl_b64 s[28:29], s[16:17], 19
	s_add_u32 s44, s22, s28
	s_addc_u32 s45, s34, s29
	s_and_b64 s[28:29], s[38:39], exec
	s_cselect_b32 s17, s45, s37
	s_cselect_b32 s28, s44, s36
	s_add_u32 s10, s10, 0x40080
	s_addc_u32 s11, s11, 0
	s_add_u32 s29, s36, 0x100
	s_addc_u32 s41, s37, 0
	s_mov_b32 s54, -2
	s_add_u32 s36, s10, 0xfffc0080
	s_addc_u32 s37, s11, -1
	s_add_i32 s55, 0, 0x10000
	s_cmp_eq_u32 s54, 12
	s_cselect_b32 s47, s19, s37
	s_cselect_b32 s46, s23, s36
	v_add_u32_e32 v142, s55, v145
	s_cselect_b32 s37, s17, s41
	s_cselect_b32 s36, s28, s29
	s_add_i32 s56, 0, 0x14000
	ds_read_b128 v[138:141], v142
	ds_read_b128 v[148:151], v142 offset:1024
	ds_read_b128 v[152:155], v142 offset:2048
	ds_read_b128 v[156:159], v142 offset:3072
	v_add_u32_e32 v142, s56, v145
	ds_read_b128 v[184:187], v142
	ds_read_b128 v[188:191], v142 offset:1024
	ds_read_b128 v[192:195], v142 offset:2048
	ds_read_b128 v[196:199], v142 offset:3072
	v_lshl_add_u64 v[142:143], s[10:11], 0, v[134:135]
	s_add_i32 m0, s35, 0xc000
	ds_read_b128 v[200:203], v147
	ds_read_b128 v[214:217], v147 offset:1024
	ds_read_b128 v[218:221], v147 offset:2048
	ds_read_b128 v[222:225], v147 offset:3072
	ds_read_b128 v[226:229], v147 offset:4096
	ds_read_b128 v[230:233], v147 offset:5120
	ds_read_b128 v[234:237], v147 offset:6144
	ds_read_b128 v[238:241], v147 offset:7168
	global_load_lds_dwordx4 v[142:143], off
	v_lshl_add_u64 v[142:143], s[10:11], 0, v[136:137]
	s_add_i32 m0, s35, 0xe000
	s_nop 0
	global_load_lds_dwordx4 v[142:143], off
	s_waitcnt vmcnt(8)
	s_waitcnt lgkmcnt(0)
	s_barrier
	s_setprio 1
	s_waitcnt lgkmcnt(0)
	v_mfma_f32_16x16x32_bf16 v[124:127], v[138:141], v[200:203], 0
	v_mfma_f32_16x16x32_bf16 v[120:123], v[152:155], v[200:203], 0
	v_mfma_f32_16x16x32_bf16 v[108:111], v[138:141], v[218:221], 0
	v_mfma_f32_16x16x32_bf16 v[104:107], v[152:155], v[218:221], 0
	v_mfma_f32_16x16x32_bf16 v[92:95], v[138:141], v[226:229], 0
	v_mfma_f32_16x16x32_bf16 v[88:91], v[152:155], v[226:229], 0
	v_mfma_f32_16x16x32_bf16 v[76:79], v[138:141], v[234:237], 0
	v_mfma_f32_16x16x32_bf16 v[72:75], v[152:155], v[234:237], 0
	v_mfma_f32_16x16x32_bf16 v[124:127], v[148:151], v[214:217], v[124:127]
	v_mfma_f32_16x16x32_bf16 v[120:123], v[156:159], v[214:217], v[120:123]
	v_mfma_f32_16x16x32_bf16 v[108:111], v[148:151], v[222:225], v[108:111]
	v_mfma_f32_16x16x32_bf16 v[104:107], v[156:159], v[222:225], v[104:107]
	v_mfma_f32_16x16x32_bf16 v[92:95], v[148:151], v[230:233], v[92:95]
	v_mfma_f32_16x16x32_bf16 v[88:91], v[156:159], v[230:233], v[88:91]
	v_mfma_f32_16x16x32_bf16 v[76:79], v[148:151], v[238:241], v[76:79]
	v_mfma_f32_16x16x32_bf16 v[72:75], v[156:159], v[238:241], v[72:75]
	v_mfma_f32_16x16x32_bf16 v[116:119], v[184:187], v[200:203], 0
	v_mfma_f32_16x16x32_bf16 v[112:115], v[192:195], v[200:203], 0
	v_mfma_f32_16x16x32_bf16 v[100:103], v[184:187], v[218:221], 0
	v_mfma_f32_16x16x32_bf16 v[96:99], v[192:195], v[218:221], 0
	v_mfma_f32_16x16x32_bf16 v[84:87], v[184:187], v[226:229], 0
	v_mfma_f32_16x16x32_bf16 v[80:83], v[192:195], v[226:229], 0
	v_mfma_f32_16x16x32_bf16 v[68:71], v[184:187], v[234:237], 0
	v_mfma_f32_16x16x32_bf16 v[64:67], v[192:195], v[234:237], 0
	v_mfma_f32_16x16x32_bf16 v[116:119], v[188:191], v[214:217], v[116:119]
	v_mfma_f32_16x16x32_bf16 v[112:115], v[196:199], v[214:217], v[112:115]
	v_mfma_f32_16x16x32_bf16 v[100:103], v[188:191], v[222:225], v[100:103]
	v_mfma_f32_16x16x32_bf16 v[96:99], v[196:199], v[222:225], v[96:99]
	v_mfma_f32_16x16x32_bf16 v[84:87], v[188:191], v[230:233], v[84:87]
	v_mfma_f32_16x16x32_bf16 v[80:83], v[196:199], v[230:233], v[80:83]
	v_mfma_f32_16x16x32_bf16 v[68:71], v[188:191], v[238:241], v[68:71]
	v_mfma_f32_16x16x32_bf16 v[64:67], v[196:199], v[238:241], v[64:67]
	s_setprio 0
	s_barrier
	s_add_i32 s55, s55, s13
	v_lshl_add_u64 v[142:143], s[36:37], 0, v[160:161]
	s_mov_b32 m0, s55
	ds_read_b128 v[200:203], v147 offset:16384
	ds_read_b128 v[214:217], v147 offset:17408
	ds_read_b128 v[218:221], v147 offset:18432
	ds_read_b128 v[222:225], v147 offset:19456
	ds_read_b128 v[226:229], v147 offset:20480
	ds_read_b128 v[230:233], v147 offset:21504
	ds_read_b128 v[234:237], v147 offset:22528
	ds_read_b128 v[238:241], v147 offset:23552
	global_load_lds_dwordx4 v[142:143], off
	s_add_i32 m0, s55, 0x2000
	s_add_u32 s58, s36, 0x40000
	v_lshl_add_u64 v[162:163], s[36:37], 0, v[128:129]
	s_addc_u32 s59, s37, 0
	s_add_i32 s55, s56, s13
	global_load_lds_dwordx4 v[162:163], off
	v_lshl_add_u64 v[242:243], s[58:59], 0, v[160:161]
	s_mov_b32 m0, s55
	v_lshl_add_u64 v[244:245], s[46:47], 0, v[130:131]
	global_load_lds_dwordx4 v[242:243], off
	v_lshl_add_u64 v[242:243], s[58:59], 0, v[128:129]
	s_add_i32 m0, s55, 0x2000
	s_nop 0
	global_load_lds_dwordx4 v[242:243], off
	v_lshl_add_u64 v[242:243], s[46:47], 0, v[132:133]
	s_mov_b32 m0, s35
	s_nop 0
	global_load_lds_dwordx4 v[242:243], off
	s_mov_b32 m0, s48
	s_nop 0
	global_load_lds_dwordx4 v[244:245], off
	s_waitcnt vmcnt(8)
	s_waitcnt lgkmcnt(0)
	s_barrier
; #define PG8_STAGE(bufoff, gbase, voff) do { _Pragma("unroll") for (int _i = 0; _i < 2; ++_i) \
;         __builtin_amdgcn_global_load_lds((const unsigned*)((const char*)(gbase) + (voff)[_i]), (PG8_LAS unsigned*)(lds + (bufoff) + ldsw + _i * 8192), 16, 0, 0); } while (0)
; #define PG8_WAIT_V(n) asm volatile("s_waitcnt vmcnt(" #n ")" ::: "memory")
; #define PG8_WAIT_L(n) asm volatile("s_waitcnt lgkmcnt(" #n ")" ::: "memory")
; #define PG8_BAR __builtin_amdgcn_s_barrier()
; #define PG8_SCHED __builtin_amdgcn_sched_barrier(0)
; template <class Epi, class Sched, bool ALIGN_EPI = false, bool SP2 = false, bool F8 = false>
; __device__ __forceinline__ void gemm_phase(PG8_LAS unsigned char* lds, const Gemm g, const Sched& S, const Epi& E) {
;     ...
;             PG8_LDB(B0, 0, 0); PG8_LDB(B1, 0, 1); PG8_SCHED; PG8_LDA(At, 0, 0); PG8_STAGE(PG8_SA(1, 1), a1 + hstep, voffA);
;             PG8_WAIT_V(8); PG8_WAIT_L(0); PG8_BAR; PG8_MMA(0, 0, At, B0); PG8_MMA(0, 1, At, B1); PG8_BAR; PG8_SCHED;
;             PG8_LDA(At, 0, 1); PG8_STAGE(PG8_SB(0, 0), b2, voffB); PG8_STAGE(PG8_SB(0, 1), b2 + hstep, voffB); PG8_STAGE(PG8_SA(0, 0), a2, voffA);
;             PG8_WAIT_V(8); PG8_WAIT_L(0); PG8_BAR; PG8_MMA(1, 0, At, B0); PG8_MMA(1, 1, At, B1); PG8_BAR; PG8_SCHED;
;             PG8_LDB(B0, 1, 0); PG8_LDB(B1, 1, 1); PG8_SCHED; PG8_LDA(At, 1, 0); PG8_STAGE(PG8_SA(0, 1), a2 + hstep, voffA);
;             PG8_WAIT_V(8); PG8_WAIT_L(0); PG8_BAR; PG8_MMA(0, 0, At, B0); PG8_MMA(0, 1, At, B1); PG8_BAR; PG8_SCHED;
;             PG8_LDA(At, 1, 1); PG8_STAGE(PG8_SB(1, 0), b3, voffB); PG8_STAGE(PG8_SB(1, 1), b3 + hstep, voffB); PG8_STAGE(PG8_SA(1, 0), a3, voffA);
;             PG8_WAIT_V(8); PG8_WAIT_L(0); PG8_BAR; PG8_MMA(1, 0, At, B0); PG8_MMA(1, 1, At, B1); PG8_BAR; PG8_SCHED;
	s_setprio 1
	s_waitcnt lgkmcnt(0)
	v_mfma_f32_16x16x32_bf16 v[60:63], v[138:141], v[200:203], 0
	v_mfma_f32_16x16x32_bf16 v[56:59], v[152:155], v[200:203], 0
	v_mfma_f32_16x16x32_bf16 v[44:47], v[138:141], v[218:221], 0
	v_mfma_f32_16x16x32_bf16 v[40:43], v[152:155], v[218:221], 0
	v_mfma_f32_16x16x32_bf16 v[28:31], v[138:141], v[226:229], 0
	v_mfma_f32_16x16x32_bf16 v[24:27], v[152:155], v[226:229], 0
	v_mfma_f32_16x16x32_bf16 v[12:15], v[138:141], v[234:237], 0
	v_mfma_f32_16x16x32_bf16 v[8:11], v[152:155], v[234:237], 0
	v_mfma_f32_16x16x32_bf16 v[60:63], v[148:151], v[214:217], v[60:63]
	v_mfma_f32_16x16x32_bf16 v[56:59], v[156:159], v[214:217], v[56:59]
	v_mfma_f32_16x16x32_bf16 v[44:47], v[148:151], v[222:225], v[44:47]
	v_mfma_f32_16x16x32_bf16 v[40:43], v[156:159], v[222:225], v[40:43]
	v_mfma_f32_16x16x32_bf16 v[28:31], v[148:151], v[230:233], v[28:31]
	v_mfma_f32_16x16x32_bf16 v[24:27], v[156:159], v[230:233], v[24:27]
	v_mfma_f32_16x16x32_bf16 v[12:15], v[148:151], v[238:241], v[12:15]
	v_mfma_f32_16x16x32_bf16 v[8:11], v[156:159], v[238:241], v[8:11]
	v_mfma_f32_16x16x32_bf16 v[52:55], v[184:187], v[200:203], 0
	v_mfma_f32_16x16x32_bf16 v[48:51], v[192:195], v[200:203], 0
	v_mfma_f32_16x16x32_bf16 v[36:39], v[184:187], v[218:221], 0
	v_mfma_f32_16x16x32_bf16 v[32:35], v[192:195], v[218:221], 0
	v_mfma_f32_16x16x32_bf16 v[20:23], v[184:187], v[226:229], 0
	v_mfma_f32_16x16x32_bf16 v[16:19], v[192:195], v[226:229], 0
	v_mfma_f32_16x16x32_bf16 v[4:7], v[184:187], v[234:237], 0
	v_mfma_f32_16x16x32_bf16 v[0:3], v[192:195], v[234:237], 0
	v_mfma_f32_16x16x32_bf16 v[52:55], v[188:191], v[214:217], v[52:55]
	v_mfma_f32_16x16x32_bf16 v[48:51], v[196:199], v[214:217], v[48:51]
	v_mfma_f32_16x16x32_bf16 v[36:39], v[188:191], v[222:225], v[36:39]
	v_mfma_f32_16x16x32_bf16 v[32:35], v[196:199], v[222:225], v[32:35]
	v_mfma_f32_16x16x32_bf16 v[20:23], v[188:191], v[230:233], v[20:23]
	v_mfma_f32_16x16x32_bf16 v[16:19], v[196:199], v[230:233], v[16:19]
	v_mfma_f32_16x16x32_bf16 v[4:7], v[188:191], v[238:241], v[4:7]
	v_mfma_f32_16x16x32_bf16 v[0:3], v[196:199], v[238:241], v[0:3]
	s_setprio 0
	s_barrier
	s_add_i32 s55, 0, 0x18000
	s_add_i32 s56, 0, 0x1c000
	v_add_u32_e32 v156, s55, v145
	v_add_u32_e32 v196, s56, v145
	ds_read_b128 v[138:141], v156
	ds_read_b128 v[148:151], v156 offset:1024
	ds_read_b128 v[152:155], v156 offset:2048
	ds_read_b128 v[156:159], v156 offset:3072
	ds_read_b128 v[184:187], v196
	ds_read_b128 v[188:191], v196 offset:1024
	ds_read_b128 v[192:195], v196 offset:2048
	ds_read_b128 v[196:199], v196 offset:3072
	s_add_u32 s46, s46, 0x40000
	s_addc_u32 s47, s47, 0
	s_mov_b32 m0, s49
	v_lshl_add_u64 v[246:247], s[46:47], 0, v[132:133]
	ds_read_b128 v[200:203], v147 offset:32768
	ds_read_b128 v[214:217], v147 offset:33792
	ds_read_b128 v[218:221], v147 offset:34816
	ds_read_b128 v[222:225], v147 offset:35840
	ds_read_b128 v[226:229], v147 offset:36864
	ds_read_b128 v[230:233], v147 offset:37888
	ds_read_b128 v[234:237], v147 offset:38912
	ds_read_b128 v[238:241], v147 offset:39936
	global_load_lds_dwordx4 v[246:247], off
	v_lshl_add_u64 v[246:247], s[46:47], 0, v[130:131]
	s_mov_b32 m0, s50
	s_nop 0
	global_load_lds_dwordx4 v[246:247], off
	s_waitcnt vmcnt(8)
	s_waitcnt lgkmcnt(0)
	s_barrier
	s_setprio 1
	s_waitcnt lgkmcnt(0)
	v_mfma_f32_16x16x32_bf16 v[124:127], v[138:141], v[200:203], v[124:127]
	v_mfma_f32_16x16x32_bf16 v[120:123], v[152:155], v[200:203], v[120:123]
	v_mfma_f32_16x16x32_bf16 v[108:111], v[138:141], v[218:221], v[108:111]
	v_mfma_f32_16x16x32_bf16 v[104:107], v[152:155], v[218:221], v[104:107]
	v_mfma_f32_16x16x32_bf16 v[92:95], v[138:141], v[226:229], v[92:95]
	v_mfma_f32_16x16x32_bf16 v[88:91], v[152:155], v[226:229], v[88:91]
	v_mfma_f32_16x16x32_bf16 v[76:79], v[138:141], v[234:237], v[76:79]
	v_mfma_f32_16x16x32_bf16 v[72:75], v[152:155], v[234:237], v[72:75]
	v_mfma_f32_16x16x32_bf16 v[124:127], v[148:151], v[214:217], v[124:127]
	v_mfma_f32_16x16x32_bf16 v[120:123], v[156:159], v[214:217], v[120:123]
	v_mfma_f32_16x16x32_bf16 v[108:111], v[148:151], v[222:225], v[108:111]
	v_mfma_f32_16x16x32_bf16 v[104:107], v[156:159], v[222:225], v[104:107]
	v_mfma_f32_16x16x32_bf16 v[92:95], v[148:151], v[230:233], v[92:95]
	v_mfma_f32_16x16x32_bf16 v[88:91], v[156:159], v[230:233], v[88:91]
	v_mfma_f32_16x16x32_bf16 v[76:79], v[148:151], v[238:241], v[76:79]
	v_mfma_f32_16x16x32_bf16 v[72:75], v[156:159], v[238:241], v[72:75]
	v_mfma_f32_16x16x32_bf16 v[116:119], v[184:187], v[200:203], v[116:119]
	v_mfma_f32_16x16x32_bf16 v[112:115], v[192:195], v[200:203], v[112:115]
	v_mfma_f32_16x16x32_bf16 v[100:103], v[184:187], v[218:221], v[100:103]
	v_mfma_f32_16x16x32_bf16 v[96:99], v[192:195], v[218:221], v[96:99]
	v_mfma_f32_16x16x32_bf16 v[84:87], v[184:187], v[226:229], v[84:87]
	v_mfma_f32_16x16x32_bf16 v[80:83], v[192:195], v[226:229], v[80:83]
	v_mfma_f32_16x16x32_bf16 v[68:71], v[184:187], v[234:237], v[68:71]
	v_mfma_f32_16x16x32_bf16 v[64:67], v[192:195], v[234:237], v[64:67]
	v_mfma_f32_16x16x32_bf16 v[116:119], v[188:191], v[214:217], v[116:119]
	v_mfma_f32_16x16x32_bf16 v[112:115], v[196:199], v[214:217], v[112:115]
	v_mfma_f32_16x16x32_bf16 v[100:103], v[188:191], v[222:225], v[100:103]
	v_mfma_f32_16x16x32_bf16 v[96:99], v[196:199], v[222:225], v[96:99]
	v_mfma_f32_16x16x32_bf16 v[84:87], v[188:191], v[230:233], v[84:87]
	v_mfma_f32_16x16x32_bf16 v[80:83], v[196:199], v[230:233], v[80:83]
	v_mfma_f32_16x16x32_bf16 v[68:71], v[188:191], v[238:241], v[68:71]
	v_mfma_f32_16x16x32_bf16 v[64:67], v[196:199], v[238:241], v[64:67]
	s_setprio 0
	s_barrier
; #define PG8_STAGE(bufoff, gbase, voff) do { _Pragma("unroll") for (int _i = 0; _i < 2; ++_i) \
;         __builtin_amdgcn_global_load_lds((const unsigned*)((const char*)(gbase) + (voff)[_i]), (PG8_LAS unsigned*)(lds + (bufoff) + ldsw + _i * 8192), 16, 0, 0); } while (0)
; #define PG8_WAIT_V(n) asm volatile("s_waitcnt vmcnt(" #n ")" ::: "memory")
; #define PG8_WAIT_L(n) asm volatile("s_waitcnt lgkmcnt(" #n ")" ::: "memory")
; #define PG8_BAR __builtin_amdgcn_s_barrier()
; #define PG8_SCHED __builtin_amdgcn_sched_barrier(0)
; template <class Epi, class Sched, bool ALIGN_EPI = false, bool SP2 = false, bool F8 = false>
; __device__ __forceinline__ void gemm_phase(PG8_LAS unsigned char* lds, const Gemm g, const Sched& S, const Epi& E) {
;     ...
;         for (int t = 0; t < nt; t += 2) {
;             const bool last = (t == nt - 2);
;             const char* a1 = cA + (size_t)(t + 1) * kstep;
;             const char* a2 = last ? nA : cA + (size_t)(t + 2) * kstep; const char* b2 = last ? nB : cB + (size_t)(t + 2) * kstep;
;             const char* a3 = a2 + kstep; const char* b3 = b2 + kstep;
;             if (last && has_next) S.a_ready(nxt);
;             if constexpr (SP2) {
;             PG8_LDB(B0, 0, 0); PG8_LDB(B1, 0, 1); PG8_SCHED; PG8_LDA(At, 0, 0); PG8_STAGE(PG8_SA(1, 1), a1 + hstep, voffA);
;             PG8_WAIT_V(8); PG8_WAIT_L(0); PG8_BAR; PG8_MMA(0, 0, At, B0); PG8_MMA(0, 1, At, B1); PG8_BAR; PG8_SCHED;
;             PG8_LDA(At, 0, 1); PG8_STAGE(PG8_SB(0, 0), b2, voffB); PG8_STAGE(PG8_SB(0, 1), b2 + hstep, voffB); PG8_STAGE(PG8_SA(0, 0), a2, voffA);
;             PG8_WAIT_V(8); PG8_WAIT_L(0); PG8_BAR; PG8_MMA(1, 0, At, B0); PG8_MMA(1, 1, At, B1); PG8_BAR; PG8_SCHED;
;             PG8_LDB(B0, 1, 0); PG8_LDB(B1, 1, 1); PG8_SCHED; PG8_LDA(At, 1, 0); PG8_STAGE(PG8_SA(0, 1), a2 + hstep, voffA);
;             PG8_WAIT_V(8); PG8_WAIT_L(0); PG8_BAR; PG8_MMA(0, 0, At, B0); PG8_MMA(0, 1, At, B1); PG8_BAR; PG8_SCHED;
;             PG8_LDA(At, 1, 1); PG8_STAGE(PG8_SB(1, 0), b3, voffB); PG8_STAGE(PG8_SB(1, 1), b3 + hstep, voffB); PG8_STAGE(PG8_SA(1, 0), a3, voffA);
;             PG8_WAIT_V(8); PG8_WAIT_L(0); PG8_BAR; PG8_MMA(1, 0, At, B0); PG8_MMA(1, 1, At, B1); PG8_BAR; PG8_SCHED;
	s_add_i32 s46, s55, s13
	v_lshl_add_u64 v[142:143], v[142:143], 0, s[14:15]
	s_mov_b32 m0, s46
	ds_read_b128 v[200:203], v147 offset:49152
	ds_read_b128 v[214:217], v147 offset:50176
	ds_read_b128 v[218:221], v147 offset:51200
	ds_read_b128 v[222:225], v147 offset:52224
	ds_read_b128 v[226:229], v147 offset:53248
	ds_read_b128 v[230:233], v147 offset:54272
	ds_read_b128 v[234:237], v147 offset:55296
	ds_read_b128 v[238:241], v147 offset:56320
	global_load_lds_dwordx4 v[142:143], off
	s_add_i32 m0, s46, 0x2000
	s_add_u32 s36, s36, 0x40080
	v_lshl_add_u64 v[142:143], v[162:163], 0, s[14:15]
	s_addc_u32 s37, s37, 0
	s_add_i32 s46, s56, s13
	global_load_lds_dwordx4 v[142:143], off
	v_lshl_add_u64 v[142:143], s[36:37], 0, v[160:161]
	s_mov_b32 m0, s46
	s_nop 0
	global_load_lds_dwordx4 v[142:143], off
	v_lshl_add_u64 v[142:143], s[36:37], 0, v[128:129]
	s_add_i32 m0, s46, 0x2000
	s_nop 0
	global_load_lds_dwordx4 v[142:143], off
	v_lshl_add_u64 v[142:143], v[242:243], 0, s[14:15]
	s_mov_b32 m0, s51
	s_nop 0
	global_load_lds_dwordx4 v[142:143], off
	v_lshl_add_u64 v[142:143], v[244:245], 0, s[14:15]
	s_mov_b32 m0, s52
	s_nop 0
	global_load_lds_dwordx4 v[142:143], off
	s_waitcnt vmcnt(8)
	s_waitcnt lgkmcnt(0)
	s_barrier
	s_setprio 1
	s_waitcnt lgkmcnt(0)
	v_mfma_f32_16x16x32_bf16 v[60:63], v[138:141], v[200:203], v[60:63]
	v_mfma_f32_16x16x32_bf16 v[56:59], v[152:155], v[200:203], v[56:59]
	v_mfma_f32_16x16x32_bf16 v[44:47], v[138:141], v[218:221], v[44:47]
	v_mfma_f32_16x16x32_bf16 v[40:43], v[152:155], v[218:221], v[40:43]
	v_mfma_f32_16x16x32_bf16 v[28:31], v[138:141], v[226:229], v[28:31]
	v_mfma_f32_16x16x32_bf16 v[24:27], v[152:155], v[226:229], v[24:27]
	v_mfma_f32_16x16x32_bf16 v[12:15], v[138:141], v[234:237], v[12:15]
	v_mfma_f32_16x16x32_bf16 v[8:11], v[152:155], v[234:237], v[8:11]
	v_mfma_f32_16x16x32_bf16 v[60:63], v[148:151], v[214:217], v[60:63]
	v_mfma_f32_16x16x32_bf16 v[56:59], v[156:159], v[214:217], v[56:59]
	v_mfma_f32_16x16x32_bf16 v[44:47], v[148:151], v[222:225], v[44:47]
	v_mfma_f32_16x16x32_bf16 v[40:43], v[156:159], v[222:225], v[40:43]
	v_mfma_f32_16x16x32_bf16 v[28:31], v[148:151], v[230:233], v[28:31]
	v_mfma_f32_16x16x32_bf16 v[24:27], v[156:159], v[230:233], v[24:27]
	v_mfma_f32_16x16x32_bf16 v[12:15], v[148:151], v[238:241], v[12:15]
	v_mfma_f32_16x16x32_bf16 v[8:11], v[156:159], v[238:241], v[8:11]
	v_mfma_f32_16x16x32_bf16 v[52:55], v[184:187], v[200:203], v[52:55]
	v_mfma_f32_16x16x32_bf16 v[48:51], v[192:195], v[200:203], v[48:51]
	v_mfma_f32_16x16x32_bf16 v[36:39], v[184:187], v[218:221], v[36:39]
	v_mfma_f32_16x16x32_bf16 v[32:35], v[192:195], v[218:221], v[32:35]
	v_mfma_f32_16x16x32_bf16 v[20:23], v[184:187], v[226:229], v[20:23]
	v_mfma_f32_16x16x32_bf16 v[16:19], v[192:195], v[226:229], v[16:19]
	v_mfma_f32_16x16x32_bf16 v[4:7], v[184:187], v[234:237], v[4:7]
	v_mfma_f32_16x16x32_bf16 v[0:3], v[192:195], v[234:237], v[0:3]
	v_mfma_f32_16x16x32_bf16 v[52:55], v[188:191], v[214:217], v[52:55]
	v_mfma_f32_16x16x32_bf16 v[48:51], v[196:199], v[214:217], v[48:51]
	v_mfma_f32_16x16x32_bf16 v[36:39], v[188:191], v[222:225], v[36:39]
	v_mfma_f32_16x16x32_bf16 v[32:35], v[196:199], v[222:225], v[32:35]
	v_mfma_f32_16x16x32_bf16 v[20:23], v[188:191], v[230:233], v[20:23]
	v_mfma_f32_16x16x32_bf16 v[16:19], v[196:199], v[230:233], v[16:19]
	v_mfma_f32_16x16x32_bf16 v[4:7], v[188:191], v[238:241], v[4:7]
	v_mfma_f32_16x16x32_bf16 v[0:3], v[196:199], v[238:241], v[0:3]
	s_setprio 0
	s_barrier
	s_add_i32 s54, s54, 2
	s_add_u32 s10, s10, 0x100
	s_addc_u32 s11, s11, 0
	s_add_u32 s29, s29, 0x100
	s_addc_u32 s41, s41, 0
	s_cmp_gt_u32 s54, 13
	s_cbranch_scc0 .LBB0_117
	s_branch .Lgk_after_117
.LBB0_117:
	s_add_u32 s36, s10, 0xfffc0080
	s_addc_u32 s37, s11, -1
	s_add_i32 s55, 0, 0x10000
	s_cmp_eq_u32 s54, 12
	s_cselect_b32 s47, s19, s37
	s_cselect_b32 s46, s23, s36
	v_add_u32_e32 v142, s55, v145
	s_cselect_b32 s37, s17, s41
	s_cselect_b32 s36, s28, s29
	s_add_i32 s56, 0, 0x14000
	ds_read_b128 v[138:141], v142
	ds_read_b128 v[148:151], v142 offset:1024
	ds_read_b128 v[152:155], v142 offset:2048
	ds_read_b128 v[156:159], v142 offset:3072
	v_add_u32_e32 v142, s56, v145
	ds_read_b128 v[184:187], v142
	ds_read_b128 v[188:191], v142 offset:1024
	ds_read_b128 v[192:195], v142 offset:2048
	ds_read_b128 v[196:199], v142 offset:3072
	v_lshl_add_u64 v[142:143], s[10:11], 0, v[134:135]
	s_add_i32 m0, s35, 0xc000
	ds_read_b128 v[200:203], v147
	ds_read_b128 v[214:217], v147 offset:1024
	ds_read_b128 v[218:221], v147 offset:2048
	ds_read_b128 v[222:225], v147 offset:3072
	ds_read_b128 v[226:229], v147 offset:4096
	ds_read_b128 v[230:233], v147 offset:5120
	ds_read_b128 v[234:237], v147 offset:6144
	ds_read_b128 v[238:241], v147 offset:7168
	global_load_lds_dwordx4 v[142:143], off
	v_lshl_add_u64 v[142:143], s[10:11], 0, v[136:137]
	s_add_i32 m0, s35, 0xe000
	s_nop 0
	global_load_lds_dwordx4 v[142:143], off
	s_waitcnt vmcnt(8)
	s_waitcnt lgkmcnt(0)
	s_barrier
; #define PG8_STAGE(bufoff, gbase, voff) do { _Pragma("unroll") for (int _i = 0; _i < 2; ++_i) \
;         __builtin_amdgcn_global_load_lds((const unsigned*)((const char*)(gbase) + (voff)[_i]), (PG8_LAS unsigned*)(lds + (bufoff) + ldsw + _i * 8192), 16, 0, 0); } while (0)
; #define PG8_WAIT_V(n) asm volatile("s_waitcnt vmcnt(" #n ")" ::: "memory")
; #define PG8_WAIT_L(n) asm volatile("s_waitcnt lgkmcnt(" #n ")" ::: "memory")
; #define PG8_BAR __builtin_amdgcn_s_barrier()
; #define PG8_SCHED __builtin_amdgcn_sched_barrier(0)
; template <class Epi, class Sched, bool ALIGN_EPI = false, bool SP2 = false, bool F8 = false>
; __device__ __forceinline__ void gemm_phase(PG8_LAS unsigned char* lds, const Gemm g, const Sched& S, const Epi& E) {
;     ...
;             PG8_LDB(B0, 0, 0); PG8_LDB(B1, 0, 1); PG8_SCHED; PG8_LDA(At, 0, 0); PG8_STAGE(PG8_SA(1, 1), a1 + hstep, voffA);
;             PG8_WAIT_V(8); PG8_WAIT_L(0); PG8_BAR; PG8_MMA(0, 0, At, B0); PG8_MMA(0, 1, At, B1); PG8_BAR; PG8_SCHED;
;             PG8_LDA(At, 0, 1); PG8_STAGE(PG8_SB(0, 0), b2, voffB); PG8_STAGE(PG8_SB(0, 1), b2 + hstep, voffB); PG8_STAGE(PG8_SA(0, 0), a2, voffA);
;             PG8_WAIT_V(8); PG8_WAIT_L(0); PG8_BAR; PG8_MMA(1, 0, At, B0); PG8_MMA(1, 1, At, B1); PG8_BAR; PG8_SCHED;
;             PG8_LDB(B0, 1, 0); PG8_LDB(B1, 1, 1); PG8_SCHED; PG8_LDA(At, 1, 0); PG8_STAGE(PG8_SA(0, 1), a2 + hstep, voffA);
;             PG8_WAIT_V(8); PG8_WAIT_L(0); PG8_BAR; PG8_MMA(0, 0, At, B0); PG8_MMA(0, 1, At, B1); PG8_BAR; PG8_SCHED;
;             PG8_LDA(At, 1, 1); PG8_STAGE(PG8_SB(1, 0), b3, voffB); PG8_STAGE(PG8_SB(1, 1), b3 + hstep, voffB); PG8_STAGE(PG8_SA(1, 0), a3, voffA);
;             PG8_WAIT_V(8); PG8_WAIT_L(0); PG8_BAR; PG8_MMA(1, 0, At, B0); PG8_MMA(1, 1, At, B1); PG8_BAR; PG8_SCHED;
	s_setprio 1
	s_waitcnt lgkmcnt(0)
	v_mfma_f32_16x16x32_bf16 v[124:127], v[138:141], v[200:203], v[124:127]
	v_mfma_f32_16x16x32_bf16 v[120:123], v[152:155], v[200:203], v[120:123]
	v_mfma_f32_16x16x32_bf16 v[108:111], v[138:141], v[218:221], v[108:111]
	v_mfma_f32_16x16x32_bf16 v[104:107], v[152:155], v[218:221], v[104:107]
	v_mfma_f32_16x16x32_bf16 v[92:95], v[138:141], v[226:229], v[92:95]
	v_mfma_f32_16x16x32_bf16 v[88:91], v[152:155], v[226:229], v[88:91]
	v_mfma_f32_16x16x32_bf16 v[76:79], v[138:141], v[234:237], v[76:79]
	v_mfma_f32_16x16x32_bf16 v[72:75], v[152:155], v[234:237], v[72:75]
	v_mfma_f32_16x16x32_bf16 v[124:127], v[148:151], v[214:217], v[124:127]
	v_mfma_f32_16x16x32_bf16 v[120:123], v[156:159], v[214:217], v[120:123]
	v_mfma_f32_16x16x32_bf16 v[108:111], v[148:151], v[222:225], v[108:111]
	v_mfma_f32_16x16x32_bf16 v[104:107], v[156:159], v[222:225], v[104:107]
	v_mfma_f32_16x16x32_bf16 v[92:95], v[148:151], v[230:233], v[92:95]
	v_mfma_f32_16x16x32_bf16 v[88:91], v[156:159], v[230:233], v[88:91]
	v_mfma_f32_16x16x32_bf16 v[76:79], v[148:151], v[238:241], v[76:79]
	v_mfma_f32_16x16x32_bf16 v[72:75], v[156:159], v[238:241], v[72:75]
	v_mfma_f32_16x16x32_bf16 v[116:119], v[184:187], v[200:203], v[116:119]
	v_mfma_f32_16x16x32_bf16 v[112:115], v[192:195], v[200:203], v[112:115]
	v_mfma_f32_16x16x32_bf16 v[100:103], v[184:187], v[218:221], v[100:103]
	v_mfma_f32_16x16x32_bf16 v[96:99], v[192:195], v[218:221], v[96:99]
	v_mfma_f32_16x16x32_bf16 v[84:87], v[184:187], v[226:229], v[84:87]
	v_mfma_f32_16x16x32_bf16 v[80:83], v[192:195], v[226:229], v[80:83]
	v_mfma_f32_16x16x32_bf16 v[68:71], v[184:187], v[234:237], v[68:71]
	v_mfma_f32_16x16x32_bf16 v[64:67], v[192:195], v[234:237], v[64:67]
	v_mfma_f32_16x16x32_bf16 v[116:119], v[188:191], v[214:217], v[116:119]
	v_mfma_f32_16x16x32_bf16 v[112:115], v[196:199], v[214:217], v[112:115]
	v_mfma_f32_16x16x32_bf16 v[100:103], v[188:191], v[222:225], v[100:103]
	v_mfma_f32_16x16x32_bf16 v[96:99], v[196:199], v[222:225], v[96:99]
	v_mfma_f32_16x16x32_bf16 v[84:87], v[188:191], v[230:233], v[84:87]
	v_mfma_f32_16x16x32_bf16 v[80:83], v[196:199], v[230:233], v[80:83]
	v_mfma_f32_16x16x32_bf16 v[68:71], v[188:191], v[238:241], v[68:71]
	v_mfma_f32_16x16x32_bf16 v[64:67], v[196:199], v[238:241], v[64:67]
	s_setprio 0
	s_barrier
	s_add_i32 s55, s55, s13
	v_lshl_add_u64 v[142:143], s[36:37], 0, v[160:161]
	s_mov_b32 m0, s55
	ds_read_b128 v[200:203], v147 offset:16384
	ds_read_b128 v[214:217], v147 offset:17408
	ds_read_b128 v[218:221], v147 offset:18432
	ds_read_b128 v[222:225], v147 offset:19456
	ds_read_b128 v[226:229], v147 offset:20480
	ds_read_b128 v[230:233], v147 offset:21504
	ds_read_b128 v[234:237], v147 offset:22528
	ds_read_b128 v[238:241], v147 offset:23552
	global_load_lds_dwordx4 v[142:143], off
	s_add_i32 m0, s55, 0x2000
	s_add_u32 s58, s36, 0x40000
	v_lshl_add_u64 v[162:163], s[36:37], 0, v[128:129]
	s_addc_u32 s59, s37, 0
	s_add_i32 s55, s56, s13
	global_load_lds_dwordx4 v[162:163], off
	v_lshl_add_u64 v[242:243], s[58:59], 0, v[160:161]
	s_mov_b32 m0, s55
	v_lshl_add_u64 v[244:245], s[46:47], 0, v[130:131]
	global_load_lds_dwordx4 v[242:243], off
	v_lshl_add_u64 v[242:243], s[58:59], 0, v[128:129]
	s_add_i32 m0, s55, 0x2000
	s_nop 0
	global_load_lds_dwordx4 v[242:243], off
	v_lshl_add_u64 v[242:243], s[46:47], 0, v[132:133]
	s_mov_b32 m0, s35
	s_nop 0
	global_load_lds_dwordx4 v[242:243], off
	s_mov_b32 m0, s48
	s_nop 0
	global_load_lds_dwordx4 v[244:245], off
	s_waitcnt vmcnt(8)
	s_waitcnt lgkmcnt(0)
	s_barrier
	s_setprio 1
	s_waitcnt lgkmcnt(0)
	v_mfma_f32_16x16x32_bf16 v[60:63], v[138:141], v[200:203], v[60:63]
	v_mfma_f32_16x16x32_bf16 v[56:59], v[152:155], v[200:203], v[56:59]
	v_mfma_f32_16x16x32_bf16 v[44:47], v[138:141], v[218:221], v[44:47]
	v_mfma_f32_16x16x32_bf16 v[40:43], v[152:155], v[218:221], v[40:43]
	v_mfma_f32_16x16x32_bf16 v[28:31], v[138:141], v[226:229], v[28:31]
	v_mfma_f32_16x16x32_bf16 v[24:27], v[152:155], v[226:229], v[24:27]
	v_mfma_f32_16x16x32_bf16 v[12:15], v[138:141], v[234:237], v[12:15]
	v_mfma_f32_16x16x32_bf16 v[8:11], v[152:155], v[234:237], v[8:11]
	v_mfma_f32_16x16x32_bf16 v[60:63], v[148:151], v[214:217], v[60:63]
	v_mfma_f32_16x16x32_bf16 v[56:59], v[156:159], v[214:217], v[56:59]
	v_mfma_f32_16x16x32_bf16 v[44:47], v[148:151], v[222:225], v[44:47]
	v_mfma_f32_16x16x32_bf16 v[40:43], v[156:159], v[222:225], v[40:43]
	v_mfma_f32_16x16x32_bf16 v[28:31], v[148:151], v[230:233], v[28:31]
	v_mfma_f32_16x16x32_bf16 v[24:27], v[156:159], v[230:233], v[24:27]
	v_mfma_f32_16x16x32_bf16 v[12:15], v[148:151], v[238:241], v[12:15]
	v_mfma_f32_16x16x32_bf16 v[8:11], v[156:159], v[238:241], v[8:11]
	v_mfma_f32_16x16x32_bf16 v[52:55], v[184:187], v[200:203], v[52:55]
	v_mfma_f32_16x16x32_bf16 v[48:51], v[192:195], v[200:203], v[48:51]
	v_mfma_f32_16x16x32_bf16 v[36:39], v[184:187], v[218:221], v[36:39]
	v_mfma_f32_16x16x32_bf16 v[32:35], v[192:195], v[218:221], v[32:35]
	v_mfma_f32_16x16x32_bf16 v[20:23], v[184:187], v[226:229], v[20:23]
	v_mfma_f32_16x16x32_bf16 v[16:19], v[192:195], v[226:229], v[16:19]
	v_mfma_f32_16x16x32_bf16 v[4:7], v[184:187], v[234:237], v[4:7]
	v_mfma_f32_16x16x32_bf16 v[0:3], v[192:195], v[234:237], v[0:3]
	v_mfma_f32_16x16x32_bf16 v[52:55], v[188:191], v[214:217], v[52:55]
	v_mfma_f32_16x16x32_bf16 v[48:51], v[196:199], v[214:217], v[48:51]
	v_mfma_f32_16x16x32_bf16 v[36:39], v[188:191], v[222:225], v[36:39]
	v_mfma_f32_16x16x32_bf16 v[32:35], v[196:199], v[222:225], v[32:35]
	v_mfma_f32_16x16x32_bf16 v[20:23], v[188:191], v[230:233], v[20:23]
	v_mfma_f32_16x16x32_bf16 v[16:19], v[196:199], v[230:233], v[16:19]
	v_mfma_f32_16x16x32_bf16 v[4:7], v[188:191], v[238:241], v[4:7]
	v_mfma_f32_16x16x32_bf16 v[0:3], v[196:199], v[238:241], v[0:3]
	s_setprio 0
	s_barrier
; #define PG8_STAGE(bufoff, gbase, voff) do { _Pragma("unroll") for (int _i = 0; _i < 2; ++_i) \
;         __builtin_amdgcn_global_load_lds((const unsigned*)((const char*)(gbase) + (voff)[_i]), (PG8_LAS unsigned*)(lds + (bufoff) + ldsw + _i * 8192), 16, 0, 0); } while (0)
; #define PG8_WAIT_V(n) asm volatile("s_waitcnt vmcnt(" #n ")" ::: "memory")
; #define PG8_WAIT_L(n) asm volatile("s_waitcnt lgkmcnt(" #n ")" ::: "memory")
; #define PG8_BAR __builtin_amdgcn_s_barrier()
; #define PG8_SCHED __builtin_amdgcn_sched_barrier(0)
; template <class Epi, class Sched, bool ALIGN_EPI = false, bool SP2 = false, bool F8 = false>
; __device__ __forceinline__ void gemm_phase(PG8_LAS unsigned char* lds, const Gemm g, const Sched& S, const Epi& E) {
;     ...
;             PG8_LDB(B0, 1, 0); PG8_LDB(B1, 1, 1); PG8_SCHED; PG8_LDA(At, 1, 0); PG8_STAGE(PG8_SA(0, 1), a2 + hstep, voffA);
;             PG8_WAIT_V(8); PG8_WAIT_L(0); PG8_BAR; PG8_MMA(0, 0, At, B0); PG8_MMA(0, 1, At, B1); PG8_BAR; PG8_SCHED;
	s_add_i32 s55, 0, 0x18000
	s_add_i32 s56, 0, 0x1c000
	v_add_u32_e32 v156, s55, v145
	v_add_u32_e32 v196, s56, v145
	ds_read_b128 v[138:141], v156
	ds_read_b128 v[148:151], v156 offset:1024
	ds_read_b128 v[152:155], v156 offset:2048
	ds_read_b128 v[156:159], v156 offset:3072
	ds_read_b128 v[184:187], v196
	ds_read_b128 v[188:191], v196 offset:1024
	ds_read_b128 v[192:195], v196 offset:2048
	ds_read_b128 v[196:199], v196 offset:3072
	s_add_u32 s46, s46, 0x40000
	s_addc_u32 s47, s47, 0
	s_mov_b32 m0, s49
	v_lshl_add_u64 v[246:247], s[46:47], 0, v[132:133]
	ds_read_b128 v[200:203], v147 offset:32768
	ds_read_b128 v[214:217], v147 offset:33792
	ds_read_b128 v[218:221], v147 offset:34816
	ds_read_b128 v[222:225], v147 offset:35840
	ds_read_b128 v[226:229], v147 offset:36864
	ds_read_b128 v[230:233], v147 offset:37888
	ds_read_b128 v[234:237], v147 offset:38912
	ds_read_b128 v[238:241], v147 offset:39936
	global_load_lds_dwordx4 v[246:247], off
	v_lshl_add_u64 v[246:247], s[46:47], 0, v[130:131]
	s_mov_b32 m0, s50
	s_nop 0
	global_load_lds_dwordx4 v[246:247], off
	s_waitcnt vmcnt(8)
	s_waitcnt lgkmcnt(0)
	s_barrier
	s_setprio 1
	s_waitcnt lgkmcnt(0)
	v_mfma_f32_16x16x32_bf16 v[124:127], v[138:141], v[200:203], v[124:127]
	v_mfma_f32_16x16x32_bf16 v[120:123], v[152:155], v[200:203], v[120:123]
	v_mfma_f32_16x16x32_bf16 v[108:111], v[138:141], v[218:221], v[108:111]
	v_mfma_f32_16x16x32_bf16 v[104:107], v[152:155], v[218:221], v[104:107]
	v_mfma_f32_16x16x32_bf16 v[92:95], v[138:141], v[226:229], v[92:95]
	v_mfma_f32_16x16x32_bf16 v[88:91], v[152:155], v[226:229], v[88:91]
	v_mfma_f32_16x16x32_bf16 v[76:79], v[138:141], v[234:237], v[76:79]
	v_mfma_f32_16x16x32_bf16 v[72:75], v[152:155], v[234:237], v[72:75]
	v_mfma_f32_16x16x32_bf16 v[124:127], v[148:151], v[214:217], v[124:127]
	v_mfma_f32_16x16x32_bf16 v[120:123], v[156:159], v[214:217], v[120:123]
	v_mfma_f32_16x16x32_bf16 v[108:111], v[148:151], v[222:225], v[108:111]
	v_mfma_f32_16x16x32_bf16 v[104:107], v[156:159], v[222:225], v[104:107]
	v_mfma_f32_16x16x32_bf16 v[92:95], v[148:151], v[230:233], v[92:95]
	v_mfma_f32_16x16x32_bf16 v[88:91], v[156:159], v[230:233], v[88:91]
	v_mfma_f32_16x16x32_bf16 v[76:79], v[148:151], v[238:241], v[76:79]
	v_mfma_f32_16x16x32_bf16 v[72:75], v[156:159], v[238:241], v[72:75]
	v_mfma_f32_16x16x32_bf16 v[116:119], v[184:187], v[200:203], v[116:119]
	v_mfma_f32_16x16x32_bf16 v[112:115], v[192:195], v[200:203], v[112:115]
	v_mfma_f32_16x16x32_bf16 v[100:103], v[184:187], v[218:221], v[100:103]
	v_mfma_f32_16x16x32_bf16 v[96:99], v[192:195], v[218:221], v[96:99]
	v_mfma_f32_16x16x32_bf16 v[84:87], v[184:187], v[226:229], v[84:87]
	v_mfma_f32_16x16x32_bf16 v[80:83], v[192:195], v[226:229], v[80:83]
	v_mfma_f32_16x16x32_bf16 v[68:71], v[184:187], v[234:237], v[68:71]
	v_mfma_f32_16x16x32_bf16 v[64:67], v[192:195], v[234:237], v[64:67]
	v_mfma_f32_16x16x32_bf16 v[116:119], v[188:191], v[214:217], v[116:119]
	v_mfma_f32_16x16x32_bf16 v[112:115], v[196:199], v[214:217], v[112:115]
	v_mfma_f32_16x16x32_bf16 v[100:103], v[188:191], v[222:225], v[100:103]
	v_mfma_f32_16x16x32_bf16 v[96:99], v[196:199], v[222:225], v[96:99]
	v_mfma_f32_16x16x32_bf16 v[84:87], v[188:191], v[230:233], v[84:87]
	v_mfma_f32_16x16x32_bf16 v[80:83], v[196:199], v[230:233], v[80:83]
	v_mfma_f32_16x16x32_bf16 v[68:71], v[188:191], v[238:241], v[68:71]
	v_mfma_f32_16x16x32_bf16 v[64:67], v[196:199], v[238:241], v[64:67]
	s_setprio 0
	s_barrier
; #define PG8_STAGE(bufoff, gbase, voff) do { _Pragma("unroll") for (int _i = 0; _i < 2; ++_i) \
;         __builtin_amdgcn_global_load_lds((const unsigned*)((const char*)(gbase) + (voff)[_i]), (PG8_LAS unsigned*)(lds + (bufoff) + ldsw + _i * 8192), 16, 0, 0); } while (0)
; #define PG8_WAIT_V(n) asm volatile("s_waitcnt vmcnt(" #n ")" ::: "memory")
; #define PG8_WAIT_L(n) asm volatile("s_waitcnt lgkmcnt(" #n ")" ::: "memory")
; #define PG8_BAR __builtin_amdgcn_s_barrier()
; #define PG8_SCHED __builtin_amdgcn_sched_barrier(0)
; template <class Epi, class Sched, bool ALIGN_EPI = false, bool SP2 = false, bool F8 = false>
; __device__ __forceinline__ void gemm_phase(PG8_LAS unsigned char* lds, const Gemm g, const Sched& S, const Epi& E) {
;     ...
;         for (int t = 0; t < nt; t += 2) {
;             const bool last = (t == nt - 2);
;             const char* a1 = cA + (size_t)(t + 1) * kstep;
;             const char* a2 = last ? nA : cA + (size_t)(t + 2) * kstep; const char* b2 = last ? nB : cB + (size_t)(t + 2) * kstep;
;             const char* a3 = a2 + kstep; const char* b3 = b2 + kstep;
;             if (last && has_next) S.a_ready(nxt);
;             if constexpr (SP2) {
;             PG8_LDB(B0, 0, 0); PG8_LDB(B1, 0, 1); PG8_SCHED; PG8_LDA(At, 0, 0); PG8_STAGE(PG8_SA(1, 1), a1 + hstep, voffA);
;             PG8_WAIT_V(8); PG8_WAIT_L(0); PG8_BAR; PG8_MMA(0, 0, At, B0); PG8_MMA(0, 1, At, B1); PG8_BAR; PG8_SCHED;
;             PG8_LDA(At, 0, 1); PG8_STAGE(PG8_SB(0, 0), b2, voffB); PG8_STAGE(PG8_SB(0, 1), b2 + hstep, voffB); PG8_STAGE(PG8_SA(0, 0), a2, voffA);
;             PG8_WAIT_V(8); PG8_WAIT_L(0); PG8_BAR; PG8_MMA(1, 0, At, B0); PG8_MMA(1, 1, At, B1); PG8_BAR; PG8_SCHED;
;             PG8_LDB(B0, 1, 0); PG8_LDB(B1, 1, 1); PG8_SCHED; PG8_LDA(At, 1, 0); PG8_STAGE(PG8_SA(0, 1), a2 + hstep, voffA);
;             PG8_WAIT_V(8); PG8_WAIT_L(0); PG8_BAR; PG8_MMA(0, 0, At, B0); PG8_MMA(0, 1, At, B1); PG8_BAR; PG8_SCHED;
;             PG8_LDA(At, 1, 1); PG8_STAGE(PG8_SB(1, 0), b3, voffB); PG8_STAGE(PG8_SB(1, 1), b3 + hstep, voffB); PG8_STAGE(PG8_SA(1, 0), a3, voffA);
;             PG8_WAIT_V(8); PG8_WAIT_L(0); PG8_BAR; PG8_MMA(1, 0, At, B0); PG8_MMA(1, 1, At, B1); PG8_BAR; PG8_SCHED;
	s_add_i32 s46, s55, s13
	v_lshl_add_u64 v[142:143], v[142:143], 0, s[14:15]
	s_mov_b32 m0, s46
	ds_read_b128 v[200:203], v147 offset:49152
	ds_read_b128 v[214:217], v147 offset:50176
	ds_read_b128 v[218:221], v147 offset:51200
	ds_read_b128 v[222:225], v147 offset:52224
	ds_read_b128 v[226:229], v147 offset:53248
	ds_read_b128 v[230:233], v147 offset:54272
	ds_read_b128 v[234:237], v147 offset:55296
	ds_read_b128 v[238:241], v147 offset:56320
	global_load_lds_dwordx4 v[142:143], off
	s_add_i32 m0, s46, 0x2000
	s_add_u32 s36, s36, 0x40080
	v_lshl_add_u64 v[142:143], v[162:163], 0, s[14:15]
	s_addc_u32 s37, s37, 0
	s_add_i32 s46, s56, s13
	global_load_lds_dwordx4 v[142:143], off
	v_lshl_add_u64 v[142:143], s[36:37], 0, v[160:161]
	s_mov_b32 m0, s46
	s_nop 0
	global_load_lds_dwordx4 v[142:143], off
	v_lshl_add_u64 v[142:143], s[36:37], 0, v[128:129]
	s_add_i32 m0, s46, 0x2000
	s_nop 0
	global_load_lds_dwordx4 v[142:143], off
	v_lshl_add_u64 v[142:143], v[242:243], 0, s[14:15]
	s_mov_b32 m0, s51
	s_nop 0
	global_load_lds_dwordx4 v[142:143], off
	v_lshl_add_u64 v[142:143], v[244:245], 0, s[14:15]
	s_mov_b32 m0, s52
	s_nop 0
	global_load_lds_dwordx4 v[142:143], off
	s_waitcnt vmcnt(8)
	s_waitcnt lgkmcnt(0)
	s_barrier
	s_setprio 1
	s_waitcnt lgkmcnt(0)
	v_mfma_f32_16x16x32_bf16 v[60:63], v[138:141], v[200:203], v[60:63]
	v_mfma_f32_16x16x32_bf16 v[56:59], v[152:155], v[200:203], v[56:59]
	v_mfma_f32_16x16x32_bf16 v[44:47], v[138:141], v[218:221], v[44:47]
	v_mfma_f32_16x16x32_bf16 v[40:43], v[152:155], v[218:221], v[40:43]
	v_mfma_f32_16x16x32_bf16 v[28:31], v[138:141], v[226:229], v[28:31]
	v_mfma_f32_16x16x32_bf16 v[24:27], v[152:155], v[226:229], v[24:27]
	v_mfma_f32_16x16x32_bf16 v[12:15], v[138:141], v[234:237], v[12:15]
	v_mfma_f32_16x16x32_bf16 v[8:11], v[152:155], v[234:237], v[8:11]
	v_mfma_f32_16x16x32_bf16 v[60:63], v[148:151], v[214:217], v[60:63]
	v_mfma_f32_16x16x32_bf16 v[56:59], v[156:159], v[214:217], v[56:59]
	v_mfma_f32_16x16x32_bf16 v[44:47], v[148:151], v[222:225], v[44:47]
	v_mfma_f32_16x16x32_bf16 v[40:43], v[156:159], v[222:225], v[40:43]
	v_mfma_f32_16x16x32_bf16 v[28:31], v[148:151], v[230:233], v[28:31]
	v_mfma_f32_16x16x32_bf16 v[24:27], v[156:159], v[230:233], v[24:27]
	v_mfma_f32_16x16x32_bf16 v[12:15], v[148:151], v[238:241], v[12:15]
	v_mfma_f32_16x16x32_bf16 v[8:11], v[156:159], v[238:241], v[8:11]
	v_mfma_f32_16x16x32_bf16 v[52:55], v[184:187], v[200:203], v[52:55]
	v_mfma_f32_16x16x32_bf16 v[48:51], v[192:195], v[200:203], v[48:51]
	v_mfma_f32_16x16x32_bf16 v[36:39], v[184:187], v[218:221], v[36:39]
	v_mfma_f32_16x16x32_bf16 v[32:35], v[192:195], v[218:221], v[32:35]
	v_mfma_f32_16x16x32_bf16 v[20:23], v[184:187], v[226:229], v[20:23]
	v_mfma_f32_16x16x32_bf16 v[16:19], v[192:195], v[226:229], v[16:19]
	v_mfma_f32_16x16x32_bf16 v[4:7], v[184:187], v[234:237], v[4:7]
	v_mfma_f32_16x16x32_bf16 v[0:3], v[192:195], v[234:237], v[0:3]
	v_mfma_f32_16x16x32_bf16 v[52:55], v[188:191], v[214:217], v[52:55]
	v_mfma_f32_16x16x32_bf16 v[48:51], v[196:199], v[214:217], v[48:51]
	v_mfma_f32_16x16x32_bf16 v[36:39], v[188:191], v[222:225], v[36:39]
	v_mfma_f32_16x16x32_bf16 v[32:35], v[196:199], v[222:225], v[32:35]
	v_mfma_f32_16x16x32_bf16 v[20:23], v[188:191], v[230:233], v[20:23]
	v_mfma_f32_16x16x32_bf16 v[16:19], v[196:199], v[230:233], v[16:19]
	v_mfma_f32_16x16x32_bf16 v[4:7], v[188:191], v[238:241], v[4:7]
	v_mfma_f32_16x16x32_bf16 v[0:3], v[196:199], v[238:241], v[0:3]
	s_setprio 0
	s_barrier
	s_add_i32 s54, s54, 2
	s_add_u32 s10, s10, 0x100
	s_addc_u32 s11, s11, 0
	s_add_u32 s29, s29, 0x100
	s_addc_u32 s41, s41, 0
	s_cmp_gt_u32 s54, 13
	s_cbranch_scc0 .LBB0_117

; #define PG8_STAGE(bufoff, gbase, voff) do { _Pragma("unroll") for (int _i = 0; _i < 2; ++_i) \
;         __builtin_amdgcn_global_load_lds((const unsigned*)((const char*)(gbase) + (voff)[_i]), (PG8_LAS unsigned*)(lds + (bufoff) + ldsw + _i * 8192), 16, 0, 0); } while (0)
; #define PG8_WAIT_V(n) asm volatile("s_waitcnt vmcnt(" #n ")" ::: "memory")
; #define PG8_WAIT_L(n) asm volatile("s_waitcnt lgkmcnt(" #n ")" ::: "memory")
; #define PG8_BAR __builtin_amdgcn_s_barrier()
; template <class Epi, class Sched, bool ALIGN_EPI = false, bool SP2 = false, bool F8 = false>
; __device__ __forceinline__ void gemm_phase(PG8_LAS unsigned char* lds, const Gemm g, const Sched& S, const Epi& E) {
;     ...
;         const bool has_next = S.next(ui + 1, nxt);
;         const char* nA = has_next ? (const char*)g.A + (size_t)nxt.pm * tstep : cA; const char* nB = has_next ? (const char*)g.Bt + (size_t)nxt.pn * tstep : cB;
;         for (int t = 0; t < nt; t += 2) {
;             const bool last = (t == nt - 2);
;             const char* a1 = cA + (size_t)(t + 1) * kstep;
;             const char* a2 = last ? nA : cA + (size_t)(t + 2) * kstep; const char* b2 = last ? nB : cB + (size_t)(t + 2) * kstep;
;             const char* a3 = a2 + kstep; const char* b3 = b2 + kstep;
;             if (last && has_next) S.a_ready(nxt);
;             if constexpr (SP2) {
;             PG8_LDB(B0, 0, 0); PG8_LDB(B1, 0, 1); PG8_SCHED; PG8_LDA(At, 0, 0); PG8_STAGE(PG8_SA(1, 1), a1 + hstep, voffA);
;             PG8_WAIT_V(8); PG8_WAIT_L(0); PG8_BAR; PG8_MMA(0, 0, At, B0); PG8_MMA(0, 1, At, B1); PG8_BAR; PG8_SCHED;
;             PG8_LDA(At, 0, 1); PG8_STAGE(PG8_SB(0, 0), b2, voffB); PG8_STAGE(PG8_SB(0, 1), b2 + hstep, voffB); PG8_STAGE(PG8_SA(0, 0), a2, voffA);
;             PG8_WAIT_V(8); PG8_WAIT_L(0); PG8_BAR; PG8_MMA(1, 0, At, B0); PG8_MMA(1, 1, At, B1); PG8_BAR; PG8_SCHED;
;             PG8_LDB(B0, 1, 0); PG8_LDB(B1, 1, 1); PG8_SCHED; PG8_LDA(At, 1, 0); PG8_STAGE(PG8_SA(0, 1), a2 + hstep, voffA);
;             PG8_WAIT_V(8); PG8_WAIT_L(0); PG8_BAR; PG8_MMA(0, 0, At, B0); PG8_MMA(0, 1, At, B1); PG8_BAR; PG8_SCHED;
;             PG8_LDA(At, 1, 1); PG8_STAGE(PG8_SB(1, 0), b3, voffB); PG8_STAGE(PG8_SB(1, 1), b3 + hstep, voffB); PG8_STAGE(PG8_SA(1, 0), a3, voffA);
;             PG8_WAIT_V(8); PG8_WAIT_L(0); PG8_BAR; PG8_MMA(1, 0, At, B0); PG8_MMA(1, 1, At, B1); PG8_BAR; PG8_SCHED;
.LBB0_1021:
	s_ashr_i32 s17, s16, 31
	s_lshl_b64 s[36:37], s[16:17], 19
	v_readlane_b32 s11, v253, 59
	s_add_u32 s36, s11, s36
	v_readlane_b32 s11, v253, 60
	s_addc_u32 s37, s11, s37
	s_and_b64 s[42:43], s[38:39], exec
	s_cselect_b32 s17, s37, s41
	s_cselect_b32 s50, s36, s40
	s_ashr_i32 s11, s10, 31
	s_lshl_b64 s[42:43], s[10:11], 19
	s_add_u32 s42, s13, s42
	s_addc_u32 s43, s19, s43
	s_and_b64 s[46:47], s[38:39], exec
	s_cselect_b32 s11, s43, s45
	s_cselect_b32 s51, s42, s44
	s_add_u32 s40, s40, 0x40080
	s_addc_u32 s41, s41, 0
	s_add_u32 s52, s44, 0x100
	s_addc_u32 s53, s45, 0
	s_mov_b32 s54, -2
	s_add_u32 s44, s40, 0xfffc0080
	s_addc_u32 s45, s41, -1
	s_add_i32 s55, 0, 0x10000
	s_cmp_eq_u32 s54, 12
	s_cselect_b32 s47, s17, s45
	s_cselect_b32 s46, s50, s44
	s_cselect_b32 s45, s11, s53
	s_cselect_b32 s44, s51, s52
	s_add_i32 s56, 0, 0x14000
	v_add_u32_e32 v0, s55, v215
	v_add_u32_e32 v12, s56, v215
	ds_read_b128 v[16:19], v0
	ds_read_b128 v[20:23], v0 offset:1024
	ds_read_b128 v[24:27], v0 offset:2048
	ds_read_b128 v[28:31], v0 offset:3072
	ds_read_b128 v[0:3], v12
	ds_read_b128 v[4:7], v12 offset:1024
	ds_read_b128 v[8:11], v12 offset:2048
	ds_read_b128 v[12:15], v12 offset:3072
	v_lshl_add_u64 v[242:243], s[40:41], 0, v[192:193]
	s_add_i32 m0, s23, 0xc000
	ds_read_b128 v[196:199], v217
	ds_read_b128 v[200:203], v217 offset:1024
	ds_read_b128 v[218:221], v217 offset:2048
	ds_read_b128 v[222:225], v217 offset:3072
	ds_read_b128 v[226:229], v217 offset:4096
	ds_read_b128 v[230:233], v217 offset:5120
	ds_read_b128 v[234:237], v217 offset:6144
	ds_read_b128 v[238:241], v217 offset:7168
	global_load_lds_dwordx4 v[242:243], off
	v_lshl_add_u64 v[242:243], s[40:41], 0, v[194:195]
	s_add_i32 m0, s23, 0xe000
	s_nop 0
	global_load_lds_dwordx4 v[242:243], off
	s_waitcnt vmcnt(8)
	s_waitcnt lgkmcnt(0)
	s_barrier
	s_setprio 1
	s_waitcnt lgkmcnt(0)
	v_mfma_scale_f32_16x16x128_f8f6f4 v[156:159], v[16:23], v[196:203], 0, v213, v213 op_sel_hi:[0,0,0]
	v_mfma_scale_f32_16x16x128_f8f6f4 v[152:155], v[24:31], v[196:203], 0, v213, v213 op_sel_hi:[0,0,0]
	v_mfma_scale_f32_16x16x128_f8f6f4 v[140:143], v[16:23], v[218:225], 0, v213, v213 op_sel_hi:[0,0,0]
	v_mfma_scale_f32_16x16x128_f8f6f4 v[136:139], v[24:31], v[218:225], 0, v213, v213 op_sel_hi:[0,0,0]
	v_mfma_scale_f32_16x16x128_f8f6f4 v[124:127], v[16:23], v[226:233], 0, v213, v213 op_sel_hi:[0,0,0]
	v_mfma_scale_f32_16x16x128_f8f6f4 v[120:123], v[24:31], v[226:233], 0, v213, v213 op_sel_hi:[0,0,0]
	v_mfma_scale_f32_16x16x128_f8f6f4 v[108:111], v[16:23], v[234:241], 0, v213, v213 op_sel_hi:[0,0,0]
	v_mfma_scale_f32_16x16x128_f8f6f4 v[104:107], v[24:31], v[234:241], 0, v213, v213 op_sel_hi:[0,0,0]
	v_mfma_scale_f32_16x16x128_f8f6f4 v[148:151], v[0:7], v[196:203], 0, v213, v213 op_sel_hi:[0,0,0]
	v_mfma_scale_f32_16x16x128_f8f6f4 v[144:147], v[8:15], v[196:203], 0, v213, v213 op_sel_hi:[0,0,0]
	v_mfma_scale_f32_16x16x128_f8f6f4 v[132:135], v[0:7], v[218:225], 0, v213, v213 op_sel_hi:[0,0,0]
	v_mfma_scale_f32_16x16x128_f8f6f4 v[128:131], v[8:15], v[218:225], 0, v213, v213 op_sel_hi:[0,0,0]
	v_mfma_scale_f32_16x16x128_f8f6f4 v[116:119], v[0:7], v[226:233], 0, v213, v213 op_sel_hi:[0,0,0]
	v_mfma_scale_f32_16x16x128_f8f6f4 v[112:115], v[8:15], v[226:233], 0, v213, v213 op_sel_hi:[0,0,0]
	v_mfma_scale_f32_16x16x128_f8f6f4 v[100:103], v[0:7], v[234:241], 0, v213, v213 op_sel_hi:[0,0,0]
	v_mfma_scale_f32_16x16x128_f8f6f4 v[96:99], v[8:15], v[234:241], 0, v213, v213 op_sel_hi:[0,0,0]
	s_setprio 0
	s_barrier
	s_add_i32 s55, s55, s22
	v_lshl_add_u64 v[196:197], s[44:45], 0, v[188:189]
	s_mov_b32 m0, s55
	ds_read_b128 v[218:221], v217 offset:16384
	ds_read_b128 v[222:225], v217 offset:17408
	ds_read_b128 v[226:229], v217 offset:18432
	ds_read_b128 v[230:233], v217 offset:19456
	ds_read_b128 v[234:237], v217 offset:20480
	ds_read_b128 v[238:241], v217 offset:21504
	ds_read_b128 v[242:245], v217 offset:22528
	ds_read_b128 v[246:249], v217 offset:23552
	global_load_lds_dwordx4 v[196:197], off
	s_add_i32 m0, s55, 0x2000
	s_add_u32 s58, s44, 0x40000
	v_lshl_add_u64 v[198:199], s[44:45], 0, v[184:185]
	s_addc_u32 s59, s45, 0
	s_add_i32 s55, s56, s22
	global_load_lds_dwordx4 v[198:199], off
	v_lshl_add_u64 v[200:201], s[58:59], 0, v[188:189]
	s_mov_b32 m0, s55
	v_lshl_add_u64 v[202:203], s[46:47], 0, v[186:187]
	global_load_lds_dwordx4 v[200:201], off
	v_lshl_add_u64 v[200:201], s[58:59], 0, v[184:185]
	s_add_i32 m0, s55, 0x2000
	s_nop 0
	global_load_lds_dwordx4 v[200:201], off
	v_lshl_add_u64 v[200:201], s[46:47], 0, v[190:191]
	s_mov_b32 m0, s23
	s_nop 0
	global_load_lds_dwordx4 v[200:201], off
	s_mov_b32 m0, s8
	s_nop 0
	global_load_lds_dwordx4 v[202:203], off
	s_waitcnt vmcnt(8)
	s_waitcnt lgkmcnt(0)
	s_barrier
	s_setprio 1
	s_waitcnt lgkmcnt(0)
	v_mfma_scale_f32_16x16x128_f8f6f4 v[92:95], v[16:23], v[218:225], 0, v213, v213 op_sel_hi:[0,0,0]
	v_mfma_scale_f32_16x16x128_f8f6f4 v[88:91], v[24:31], v[218:225], 0, v213, v213 op_sel_hi:[0,0,0]
	v_mfma_scale_f32_16x16x128_f8f6f4 v[76:79], v[16:23], v[226:233], 0, v213, v213 op_sel_hi:[0,0,0]
	v_mfma_scale_f32_16x16x128_f8f6f4 v[72:75], v[24:31], v[226:233], 0, v213, v213 op_sel_hi:[0,0,0]
	v_mfma_scale_f32_16x16x128_f8f6f4 v[60:63], v[16:23], v[234:241], 0, v213, v213 op_sel_hi:[0,0,0]
	v_mfma_scale_f32_16x16x128_f8f6f4 v[56:59], v[24:31], v[234:241], 0, v213, v213 op_sel_hi:[0,0,0]
	v_mfma_scale_f32_16x16x128_f8f6f4 v[44:47], v[16:23], v[242:249], 0, v213, v213 op_sel_hi:[0,0,0]
	v_mfma_scale_f32_16x16x128_f8f6f4 v[40:43], v[24:31], v[242:249], 0, v213, v213 op_sel_hi:[0,0,0]
	v_mfma_scale_f32_16x16x128_f8f6f4 v[84:87], v[0:7], v[218:225], 0, v213, v213 op_sel_hi:[0,0,0]
	v_mfma_scale_f32_16x16x128_f8f6f4 v[80:83], v[8:15], v[218:225], 0, v213, v213 op_sel_hi:[0,0,0]
	v_mfma_scale_f32_16x16x128_f8f6f4 v[68:71], v[0:7], v[226:233], 0, v213, v213 op_sel_hi:[0,0,0]
	v_mfma_scale_f32_16x16x128_f8f6f4 v[64:67], v[8:15], v[226:233], 0, v213, v213 op_sel_hi:[0,0,0]
	v_mfma_scale_f32_16x16x128_f8f6f4 v[52:55], v[0:7], v[234:241], 0, v213, v213 op_sel_hi:[0,0,0]
	v_mfma_scale_f32_16x16x128_f8f6f4 v[48:51], v[8:15], v[234:241], 0, v213, v213 op_sel_hi:[0,0,0]
	v_mfma_scale_f32_16x16x128_f8f6f4 v[36:39], v[0:7], v[242:249], 0, v213, v213 op_sel_hi:[0,0,0]
	v_mfma_scale_f32_16x16x128_f8f6f4 v[32:35], v[8:15], v[242:249], 0, v213, v213 op_sel_hi:[0,0,0]
	s_setprio 0
	s_barrier
; #define PG8_STAGE(bufoff, gbase, voff) do { _Pragma("unroll") for (int _i = 0; _i < 2; ++_i) \
;         __builtin_amdgcn_global_load_lds((const unsigned*)((const char*)(gbase) + (voff)[_i]), (PG8_LAS unsigned*)(lds + (bufoff) + ldsw + _i * 8192), 16, 0, 0); } while (0)
; #define PG8_WAIT_V(n) asm volatile("s_waitcnt vmcnt(" #n ")" ::: "memory")
; #define PG8_WAIT_L(n) asm volatile("s_waitcnt lgkmcnt(" #n ")" ::: "memory")
; #define PG8_BAR __builtin_amdgcn_s_barrier()
; #define PG8_SCHED __builtin_amdgcn_sched_barrier(0)
; template <class Epi, class Sched, bool ALIGN_EPI = false, bool SP2 = false, bool F8 = false>
; __device__ __forceinline__ void gemm_phase(PG8_LAS unsigned char* lds, const Gemm g, const Sched& S, const Epi& E) {
;     ...
;             PG8_LDB(B0, 0, 0); PG8_LDB(B1, 0, 1); PG8_SCHED; PG8_LDA(At, 0, 0); PG8_STAGE(PG8_SA(1, 1), a1 + hstep, voffA);
;             PG8_WAIT_V(8); PG8_WAIT_L(0); PG8_BAR; PG8_MMA(0, 0, At, B0); PG8_MMA(0, 1, At, B1); PG8_BAR; PG8_SCHED;
;             PG8_LDA(At, 0, 1); PG8_STAGE(PG8_SB(0, 0), b2, voffB); PG8_STAGE(PG8_SB(0, 1), b2 + hstep, voffB); PG8_STAGE(PG8_SA(0, 0), a2, voffA);
;             PG8_WAIT_V(8); PG8_WAIT_L(0); PG8_BAR; PG8_MMA(1, 0, At, B0); PG8_MMA(1, 1, At, B1); PG8_BAR; PG8_SCHED;
;             PG8_LDB(B0, 1, 0); PG8_LDB(B1, 1, 1); PG8_SCHED; PG8_LDA(At, 1, 0); PG8_STAGE(PG8_SA(0, 1), a2 + hstep, voffA);
;             PG8_WAIT_V(8); PG8_WAIT_L(0); PG8_BAR; PG8_MMA(0, 0, At, B0); PG8_MMA(0, 1, At, B1); PG8_BAR; PG8_SCHED;
;             PG8_LDA(At, 1, 1); PG8_STAGE(PG8_SB(1, 0), b3, voffB); PG8_STAGE(PG8_SB(1, 1), b3 + hstep, voffB); PG8_STAGE(PG8_SA(1, 0), a3, voffA);
;             PG8_WAIT_V(8); PG8_WAIT_L(0); PG8_BAR; PG8_MMA(1, 0, At, B0); PG8_MMA(1, 1, At, B1); PG8_BAR; PG8_SCHED;
	s_add_i32 s55, 0, 0x18000
	s_add_i32 s56, 0, 0x1c000
	v_add_u32_e32 v12, s55, v215
	v_add_u32_e32 v28, s56, v215
	ds_read_b128 v[0:3], v12
	ds_read_b128 v[4:7], v12 offset:1024
	ds_read_b128 v[8:11], v12 offset:2048
	ds_read_b128 v[12:15], v12 offset:3072
	ds_read_b128 v[16:19], v28
	ds_read_b128 v[20:23], v28 offset:1024
	ds_read_b128 v[24:27], v28 offset:2048
	ds_read_b128 v[28:31], v28 offset:3072
	s_add_u32 s46, s46, 0x40000
	s_addc_u32 s47, s47, 0
	s_mov_b32 m0, s9
	v_lshl_add_u64 v[162:163], s[46:47], 0, v[190:191]
	ds_read_b128 v[218:221], v217 offset:32768
	ds_read_b128 v[222:225], v217 offset:33792
	ds_read_b128 v[226:229], v217 offset:34816
	ds_read_b128 v[230:233], v217 offset:35840
	ds_read_b128 v[234:237], v217 offset:36864
	ds_read_b128 v[238:241], v217 offset:37888
	ds_read_b128 v[242:245], v217 offset:38912
	ds_read_b128 v[246:249], v217 offset:39936
	global_load_lds_dwordx4 v[162:163], off
	v_lshl_add_u64 v[162:163], s[46:47], 0, v[186:187]
	s_mov_b32 m0, s28
	s_nop 0
	global_load_lds_dwordx4 v[162:163], off
	s_waitcnt vmcnt(8)
	s_waitcnt lgkmcnt(0)
	s_barrier
	s_setprio 1
	s_waitcnt lgkmcnt(0)
	v_mfma_scale_f32_16x16x128_f8f6f4 v[156:159], v[0:7], v[218:225], v[156:159], v213, v213 op_sel_hi:[0,0,0]
	v_mfma_scale_f32_16x16x128_f8f6f4 v[152:155], v[8:15], v[218:225], v[152:155], v213, v213 op_sel_hi:[0,0,0]
	v_mfma_scale_f32_16x16x128_f8f6f4 v[140:143], v[0:7], v[226:233], v[140:143], v213, v213 op_sel_hi:[0,0,0]
	v_mfma_scale_f32_16x16x128_f8f6f4 v[136:139], v[8:15], v[226:233], v[136:139], v213, v213 op_sel_hi:[0,0,0]
	v_mfma_scale_f32_16x16x128_f8f6f4 v[124:127], v[0:7], v[234:241], v[124:127], v213, v213 op_sel_hi:[0,0,0]
	v_mfma_scale_f32_16x16x128_f8f6f4 v[120:123], v[8:15], v[234:241], v[120:123], v213, v213 op_sel_hi:[0,0,0]
	v_mfma_scale_f32_16x16x128_f8f6f4 v[108:111], v[0:7], v[242:249], v[108:111], v213, v213 op_sel_hi:[0,0,0]
	v_mfma_scale_f32_16x16x128_f8f6f4 v[104:107], v[8:15], v[242:249], v[104:107], v213, v213 op_sel_hi:[0,0,0]
	v_mfma_scale_f32_16x16x128_f8f6f4 v[148:151], v[16:23], v[218:225], v[148:151], v213, v213 op_sel_hi:[0,0,0]
	v_mfma_scale_f32_16x16x128_f8f6f4 v[144:147], v[24:31], v[218:225], v[144:147], v213, v213 op_sel_hi:[0,0,0]
	v_mfma_scale_f32_16x16x128_f8f6f4 v[132:135], v[16:23], v[226:233], v[132:135], v213, v213 op_sel_hi:[0,0,0]
	v_mfma_scale_f32_16x16x128_f8f6f4 v[128:131], v[24:31], v[226:233], v[128:131], v213, v213 op_sel_hi:[0,0,0]
	v_mfma_scale_f32_16x16x128_f8f6f4 v[116:119], v[16:23], v[234:241], v[116:119], v213, v213 op_sel_hi:[0,0,0]
	v_mfma_scale_f32_16x16x128_f8f6f4 v[112:115], v[24:31], v[234:241], v[112:115], v213, v213 op_sel_hi:[0,0,0]
	v_mfma_scale_f32_16x16x128_f8f6f4 v[100:103], v[16:23], v[242:249], v[100:103], v213, v213 op_sel_hi:[0,0,0]
	v_mfma_scale_f32_16x16x128_f8f6f4 v[96:99], v[24:31], v[242:249], v[96:99], v213, v213 op_sel_hi:[0,0,0]
	s_setprio 0
	s_barrier
	s_add_i32 s46, s55, s22
	v_lshl_add_u64 v[162:163], v[196:197], 0, s[14:15]
	s_mov_b32 m0, s46
	ds_read_b128 v[218:221], v217 offset:49152
	ds_read_b128 v[222:225], v217 offset:50176
	ds_read_b128 v[226:229], v217 offset:51200
	ds_read_b128 v[230:233], v217 offset:52224
	ds_read_b128 v[234:237], v217 offset:53248
	ds_read_b128 v[238:241], v217 offset:54272
	ds_read_b128 v[242:245], v217 offset:55296
	ds_read_b128 v[246:249], v217 offset:56320
	global_load_lds_dwordx4 v[162:163], off
	s_add_i32 m0, s46, 0x2000
	s_add_u32 s44, s44, 0x40080
	v_lshl_add_u64 v[162:163], v[198:199], 0, s[14:15]
	s_addc_u32 s45, s45, 0
	s_add_i32 s46, s56, s22
	global_load_lds_dwordx4 v[162:163], off
	v_lshl_add_u64 v[162:163], s[44:45], 0, v[188:189]
	s_mov_b32 m0, s46
	s_nop 0
	global_load_lds_dwordx4 v[162:163], off
	v_lshl_add_u64 v[162:163], s[44:45], 0, v[184:185]
	s_add_i32 m0, s46, 0x2000
	s_nop 0
	global_load_lds_dwordx4 v[162:163], off
	v_lshl_add_u64 v[162:163], v[200:201], 0, s[14:15]
	s_mov_b32 m0, s29
	s_nop 0
	global_load_lds_dwordx4 v[162:163], off
	v_lshl_add_u64 v[162:163], v[202:203], 0, s[14:15]
	s_mov_b32 m0, s48
	s_nop 0
	global_load_lds_dwordx4 v[162:163], off
	s_waitcnt vmcnt(8)
	s_waitcnt lgkmcnt(0)
	s_barrier
	s_setprio 1
	s_waitcnt lgkmcnt(0)
	v_mfma_scale_f32_16x16x128_f8f6f4 v[92:95], v[0:7], v[218:225], v[92:95], v213, v213 op_sel_hi:[0,0,0]
	v_mfma_scale_f32_16x16x128_f8f6f4 v[88:91], v[8:15], v[218:225], v[88:91], v213, v213 op_sel_hi:[0,0,0]
	v_mfma_scale_f32_16x16x128_f8f6f4 v[76:79], v[0:7], v[226:233], v[76:79], v213, v213 op_sel_hi:[0,0,0]
	v_mfma_scale_f32_16x16x128_f8f6f4 v[72:75], v[8:15], v[226:233], v[72:75], v213, v213 op_sel_hi:[0,0,0]
	v_mfma_scale_f32_16x16x128_f8f6f4 v[60:63], v[0:7], v[234:241], v[60:63], v213, v213 op_sel_hi:[0,0,0]
	v_mfma_scale_f32_16x16x128_f8f6f4 v[56:59], v[8:15], v[234:241], v[56:59], v213, v213 op_sel_hi:[0,0,0]
	v_mfma_scale_f32_16x16x128_f8f6f4 v[44:47], v[0:7], v[242:249], v[44:47], v213, v213 op_sel_hi:[0,0,0]
	v_mfma_scale_f32_16x16x128_f8f6f4 v[40:43], v[8:15], v[242:249], v[40:43], v213, v213 op_sel_hi:[0,0,0]
	v_mfma_scale_f32_16x16x128_f8f6f4 v[84:87], v[16:23], v[218:225], v[84:87], v213, v213 op_sel_hi:[0,0,0]
	v_mfma_scale_f32_16x16x128_f8f6f4 v[80:83], v[24:31], v[218:225], v[80:83], v213, v213 op_sel_hi:[0,0,0]
	v_mfma_scale_f32_16x16x128_f8f6f4 v[68:71], v[16:23], v[226:233], v[68:71], v213, v213 op_sel_hi:[0,0,0]
	v_mfma_scale_f32_16x16x128_f8f6f4 v[64:67], v[24:31], v[226:233], v[64:67], v213, v213 op_sel_hi:[0,0,0]
	v_mfma_scale_f32_16x16x128_f8f6f4 v[52:55], v[16:23], v[234:241], v[52:55], v213, v213 op_sel_hi:[0,0,0]
	v_mfma_scale_f32_16x16x128_f8f6f4 v[48:51], v[24:31], v[234:241], v[48:51], v213, v213 op_sel_hi:[0,0,0]
	v_mfma_scale_f32_16x16x128_f8f6f4 v[36:39], v[16:23], v[242:249], v[36:39], v213, v213 op_sel_hi:[0,0,0]
	v_mfma_scale_f32_16x16x128_f8f6f4 v[32:35], v[24:31], v[242:249], v[32:35], v213, v213 op_sel_hi:[0,0,0]
	s_setprio 0
	s_barrier
	s_add_i32 s54, s54, 2
	s_add_u32 s40, s40, 0x100
	s_addc_u32 s41, s41, 0
	s_add_u32 s52, s52, 0x100
	s_addc_u32 s53, s53, 0
	s_cmp_gt_u32 s54, 13
	s_cbranch_scc0 .LBB0_1022
	s_branch .Lgk_after_1022
; #define PG8_STAGE(bufoff, gbase, voff) do { _Pragma("unroll") for (int _i = 0; _i < 2; ++_i) \
;         __builtin_amdgcn_global_load_lds((const unsigned*)((const char*)(gbase) + (voff)[_i]), (PG8_LAS unsigned*)(lds + (bufoff) + ldsw + _i * 8192), 16, 0, 0); } while (0)
; #define PG8_WAIT_V(n) asm volatile("s_waitcnt vmcnt(" #n ")" ::: "memory")
; #define PG8_WAIT_L(n) asm volatile("s_waitcnt lgkmcnt(" #n ")" ::: "memory")
; #define PG8_BAR __builtin_amdgcn_s_barrier()
; #define PG8_SCHED __builtin_amdgcn_sched_barrier(0)
; template <class Epi, class Sched, bool ALIGN_EPI = false, bool SP2 = false, bool F8 = false>
; __device__ __forceinline__ void gemm_phase(PG8_LAS unsigned char* lds, const Gemm g, const Sched& S, const Epi& E) {
;     ...
;             const bool last = (t == nt - 2);
;             const char* a1 = cA + (size_t)(t + 1) * kstep;
;             const char* a2 = last ? nA : cA + (size_t)(t + 2) * kstep; const char* b2 = last ? nB : cB + (size_t)(t + 2) * kstep;
;             const char* a3 = a2 + kstep; const char* b3 = b2 + kstep;
;             if (last && has_next) S.a_ready(nxt);
;             if constexpr (SP2) {
;             PG8_LDB(B0, 0, 0); PG8_LDB(B1, 0, 1); PG8_SCHED; PG8_LDA(At, 0, 0); PG8_STAGE(PG8_SA(1, 1), a1 + hstep, voffA);
;             PG8_WAIT_V(8); PG8_WAIT_L(0); PG8_BAR; PG8_MMA(0, 0, At, B0); PG8_MMA(0, 1, At, B1); PG8_BAR; PG8_SCHED;
;             PG8_LDA(At, 0, 1); PG8_STAGE(PG8_SB(0, 0), b2, voffB); PG8_STAGE(PG8_SB(0, 1), b2 + hstep, voffB); PG8_STAGE(PG8_SA(0, 0), a2, voffA);
;             PG8_WAIT_V(8); PG8_WAIT_L(0); PG8_BAR; PG8_MMA(1, 0, At, B0); PG8_MMA(1, 1, At, B1); PG8_BAR; PG8_SCHED;
.LBB0_1022:
	s_add_u32 s44, s40, 0xfffc0080
	s_addc_u32 s45, s41, -1
	s_add_i32 s55, 0, 0x10000
	s_cmp_eq_u32 s54, 12
	s_cselect_b32 s47, s17, s45
	s_cselect_b32 s46, s50, s44
	s_cselect_b32 s45, s11, s53
	s_cselect_b32 s44, s51, s52
	s_add_i32 s56, 0, 0x14000
	v_add_u32_e32 v0, s55, v215
	v_add_u32_e32 v12, s56, v215
	ds_read_b128 v[16:19], v0
	ds_read_b128 v[20:23], v0 offset:1024
	ds_read_b128 v[24:27], v0 offset:2048
	ds_read_b128 v[28:31], v0 offset:3072
	ds_read_b128 v[0:3], v12
	ds_read_b128 v[4:7], v12 offset:1024
	ds_read_b128 v[8:11], v12 offset:2048
	ds_read_b128 v[12:15], v12 offset:3072
	v_lshl_add_u64 v[242:243], s[40:41], 0, v[192:193]
	s_add_i32 m0, s23, 0xc000
	ds_read_b128 v[196:199], v217
	ds_read_b128 v[200:203], v217 offset:1024
	ds_read_b128 v[218:221], v217 offset:2048
	ds_read_b128 v[222:225], v217 offset:3072
	ds_read_b128 v[226:229], v217 offset:4096
	ds_read_b128 v[230:233], v217 offset:5120
	ds_read_b128 v[234:237], v217 offset:6144
	ds_read_b128 v[238:241], v217 offset:7168
	global_load_lds_dwordx4 v[242:243], off
	v_lshl_add_u64 v[242:243], s[40:41], 0, v[194:195]
	s_add_i32 m0, s23, 0xe000
	s_nop 0
	global_load_lds_dwordx4 v[242:243], off
	s_waitcnt vmcnt(8)
	s_waitcnt lgkmcnt(0)
	s_barrier
	s_setprio 1
	s_waitcnt lgkmcnt(0)
	v_mfma_scale_f32_16x16x128_f8f6f4 v[156:159], v[16:23], v[196:203], v[156:159], v213, v213 op_sel_hi:[0,0,0]
	v_mfma_scale_f32_16x16x128_f8f6f4 v[152:155], v[24:31], v[196:203], v[152:155], v213, v213 op_sel_hi:[0,0,0]
	v_mfma_scale_f32_16x16x128_f8f6f4 v[140:143], v[16:23], v[218:225], v[140:143], v213, v213 op_sel_hi:[0,0,0]
	v_mfma_scale_f32_16x16x128_f8f6f4 v[136:139], v[24:31], v[218:225], v[136:139], v213, v213 op_sel_hi:[0,0,0]
	v_mfma_scale_f32_16x16x128_f8f6f4 v[124:127], v[16:23], v[226:233], v[124:127], v213, v213 op_sel_hi:[0,0,0]
	v_mfma_scale_f32_16x16x128_f8f6f4 v[120:123], v[24:31], v[226:233], v[120:123], v213, v213 op_sel_hi:[0,0,0]
	v_mfma_scale_f32_16x16x128_f8f6f4 v[108:111], v[16:23], v[234:241], v[108:111], v213, v213 op_sel_hi:[0,0,0]
	v_mfma_scale_f32_16x16x128_f8f6f4 v[104:107], v[24:31], v[234:241], v[104:107], v213, v213 op_sel_hi:[0,0,0]
	v_mfma_scale_f32_16x16x128_f8f6f4 v[148:151], v[0:7], v[196:203], v[148:151], v213, v213 op_sel_hi:[0,0,0]
	v_mfma_scale_f32_16x16x128_f8f6f4 v[144:147], v[8:15], v[196:203], v[144:147], v213, v213 op_sel_hi:[0,0,0]
	v_mfma_scale_f32_16x16x128_f8f6f4 v[132:135], v[0:7], v[218:225], v[132:135], v213, v213 op_sel_hi:[0,0,0]
	v_mfma_scale_f32_16x16x128_f8f6f4 v[128:131], v[8:15], v[218:225], v[128:131], v213, v213 op_sel_hi:[0,0,0]
	v_mfma_scale_f32_16x16x128_f8f6f4 v[116:119], v[0:7], v[226:233], v[116:119], v213, v213 op_sel_hi:[0,0,0]
	v_mfma_scale_f32_16x16x128_f8f6f4 v[112:115], v[8:15], v[226:233], v[112:115], v213, v213 op_sel_hi:[0,0,0]
	v_mfma_scale_f32_16x16x128_f8f6f4 v[100:103], v[0:7], v[234:241], v[100:103], v213, v213 op_sel_hi:[0,0,0]
	v_mfma_scale_f32_16x16x128_f8f6f4 v[96:99], v[8:15], v[234:241], v[96:99], v213, v213 op_sel_hi:[0,0,0]
	s_setprio 0
	s_barrier
	s_add_i32 s55, s55, s22
	v_lshl_add_u64 v[196:197], s[44:45], 0, v[188:189]
	s_mov_b32 m0, s55
	ds_read_b128 v[218:221], v217 offset:16384
	ds_read_b128 v[222:225], v217 offset:17408
	ds_read_b128 v[226:229], v217 offset:18432
	ds_read_b128 v[230:233], v217 offset:19456
	ds_read_b128 v[234:237], v217 offset:20480
	ds_read_b128 v[238:241], v217 offset:21504
	ds_read_b128 v[242:245], v217 offset:22528
	ds_read_b128 v[246:249], v217 offset:23552
	global_load_lds_dwordx4 v[196:197], off
	s_add_i32 m0, s55, 0x2000
	s_add_u32 s58, s44, 0x40000
	v_lshl_add_u64 v[198:199], s[44:45], 0, v[184:185]
	s_addc_u32 s59, s45, 0
	s_add_i32 s55, s56, s22
	global_load_lds_dwordx4 v[198:199], off
	v_lshl_add_u64 v[200:201], s[58:59], 0, v[188:189]
	s_mov_b32 m0, s55
	v_lshl_add_u64 v[202:203], s[46:47], 0, v[186:187]
	global_load_lds_dwordx4 v[200:201], off
	v_lshl_add_u64 v[200:201], s[58:59], 0, v[184:185]
	s_add_i32 m0, s55, 0x2000
	s_nop 0
	global_load_lds_dwordx4 v[200:201], off
	v_lshl_add_u64 v[200:201], s[46:47], 0, v[190:191]
	s_mov_b32 m0, s23
	s_nop 0
	global_load_lds_dwordx4 v[200:201], off
	s_mov_b32 m0, s8
	s_nop 0
	global_load_lds_dwordx4 v[202:203], off
	s_waitcnt vmcnt(8)
	s_waitcnt lgkmcnt(0)
	s_barrier
	s_setprio 1
	s_waitcnt lgkmcnt(0)
	v_mfma_scale_f32_16x16x128_f8f6f4 v[92:95], v[16:23], v[218:225], v[92:95], v213, v213 op_sel_hi:[0,0,0]
	v_mfma_scale_f32_16x16x128_f8f6f4 v[88:91], v[24:31], v[218:225], v[88:91], v213, v213 op_sel_hi:[0,0,0]
	v_mfma_scale_f32_16x16x128_f8f6f4 v[76:79], v[16:23], v[226:233], v[76:79], v213, v213 op_sel_hi:[0,0,0]
	v_mfma_scale_f32_16x16x128_f8f6f4 v[72:75], v[24:31], v[226:233], v[72:75], v213, v213 op_sel_hi:[0,0,0]
	v_mfma_scale_f32_16x16x128_f8f6f4 v[60:63], v[16:23], v[234:241], v[60:63], v213, v213 op_sel_hi:[0,0,0]
	v_mfma_scale_f32_16x16x128_f8f6f4 v[56:59], v[24:31], v[234:241], v[56:59], v213, v213 op_sel_hi:[0,0,0]
	v_mfma_scale_f32_16x16x128_f8f6f4 v[44:47], v[16:23], v[242:249], v[44:47], v213, v213 op_sel_hi:[0,0,0]
	v_mfma_scale_f32_16x16x128_f8f6f4 v[40:43], v[24:31], v[242:249], v[40:43], v213, v213 op_sel_hi:[0,0,0]
	v_mfma_scale_f32_16x16x128_f8f6f4 v[84:87], v[0:7], v[218:225], v[84:87], v213, v213 op_sel_hi:[0,0,0]
	v_mfma_scale_f32_16x16x128_f8f6f4 v[80:83], v[8:15], v[218:225], v[80:83], v213, v213 op_sel_hi:[0,0,0]
	v_mfma_scale_f32_16x16x128_f8f6f4 v[68:71], v[0:7], v[226:233], v[68:71], v213, v213 op_sel_hi:[0,0,0]
	v_mfma_scale_f32_16x16x128_f8f6f4 v[64:67], v[8:15], v[226:233], v[64:67], v213, v213 op_sel_hi:[0,0,0]
	v_mfma_scale_f32_16x16x128_f8f6f4 v[52:55], v[0:7], v[234:241], v[52:55], v213, v213 op_sel_hi:[0,0,0]
	v_mfma_scale_f32_16x16x128_f8f6f4 v[48:51], v[8:15], v[234:241], v[48:51], v213, v213 op_sel_hi:[0,0,0]
	v_mfma_scale_f32_16x16x128_f8f6f4 v[36:39], v[0:7], v[242:249], v[36:39], v213, v213 op_sel_hi:[0,0,0]
	v_mfma_scale_f32_16x16x128_f8f6f4 v[32:35], v[8:15], v[242:249], v[32:35], v213, v213 op_sel_hi:[0,0,0]
	s_setprio 0
	s_barrier
; #define PG8_STAGE(bufoff, gbase, voff) do { _Pragma("unroll") for (int _i = 0; _i < 2; ++_i) \
;         __builtin_amdgcn_global_load_lds((const unsigned*)((const char*)(gbase) + (voff)[_i]), (PG8_LAS unsigned*)(lds + (bufoff) + ldsw + _i * 8192), 16, 0, 0); } while (0)
; #define PG8_WAIT_V(n) asm volatile("s_waitcnt vmcnt(" #n ")" ::: "memory")
; #define PG8_WAIT_L(n) asm volatile("s_waitcnt lgkmcnt(" #n ")" ::: "memory")
; #define PG8_BAR __builtin_amdgcn_s_barrier()
; #define PG8_SCHED __builtin_amdgcn_sched_barrier(0)
; template <class Epi, class Sched, bool ALIGN_EPI = false, bool SP2 = false, bool F8 = false>
; __device__ __forceinline__ void gemm_phase(PG8_LAS unsigned char* lds, const Gemm g, const Sched& S, const Epi& E) {
;     ...
;         for (int t = 0; t < nt; t += 2) {
;     ...
;             PG8_LDB(B0, 1, 0); PG8_LDB(B1, 1, 1); PG8_SCHED; PG8_LDA(At, 1, 0); PG8_STAGE(PG8_SA(0, 1), a2 + hstep, voffA);
;             PG8_WAIT_V(8); PG8_WAIT_L(0); PG8_BAR; PG8_MMA(0, 0, At, B0); PG8_MMA(0, 1, At, B1); PG8_BAR; PG8_SCHED;
;             PG8_LDA(At, 1, 1); PG8_STAGE(PG8_SB(1, 0), b3, voffB); PG8_STAGE(PG8_SB(1, 1), b3 + hstep, voffB); PG8_STAGE(PG8_SA(1, 0), a3, voffA);
;             PG8_WAIT_V(8); PG8_WAIT_L(0); PG8_BAR; PG8_MMA(1, 0, At, B0); PG8_MMA(1, 1, At, B1); PG8_BAR; PG8_SCHED;
	s_add_i32 s55, 0, 0x18000
	s_add_i32 s56, 0, 0x1c000
	v_add_u32_e32 v12, s55, v215
	v_add_u32_e32 v28, s56, v215
	ds_read_b128 v[0:3], v12
	ds_read_b128 v[4:7], v12 offset:1024
	ds_read_b128 v[8:11], v12 offset:2048
	ds_read_b128 v[12:15], v12 offset:3072
	ds_read_b128 v[16:19], v28
	ds_read_b128 v[20:23], v28 offset:1024
	ds_read_b128 v[24:27], v28 offset:2048
	ds_read_b128 v[28:31], v28 offset:3072
	s_add_u32 s46, s46, 0x40000
	s_addc_u32 s47, s47, 0
	s_mov_b32 m0, s9
	v_lshl_add_u64 v[162:163], s[46:47], 0, v[190:191]
	ds_read_b128 v[218:221], v217 offset:32768
	ds_read_b128 v[222:225], v217 offset:33792
	ds_read_b128 v[226:229], v217 offset:34816
	ds_read_b128 v[230:233], v217 offset:35840
	ds_read_b128 v[234:237], v217 offset:36864
	ds_read_b128 v[238:241], v217 offset:37888
	ds_read_b128 v[242:245], v217 offset:38912
	ds_read_b128 v[246:249], v217 offset:39936
	global_load_lds_dwordx4 v[162:163], off
	v_lshl_add_u64 v[162:163], s[46:47], 0, v[186:187]
	s_mov_b32 m0, s28
	s_nop 0
	global_load_lds_dwordx4 v[162:163], off
	s_waitcnt vmcnt(8)
	s_waitcnt lgkmcnt(0)
	s_barrier
	s_setprio 1
	s_waitcnt lgkmcnt(0)
	v_mfma_scale_f32_16x16x128_f8f6f4 v[156:159], v[0:7], v[218:225], v[156:159], v213, v213 op_sel_hi:[0,0,0]
	v_mfma_scale_f32_16x16x128_f8f6f4 v[152:155], v[8:15], v[218:225], v[152:155], v213, v213 op_sel_hi:[0,0,0]
	v_mfma_scale_f32_16x16x128_f8f6f4 v[140:143], v[0:7], v[226:233], v[140:143], v213, v213 op_sel_hi:[0,0,0]
	v_mfma_scale_f32_16x16x128_f8f6f4 v[136:139], v[8:15], v[226:233], v[136:139], v213, v213 op_sel_hi:[0,0,0]
	v_mfma_scale_f32_16x16x128_f8f6f4 v[124:127], v[0:7], v[234:241], v[124:127], v213, v213 op_sel_hi:[0,0,0]
	v_mfma_scale_f32_16x16x128_f8f6f4 v[120:123], v[8:15], v[234:241], v[120:123], v213, v213 op_sel_hi:[0,0,0]
	v_mfma_scale_f32_16x16x128_f8f6f4 v[108:111], v[0:7], v[242:249], v[108:111], v213, v213 op_sel_hi:[0,0,0]
	v_mfma_scale_f32_16x16x128_f8f6f4 v[104:107], v[8:15], v[242:249], v[104:107], v213, v213 op_sel_hi:[0,0,0]
	v_mfma_scale_f32_16x16x128_f8f6f4 v[148:151], v[16:23], v[218:225], v[148:151], v213, v213 op_sel_hi:[0,0,0]
	v_mfma_scale_f32_16x16x128_f8f6f4 v[144:147], v[24:31], v[218:225], v[144:147], v213, v213 op_sel_hi:[0,0,0]
	v_mfma_scale_f32_16x16x128_f8f6f4 v[132:135], v[16:23], v[226:233], v[132:135], v213, v213 op_sel_hi:[0,0,0]
	v_mfma_scale_f32_16x16x128_f8f6f4 v[128:131], v[24:31], v[226:233], v[128:131], v213, v213 op_sel_hi:[0,0,0]
	v_mfma_scale_f32_16x16x128_f8f6f4 v[116:119], v[16:23], v[234:241], v[116:119], v213, v213 op_sel_hi:[0,0,0]
	v_mfma_scale_f32_16x16x128_f8f6f4 v[112:115], v[24:31], v[234:241], v[112:115], v213, v213 op_sel_hi:[0,0,0]
	v_mfma_scale_f32_16x16x128_f8f6f4 v[100:103], v[16:23], v[242:249], v[100:103], v213, v213 op_sel_hi:[0,0,0]
	v_mfma_scale_f32_16x16x128_f8f6f4 v[96:99], v[24:31], v[242:249], v[96:99], v213, v213 op_sel_hi:[0,0,0]
	s_setprio 0
	s_barrier
	s_add_i32 s46, s55, s22
	v_lshl_add_u64 v[162:163], v[196:197], 0, s[14:15]
	s_mov_b32 m0, s46
	ds_read_b128 v[218:221], v217 offset:49152
	ds_read_b128 v[222:225], v217 offset:50176
	ds_read_b128 v[226:229], v217 offset:51200
	ds_read_b128 v[230:233], v217 offset:52224
	ds_read_b128 v[234:237], v217 offset:53248
	ds_read_b128 v[238:241], v217 offset:54272
	ds_read_b128 v[242:245], v217 offset:55296
	ds_read_b128 v[246:249], v217 offset:56320
	global_load_lds_dwordx4 v[162:163], off
	s_add_i32 m0, s46, 0x2000
	s_add_u32 s44, s44, 0x40080
	v_lshl_add_u64 v[162:163], v[198:199], 0, s[14:15]
	s_addc_u32 s45, s45, 0
	s_add_i32 s46, s56, s22
	global_load_lds_dwordx4 v[162:163], off
	v_lshl_add_u64 v[162:163], s[44:45], 0, v[188:189]
	s_mov_b32 m0, s46
	s_nop 0
	global_load_lds_dwordx4 v[162:163], off
	v_lshl_add_u64 v[162:163], s[44:45], 0, v[184:185]
	s_add_i32 m0, s46, 0x2000
	s_nop 0
	global_load_lds_dwordx4 v[162:163], off
	v_lshl_add_u64 v[162:163], v[200:201], 0, s[14:15]
	s_mov_b32 m0, s29
	s_nop 0
	global_load_lds_dwordx4 v[162:163], off
	v_lshl_add_u64 v[162:163], v[202:203], 0, s[14:15]
	s_mov_b32 m0, s48
	s_nop 0
	global_load_lds_dwordx4 v[162:163], off
	s_waitcnt vmcnt(8)
	s_waitcnt lgkmcnt(0)
	s_barrier
	s_setprio 1
	s_waitcnt lgkmcnt(0)
	v_mfma_scale_f32_16x16x128_f8f6f4 v[92:95], v[0:7], v[218:225], v[92:95], v213, v213 op_sel_hi:[0,0,0]
	v_mfma_scale_f32_16x16x128_f8f6f4 v[88:91], v[8:15], v[218:225], v[88:91], v213, v213 op_sel_hi:[0,0,0]
	v_mfma_scale_f32_16x16x128_f8f6f4 v[76:79], v[0:7], v[226:233], v[76:79], v213, v213 op_sel_hi:[0,0,0]
	v_mfma_scale_f32_16x16x128_f8f6f4 v[72:75], v[8:15], v[226:233], v[72:75], v213, v213 op_sel_hi:[0,0,0]
	v_mfma_scale_f32_16x16x128_f8f6f4 v[60:63], v[0:7], v[234:241], v[60:63], v213, v213 op_sel_hi:[0,0,0]
	v_mfma_scale_f32_16x16x128_f8f6f4 v[56:59], v[8:15], v[234:241], v[56:59], v213, v213 op_sel_hi:[0,0,0]
	v_mfma_scale_f32_16x16x128_f8f6f4 v[44:47], v[0:7], v[242:249], v[44:47], v213, v213 op_sel_hi:[0,0,0]
	v_mfma_scale_f32_16x16x128_f8f6f4 v[40:43], v[8:15], v[242:249], v[40:43], v213, v213 op_sel_hi:[0,0,0]
	v_mfma_scale_f32_16x16x128_f8f6f4 v[84:87], v[16:23], v[218:225], v[84:87], v213, v213 op_sel_hi:[0,0,0]
	v_mfma_scale_f32_16x16x128_f8f6f4 v[80:83], v[24:31], v[218:225], v[80:83], v213, v213 op_sel_hi:[0,0,0]
	v_mfma_scale_f32_16x16x128_f8f6f4 v[68:71], v[16:23], v[226:233], v[68:71], v213, v213 op_sel_hi:[0,0,0]
	v_mfma_scale_f32_16x16x128_f8f6f4 v[64:67], v[24:31], v[226:233], v[64:67], v213, v213 op_sel_hi:[0,0,0]
	v_mfma_scale_f32_16x16x128_f8f6f4 v[52:55], v[16:23], v[234:241], v[52:55], v213, v213 op_sel_hi:[0,0,0]
	v_mfma_scale_f32_16x16x128_f8f6f4 v[48:51], v[24:31], v[234:241], v[48:51], v213, v213 op_sel_hi:[0,0,0]
	v_mfma_scale_f32_16x16x128_f8f6f4 v[36:39], v[16:23], v[242:249], v[36:39], v213, v213 op_sel_hi:[0,0,0]
	v_mfma_scale_f32_16x16x128_f8f6f4 v[32:35], v[24:31], v[242:249], v[32:35], v213, v213 op_sel_hi:[0,0,0]
	s_setprio 0
	s_barrier
	s_add_i32 s54, s54, 2
	s_add_u32 s40, s40, 0x100
	s_addc_u32 s41, s41, 0
	s_add_u32 s52, s52, 0x100
	s_addc_u32 s53, s53, 0
	s_cmp_gt_u32 s54, 13
	s_cbranch_scc0 .LBB0_1022

; #define PG8_STAGE(bufoff, gbase, voff) do { _Pragma("unroll") for (int _i = 0; _i < 2; ++_i) \
;         __builtin_amdgcn_global_load_lds((const unsigned*)((const char*)(gbase) + (voff)[_i]), (PG8_LAS unsigned*)(lds + (bufoff) + ldsw + _i * 8192), 16, 0, 0); } while (0)
; #define PG8_WAIT_V(n) asm volatile("s_waitcnt vmcnt(" #n ")" ::: "memory")
; #define PG8_WAIT_L(n) asm volatile("s_waitcnt lgkmcnt(" #n ")" ::: "memory")
; #define PG8_BAR __builtin_amdgcn_s_barrier()
; #define PG8_SCHED __builtin_amdgcn_sched_barrier(0)
; template <class Epi, class Sched, bool ALIGN_EPI = false, bool SP2 = false, bool F8 = false>
; __device__ __forceinline__ void gemm_phase(PG8_LAS unsigned char* lds, const Gemm g, const Sched& S, const Epi& E) {
;     ...
;         const bool has_next = S.next(ui + 1, nxt);
;         const char* nA = has_next ? (const char*)g.A + (size_t)nxt.pm * tstep : cA; const char* nB = has_next ? (const char*)g.Bt + (size_t)nxt.pn * tstep : cB;
;         for (int t = 0; t < nt; t += 2) {
;             const bool last = (t == nt - 2);
;             const char* a1 = cA + (size_t)(t + 1) * kstep;
;             const char* a2 = last ? nA : cA + (size_t)(t + 2) * kstep; const char* b2 = last ? nB : cB + (size_t)(t + 2) * kstep;
;             const char* a3 = a2 + kstep; const char* b3 = b2 + kstep;
;             if (last && has_next) S.a_ready(nxt);
;             if constexpr (SP2) {
;             PG8_LDB(B0, 0, 0); PG8_LDB(B1, 0, 1); PG8_SCHED; PG8_LDA(At, 0, 0); PG8_STAGE(PG8_SA(1, 1), a1 + hstep, voffA);
;             PG8_WAIT_V(8); PG8_WAIT_L(0); PG8_BAR; PG8_MMA(0, 0, At, B0); PG8_MMA(0, 1, At, B1); PG8_BAR; PG8_SCHED;
;             PG8_LDA(At, 0, 1); PG8_STAGE(PG8_SB(0, 0), b2, voffB); PG8_STAGE(PG8_SB(0, 1), b2 + hstep, voffB); PG8_STAGE(PG8_SA(0, 0), a2, voffA);
;             PG8_WAIT_V(8); PG8_WAIT_L(0); PG8_BAR; PG8_MMA(1, 0, At, B0); PG8_MMA(1, 1, At, B1); PG8_BAR; PG8_SCHED;
.LBB0_1101:
	s_ashr_i32 s17, s16, 31
	s_lshl_b64 s[36:37], s[16:17], 20
	v_readlane_b32 s40, v251, 7
	v_readlane_b32 s41, v251, 8
	s_add_u32 s36, s40, s36
	s_addc_u32 s37, s41, s37
	s_and_b64 s[40:41], s[38:39], exec
	s_cselect_b32 s17, s37, s43
	s_cselect_b32 s48, s36, s42
	s_ashr_i32 s11, s10, 31
	s_lshl_b64 s[40:41], s[10:11], 20
	v_readlane_b32 s11, v250, 22
	s_add_u32 s40, s11, s40
	v_readlane_b32 s11, v250, 23
	s_addc_u32 s41, s11, s41
	s_and_b64 s[46:47], s[38:39], exec
	s_cselect_b32 s11, s41, s45
	s_cselect_b32 s49, s40, s44
	s_add_u32 s42, s42, 0x80080
	s_addc_u32 s43, s43, 0
	s_add_u32 s50, s44, 0x100
	s_addc_u32 s51, s45, 0
	s_mov_b32 s52, -2
	s_add_u32 s44, s42, 0xfff80080
	s_addc_u32 s45, s43, -1
	s_add_i32 s53, 0, 0x10000
	s_cmp_eq_u32 s52, 28
	s_cselect_b32 s47, s17, s45
	s_cselect_b32 s46, s48, s44
	s_cselect_b32 s45, s11, s51
	s_cselect_b32 s44, s49, s50
	s_add_i32 s56, 0, 0x14000
	v_add_u32_e32 v154, s53, v139
	v_add_u32_e32 v158, s56, v139
	ds_read_b128 v[142:145], v154
	ds_read_b128 v[146:149], v154 offset:1024
	ds_read_b128 v[150:153], v154 offset:2048
	ds_read_b128 v[154:157], v154 offset:3072
	ds_read_b128 v[184:187], v158
	ds_read_b128 v[188:191], v158 offset:1024
	ds_read_b128 v[192:195], v158 offset:2048
	ds_read_b128 v[196:199], v158 offset:3072
	v_lshl_add_u64 v[158:159], s[42:43], 0, v[134:135]
	s_add_i32 m0, s9, 0xc000
	ds_read_b128 v[200:203], v141
	ds_read_b128 v[214:217], v141 offset:1024
	ds_read_b128 v[218:221], v141 offset:2048
	ds_read_b128 v[222:225], v141 offset:3072
	ds_read_b128 v[226:229], v141 offset:4096
	ds_read_b128 v[230:233], v141 offset:5120
	ds_read_b128 v[234:237], v141 offset:6144
	ds_read_b128 v[238:241], v141 offset:7168
	global_load_lds_dwordx4 v[158:159], off
	v_lshl_add_u64 v[158:159], s[42:43], 0, v[136:137]
	s_add_i32 m0, s9, 0xe000
	s_nop 0
	global_load_lds_dwordx4 v[158:159], off
	s_waitcnt vmcnt(8)
	s_waitcnt lgkmcnt(0)
	s_barrier
	s_setprio 1
	s_waitcnt lgkmcnt(0)
	v_mfma_f32_16x16x32_bf16 v[124:127], v[142:145], v[200:203], 0
	v_mfma_f32_16x16x32_bf16 v[120:123], v[150:153], v[200:203], 0
	v_mfma_f32_16x16x32_bf16 v[116:119], v[142:145], v[218:221], 0
	v_mfma_f32_16x16x32_bf16 v[112:115], v[150:153], v[218:221], 0
	v_mfma_f32_16x16x32_bf16 v[108:111], v[142:145], v[226:229], 0
	v_mfma_f32_16x16x32_bf16 v[100:103], v[150:153], v[226:229], 0
	v_mfma_f32_16x16x32_bf16 v[92:95], v[142:145], v[234:237], 0
	v_mfma_f32_16x16x32_bf16 v[84:87], v[150:153], v[234:237], 0
	v_mfma_f32_16x16x32_bf16 v[124:127], v[146:149], v[214:217], v[124:127]
	v_mfma_f32_16x16x32_bf16 v[120:123], v[154:157], v[214:217], v[120:123]
	v_mfma_f32_16x16x32_bf16 v[116:119], v[146:149], v[222:225], v[116:119]
	v_mfma_f32_16x16x32_bf16 v[112:115], v[154:157], v[222:225], v[112:115]
	v_mfma_f32_16x16x32_bf16 v[108:111], v[146:149], v[230:233], v[108:111]
	v_mfma_f32_16x16x32_bf16 v[100:103], v[154:157], v[230:233], v[100:103]
	v_mfma_f32_16x16x32_bf16 v[92:95], v[146:149], v[238:241], v[92:95]
	v_mfma_f32_16x16x32_bf16 v[84:87], v[154:157], v[238:241], v[84:87]
	v_mfma_f32_16x16x32_bf16 v[104:107], v[184:187], v[200:203], 0
	v_mfma_f32_16x16x32_bf16 v[96:99], v[192:195], v[200:203], 0
	v_mfma_f32_16x16x32_bf16 v[88:91], v[184:187], v[218:221], 0
	v_mfma_f32_16x16x32_bf16 v[80:83], v[192:195], v[218:221], 0
	v_mfma_f32_16x16x32_bf16 v[76:79], v[184:187], v[226:229], 0
	v_mfma_f32_16x16x32_bf16 v[72:75], v[192:195], v[226:229], 0
	v_mfma_f32_16x16x32_bf16 v[68:71], v[184:187], v[234:237], 0
	v_mfma_f32_16x16x32_bf16 v[64:67], v[192:195], v[234:237], 0
	v_mfma_f32_16x16x32_bf16 v[104:107], v[188:191], v[214:217], v[104:107]
	v_mfma_f32_16x16x32_bf16 v[96:99], v[196:199], v[214:217], v[96:99]
	v_mfma_f32_16x16x32_bf16 v[88:91], v[188:191], v[222:225], v[88:91]
	v_mfma_f32_16x16x32_bf16 v[80:83], v[196:199], v[222:225], v[80:83]
	v_mfma_f32_16x16x32_bf16 v[76:79], v[188:191], v[230:233], v[76:79]
	v_mfma_f32_16x16x32_bf16 v[72:75], v[196:199], v[230:233], v[72:75]
	v_mfma_f32_16x16x32_bf16 v[68:71], v[188:191], v[238:241], v[68:71]
	v_mfma_f32_16x16x32_bf16 v[64:67], v[196:199], v[238:241], v[64:67]
	s_setprio 0
	s_barrier
	s_add_i32 s53, s53, s8
	v_lshl_add_u64 v[158:159], s[44:45], 0, v[160:161]
	s_mov_b32 m0, s53
	ds_read_b128 v[200:203], v141 offset:16384
	ds_read_b128 v[214:217], v141 offset:17408
	ds_read_b128 v[218:221], v141 offset:18432
	ds_read_b128 v[222:225], v141 offset:19456
	ds_read_b128 v[226:229], v141 offset:20480
	ds_read_b128 v[230:233], v141 offset:21504
	ds_read_b128 v[234:237], v141 offset:22528
	ds_read_b128 v[238:241], v141 offset:23552
	global_load_lds_dwordx4 v[158:159], off
	s_add_i32 m0, s53, 0x2000
	s_add_u32 s54, s44, 0x80000
	v_lshl_add_u64 v[162:163], s[44:45], 0, v[128:129]
	s_addc_u32 s55, s45, 0
	s_add_i32 s53, s56, s8
	global_load_lds_dwordx4 v[162:163], off
	v_lshl_add_u64 v[242:243], s[54:55], 0, v[160:161]
	s_mov_b32 m0, s53
	v_lshl_add_u64 v[244:245], s[46:47], 0, v[130:131]
	global_load_lds_dwordx4 v[242:243], off
	v_lshl_add_u64 v[242:243], s[54:55], 0, v[128:129]
	s_add_i32 m0, s53, 0x2000
	s_nop 0
	global_load_lds_dwordx4 v[242:243], off
	v_lshl_add_u64 v[242:243], s[46:47], 0, v[132:133]
	s_mov_b32 m0, s9
	s_nop 0
	global_load_lds_dwordx4 v[242:243], off
	s_mov_b32 m0, s13
	s_nop 0
	global_load_lds_dwordx4 v[244:245], off
	s_waitcnt vmcnt(8)
	s_waitcnt lgkmcnt(0)
	s_barrier
; #define PG8_STAGE(bufoff, gbase, voff) do { _Pragma("unroll") for (int _i = 0; _i < 2; ++_i) \
;         __builtin_amdgcn_global_load_lds((const unsigned*)((const char*)(gbase) + (voff)[_i]), (PG8_LAS unsigned*)(lds + (bufoff) + ldsw + _i * 8192), 16, 0, 0); } while (0)
; #define PG8_WAIT_V(n) asm volatile("s_waitcnt vmcnt(" #n ")" ::: "memory")
; #define PG8_WAIT_L(n) asm volatile("s_waitcnt lgkmcnt(" #n ")" ::: "memory")
; #define PG8_BAR __builtin_amdgcn_s_barrier()
; #define PG8_SCHED __builtin_amdgcn_sched_barrier(0)
; template <class Epi, class Sched, bool ALIGN_EPI = false, bool SP2 = false, bool F8 = false>
; __device__ __forceinline__ void gemm_phase(PG8_LAS unsigned char* lds, const Gemm g, const Sched& S, const Epi& E) {
;     ...
;             PG8_WAIT_V(8); PG8_WAIT_L(0); PG8_BAR; PG8_MMA(1, 0, At, B0); PG8_MMA(1, 1, At, B1); PG8_BAR; PG8_SCHED;
;             PG8_LDB(B0, 1, 0); PG8_LDB(B1, 1, 1); PG8_SCHED; PG8_LDA(At, 1, 0); PG8_STAGE(PG8_SA(0, 1), a2 + hstep, voffA);
;             PG8_WAIT_V(8); PG8_WAIT_L(0); PG8_BAR; PG8_MMA(0, 0, At, B0); PG8_MMA(0, 1, At, B1); PG8_BAR; PG8_SCHED;
	s_setprio 1
	s_waitcnt lgkmcnt(0)
	v_mfma_f32_16x16x32_bf16 v[60:63], v[142:145], v[200:203], 0
	v_mfma_f32_16x16x32_bf16 v[56:59], v[150:153], v[200:203], 0
	v_mfma_f32_16x16x32_bf16 v[52:55], v[142:145], v[218:221], 0
	v_mfma_f32_16x16x32_bf16 v[48:51], v[150:153], v[218:221], 0
	v_mfma_f32_16x16x32_bf16 v[44:47], v[142:145], v[226:229], 0
	v_mfma_f32_16x16x32_bf16 v[36:39], v[150:153], v[226:229], 0
	v_mfma_f32_16x16x32_bf16 v[28:31], v[142:145], v[234:237], 0
	v_mfma_f32_16x16x32_bf16 v[20:23], v[150:153], v[234:237], 0
	v_mfma_f32_16x16x32_bf16 v[60:63], v[146:149], v[214:217], v[60:63]
	v_mfma_f32_16x16x32_bf16 v[56:59], v[154:157], v[214:217], v[56:59]
	v_mfma_f32_16x16x32_bf16 v[52:55], v[146:149], v[222:225], v[52:55]
	v_mfma_f32_16x16x32_bf16 v[48:51], v[154:157], v[222:225], v[48:51]
	v_mfma_f32_16x16x32_bf16 v[44:47], v[146:149], v[230:233], v[44:47]
	v_mfma_f32_16x16x32_bf16 v[36:39], v[154:157], v[230:233], v[36:39]
	v_mfma_f32_16x16x32_bf16 v[28:31], v[146:149], v[238:241], v[28:31]
	v_mfma_f32_16x16x32_bf16 v[20:23], v[154:157], v[238:241], v[20:23]
	v_mfma_f32_16x16x32_bf16 v[40:43], v[184:187], v[200:203], 0
	v_mfma_f32_16x16x32_bf16 v[32:35], v[192:195], v[200:203], 0
	v_mfma_f32_16x16x32_bf16 v[24:27], v[184:187], v[218:221], 0
	v_mfma_f32_16x16x32_bf16 v[16:19], v[192:195], v[218:221], 0
	v_mfma_f32_16x16x32_bf16 v[12:15], v[184:187], v[226:229], 0
	v_mfma_f32_16x16x32_bf16 v[8:11], v[192:195], v[226:229], 0
	v_mfma_f32_16x16x32_bf16 v[4:7], v[184:187], v[234:237], 0
	v_mfma_f32_16x16x32_bf16 v[0:3], v[192:195], v[234:237], 0
	v_mfma_f32_16x16x32_bf16 v[40:43], v[188:191], v[214:217], v[40:43]
	v_mfma_f32_16x16x32_bf16 v[32:35], v[196:199], v[214:217], v[32:35]
	v_mfma_f32_16x16x32_bf16 v[24:27], v[188:191], v[222:225], v[24:27]
	v_mfma_f32_16x16x32_bf16 v[16:19], v[196:199], v[222:225], v[16:19]
	v_mfma_f32_16x16x32_bf16 v[12:15], v[188:191], v[230:233], v[12:15]
	v_mfma_f32_16x16x32_bf16 v[8:11], v[196:199], v[230:233], v[8:11]
	v_mfma_f32_16x16x32_bf16 v[4:7], v[188:191], v[238:241], v[4:7]
	v_mfma_f32_16x16x32_bf16 v[0:3], v[196:199], v[238:241], v[0:3]
	s_setprio 0
	s_barrier
	s_add_i32 s53, 0, 0x18000
	s_add_i32 s54, 0, 0x1c000
	v_add_u32_e32 v154, s53, v139
	v_add_u32_e32 v196, s54, v139
	ds_read_b128 v[142:145], v154
	ds_read_b128 v[146:149], v154 offset:1024
	ds_read_b128 v[150:153], v154 offset:2048
	ds_read_b128 v[154:157], v154 offset:3072
	ds_read_b128 v[184:187], v196
	ds_read_b128 v[188:191], v196 offset:1024
	ds_read_b128 v[192:195], v196 offset:2048
	ds_read_b128 v[196:199], v196 offset:3072
	s_add_u32 s46, s46, 0x80000
	s_addc_u32 s47, s47, 0
	s_mov_b32 m0, s19
	v_lshl_add_u64 v[246:247], s[46:47], 0, v[132:133]
	ds_read_b128 v[200:203], v141 offset:32768
	ds_read_b128 v[214:217], v141 offset:33792
	ds_read_b128 v[218:221], v141 offset:34816
	ds_read_b128 v[222:225], v141 offset:35840
	ds_read_b128 v[226:229], v141 offset:36864
	ds_read_b128 v[230:233], v141 offset:37888
	ds_read_b128 v[234:237], v141 offset:38912
	ds_read_b128 v[238:241], v141 offset:39936
	global_load_lds_dwordx4 v[246:247], off
	v_lshl_add_u64 v[246:247], s[46:47], 0, v[130:131]
	s_mov_b32 m0, s22
	s_nop 0
	global_load_lds_dwordx4 v[246:247], off
	s_waitcnt vmcnt(8)
	s_waitcnt lgkmcnt(0)
	s_barrier
	s_setprio 1
	s_waitcnt lgkmcnt(0)
	v_mfma_f32_16x16x32_bf16 v[124:127], v[142:145], v[200:203], v[124:127]
	v_mfma_f32_16x16x32_bf16 v[120:123], v[150:153], v[200:203], v[120:123]
	v_mfma_f32_16x16x32_bf16 v[116:119], v[142:145], v[218:221], v[116:119]
	v_mfma_f32_16x16x32_bf16 v[112:115], v[150:153], v[218:221], v[112:115]
	v_mfma_f32_16x16x32_bf16 v[108:111], v[142:145], v[226:229], v[108:111]
	v_mfma_f32_16x16x32_bf16 v[100:103], v[150:153], v[226:229], v[100:103]
	v_mfma_f32_16x16x32_bf16 v[92:95], v[142:145], v[234:237], v[92:95]
	v_mfma_f32_16x16x32_bf16 v[84:87], v[150:153], v[234:237], v[84:87]
	v_mfma_f32_16x16x32_bf16 v[124:127], v[146:149], v[214:217], v[124:127]
	v_mfma_f32_16x16x32_bf16 v[120:123], v[154:157], v[214:217], v[120:123]
	v_mfma_f32_16x16x32_bf16 v[116:119], v[146:149], v[222:225], v[116:119]
	v_mfma_f32_16x16x32_bf16 v[112:115], v[154:157], v[222:225], v[112:115]
	v_mfma_f32_16x16x32_bf16 v[108:111], v[146:149], v[230:233], v[108:111]
	v_mfma_f32_16x16x32_bf16 v[100:103], v[154:157], v[230:233], v[100:103]
	v_mfma_f32_16x16x32_bf16 v[92:95], v[146:149], v[238:241], v[92:95]
	v_mfma_f32_16x16x32_bf16 v[84:87], v[154:157], v[238:241], v[84:87]
	v_mfma_f32_16x16x32_bf16 v[104:107], v[184:187], v[200:203], v[104:107]
	v_mfma_f32_16x16x32_bf16 v[96:99], v[192:195], v[200:203], v[96:99]
	v_mfma_f32_16x16x32_bf16 v[88:91], v[184:187], v[218:221], v[88:91]
	v_mfma_f32_16x16x32_bf16 v[80:83], v[192:195], v[218:221], v[80:83]
	v_mfma_f32_16x16x32_bf16 v[76:79], v[184:187], v[226:229], v[76:79]
	v_mfma_f32_16x16x32_bf16 v[72:75], v[192:195], v[226:229], v[72:75]
	v_mfma_f32_16x16x32_bf16 v[68:71], v[184:187], v[234:237], v[68:71]
	v_mfma_f32_16x16x32_bf16 v[64:67], v[192:195], v[234:237], v[64:67]
	v_mfma_f32_16x16x32_bf16 v[104:107], v[188:191], v[214:217], v[104:107]
	v_mfma_f32_16x16x32_bf16 v[96:99], v[196:199], v[214:217], v[96:99]
	v_mfma_f32_16x16x32_bf16 v[88:91], v[188:191], v[222:225], v[88:91]
	v_mfma_f32_16x16x32_bf16 v[80:83], v[196:199], v[222:225], v[80:83]
	v_mfma_f32_16x16x32_bf16 v[76:79], v[188:191], v[230:233], v[76:79]
	v_mfma_f32_16x16x32_bf16 v[72:75], v[196:199], v[230:233], v[72:75]
	v_mfma_f32_16x16x32_bf16 v[68:71], v[188:191], v[238:241], v[68:71]
	v_mfma_f32_16x16x32_bf16 v[64:67], v[196:199], v[238:241], v[64:67]
	s_setprio 0
	s_barrier
; #define PG8_STAGE(bufoff, gbase, voff) do { _Pragma("unroll") for (int _i = 0; _i < 2; ++_i) \
;         __builtin_amdgcn_global_load_lds((const unsigned*)((const char*)(gbase) + (voff)[_i]), (PG8_LAS unsigned*)(lds + (bufoff) + ldsw + _i * 8192), 16, 0, 0); } while (0)
; #define PG8_WAIT_V(n) asm volatile("s_waitcnt vmcnt(" #n ")" ::: "memory")
; #define PG8_WAIT_L(n) asm volatile("s_waitcnt lgkmcnt(" #n ")" ::: "memory")
; #define PG8_BAR __builtin_amdgcn_s_barrier()
; #define PG8_SCHED __builtin_amdgcn_sched_barrier(0)
; template <class Epi, class Sched, bool ALIGN_EPI = false, bool SP2 = false, bool F8 = false>
; __device__ __forceinline__ void gemm_phase(PG8_LAS unsigned char* lds, const Gemm g, const Sched& S, const Epi& E) {
;     ...
;         for (int t = 0; t < nt; t += 2) {
;             const bool last = (t == nt - 2);
;             const char* a1 = cA + (size_t)(t + 1) * kstep;
;             const char* a2 = last ? nA : cA + (size_t)(t + 2) * kstep; const char* b2 = last ? nB : cB + (size_t)(t + 2) * kstep;
;             const char* a3 = a2 + kstep; const char* b3 = b2 + kstep;
;             if (last && has_next) S.a_ready(nxt);
;             if constexpr (SP2) {
;             PG8_LDB(B0, 0, 0); PG8_LDB(B1, 0, 1); PG8_SCHED; PG8_LDA(At, 0, 0); PG8_STAGE(PG8_SA(1, 1), a1 + hstep, voffA);
;             PG8_WAIT_V(8); PG8_WAIT_L(0); PG8_BAR; PG8_MMA(0, 0, At, B0); PG8_MMA(0, 1, At, B1); PG8_BAR; PG8_SCHED;
;             PG8_LDA(At, 0, 1); PG8_STAGE(PG8_SB(0, 0), b2, voffB); PG8_STAGE(PG8_SB(0, 1), b2 + hstep, voffB); PG8_STAGE(PG8_SA(0, 0), a2, voffA);
;             PG8_WAIT_V(8); PG8_WAIT_L(0); PG8_BAR; PG8_MMA(1, 0, At, B0); PG8_MMA(1, 1, At, B1); PG8_BAR; PG8_SCHED;
;             PG8_LDB(B0, 1, 0); PG8_LDB(B1, 1, 1); PG8_SCHED; PG8_LDA(At, 1, 0); PG8_STAGE(PG8_SA(0, 1), a2 + hstep, voffA);
;             PG8_WAIT_V(8); PG8_WAIT_L(0); PG8_BAR; PG8_MMA(0, 0, At, B0); PG8_MMA(0, 1, At, B1); PG8_BAR; PG8_SCHED;
;             PG8_LDA(At, 1, 1); PG8_STAGE(PG8_SB(1, 0), b3, voffB); PG8_STAGE(PG8_SB(1, 1), b3 + hstep, voffB); PG8_STAGE(PG8_SA(1, 0), a3, voffA);
;             PG8_WAIT_V(8); PG8_WAIT_L(0); PG8_BAR; PG8_MMA(1, 0, At, B0); PG8_MMA(1, 1, At, B1); PG8_BAR; PG8_SCHED;
	s_add_i32 s46, s53, s8
	v_lshl_add_u64 v[158:159], v[158:159], 0, s[14:15]
	s_mov_b32 m0, s46
	ds_read_b128 v[200:203], v141 offset:49152
	ds_read_b128 v[214:217], v141 offset:50176
	ds_read_b128 v[218:221], v141 offset:51200
	ds_read_b128 v[222:225], v141 offset:52224
	ds_read_b128 v[226:229], v141 offset:53248
	ds_read_b128 v[230:233], v141 offset:54272
	ds_read_b128 v[234:237], v141 offset:55296
	ds_read_b128 v[238:241], v141 offset:56320
	global_load_lds_dwordx4 v[158:159], off
	s_add_i32 m0, s46, 0x2000
	s_add_u32 s44, s44, 0x80080
	v_lshl_add_u64 v[158:159], v[162:163], 0, s[14:15]
	s_addc_u32 s45, s45, 0
	s_add_i32 s46, s54, s8
	global_load_lds_dwordx4 v[158:159], off
	v_lshl_add_u64 v[158:159], s[44:45], 0, v[160:161]
	s_mov_b32 m0, s46
	s_nop 0
	global_load_lds_dwordx4 v[158:159], off
	v_lshl_add_u64 v[158:159], s[44:45], 0, v[128:129]
	s_add_i32 m0, s46, 0x2000
	s_nop 0
	global_load_lds_dwordx4 v[158:159], off
	v_lshl_add_u64 v[158:159], v[242:243], 0, s[14:15]
	s_mov_b32 m0, s23
	s_nop 0
	global_load_lds_dwordx4 v[158:159], off
	v_lshl_add_u64 v[158:159], v[244:245], 0, s[14:15]
	s_mov_b32 m0, s28
	s_nop 0
	global_load_lds_dwordx4 v[158:159], off
	s_waitcnt vmcnt(8)
	s_waitcnt lgkmcnt(0)
	s_barrier
	s_setprio 1
	s_waitcnt lgkmcnt(0)
	v_mfma_f32_16x16x32_bf16 v[60:63], v[142:145], v[200:203], v[60:63]
	v_mfma_f32_16x16x32_bf16 v[56:59], v[150:153], v[200:203], v[56:59]
	v_mfma_f32_16x16x32_bf16 v[52:55], v[142:145], v[218:221], v[52:55]
	v_mfma_f32_16x16x32_bf16 v[48:51], v[150:153], v[218:221], v[48:51]
	v_mfma_f32_16x16x32_bf16 v[44:47], v[142:145], v[226:229], v[44:47]
	v_mfma_f32_16x16x32_bf16 v[36:39], v[150:153], v[226:229], v[36:39]
	v_mfma_f32_16x16x32_bf16 v[28:31], v[142:145], v[234:237], v[28:31]
	v_mfma_f32_16x16x32_bf16 v[20:23], v[150:153], v[234:237], v[20:23]
	v_mfma_f32_16x16x32_bf16 v[60:63], v[146:149], v[214:217], v[60:63]
	v_mfma_f32_16x16x32_bf16 v[56:59], v[154:157], v[214:217], v[56:59]
	v_mfma_f32_16x16x32_bf16 v[52:55], v[146:149], v[222:225], v[52:55]
	v_mfma_f32_16x16x32_bf16 v[48:51], v[154:157], v[222:225], v[48:51]
	v_mfma_f32_16x16x32_bf16 v[44:47], v[146:149], v[230:233], v[44:47]
	v_mfma_f32_16x16x32_bf16 v[36:39], v[154:157], v[230:233], v[36:39]
	v_mfma_f32_16x16x32_bf16 v[28:31], v[146:149], v[238:241], v[28:31]
	v_mfma_f32_16x16x32_bf16 v[20:23], v[154:157], v[238:241], v[20:23]
	v_mfma_f32_16x16x32_bf16 v[40:43], v[184:187], v[200:203], v[40:43]
	v_mfma_f32_16x16x32_bf16 v[32:35], v[192:195], v[200:203], v[32:35]
	v_mfma_f32_16x16x32_bf16 v[24:27], v[184:187], v[218:221], v[24:27]
	v_mfma_f32_16x16x32_bf16 v[16:19], v[192:195], v[218:221], v[16:19]
	v_mfma_f32_16x16x32_bf16 v[12:15], v[184:187], v[226:229], v[12:15]
	v_mfma_f32_16x16x32_bf16 v[8:11], v[192:195], v[226:229], v[8:11]
	v_mfma_f32_16x16x32_bf16 v[4:7], v[184:187], v[234:237], v[4:7]
	v_mfma_f32_16x16x32_bf16 v[0:3], v[192:195], v[234:237], v[0:3]
	v_mfma_f32_16x16x32_bf16 v[40:43], v[188:191], v[214:217], v[40:43]
	v_mfma_f32_16x16x32_bf16 v[32:35], v[196:199], v[214:217], v[32:35]
	v_mfma_f32_16x16x32_bf16 v[24:27], v[188:191], v[222:225], v[24:27]
	v_mfma_f32_16x16x32_bf16 v[16:19], v[196:199], v[222:225], v[16:19]
	v_mfma_f32_16x16x32_bf16 v[12:15], v[188:191], v[230:233], v[12:15]
	v_mfma_f32_16x16x32_bf16 v[8:11], v[196:199], v[230:233], v[8:11]
	v_mfma_f32_16x16x32_bf16 v[4:7], v[188:191], v[238:241], v[4:7]
	v_mfma_f32_16x16x32_bf16 v[0:3], v[196:199], v[238:241], v[0:3]
	s_setprio 0
	s_barrier
	s_add_i32 s52, s52, 2
	s_add_u32 s42, s42, 0x100
	s_addc_u32 s43, s43, 0
	s_add_u32 s50, s50, 0x100
	s_addc_u32 s51, s51, 0
	s_cmp_gt_u32 s52, 29
	s_cbranch_scc0 .LBB0_1102
	s_branch .Lgk_after_1102
.LBB0_1102:
	s_add_u32 s44, s42, 0xfff80080
	s_addc_u32 s45, s43, -1
	s_add_i32 s53, 0, 0x10000
	s_cmp_eq_u32 s52, 28
	s_cselect_b32 s47, s17, s45
	s_cselect_b32 s46, s48, s44
	s_cselect_b32 s45, s11, s51
	s_cselect_b32 s44, s49, s50
	s_add_i32 s56, 0, 0x14000
	v_add_u32_e32 v154, s53, v139
	v_add_u32_e32 v158, s56, v139
	ds_read_b128 v[142:145], v154
	ds_read_b128 v[146:149], v154 offset:1024
	ds_read_b128 v[150:153], v154 offset:2048
	ds_read_b128 v[154:157], v154 offset:3072
	ds_read_b128 v[184:187], v158
	ds_read_b128 v[188:191], v158 offset:1024
	ds_read_b128 v[192:195], v158 offset:2048
	ds_read_b128 v[196:199], v158 offset:3072
	v_lshl_add_u64 v[158:159], s[42:43], 0, v[134:135]
	s_add_i32 m0, s9, 0xc000
	ds_read_b128 v[200:203], v141
	ds_read_b128 v[214:217], v141 offset:1024
	ds_read_b128 v[218:221], v141 offset:2048
	ds_read_b128 v[222:225], v141 offset:3072
	ds_read_b128 v[226:229], v141 offset:4096
	ds_read_b128 v[230:233], v141 offset:5120
	ds_read_b128 v[234:237], v141 offset:6144
	ds_read_b128 v[238:241], v141 offset:7168
	global_load_lds_dwordx4 v[158:159], off
	v_lshl_add_u64 v[158:159], s[42:43], 0, v[136:137]
	s_add_i32 m0, s9, 0xe000
	s_nop 0
	global_load_lds_dwordx4 v[158:159], off
	s_waitcnt vmcnt(8)
	s_waitcnt lgkmcnt(0)
	s_barrier
; #define PG8_STAGE(bufoff, gbase, voff) do { _Pragma("unroll") for (int _i = 0; _i < 2; ++_i) \
;         __builtin_amdgcn_global_load_lds((const unsigned*)((const char*)(gbase) + (voff)[_i]), (PG8_LAS unsigned*)(lds + (bufoff) + ldsw + _i * 8192), 16, 0, 0); } while (0)
; #define PG8_WAIT_V(n) asm volatile("s_waitcnt vmcnt(" #n ")" ::: "memory")
; #define PG8_WAIT_L(n) asm volatile("s_waitcnt lgkmcnt(" #n ")" ::: "memory")
; #define PG8_BAR __builtin_amdgcn_s_barrier()
; #define PG8_SCHED __builtin_amdgcn_sched_barrier(0)
; template <class Epi, class Sched, bool ALIGN_EPI = false, bool SP2 = false, bool F8 = false>
; __device__ __forceinline__ void gemm_phase(PG8_LAS unsigned char* lds, const Gemm g, const Sched& S, const Epi& E) {
;     ...
;             PG8_LDB(B0, 0, 0); PG8_LDB(B1, 0, 1); PG8_SCHED; PG8_LDA(At, 0, 0); PG8_STAGE(PG8_SA(1, 1), a1 + hstep, voffA);
;             PG8_WAIT_V(8); PG8_WAIT_L(0); PG8_BAR; PG8_MMA(0, 0, At, B0); PG8_MMA(0, 1, At, B1); PG8_BAR; PG8_SCHED;
;             PG8_LDA(At, 0, 1); PG8_STAGE(PG8_SB(0, 0), b2, voffB); PG8_STAGE(PG8_SB(0, 1), b2 + hstep, voffB); PG8_STAGE(PG8_SA(0, 0), a2, voffA);
;             PG8_WAIT_V(8); PG8_WAIT_L(0); PG8_BAR; PG8_MMA(1, 0, At, B0); PG8_MMA(1, 1, At, B1); PG8_BAR; PG8_SCHED;
	s_setprio 1
	s_waitcnt lgkmcnt(0)
	v_mfma_f32_16x16x32_bf16 v[124:127], v[142:145], v[200:203], v[124:127]
	v_mfma_f32_16x16x32_bf16 v[120:123], v[150:153], v[200:203], v[120:123]
	v_mfma_f32_16x16x32_bf16 v[116:119], v[142:145], v[218:221], v[116:119]
	v_mfma_f32_16x16x32_bf16 v[112:115], v[150:153], v[218:221], v[112:115]
	v_mfma_f32_16x16x32_bf16 v[108:111], v[142:145], v[226:229], v[108:111]
	v_mfma_f32_16x16x32_bf16 v[100:103], v[150:153], v[226:229], v[100:103]
	v_mfma_f32_16x16x32_bf16 v[92:95], v[142:145], v[234:237], v[92:95]
	v_mfma_f32_16x16x32_bf16 v[84:87], v[150:153], v[234:237], v[84:87]
	v_mfma_f32_16x16x32_bf16 v[124:127], v[146:149], v[214:217], v[124:127]
	v_mfma_f32_16x16x32_bf16 v[120:123], v[154:157], v[214:217], v[120:123]
	v_mfma_f32_16x16x32_bf16 v[116:119], v[146:149], v[222:225], v[116:119]
	v_mfma_f32_16x16x32_bf16 v[112:115], v[154:157], v[222:225], v[112:115]
	v_mfma_f32_16x16x32_bf16 v[108:111], v[146:149], v[230:233], v[108:111]
	v_mfma_f32_16x16x32_bf16 v[100:103], v[154:157], v[230:233], v[100:103]
	v_mfma_f32_16x16x32_bf16 v[92:95], v[146:149], v[238:241], v[92:95]
	v_mfma_f32_16x16x32_bf16 v[84:87], v[154:157], v[238:241], v[84:87]
	v_mfma_f32_16x16x32_bf16 v[104:107], v[184:187], v[200:203], v[104:107]
	v_mfma_f32_16x16x32_bf16 v[96:99], v[192:195], v[200:203], v[96:99]
	v_mfma_f32_16x16x32_bf16 v[88:91], v[184:187], v[218:221], v[88:91]
	v_mfma_f32_16x16x32_bf16 v[80:83], v[192:195], v[218:221], v[80:83]
	v_mfma_f32_16x16x32_bf16 v[76:79], v[184:187], v[226:229], v[76:79]
	v_mfma_f32_16x16x32_bf16 v[72:75], v[192:195], v[226:229], v[72:75]
	v_mfma_f32_16x16x32_bf16 v[68:71], v[184:187], v[234:237], v[68:71]
	v_mfma_f32_16x16x32_bf16 v[64:67], v[192:195], v[234:237], v[64:67]
	v_mfma_f32_16x16x32_bf16 v[104:107], v[188:191], v[214:217], v[104:107]
	v_mfma_f32_16x16x32_bf16 v[96:99], v[196:199], v[214:217], v[96:99]
	v_mfma_f32_16x16x32_bf16 v[88:91], v[188:191], v[222:225], v[88:91]
	v_mfma_f32_16x16x32_bf16 v[80:83], v[196:199], v[222:225], v[80:83]
	v_mfma_f32_16x16x32_bf16 v[76:79], v[188:191], v[230:233], v[76:79]
	v_mfma_f32_16x16x32_bf16 v[72:75], v[196:199], v[230:233], v[72:75]
	v_mfma_f32_16x16x32_bf16 v[68:71], v[188:191], v[238:241], v[68:71]
	v_mfma_f32_16x16x32_bf16 v[64:67], v[196:199], v[238:241], v[64:67]
	s_setprio 0
	s_barrier
	s_add_i32 s53, s53, s8
	v_lshl_add_u64 v[158:159], s[44:45], 0, v[160:161]
	s_mov_b32 m0, s53
	ds_read_b128 v[200:203], v141 offset:16384
	ds_read_b128 v[214:217], v141 offset:17408
	ds_read_b128 v[218:221], v141 offset:18432
	ds_read_b128 v[222:225], v141 offset:19456
	ds_read_b128 v[226:229], v141 offset:20480
	ds_read_b128 v[230:233], v141 offset:21504
	ds_read_b128 v[234:237], v141 offset:22528
	ds_read_b128 v[238:241], v141 offset:23552
	global_load_lds_dwordx4 v[158:159], off
	s_add_i32 m0, s53, 0x2000
	s_add_u32 s54, s44, 0x80000
	v_lshl_add_u64 v[162:163], s[44:45], 0, v[128:129]
	s_addc_u32 s55, s45, 0
	s_add_i32 s53, s56, s8
	global_load_lds_dwordx4 v[162:163], off
	v_lshl_add_u64 v[242:243], s[54:55], 0, v[160:161]
	s_mov_b32 m0, s53
	v_lshl_add_u64 v[244:245], s[46:47], 0, v[130:131]
	global_load_lds_dwordx4 v[242:243], off
	v_lshl_add_u64 v[242:243], s[54:55], 0, v[128:129]
	s_add_i32 m0, s53, 0x2000
	s_nop 0
	global_load_lds_dwordx4 v[242:243], off
	v_lshl_add_u64 v[242:243], s[46:47], 0, v[132:133]
	s_mov_b32 m0, s9
	s_nop 0
	global_load_lds_dwordx4 v[242:243], off
	s_mov_b32 m0, s13
	s_nop 0
	global_load_lds_dwordx4 v[244:245], off
	s_waitcnt vmcnt(8)
	s_waitcnt lgkmcnt(0)
	s_barrier
	s_setprio 1
	s_waitcnt lgkmcnt(0)
	v_mfma_f32_16x16x32_bf16 v[60:63], v[142:145], v[200:203], v[60:63]
	v_mfma_f32_16x16x32_bf16 v[56:59], v[150:153], v[200:203], v[56:59]
	v_mfma_f32_16x16x32_bf16 v[52:55], v[142:145], v[218:221], v[52:55]
	v_mfma_f32_16x16x32_bf16 v[48:51], v[150:153], v[218:221], v[48:51]
	v_mfma_f32_16x16x32_bf16 v[44:47], v[142:145], v[226:229], v[44:47]
	v_mfma_f32_16x16x32_bf16 v[36:39], v[150:153], v[226:229], v[36:39]
	v_mfma_f32_16x16x32_bf16 v[28:31], v[142:145], v[234:237], v[28:31]
	v_mfma_f32_16x16x32_bf16 v[20:23], v[150:153], v[234:237], v[20:23]
	v_mfma_f32_16x16x32_bf16 v[60:63], v[146:149], v[214:217], v[60:63]
	v_mfma_f32_16x16x32_bf16 v[56:59], v[154:157], v[214:217], v[56:59]
	v_mfma_f32_16x16x32_bf16 v[52:55], v[146:149], v[222:225], v[52:55]
	v_mfma_f32_16x16x32_bf16 v[48:51], v[154:157], v[222:225], v[48:51]
	v_mfma_f32_16x16x32_bf16 v[44:47], v[146:149], v[230:233], v[44:47]
	v_mfma_f32_16x16x32_bf16 v[36:39], v[154:157], v[230:233], v[36:39]
	v_mfma_f32_16x16x32_bf16 v[28:31], v[146:149], v[238:241], v[28:31]
	v_mfma_f32_16x16x32_bf16 v[20:23], v[154:157], v[238:241], v[20:23]
	v_mfma_f32_16x16x32_bf16 v[40:43], v[184:187], v[200:203], v[40:43]
	v_mfma_f32_16x16x32_bf16 v[32:35], v[192:195], v[200:203], v[32:35]
	v_mfma_f32_16x16x32_bf16 v[24:27], v[184:187], v[218:221], v[24:27]
	v_mfma_f32_16x16x32_bf16 v[16:19], v[192:195], v[218:221], v[16:19]
	v_mfma_f32_16x16x32_bf16 v[12:15], v[184:187], v[226:229], v[12:15]
	v_mfma_f32_16x16x32_bf16 v[8:11], v[192:195], v[226:229], v[8:11]
	v_mfma_f32_16x16x32_bf16 v[4:7], v[184:187], v[234:237], v[4:7]
	v_mfma_f32_16x16x32_bf16 v[0:3], v[192:195], v[234:237], v[0:3]
	v_mfma_f32_16x16x32_bf16 v[40:43], v[188:191], v[214:217], v[40:43]
	v_mfma_f32_16x16x32_bf16 v[32:35], v[196:199], v[214:217], v[32:35]
	v_mfma_f32_16x16x32_bf16 v[24:27], v[188:191], v[222:225], v[24:27]
	v_mfma_f32_16x16x32_bf16 v[16:19], v[196:199], v[222:225], v[16:19]
	v_mfma_f32_16x16x32_bf16 v[12:15], v[188:191], v[230:233], v[12:15]
	v_mfma_f32_16x16x32_bf16 v[8:11], v[196:199], v[230:233], v[8:11]
	v_mfma_f32_16x16x32_bf16 v[4:7], v[188:191], v[238:241], v[4:7]
	v_mfma_f32_16x16x32_bf16 v[0:3], v[196:199], v[238:241], v[0:3]
	s_setprio 0
	s_barrier
; #define PG8_STAGE(bufoff, gbase, voff) do { _Pragma("unroll") for (int _i = 0; _i < 2; ++_i) \
;         __builtin_amdgcn_global_load_lds((const unsigned*)((const char*)(gbase) + (voff)[_i]), (PG8_LAS unsigned*)(lds + (bufoff) + ldsw + _i * 8192), 16, 0, 0); } while (0)
; #define PG8_WAIT_V(n) asm volatile("s_waitcnt vmcnt(" #n ")" ::: "memory")
; #define PG8_WAIT_L(n) asm volatile("s_waitcnt lgkmcnt(" #n ")" ::: "memory")
; #define PG8_BAR __builtin_amdgcn_s_barrier()
; #define PG8_SCHED __builtin_amdgcn_sched_barrier(0)
; template <class Epi, class Sched, bool ALIGN_EPI = false, bool SP2 = false, bool F8 = false>
; __device__ __forceinline__ void gemm_phase(PG8_LAS unsigned char* lds, const Gemm g, const Sched& S, const Epi& E) {
;     ...
;             PG8_LDB(B0, 1, 0); PG8_LDB(B1, 1, 1); PG8_SCHED; PG8_LDA(At, 1, 0); PG8_STAGE(PG8_SA(0, 1), a2 + hstep, voffA);
;             PG8_WAIT_V(8); PG8_WAIT_L(0); PG8_BAR; PG8_MMA(0, 0, At, B0); PG8_MMA(0, 1, At, B1); PG8_BAR; PG8_SCHED;
	s_add_i32 s53, 0, 0x18000
	s_add_i32 s54, 0, 0x1c000
	v_add_u32_e32 v154, s53, v139
	v_add_u32_e32 v196, s54, v139
	ds_read_b128 v[142:145], v154
	ds_read_b128 v[146:149], v154 offset:1024
	ds_read_b128 v[150:153], v154 offset:2048
	ds_read_b128 v[154:157], v154 offset:3072
	ds_read_b128 v[184:187], v196
	ds_read_b128 v[188:191], v196 offset:1024
	ds_read_b128 v[192:195], v196 offset:2048
	ds_read_b128 v[196:199], v196 offset:3072
	s_add_u32 s46, s46, 0x80000
	s_addc_u32 s47, s47, 0
	s_mov_b32 m0, s19
	v_lshl_add_u64 v[246:247], s[46:47], 0, v[132:133]
	ds_read_b128 v[200:203], v141 offset:32768
	ds_read_b128 v[214:217], v141 offset:33792
	ds_read_b128 v[218:221], v141 offset:34816
	ds_read_b128 v[222:225], v141 offset:35840
	ds_read_b128 v[226:229], v141 offset:36864
	ds_read_b128 v[230:233], v141 offset:37888
	ds_read_b128 v[234:237], v141 offset:38912
	ds_read_b128 v[238:241], v141 offset:39936
	global_load_lds_dwordx4 v[246:247], off
	v_lshl_add_u64 v[246:247], s[46:47], 0, v[130:131]
	s_mov_b32 m0, s22
	s_nop 0
	global_load_lds_dwordx4 v[246:247], off
	s_waitcnt vmcnt(8)
	s_waitcnt lgkmcnt(0)
	s_barrier
	s_setprio 1
	s_waitcnt lgkmcnt(0)
	v_mfma_f32_16x16x32_bf16 v[124:127], v[142:145], v[200:203], v[124:127]
	v_mfma_f32_16x16x32_bf16 v[120:123], v[150:153], v[200:203], v[120:123]
	v_mfma_f32_16x16x32_bf16 v[116:119], v[142:145], v[218:221], v[116:119]
	v_mfma_f32_16x16x32_bf16 v[112:115], v[150:153], v[218:221], v[112:115]
	v_mfma_f32_16x16x32_bf16 v[108:111], v[142:145], v[226:229], v[108:111]
	v_mfma_f32_16x16x32_bf16 v[100:103], v[150:153], v[226:229], v[100:103]
	v_mfma_f32_16x16x32_bf16 v[92:95], v[142:145], v[234:237], v[92:95]
	v_mfma_f32_16x16x32_bf16 v[84:87], v[150:153], v[234:237], v[84:87]
	v_mfma_f32_16x16x32_bf16 v[124:127], v[146:149], v[214:217], v[124:127]
	v_mfma_f32_16x16x32_bf16 v[120:123], v[154:157], v[214:217], v[120:123]
	v_mfma_f32_16x16x32_bf16 v[116:119], v[146:149], v[222:225], v[116:119]
	v_mfma_f32_16x16x32_bf16 v[112:115], v[154:157], v[222:225], v[112:115]
	v_mfma_f32_16x16x32_bf16 v[108:111], v[146:149], v[230:233], v[108:111]
	v_mfma_f32_16x16x32_bf16 v[100:103], v[154:157], v[230:233], v[100:103]
	v_mfma_f32_16x16x32_bf16 v[92:95], v[146:149], v[238:241], v[92:95]
	v_mfma_f32_16x16x32_bf16 v[84:87], v[154:157], v[238:241], v[84:87]
	v_mfma_f32_16x16x32_bf16 v[104:107], v[184:187], v[200:203], v[104:107]
	v_mfma_f32_16x16x32_bf16 v[96:99], v[192:195], v[200:203], v[96:99]
	v_mfma_f32_16x16x32_bf16 v[88:91], v[184:187], v[218:221], v[88:91]
	v_mfma_f32_16x16x32_bf16 v[80:83], v[192:195], v[218:221], v[80:83]
	v_mfma_f32_16x16x32_bf16 v[76:79], v[184:187], v[226:229], v[76:79]
	v_mfma_f32_16x16x32_bf16 v[72:75], v[192:195], v[226:229], v[72:75]
	v_mfma_f32_16x16x32_bf16 v[68:71], v[184:187], v[234:237], v[68:71]
	v_mfma_f32_16x16x32_bf16 v[64:67], v[192:195], v[234:237], v[64:67]
	v_mfma_f32_16x16x32_bf16 v[104:107], v[188:191], v[214:217], v[104:107]
	v_mfma_f32_16x16x32_bf16 v[96:99], v[196:199], v[214:217], v[96:99]
	v_mfma_f32_16x16x32_bf16 v[88:91], v[188:191], v[222:225], v[88:91]
	v_mfma_f32_16x16x32_bf16 v[80:83], v[196:199], v[222:225], v[80:83]
	v_mfma_f32_16x16x32_bf16 v[76:79], v[188:191], v[230:233], v[76:79]
	v_mfma_f32_16x16x32_bf16 v[72:75], v[196:199], v[230:233], v[72:75]
	v_mfma_f32_16x16x32_bf16 v[68:71], v[188:191], v[238:241], v[68:71]
	v_mfma_f32_16x16x32_bf16 v[64:67], v[196:199], v[238:241], v[64:67]
	s_setprio 0
	s_barrier
; #define PG8_STAGE(bufoff, gbase, voff) do { _Pragma("unroll") for (int _i = 0; _i < 2; ++_i) \
;         __builtin_amdgcn_global_load_lds((const unsigned*)((const char*)(gbase) + (voff)[_i]), (PG8_LAS unsigned*)(lds + (bufoff) + ldsw + _i * 8192), 16, 0, 0); } while (0)
; #define PG8_WAIT_V(n) asm volatile("s_waitcnt vmcnt(" #n ")" ::: "memory")
; #define PG8_WAIT_L(n) asm volatile("s_waitcnt lgkmcnt(" #n ")" ::: "memory")
; #define PG8_BAR __builtin_amdgcn_s_barrier()
; #define PG8_SCHED __builtin_amdgcn_sched_barrier(0)
; template <class Epi, class Sched, bool ALIGN_EPI = false, bool SP2 = false, bool F8 = false>
; __device__ __forceinline__ void gemm_phase(PG8_LAS unsigned char* lds, const Gemm g, const Sched& S, const Epi& E) {
;     ...
;         for (int t = 0; t < nt; t += 2) {
;     ...
;             PG8_LDA(At, 1, 1); PG8_STAGE(PG8_SB(1, 0), b3, voffB); PG8_STAGE(PG8_SB(1, 1), b3 + hstep, voffB); PG8_STAGE(PG8_SA(1, 0), a3, voffA);
;             PG8_WAIT_V(8); PG8_WAIT_L(0); PG8_BAR; PG8_MMA(1, 0, At, B0); PG8_MMA(1, 1, At, B1); PG8_BAR; PG8_SCHED;
	s_add_i32 s46, s53, s8
	v_lshl_add_u64 v[158:159], v[158:159], 0, s[14:15]
	s_mov_b32 m0, s46
	ds_read_b128 v[200:203], v141 offset:49152
	ds_read_b128 v[214:217], v141 offset:50176
	ds_read_b128 v[218:221], v141 offset:51200
	ds_read_b128 v[222:225], v141 offset:52224
	ds_read_b128 v[226:229], v141 offset:53248
	ds_read_b128 v[230:233], v141 offset:54272
	ds_read_b128 v[234:237], v141 offset:55296
	ds_read_b128 v[238:241], v141 offset:56320
	global_load_lds_dwordx4 v[158:159], off
	s_add_i32 m0, s46, 0x2000
	s_add_u32 s44, s44, 0x80080
	v_lshl_add_u64 v[158:159], v[162:163], 0, s[14:15]
	s_addc_u32 s45, s45, 0
	s_add_i32 s46, s54, s8
	global_load_lds_dwordx4 v[158:159], off
	v_lshl_add_u64 v[158:159], s[44:45], 0, v[160:161]
	s_mov_b32 m0, s46
	s_nop 0
	global_load_lds_dwordx4 v[158:159], off
	v_lshl_add_u64 v[158:159], s[44:45], 0, v[128:129]
	s_add_i32 m0, s46, 0x2000
	s_nop 0
	global_load_lds_dwordx4 v[158:159], off
	v_lshl_add_u64 v[158:159], v[242:243], 0, s[14:15]
	s_mov_b32 m0, s23
	s_nop 0
	global_load_lds_dwordx4 v[158:159], off
	v_lshl_add_u64 v[158:159], v[244:245], 0, s[14:15]
	s_mov_b32 m0, s28
	s_nop 0
	global_load_lds_dwordx4 v[158:159], off
	s_waitcnt vmcnt(8)
	s_waitcnt lgkmcnt(0)
	s_barrier
	s_setprio 1
	s_waitcnt lgkmcnt(0)
	v_mfma_f32_16x16x32_bf16 v[60:63], v[142:145], v[200:203], v[60:63]
	v_mfma_f32_16x16x32_bf16 v[56:59], v[150:153], v[200:203], v[56:59]
	v_mfma_f32_16x16x32_bf16 v[52:55], v[142:145], v[218:221], v[52:55]
	v_mfma_f32_16x16x32_bf16 v[48:51], v[150:153], v[218:221], v[48:51]
	v_mfma_f32_16x16x32_bf16 v[44:47], v[142:145], v[226:229], v[44:47]
	v_mfma_f32_16x16x32_bf16 v[36:39], v[150:153], v[226:229], v[36:39]
	v_mfma_f32_16x16x32_bf16 v[28:31], v[142:145], v[234:237], v[28:31]
	v_mfma_f32_16x16x32_bf16 v[20:23], v[150:153], v[234:237], v[20:23]
	v_mfma_f32_16x16x32_bf16 v[60:63], v[146:149], v[214:217], v[60:63]
	v_mfma_f32_16x16x32_bf16 v[56:59], v[154:157], v[214:217], v[56:59]
	v_mfma_f32_16x16x32_bf16 v[52:55], v[146:149], v[222:225], v[52:55]
	v_mfma_f32_16x16x32_bf16 v[48:51], v[154:157], v[222:225], v[48:51]
	v_mfma_f32_16x16x32_bf16 v[44:47], v[146:149], v[230:233], v[44:47]
	v_mfma_f32_16x16x32_bf16 v[36:39], v[154:157], v[230:233], v[36:39]
	v_mfma_f32_16x16x32_bf16 v[28:31], v[146:149], v[238:241], v[28:31]
	v_mfma_f32_16x16x32_bf16 v[20:23], v[154:157], v[238:241], v[20:23]
	v_mfma_f32_16x16x32_bf16 v[40:43], v[184:187], v[200:203], v[40:43]
	v_mfma_f32_16x16x32_bf16 v[32:35], v[192:195], v[200:203], v[32:35]
	v_mfma_f32_16x16x32_bf16 v[24:27], v[184:187], v[218:221], v[24:27]
	v_mfma_f32_16x16x32_bf16 v[16:19], v[192:195], v[218:221], v[16:19]
	v_mfma_f32_16x16x32_bf16 v[12:15], v[184:187], v[226:229], v[12:15]
	v_mfma_f32_16x16x32_bf16 v[8:11], v[192:195], v[226:229], v[8:11]
	v_mfma_f32_16x16x32_bf16 v[4:7], v[184:187], v[234:237], v[4:7]
	v_mfma_f32_16x16x32_bf16 v[0:3], v[192:195], v[234:237], v[0:3]
	v_mfma_f32_16x16x32_bf16 v[40:43], v[188:191], v[214:217], v[40:43]
	v_mfma_f32_16x16x32_bf16 v[32:35], v[196:199], v[214:217], v[32:35]
	v_mfma_f32_16x16x32_bf16 v[24:27], v[188:191], v[222:225], v[24:27]
	v_mfma_f32_16x16x32_bf16 v[16:19], v[196:199], v[222:225], v[16:19]
	v_mfma_f32_16x16x32_bf16 v[12:15], v[188:191], v[230:233], v[12:15]
	v_mfma_f32_16x16x32_bf16 v[8:11], v[196:199], v[230:233], v[8:11]
	v_mfma_f32_16x16x32_bf16 v[4:7], v[188:191], v[238:241], v[4:7]
	v_mfma_f32_16x16x32_bf16 v[0:3], v[196:199], v[238:241], v[0:3]
	s_setprio 0
	s_barrier
	s_add_i32 s52, s52, 2
	s_add_u32 s42, s42, 0x100
	s_addc_u32 s43, s43, 0
	s_add_u32 s50, s50, 0x100
	s_addc_u32 s51, s51, 0
	s_cmp_gt_u32 s52, 29
	s_cbranch_scc0 .LBB0_1102

; #define PG8_STAGE(bufoff, gbase, voff) do { _Pragma("unroll") for (int _i = 0; _i < 2; ++_i) \
;         __builtin_amdgcn_global_load_lds((const unsigned*)((const char*)(gbase) + (voff)[_i]), (PG8_LAS unsigned*)(lds + (bufoff) + ldsw + _i * 8192), 16, 0, 0); } while (0)
; #define PG8_WAIT_V(n) asm volatile("s_waitcnt vmcnt(" #n ")" ::: "memory")
; #define PG8_WAIT_L(n) asm volatile("s_waitcnt lgkmcnt(" #n ")" ::: "memory")
; #define PG8_BAR __builtin_amdgcn_s_barrier()
; #define PG8_SCHED __builtin_amdgcn_sched_barrier(0)
; template <class Epi, class Sched, bool ALIGN_EPI = false, bool SP2 = false, bool F8 = false>
; __device__ __forceinline__ void gemm_phase(PG8_LAS unsigned char* lds, const Gemm g, const Sched& S, const Epi& E) {
;     ...
;         const bool has_next = S.next(ui + 1, nxt);
;         const char* nA = has_next ? (const char*)g.A + (size_t)nxt.pm * tstep : cA; const char* nB = has_next ? (const char*)g.Bt + (size_t)nxt.pn * tstep : cB;
;         for (int t = 0; t < nt; t += 2) {
;             const bool last = (t == nt - 2);
;             const char* a1 = cA + (size_t)(t + 1) * kstep;
;             const char* a2 = last ? nA : cA + (size_t)(t + 2) * kstep; const char* b2 = last ? nB : cB + (size_t)(t + 2) * kstep;
;             const char* a3 = a2 + kstep; const char* b3 = b2 + kstep;
;             if (last && has_next) S.a_ready(nxt);
;             if constexpr (SP2) {
;             PG8_LDB(B0, 0, 0); PG8_LDB(B1, 0, 1); PG8_SCHED; PG8_LDA(At, 0, 0); PG8_STAGE(PG8_SA(1, 1), a1 + hstep, voffA);
;             PG8_WAIT_V(8); PG8_WAIT_L(0); PG8_BAR; PG8_MMA(0, 0, At, B0); PG8_MMA(0, 1, At, B1); PG8_BAR; PG8_SCHED;
;             PG8_LDA(At, 0, 1); PG8_STAGE(PG8_SB(0, 0), b2, voffB); PG8_STAGE(PG8_SB(0, 1), b2 + hstep, voffB); PG8_STAGE(PG8_SA(0, 0), a2, voffA);
;             PG8_WAIT_V(8); PG8_WAIT_L(0); PG8_BAR; PG8_MMA(1, 0, At, B0); PG8_MMA(1, 1, At, B1); PG8_BAR; PG8_SCHED;
.LBB0_1121:
	s_ashr_i32 s43, s42, 31
	s_lshl_b64 s[28:29], s[42:43], 19
	v_readlane_b32 s19, v253, 59
	s_add_u32 s44, s19, s28
	v_readlane_b32 s19, v253, 60
	s_addc_u32 s45, s19, s29
	s_and_b64 s[28:29], s[38:39], exec
	s_cselect_b32 s19, s45, s11
	s_cselect_b32 s23, s44, s10
	s_ashr_i32 s41, s40, 31
	s_lshl_b64 s[28:29], s[40:41], 19
	s_add_u32 s46, s22, s28
	s_addc_u32 s47, s50, s29
	s_and_b64 s[28:29], s[38:39], exec
	s_cselect_b32 s28, s47, s37
	s_cselect_b32 s29, s46, s36
	s_add_u32 s10, s10, 0x40080
	s_addc_u32 s11, s11, 0
	s_add_u32 s34, s36, 0x100
	s_addc_u32 s35, s37, 0
	s_mov_b32 s41, -2
	s_add_u32 s36, s10, 0xfffc0080
	s_addc_u32 s37, s11, -1
	s_add_i32 s43, 0, 0x10000
	s_cmp_eq_u32 s41, 12
	s_cselect_b32 s49, s19, s37
	s_cselect_b32 s48, s23, s36
	s_cselect_b32 s37, s28, s35
	s_cselect_b32 s36, s29, s34
	s_add_i32 s56, 0, 0x14000
	v_add_u32_e32 v0, s43, v213
	v_add_u32_e32 v12, s56, v213
	ds_read_b128 v[16:19], v0
	ds_read_b128 v[20:23], v0 offset:1024
	ds_read_b128 v[24:27], v0 offset:2048
	ds_read_b128 v[28:31], v0 offset:3072
	ds_read_b128 v[0:3], v12
	ds_read_b128 v[4:7], v12 offset:1024
	ds_read_b128 v[8:11], v12 offset:2048
	ds_read_b128 v[12:15], v12 offset:3072
	v_lshl_add_u64 v[162:163], s[10:11], 0, v[190:191]
	s_add_i32 m0, s51, 0xc000
	ds_read_b128 v[194:197], v215
	ds_read_b128 v[198:201], v215 offset:1024
	ds_read_b128 v[216:219], v215 offset:2048
	ds_read_b128 v[220:223], v215 offset:3072
	ds_read_b128 v[224:227], v215 offset:4096
	ds_read_b128 v[228:231], v215 offset:5120
	ds_read_b128 v[232:235], v215 offset:6144
	ds_read_b128 v[236:239], v215 offset:7168
	global_load_lds_dwordx4 v[162:163], off
	v_lshl_add_u64 v[162:163], s[10:11], 0, v[192:193]
	s_add_i32 m0, s51, 0xe000
	s_nop 0
	global_load_lds_dwordx4 v[162:163], off
	s_waitcnt vmcnt(8)
	s_waitcnt lgkmcnt(0)
	s_barrier
	s_setprio 1
	s_waitcnt lgkmcnt(0)
	v_mfma_scale_f32_16x16x128_f8f6f4 v[156:159], v[16:23], v[194:201], 0, v202, v202 op_sel_hi:[0,0,0]
	v_mfma_scale_f32_16x16x128_f8f6f4 v[152:155], v[24:31], v[194:201], 0, v202, v202 op_sel_hi:[0,0,0]
	v_mfma_scale_f32_16x16x128_f8f6f4 v[140:143], v[16:23], v[216:223], 0, v202, v202 op_sel_hi:[0,0,0]
	v_mfma_scale_f32_16x16x128_f8f6f4 v[136:139], v[24:31], v[216:223], 0, v202, v202 op_sel_hi:[0,0,0]
	v_mfma_scale_f32_16x16x128_f8f6f4 v[124:127], v[16:23], v[224:231], 0, v202, v202 op_sel_hi:[0,0,0]
	v_mfma_scale_f32_16x16x128_f8f6f4 v[120:123], v[24:31], v[224:231], 0, v202, v202 op_sel_hi:[0,0,0]
	v_mfma_scale_f32_16x16x128_f8f6f4 v[108:111], v[16:23], v[232:239], 0, v202, v202 op_sel_hi:[0,0,0]
	v_mfma_scale_f32_16x16x128_f8f6f4 v[104:107], v[24:31], v[232:239], 0, v202, v202 op_sel_hi:[0,0,0]
	v_mfma_scale_f32_16x16x128_f8f6f4 v[148:151], v[0:7], v[194:201], 0, v202, v202 op_sel_hi:[0,0,0]
	v_mfma_scale_f32_16x16x128_f8f6f4 v[144:147], v[8:15], v[194:201], 0, v202, v202 op_sel_hi:[0,0,0]
	v_mfma_scale_f32_16x16x128_f8f6f4 v[132:135], v[0:7], v[216:223], 0, v202, v202 op_sel_hi:[0,0,0]
	v_mfma_scale_f32_16x16x128_f8f6f4 v[128:131], v[8:15], v[216:223], 0, v202, v202 op_sel_hi:[0,0,0]
	v_mfma_scale_f32_16x16x128_f8f6f4 v[116:119], v[0:7], v[224:231], 0, v202, v202 op_sel_hi:[0,0,0]
	v_mfma_scale_f32_16x16x128_f8f6f4 v[112:115], v[8:15], v[224:231], 0, v202, v202 op_sel_hi:[0,0,0]
	v_mfma_scale_f32_16x16x128_f8f6f4 v[100:103], v[0:7], v[232:239], 0, v202, v202 op_sel_hi:[0,0,0]
	v_mfma_scale_f32_16x16x128_f8f6f4 v[96:99], v[8:15], v[232:239], 0, v202, v202 op_sel_hi:[0,0,0]
	s_setprio 0
	s_barrier
	s_add_i32 s43, s43, s13
	v_lshl_add_u64 v[194:195], s[36:37], 0, v[160:161]
	s_mov_b32 m0, s43
	ds_read_b128 v[216:219], v215 offset:16384
	ds_read_b128 v[220:223], v215 offset:17408
	ds_read_b128 v[224:227], v215 offset:18432
	ds_read_b128 v[228:231], v215 offset:19456
	ds_read_b128 v[232:235], v215 offset:20480
	ds_read_b128 v[236:239], v215 offset:21504
	ds_read_b128 v[240:243], v215 offset:22528
	ds_read_b128 v[244:247], v215 offset:23552
	global_load_lds_dwordx4 v[194:195], off
	s_add_i32 m0, s43, 0x2000
	s_add_u32 s60, s36, 0x40000
	v_lshl_add_u64 v[196:197], s[36:37], 0, v[184:185]
	s_addc_u32 s61, s37, 0
	s_add_i32 s43, s56, s13
	global_load_lds_dwordx4 v[196:197], off
	v_lshl_add_u64 v[162:163], s[60:61], 0, v[160:161]
	s_mov_b32 m0, s43
	v_lshl_add_u64 v[198:199], s[48:49], 0, v[188:189]
	global_load_lds_dwordx4 v[162:163], off
	v_lshl_add_u64 v[162:163], s[60:61], 0, v[184:185]
	s_add_i32 m0, s43, 0x2000
	v_lshl_add_u64 v[200:201], s[48:49], 0, v[186:187]
	global_load_lds_dwordx4 v[162:163], off
	s_mov_b32 m0, s51
	s_nop 0
	global_load_lds_dwordx4 v[198:199], off
	s_mov_b32 m0, s52
	s_nop 0
	global_load_lds_dwordx4 v[200:201], off
	s_waitcnt vmcnt(8)
	s_waitcnt lgkmcnt(0)
	s_barrier
	s_setprio 1
	s_waitcnt lgkmcnt(0)
	v_mfma_scale_f32_16x16x128_f8f6f4 v[92:95], v[16:23], v[216:223], 0, v202, v202 op_sel_hi:[0,0,0]
	v_mfma_scale_f32_16x16x128_f8f6f4 v[88:91], v[24:31], v[216:223], 0, v202, v202 op_sel_hi:[0,0,0]
	v_mfma_scale_f32_16x16x128_f8f6f4 v[76:79], v[16:23], v[224:231], 0, v202, v202 op_sel_hi:[0,0,0]
	v_mfma_scale_f32_16x16x128_f8f6f4 v[72:75], v[24:31], v[224:231], 0, v202, v202 op_sel_hi:[0,0,0]
	v_mfma_scale_f32_16x16x128_f8f6f4 v[60:63], v[16:23], v[232:239], 0, v202, v202 op_sel_hi:[0,0,0]
	v_mfma_scale_f32_16x16x128_f8f6f4 v[56:59], v[24:31], v[232:239], 0, v202, v202 op_sel_hi:[0,0,0]
	v_mfma_scale_f32_16x16x128_f8f6f4 v[44:47], v[16:23], v[240:247], 0, v202, v202 op_sel_hi:[0,0,0]
	v_mfma_scale_f32_16x16x128_f8f6f4 v[40:43], v[24:31], v[240:247], 0, v202, v202 op_sel_hi:[0,0,0]
	v_mfma_scale_f32_16x16x128_f8f6f4 v[84:87], v[0:7], v[216:223], 0, v202, v202 op_sel_hi:[0,0,0]
	v_mfma_scale_f32_16x16x128_f8f6f4 v[80:83], v[8:15], v[216:223], 0, v202, v202 op_sel_hi:[0,0,0]
	v_mfma_scale_f32_16x16x128_f8f6f4 v[68:71], v[0:7], v[224:231], 0, v202, v202 op_sel_hi:[0,0,0]
	v_mfma_scale_f32_16x16x128_f8f6f4 v[64:67], v[8:15], v[224:231], 0, v202, v202 op_sel_hi:[0,0,0]
	v_mfma_scale_f32_16x16x128_f8f6f4 v[52:55], v[0:7], v[232:239], 0, v202, v202 op_sel_hi:[0,0,0]
	v_mfma_scale_f32_16x16x128_f8f6f4 v[48:51], v[8:15], v[232:239], 0, v202, v202 op_sel_hi:[0,0,0]
	v_mfma_scale_f32_16x16x128_f8f6f4 v[36:39], v[0:7], v[240:247], 0, v202, v202 op_sel_hi:[0,0,0]
	v_mfma_scale_f32_16x16x128_f8f6f4 v[32:35], v[8:15], v[240:247], 0, v202, v202 op_sel_hi:[0,0,0]
	s_setprio 0
	s_barrier
; #define PG8_STAGE(bufoff, gbase, voff) do { _Pragma("unroll") for (int _i = 0; _i < 2; ++_i) \
;         __builtin_amdgcn_global_load_lds((const unsigned*)((const char*)(gbase) + (voff)[_i]), (PG8_LAS unsigned*)(lds + (bufoff) + ldsw + _i * 8192), 16, 0, 0); } while (0)
; #define PG8_WAIT_V(n) asm volatile("s_waitcnt vmcnt(" #n ")" ::: "memory")
; #define PG8_WAIT_L(n) asm volatile("s_waitcnt lgkmcnt(" #n ")" ::: "memory")
; #define PG8_BAR __builtin_amdgcn_s_barrier()
; #define PG8_SCHED __builtin_amdgcn_sched_barrier(0)
; template <class Epi, class Sched, bool ALIGN_EPI = false, bool SP2 = false, bool F8 = false>
; __device__ __forceinline__ void gemm_phase(PG8_LAS unsigned char* lds, const Gemm g, const Sched& S, const Epi& E) {
;     ...
;         for (int t = 0; t < nt; t += 2) {
;     ...
;             PG8_LDB(B0, 1, 0); PG8_LDB(B1, 1, 1); PG8_SCHED; PG8_LDA(At, 1, 0); PG8_STAGE(PG8_SA(0, 1), a2 + hstep, voffA);
;             PG8_WAIT_V(8); PG8_WAIT_L(0); PG8_BAR; PG8_MMA(0, 0, At, B0); PG8_MMA(0, 1, At, B1); PG8_BAR; PG8_SCHED;
;             PG8_LDA(At, 1, 1); PG8_STAGE(PG8_SB(1, 0), b3, voffB); PG8_STAGE(PG8_SB(1, 1), b3 + hstep, voffB); PG8_STAGE(PG8_SA(1, 0), a3, voffA);
;             PG8_WAIT_V(8); PG8_WAIT_L(0); PG8_BAR; PG8_MMA(1, 0, At, B0); PG8_MMA(1, 1, At, B1); PG8_BAR; PG8_SCHED;
	s_add_i32 s43, 0, 0x18000
	s_add_i32 s56, 0, 0x1c000
	v_add_u32_e32 v12, s43, v213
	v_add_u32_e32 v28, s56, v213
	ds_read_b128 v[0:3], v12
	ds_read_b128 v[4:7], v12 offset:1024
	ds_read_b128 v[8:11], v12 offset:2048
	ds_read_b128 v[12:15], v12 offset:3072
	ds_read_b128 v[16:19], v28
	ds_read_b128 v[20:23], v28 offset:1024
	ds_read_b128 v[24:27], v28 offset:2048
	ds_read_b128 v[28:31], v28 offset:3072
	s_add_u32 s48, s48, 0x40000
	s_addc_u32 s49, s49, 0
	s_mov_b32 m0, s53
	v_lshl_add_u64 v[162:163], s[48:49], 0, v[188:189]
	ds_read_b128 v[216:219], v215 offset:32768
	ds_read_b128 v[220:223], v215 offset:33792
	ds_read_b128 v[224:227], v215 offset:34816
	ds_read_b128 v[228:231], v215 offset:35840
	ds_read_b128 v[232:235], v215 offset:36864
	ds_read_b128 v[236:239], v215 offset:37888
	ds_read_b128 v[240:243], v215 offset:38912
	ds_read_b128 v[244:247], v215 offset:39936
	global_load_lds_dwordx4 v[162:163], off
	v_lshl_add_u64 v[162:163], s[48:49], 0, v[186:187]
	s_mov_b32 m0, s54
	s_nop 0
	global_load_lds_dwordx4 v[162:163], off
	s_waitcnt vmcnt(8)
	s_waitcnt lgkmcnt(0)
	s_barrier
	s_setprio 1
	s_waitcnt lgkmcnt(0)
	v_mfma_scale_f32_16x16x128_f8f6f4 v[156:159], v[0:7], v[216:223], v[156:159], v202, v202 op_sel_hi:[0,0,0]
	v_mfma_scale_f32_16x16x128_f8f6f4 v[152:155], v[8:15], v[216:223], v[152:155], v202, v202 op_sel_hi:[0,0,0]
	v_mfma_scale_f32_16x16x128_f8f6f4 v[140:143], v[0:7], v[224:231], v[140:143], v202, v202 op_sel_hi:[0,0,0]
	v_mfma_scale_f32_16x16x128_f8f6f4 v[136:139], v[8:15], v[224:231], v[136:139], v202, v202 op_sel_hi:[0,0,0]
	v_mfma_scale_f32_16x16x128_f8f6f4 v[124:127], v[0:7], v[232:239], v[124:127], v202, v202 op_sel_hi:[0,0,0]
	v_mfma_scale_f32_16x16x128_f8f6f4 v[120:123], v[8:15], v[232:239], v[120:123], v202, v202 op_sel_hi:[0,0,0]
	v_mfma_scale_f32_16x16x128_f8f6f4 v[108:111], v[0:7], v[240:247], v[108:111], v202, v202 op_sel_hi:[0,0,0]
	v_mfma_scale_f32_16x16x128_f8f6f4 v[104:107], v[8:15], v[240:247], v[104:107], v202, v202 op_sel_hi:[0,0,0]
	v_mfma_scale_f32_16x16x128_f8f6f4 v[148:151], v[16:23], v[216:223], v[148:151], v202, v202 op_sel_hi:[0,0,0]
	v_mfma_scale_f32_16x16x128_f8f6f4 v[144:147], v[24:31], v[216:223], v[144:147], v202, v202 op_sel_hi:[0,0,0]
	v_mfma_scale_f32_16x16x128_f8f6f4 v[132:135], v[16:23], v[224:231], v[132:135], v202, v202 op_sel_hi:[0,0,0]
	v_mfma_scale_f32_16x16x128_f8f6f4 v[128:131], v[24:31], v[224:231], v[128:131], v202, v202 op_sel_hi:[0,0,0]
	v_mfma_scale_f32_16x16x128_f8f6f4 v[116:119], v[16:23], v[232:239], v[116:119], v202, v202 op_sel_hi:[0,0,0]
	v_mfma_scale_f32_16x16x128_f8f6f4 v[112:115], v[24:31], v[232:239], v[112:115], v202, v202 op_sel_hi:[0,0,0]
	v_mfma_scale_f32_16x16x128_f8f6f4 v[100:103], v[16:23], v[240:247], v[100:103], v202, v202 op_sel_hi:[0,0,0]
	v_mfma_scale_f32_16x16x128_f8f6f4 v[96:99], v[24:31], v[240:247], v[96:99], v202, v202 op_sel_hi:[0,0,0]
	s_setprio 0
	s_barrier
	s_add_i32 s43, s43, s13
	v_lshl_add_u64 v[162:163], v[194:195], 0, s[14:15]
	s_mov_b32 m0, s43
	ds_read_b128 v[216:219], v215 offset:49152
	ds_read_b128 v[220:223], v215 offset:50176
	ds_read_b128 v[224:227], v215 offset:51200
	ds_read_b128 v[228:231], v215 offset:52224
	ds_read_b128 v[232:235], v215 offset:53248
	ds_read_b128 v[236:239], v215 offset:54272
	ds_read_b128 v[240:243], v215 offset:55296
	ds_read_b128 v[244:247], v215 offset:56320
	global_load_lds_dwordx4 v[162:163], off
	s_add_i32 m0, s43, 0x2000
	s_add_u32 s36, s36, 0x40080
	v_lshl_add_u64 v[162:163], v[196:197], 0, s[14:15]
	s_addc_u32 s37, s37, 0
	s_add_i32 s43, s56, s13
	global_load_lds_dwordx4 v[162:163], off
	v_lshl_add_u64 v[162:163], s[36:37], 0, v[160:161]
	s_mov_b32 m0, s43
	s_nop 0
	global_load_lds_dwordx4 v[162:163], off
	v_lshl_add_u64 v[162:163], s[36:37], 0, v[184:185]
	s_add_i32 m0, s43, 0x2000
	s_nop 0
	global_load_lds_dwordx4 v[162:163], off
	v_lshl_add_u64 v[162:163], v[198:199], 0, s[14:15]
	s_mov_b32 m0, s55
	s_nop 0
	global_load_lds_dwordx4 v[162:163], off
	v_lshl_add_u64 v[162:163], v[200:201], 0, s[14:15]
	s_mov_b32 m0, s58
	s_nop 0
	global_load_lds_dwordx4 v[162:163], off
	s_waitcnt vmcnt(8)
	s_waitcnt lgkmcnt(0)
	s_barrier
	s_setprio 1
	s_waitcnt lgkmcnt(0)
	v_mfma_scale_f32_16x16x128_f8f6f4 v[92:95], v[0:7], v[216:223], v[92:95], v202, v202 op_sel_hi:[0,0,0]
	v_mfma_scale_f32_16x16x128_f8f6f4 v[88:91], v[8:15], v[216:223], v[88:91], v202, v202 op_sel_hi:[0,0,0]
	v_mfma_scale_f32_16x16x128_f8f6f4 v[76:79], v[0:7], v[224:231], v[76:79], v202, v202 op_sel_hi:[0,0,0]
	v_mfma_scale_f32_16x16x128_f8f6f4 v[72:75], v[8:15], v[224:231], v[72:75], v202, v202 op_sel_hi:[0,0,0]
	v_mfma_scale_f32_16x16x128_f8f6f4 v[60:63], v[0:7], v[232:239], v[60:63], v202, v202 op_sel_hi:[0,0,0]
	v_mfma_scale_f32_16x16x128_f8f6f4 v[56:59], v[8:15], v[232:239], v[56:59], v202, v202 op_sel_hi:[0,0,0]
	v_mfma_scale_f32_16x16x128_f8f6f4 v[44:47], v[0:7], v[240:247], v[44:47], v202, v202 op_sel_hi:[0,0,0]
	v_mfma_scale_f32_16x16x128_f8f6f4 v[40:43], v[8:15], v[240:247], v[40:43], v202, v202 op_sel_hi:[0,0,0]
	v_mfma_scale_f32_16x16x128_f8f6f4 v[84:87], v[16:23], v[216:223], v[84:87], v202, v202 op_sel_hi:[0,0,0]
	v_mfma_scale_f32_16x16x128_f8f6f4 v[80:83], v[24:31], v[216:223], v[80:83], v202, v202 op_sel_hi:[0,0,0]
	v_mfma_scale_f32_16x16x128_f8f6f4 v[68:71], v[16:23], v[224:231], v[68:71], v202, v202 op_sel_hi:[0,0,0]
	v_mfma_scale_f32_16x16x128_f8f6f4 v[64:67], v[24:31], v[224:231], v[64:67], v202, v202 op_sel_hi:[0,0,0]
	v_mfma_scale_f32_16x16x128_f8f6f4 v[52:55], v[16:23], v[232:239], v[52:55], v202, v202 op_sel_hi:[0,0,0]
	v_mfma_scale_f32_16x16x128_f8f6f4 v[48:51], v[24:31], v[232:239], v[48:51], v202, v202 op_sel_hi:[0,0,0]
	v_mfma_scale_f32_16x16x128_f8f6f4 v[36:39], v[16:23], v[240:247], v[36:39], v202, v202 op_sel_hi:[0,0,0]
	v_mfma_scale_f32_16x16x128_f8f6f4 v[32:35], v[24:31], v[240:247], v[32:35], v202, v202 op_sel_hi:[0,0,0]
	s_setprio 0
	s_barrier
	s_add_i32 s41, s41, 2
	s_add_u32 s10, s10, 0x100
	s_addc_u32 s11, s11, 0
	s_add_u32 s34, s34, 0x100
	s_addc_u32 s35, s35, 0
	s_cmp_gt_u32 s41, 13
	s_cbranch_scc0 .LBB0_1122
	s_branch .Lgk_after_1122
; #define PG8_STAGE(bufoff, gbase, voff) do { _Pragma("unroll") for (int _i = 0; _i < 2; ++_i) \
;         __builtin_amdgcn_global_load_lds((const unsigned*)((const char*)(gbase) + (voff)[_i]), (PG8_LAS unsigned*)(lds + (bufoff) + ldsw + _i * 8192), 16, 0, 0); } while (0)
; #define PG8_WAIT_V(n) asm volatile("s_waitcnt vmcnt(" #n ")" ::: "memory")
; #define PG8_WAIT_L(n) asm volatile("s_waitcnt lgkmcnt(" #n ")" ::: "memory")
; #define PG8_BAR __builtin_amdgcn_s_barrier()
; #define PG8_SCHED __builtin_amdgcn_sched_barrier(0)
; template <class Epi, class Sched, bool ALIGN_EPI = false, bool SP2 = false, bool F8 = false>
; __device__ __forceinline__ void gemm_phase(PG8_LAS unsigned char* lds, const Gemm g, const Sched& S, const Epi& E) {
;     ...
;             const bool last = (t == nt - 2);
;             const char* a1 = cA + (size_t)(t + 1) * kstep;
;             const char* a2 = last ? nA : cA + (size_t)(t + 2) * kstep; const char* b2 = last ? nB : cB + (size_t)(t + 2) * kstep;
;             const char* a3 = a2 + kstep; const char* b3 = b2 + kstep;
;             if (last && has_next) S.a_ready(nxt);
;             if constexpr (SP2) {
;             PG8_LDB(B0, 0, 0); PG8_LDB(B1, 0, 1); PG8_SCHED; PG8_LDA(At, 0, 0); PG8_STAGE(PG8_SA(1, 1), a1 + hstep, voffA);
;             PG8_WAIT_V(8); PG8_WAIT_L(0); PG8_BAR; PG8_MMA(0, 0, At, B0); PG8_MMA(0, 1, At, B1); PG8_BAR; PG8_SCHED;
;             PG8_LDA(At, 0, 1); PG8_STAGE(PG8_SB(0, 0), b2, voffB); PG8_STAGE(PG8_SB(0, 1), b2 + hstep, voffB); PG8_STAGE(PG8_SA(0, 0), a2, voffA);
;             PG8_WAIT_V(8); PG8_WAIT_L(0); PG8_BAR; PG8_MMA(1, 0, At, B0); PG8_MMA(1, 1, At, B1); PG8_BAR; PG8_SCHED;
.LBB0_1122:
	s_add_u32 s36, s10, 0xfffc0080
	s_addc_u32 s37, s11, -1
	s_add_i32 s43, 0, 0x10000
	s_cmp_eq_u32 s41, 12
	s_cselect_b32 s49, s19, s37
	s_cselect_b32 s48, s23, s36
	s_cselect_b32 s37, s28, s35
	s_cselect_b32 s36, s29, s34
	s_add_i32 s56, 0, 0x14000
	v_add_u32_e32 v0, s43, v213
	v_add_u32_e32 v12, s56, v213
	ds_read_b128 v[16:19], v0
	ds_read_b128 v[20:23], v0 offset:1024
	ds_read_b128 v[24:27], v0 offset:2048
	ds_read_b128 v[28:31], v0 offset:3072
	ds_read_b128 v[0:3], v12
	ds_read_b128 v[4:7], v12 offset:1024
	ds_read_b128 v[8:11], v12 offset:2048
	ds_read_b128 v[12:15], v12 offset:3072
	v_lshl_add_u64 v[162:163], s[10:11], 0, v[190:191]
	s_add_i32 m0, s51, 0xc000
	ds_read_b128 v[194:197], v215
	ds_read_b128 v[198:201], v215 offset:1024
	ds_read_b128 v[216:219], v215 offset:2048
	ds_read_b128 v[220:223], v215 offset:3072
	ds_read_b128 v[224:227], v215 offset:4096
	ds_read_b128 v[228:231], v215 offset:5120
	ds_read_b128 v[232:235], v215 offset:6144
	ds_read_b128 v[236:239], v215 offset:7168
	global_load_lds_dwordx4 v[162:163], off
	v_lshl_add_u64 v[162:163], s[10:11], 0, v[192:193]
	s_add_i32 m0, s51, 0xe000
	s_nop 0
	global_load_lds_dwordx4 v[162:163], off
	s_waitcnt vmcnt(8)
	s_waitcnt lgkmcnt(0)
	s_barrier
	s_setprio 1
	s_waitcnt lgkmcnt(0)
	v_mfma_scale_f32_16x16x128_f8f6f4 v[156:159], v[16:23], v[194:201], v[156:159], v202, v202 op_sel_hi:[0,0,0]
	v_mfma_scale_f32_16x16x128_f8f6f4 v[152:155], v[24:31], v[194:201], v[152:155], v202, v202 op_sel_hi:[0,0,0]
	v_mfma_scale_f32_16x16x128_f8f6f4 v[140:143], v[16:23], v[216:223], v[140:143], v202, v202 op_sel_hi:[0,0,0]
	v_mfma_scale_f32_16x16x128_f8f6f4 v[136:139], v[24:31], v[216:223], v[136:139], v202, v202 op_sel_hi:[0,0,0]
	v_mfma_scale_f32_16x16x128_f8f6f4 v[124:127], v[16:23], v[224:231], v[124:127], v202, v202 op_sel_hi:[0,0,0]
	v_mfma_scale_f32_16x16x128_f8f6f4 v[120:123], v[24:31], v[224:231], v[120:123], v202, v202 op_sel_hi:[0,0,0]
	v_mfma_scale_f32_16x16x128_f8f6f4 v[108:111], v[16:23], v[232:239], v[108:111], v202, v202 op_sel_hi:[0,0,0]
	v_mfma_scale_f32_16x16x128_f8f6f4 v[104:107], v[24:31], v[232:239], v[104:107], v202, v202 op_sel_hi:[0,0,0]
	v_mfma_scale_f32_16x16x128_f8f6f4 v[148:151], v[0:7], v[194:201], v[148:151], v202, v202 op_sel_hi:[0,0,0]
	v_mfma_scale_f32_16x16x128_f8f6f4 v[144:147], v[8:15], v[194:201], v[144:147], v202, v202 op_sel_hi:[0,0,0]
	v_mfma_scale_f32_16x16x128_f8f6f4 v[132:135], v[0:7], v[216:223], v[132:135], v202, v202 op_sel_hi:[0,0,0]
	v_mfma_scale_f32_16x16x128_f8f6f4 v[128:131], v[8:15], v[216:223], v[128:131], v202, v202 op_sel_hi:[0,0,0]
	v_mfma_scale_f32_16x16x128_f8f6f4 v[116:119], v[0:7], v[224:231], v[116:119], v202, v202 op_sel_hi:[0,0,0]
	v_mfma_scale_f32_16x16x128_f8f6f4 v[112:115], v[8:15], v[224:231], v[112:115], v202, v202 op_sel_hi:[0,0,0]
	v_mfma_scale_f32_16x16x128_f8f6f4 v[100:103], v[0:7], v[232:239], v[100:103], v202, v202 op_sel_hi:[0,0,0]
	v_mfma_scale_f32_16x16x128_f8f6f4 v[96:99], v[8:15], v[232:239], v[96:99], v202, v202 op_sel_hi:[0,0,0]
	s_setprio 0
	s_barrier
	s_add_i32 s43, s43, s13
	v_lshl_add_u64 v[194:195], s[36:37], 0, v[160:161]
	s_mov_b32 m0, s43
	ds_read_b128 v[216:219], v215 offset:16384
	ds_read_b128 v[220:223], v215 offset:17408
	ds_read_b128 v[224:227], v215 offset:18432
	ds_read_b128 v[228:231], v215 offset:19456
	ds_read_b128 v[232:235], v215 offset:20480
	ds_read_b128 v[236:239], v215 offset:21504
	ds_read_b128 v[240:243], v215 offset:22528
	ds_read_b128 v[244:247], v215 offset:23552
	global_load_lds_dwordx4 v[194:195], off
	s_add_i32 m0, s43, 0x2000
	s_add_u32 s60, s36, 0x40000
	v_lshl_add_u64 v[196:197], s[36:37], 0, v[184:185]
	s_addc_u32 s61, s37, 0
	s_add_i32 s43, s56, s13
	global_load_lds_dwordx4 v[196:197], off
	v_lshl_add_u64 v[162:163], s[60:61], 0, v[160:161]
	s_mov_b32 m0, s43
	v_lshl_add_u64 v[198:199], s[48:49], 0, v[188:189]
	global_load_lds_dwordx4 v[162:163], off
	v_lshl_add_u64 v[162:163], s[60:61], 0, v[184:185]
	s_add_i32 m0, s43, 0x2000
	v_lshl_add_u64 v[200:201], s[48:49], 0, v[186:187]
	global_load_lds_dwordx4 v[162:163], off
	s_mov_b32 m0, s51
	s_nop 0
	global_load_lds_dwordx4 v[198:199], off
	s_mov_b32 m0, s52
	s_nop 0
	global_load_lds_dwordx4 v[200:201], off
	s_waitcnt vmcnt(8)
	s_waitcnt lgkmcnt(0)
	s_barrier
	s_setprio 1
	s_waitcnt lgkmcnt(0)
	v_mfma_scale_f32_16x16x128_f8f6f4 v[92:95], v[16:23], v[216:223], v[92:95], v202, v202 op_sel_hi:[0,0,0]
	v_mfma_scale_f32_16x16x128_f8f6f4 v[88:91], v[24:31], v[216:223], v[88:91], v202, v202 op_sel_hi:[0,0,0]
	v_mfma_scale_f32_16x16x128_f8f6f4 v[76:79], v[16:23], v[224:231], v[76:79], v202, v202 op_sel_hi:[0,0,0]
	v_mfma_scale_f32_16x16x128_f8f6f4 v[72:75], v[24:31], v[224:231], v[72:75], v202, v202 op_sel_hi:[0,0,0]
	v_mfma_scale_f32_16x16x128_f8f6f4 v[60:63], v[16:23], v[232:239], v[60:63], v202, v202 op_sel_hi:[0,0,0]
	v_mfma_scale_f32_16x16x128_f8f6f4 v[56:59], v[24:31], v[232:239], v[56:59], v202, v202 op_sel_hi:[0,0,0]
	v_mfma_scale_f32_16x16x128_f8f6f4 v[44:47], v[16:23], v[240:247], v[44:47], v202, v202 op_sel_hi:[0,0,0]
	v_mfma_scale_f32_16x16x128_f8f6f4 v[40:43], v[24:31], v[240:247], v[40:43], v202, v202 op_sel_hi:[0,0,0]
	v_mfma_scale_f32_16x16x128_f8f6f4 v[84:87], v[0:7], v[216:223], v[84:87], v202, v202 op_sel_hi:[0,0,0]
	v_mfma_scale_f32_16x16x128_f8f6f4 v[80:83], v[8:15], v[216:223], v[80:83], v202, v202 op_sel_hi:[0,0,0]
	v_mfma_scale_f32_16x16x128_f8f6f4 v[68:71], v[0:7], v[224:231], v[68:71], v202, v202 op_sel_hi:[0,0,0]
	v_mfma_scale_f32_16x16x128_f8f6f4 v[64:67], v[8:15], v[224:231], v[64:67], v202, v202 op_sel_hi:[0,0,0]
	v_mfma_scale_f32_16x16x128_f8f6f4 v[52:55], v[0:7], v[232:239], v[52:55], v202, v202 op_sel_hi:[0,0,0]
	v_mfma_scale_f32_16x16x128_f8f6f4 v[48:51], v[8:15], v[232:239], v[48:51], v202, v202 op_sel_hi:[0,0,0]
	v_mfma_scale_f32_16x16x128_f8f6f4 v[36:39], v[0:7], v[240:247], v[36:39], v202, v202 op_sel_hi:[0,0,0]
	v_mfma_scale_f32_16x16x128_f8f6f4 v[32:35], v[8:15], v[240:247], v[32:35], v202, v202 op_sel_hi:[0,0,0]
	s_setprio 0
	s_barrier
; #define PG8_STAGE(bufoff, gbase, voff) do { _Pragma("unroll") for (int _i = 0; _i < 2; ++_i) \
;         __builtin_amdgcn_global_load_lds((const unsigned*)((const char*)(gbase) + (voff)[_i]), (PG8_LAS unsigned*)(lds + (bufoff) + ldsw + _i * 8192), 16, 0, 0); } while (0)
; #define PG8_WAIT_V(n) asm volatile("s_waitcnt vmcnt(" #n ")" ::: "memory")
; #define PG8_WAIT_L(n) asm volatile("s_waitcnt lgkmcnt(" #n ")" ::: "memory")
; #define PG8_BAR __builtin_amdgcn_s_barrier()
; #define PG8_SCHED __builtin_amdgcn_sched_barrier(0)
; template <class Epi, class Sched, bool ALIGN_EPI = false, bool SP2 = false, bool F8 = false>
; __device__ __forceinline__ void gemm_phase(PG8_LAS unsigned char* lds, const Gemm g, const Sched& S, const Epi& E) {
;     ...
;         for (int t = 0; t < nt; t += 2) {
;     ...
;             PG8_LDB(B0, 1, 0); PG8_LDB(B1, 1, 1); PG8_SCHED; PG8_LDA(At, 1, 0); PG8_STAGE(PG8_SA(0, 1), a2 + hstep, voffA);
;             PG8_WAIT_V(8); PG8_WAIT_L(0); PG8_BAR; PG8_MMA(0, 0, At, B0); PG8_MMA(0, 1, At, B1); PG8_BAR; PG8_SCHED;
;             PG8_LDA(At, 1, 1); PG8_STAGE(PG8_SB(1, 0), b3, voffB); PG8_STAGE(PG8_SB(1, 1), b3 + hstep, voffB); PG8_STAGE(PG8_SA(1, 0), a3, voffA);
;             PG8_WAIT_V(8); PG8_WAIT_L(0); PG8_BAR; PG8_MMA(1, 0, At, B0); PG8_MMA(1, 1, At, B1); PG8_BAR; PG8_SCHED;
	s_add_i32 s43, 0, 0x18000
	s_add_i32 s56, 0, 0x1c000
	v_add_u32_e32 v12, s43, v213
	v_add_u32_e32 v28, s56, v213
	ds_read_b128 v[0:3], v12
	ds_read_b128 v[4:7], v12 offset:1024
	ds_read_b128 v[8:11], v12 offset:2048
	ds_read_b128 v[12:15], v12 offset:3072
	ds_read_b128 v[16:19], v28
	ds_read_b128 v[20:23], v28 offset:1024
	ds_read_b128 v[24:27], v28 offset:2048
	ds_read_b128 v[28:31], v28 offset:3072
	s_add_u32 s48, s48, 0x40000
	s_addc_u32 s49, s49, 0
	s_mov_b32 m0, s53
	v_lshl_add_u64 v[162:163], s[48:49], 0, v[188:189]
	ds_read_b128 v[216:219], v215 offset:32768
	ds_read_b128 v[220:223], v215 offset:33792
	ds_read_b128 v[224:227], v215 offset:34816
	ds_read_b128 v[228:231], v215 offset:35840
	ds_read_b128 v[232:235], v215 offset:36864
	ds_read_b128 v[236:239], v215 offset:37888
	ds_read_b128 v[240:243], v215 offset:38912
	ds_read_b128 v[244:247], v215 offset:39936
	global_load_lds_dwordx4 v[162:163], off
	v_lshl_add_u64 v[162:163], s[48:49], 0, v[186:187]
	s_mov_b32 m0, s54
	s_nop 0
	global_load_lds_dwordx4 v[162:163], off
	s_waitcnt vmcnt(8)
	s_waitcnt lgkmcnt(0)
	s_barrier
	s_setprio 1
	s_waitcnt lgkmcnt(0)
	v_mfma_scale_f32_16x16x128_f8f6f4 v[156:159], v[0:7], v[216:223], v[156:159], v202, v202 op_sel_hi:[0,0,0]
	v_mfma_scale_f32_16x16x128_f8f6f4 v[152:155], v[8:15], v[216:223], v[152:155], v202, v202 op_sel_hi:[0,0,0]
	v_mfma_scale_f32_16x16x128_f8f6f4 v[140:143], v[0:7], v[224:231], v[140:143], v202, v202 op_sel_hi:[0,0,0]
	v_mfma_scale_f32_16x16x128_f8f6f4 v[136:139], v[8:15], v[224:231], v[136:139], v202, v202 op_sel_hi:[0,0,0]
	v_mfma_scale_f32_16x16x128_f8f6f4 v[124:127], v[0:7], v[232:239], v[124:127], v202, v202 op_sel_hi:[0,0,0]
	v_mfma_scale_f32_16x16x128_f8f6f4 v[120:123], v[8:15], v[232:239], v[120:123], v202, v202 op_sel_hi:[0,0,0]
	v_mfma_scale_f32_16x16x128_f8f6f4 v[108:111], v[0:7], v[240:247], v[108:111], v202, v202 op_sel_hi:[0,0,0]
	v_mfma_scale_f32_16x16x128_f8f6f4 v[104:107], v[8:15], v[240:247], v[104:107], v202, v202 op_sel_hi:[0,0,0]
	v_mfma_scale_f32_16x16x128_f8f6f4 v[148:151], v[16:23], v[216:223], v[148:151], v202, v202 op_sel_hi:[0,0,0]
	v_mfma_scale_f32_16x16x128_f8f6f4 v[144:147], v[24:31], v[216:223], v[144:147], v202, v202 op_sel_hi:[0,0,0]
	v_mfma_scale_f32_16x16x128_f8f6f4 v[132:135], v[16:23], v[224:231], v[132:135], v202, v202 op_sel_hi:[0,0,0]
	v_mfma_scale_f32_16x16x128_f8f6f4 v[128:131], v[24:31], v[224:231], v[128:131], v202, v202 op_sel_hi:[0,0,0]
	v_mfma_scale_f32_16x16x128_f8f6f4 v[116:119], v[16:23], v[232:239], v[116:119], v202, v202 op_sel_hi:[0,0,0]
	v_mfma_scale_f32_16x16x128_f8f6f4 v[112:115], v[24:31], v[232:239], v[112:115], v202, v202 op_sel_hi:[0,0,0]
	v_mfma_scale_f32_16x16x128_f8f6f4 v[100:103], v[16:23], v[240:247], v[100:103], v202, v202 op_sel_hi:[0,0,0]
	v_mfma_scale_f32_16x16x128_f8f6f4 v[96:99], v[24:31], v[240:247], v[96:99], v202, v202 op_sel_hi:[0,0,0]
	s_setprio 0
	s_barrier
	s_add_i32 s43, s43, s13
	v_lshl_add_u64 v[162:163], v[194:195], 0, s[14:15]
	s_mov_b32 m0, s43
	ds_read_b128 v[216:219], v215 offset:49152
	ds_read_b128 v[220:223], v215 offset:50176
	ds_read_b128 v[224:227], v215 offset:51200
	ds_read_b128 v[228:231], v215 offset:52224
	ds_read_b128 v[232:235], v215 offset:53248
	ds_read_b128 v[236:239], v215 offset:54272
	ds_read_b128 v[240:243], v215 offset:55296
	ds_read_b128 v[244:247], v215 offset:56320
	global_load_lds_dwordx4 v[162:163], off
	s_add_i32 m0, s43, 0x2000
	s_add_u32 s36, s36, 0x40080
	v_lshl_add_u64 v[162:163], v[196:197], 0, s[14:15]
	s_addc_u32 s37, s37, 0
	s_add_i32 s43, s56, s13
	global_load_lds_dwordx4 v[162:163], off
	v_lshl_add_u64 v[162:163], s[36:37], 0, v[160:161]
	s_mov_b32 m0, s43
	s_nop 0
	global_load_lds_dwordx4 v[162:163], off
	v_lshl_add_u64 v[162:163], s[36:37], 0, v[184:185]
	s_add_i32 m0, s43, 0x2000
	s_nop 0
	global_load_lds_dwordx4 v[162:163], off
	v_lshl_add_u64 v[162:163], v[198:199], 0, s[14:15]
	s_mov_b32 m0, s55
	s_nop 0
	global_load_lds_dwordx4 v[162:163], off
	v_lshl_add_u64 v[162:163], v[200:201], 0, s[14:15]
	s_mov_b32 m0, s58
	s_nop 0
	global_load_lds_dwordx4 v[162:163], off
	s_waitcnt vmcnt(8)
	s_waitcnt lgkmcnt(0)
	s_barrier
	s_setprio 1
	s_waitcnt lgkmcnt(0)
	v_mfma_scale_f32_16x16x128_f8f6f4 v[92:95], v[0:7], v[216:223], v[92:95], v202, v202 op_sel_hi:[0,0,0]
	v_mfma_scale_f32_16x16x128_f8f6f4 v[88:91], v[8:15], v[216:223], v[88:91], v202, v202 op_sel_hi:[0,0,0]
	v_mfma_scale_f32_16x16x128_f8f6f4 v[76:79], v[0:7], v[224:231], v[76:79], v202, v202 op_sel_hi:[0,0,0]
	v_mfma_scale_f32_16x16x128_f8f6f4 v[72:75], v[8:15], v[224:231], v[72:75], v202, v202 op_sel_hi:[0,0,0]
	v_mfma_scale_f32_16x16x128_f8f6f4 v[60:63], v[0:7], v[232:239], v[60:63], v202, v202 op_sel_hi:[0,0,0]
	v_mfma_scale_f32_16x16x128_f8f6f4 v[56:59], v[8:15], v[232:239], v[56:59], v202, v202 op_sel_hi:[0,0,0]
	v_mfma_scale_f32_16x16x128_f8f6f4 v[44:47], v[0:7], v[240:247], v[44:47], v202, v202 op_sel_hi:[0,0,0]
	v_mfma_scale_f32_16x16x128_f8f6f4 v[40:43], v[8:15], v[240:247], v[40:43], v202, v202 op_sel_hi:[0,0,0]
	v_mfma_scale_f32_16x16x128_f8f6f4 v[84:87], v[16:23], v[216:223], v[84:87], v202, v202 op_sel_hi:[0,0,0]
	v_mfma_scale_f32_16x16x128_f8f6f4 v[80:83], v[24:31], v[216:223], v[80:83], v202, v202 op_sel_hi:[0,0,0]
	v_mfma_scale_f32_16x16x128_f8f6f4 v[68:71], v[16:23], v[224:231], v[68:71], v202, v202 op_sel_hi:[0,0,0]
	v_mfma_scale_f32_16x16x128_f8f6f4 v[64:67], v[24:31], v[224:231], v[64:67], v202, v202 op_sel_hi:[0,0,0]
	v_mfma_scale_f32_16x16x128_f8f6f4 v[52:55], v[16:23], v[232:239], v[52:55], v202, v202 op_sel_hi:[0,0,0]
	v_mfma_scale_f32_16x16x128_f8f6f4 v[48:51], v[24:31], v[232:239], v[48:51], v202, v202 op_sel_hi:[0,0,0]
	v_mfma_scale_f32_16x16x128_f8f6f4 v[36:39], v[16:23], v[240:247], v[36:39], v202, v202 op_sel_hi:[0,0,0]
	v_mfma_scale_f32_16x16x128_f8f6f4 v[32:35], v[24:31], v[240:247], v[32:35], v202, v202 op_sel_hi:[0,0,0]
	s_setprio 0
	s_barrier
	s_add_i32 s41, s41, 2
	s_add_u32 s10, s10, 0x100
	s_addc_u32 s11, s11, 0
	s_add_u32 s34, s34, 0x100
	s_addc_u32 s35, s35, 0
	s_cmp_gt_u32 s41, 13
	s_cbranch_scc0 .LBB0_1122

; #define PG8_STAGE(bufoff, gbase, voff) do { _Pragma("unroll") for (int _i = 0; _i < 2; ++_i) \
;         __builtin_amdgcn_global_load_lds((const unsigned*)((const char*)(gbase) + (voff)[_i]), (PG8_LAS unsigned*)(lds + (bufoff) + ldsw + _i * 8192), 16, 0, 0); } while (0)
; #define PG8_WAIT_V(n) asm volatile("s_waitcnt vmcnt(" #n ")" ::: "memory")
; #define PG8_WAIT_L(n) asm volatile("s_waitcnt lgkmcnt(" #n ")" ::: "memory")
; #define PG8_BAR __builtin_amdgcn_s_barrier()
; #define PG8_SCHED __builtin_amdgcn_sched_barrier(0)
; template <class Epi, class Sched, bool ALIGN_EPI = false, bool SP2 = false, bool F8 = false>
; __device__ __forceinline__ void gemm_phase(PG8_LAS unsigned char* lds, const Gemm g, const Sched& S, const Epi& E) {
;     ...
;         const bool has_next = S.next(ui + 1, nxt);
;         const char* nA = has_next ? (const char*)g.A + (size_t)nxt.pm * tstep : cA; const char* nB = has_next ? (const char*)g.Bt + (size_t)nxt.pn * tstep : cB;
;         for (int t = 0; t < nt; t += 2) {
;             const bool last = (t == nt - 2);
;             const char* a1 = cA + (size_t)(t + 1) * kstep;
;             const char* a2 = last ? nA : cA + (size_t)(t + 2) * kstep; const char* b2 = last ? nB : cB + (size_t)(t + 2) * kstep;
;             const char* a3 = a2 + kstep; const char* b3 = b2 + kstep;
;             if (last && has_next) S.a_ready(nxt);
;             if constexpr (SP2) {
;             PG8_LDB(B0, 0, 0); PG8_LDB(B1, 0, 1); PG8_SCHED; PG8_LDA(At, 0, 0); PG8_STAGE(PG8_SA(1, 1), a1 + hstep, voffA);
;             PG8_WAIT_V(8); PG8_WAIT_L(0); PG8_BAR; PG8_MMA(0, 0, At, B0); PG8_MMA(0, 1, At, B1); PG8_BAR; PG8_SCHED;
;             PG8_LDA(At, 0, 1); PG8_STAGE(PG8_SB(0, 0), b2, voffB); PG8_STAGE(PG8_SB(0, 1), b2 + hstep, voffB); PG8_STAGE(PG8_SA(0, 0), a2, voffA);
;             PG8_WAIT_V(8); PG8_WAIT_L(0); PG8_BAR; PG8_MMA(1, 0, At, B0); PG8_MMA(1, 1, At, B1); PG8_BAR; PG8_SCHED;
.LBB0_1147:
	s_ashr_i32 s37, s36, 31
	s_lshl_b64 s[40:41], s[36:37], 22
	s_add_u32 s40, s20, s40
	s_addc_u32 s41, s21, s41
	s_and_b64 s[42:43], s[38:39], exec
	s_cselect_b32 s37, s41, s47
	s_cselect_b32 s52, s40, s46
	s_ashr_i32 s17, s16, 31
	s_lshl_b64 s[42:43], s[16:17], 22
	s_add_u32 s42, s13, s42
	s_addc_u32 s43, s19, s43
	s_and_b64 s[50:51], s[38:39], exec
	s_cselect_b32 s17, s43, s49
	s_cselect_b32 s53, s42, s48
	s_add_u32 s46, s46, 0x200080
	s_addc_u32 s47, s47, 0
	s_add_u32 s54, s48, 0x100
	s_addc_u32 s55, s49, 0
	s_mov_b32 s56, -2
	s_add_u32 s48, s46, 0xffe00080
	s_addc_u32 s49, s47, -1
	s_add_i32 s58, 0, 0x10000
	s_cmpk_eq_i32 s56, 0x7c
	s_cselect_b32 s51, s37, s49
	s_cselect_b32 s50, s52, s48
	s_cselect_b32 s49, s17, s55
	s_cselect_b32 s48, s53, s54
	s_add_i32 s60, 0, 0x14000
	v_add_u32_e32 v154, s58, v147
	v_add_u32_e32 v158, s60, v147
	ds_read_b128 v[138:141], v154
	ds_read_b128 v[142:145], v154 offset:1024
	ds_read_b128 v[150:153], v154 offset:2048
	ds_read_b128 v[154:157], v154 offset:3072
	ds_read_b128 v[184:187], v158
	ds_read_b128 v[188:191], v158 offset:1024
	ds_read_b128 v[192:195], v158 offset:2048
	ds_read_b128 v[196:199], v158 offset:3072
	v_lshl_add_u64 v[158:159], s[46:47], 0, v[134:135]
	s_add_i32 m0, s23, 0xc000
	ds_read_b128 v[200:203], v149
	ds_read_b128 v[214:217], v149 offset:1024
	ds_read_b128 v[218:221], v149 offset:2048
	ds_read_b128 v[222:225], v149 offset:3072
	ds_read_b128 v[226:229], v149 offset:4096
	ds_read_b128 v[230:233], v149 offset:5120
	ds_read_b128 v[234:237], v149 offset:6144
	ds_read_b128 v[238:241], v149 offset:7168
	global_load_lds_dwordx4 v[158:159], off
	v_lshl_add_u64 v[158:159], s[46:47], 0, v[136:137]
	s_add_i32 m0, s23, 0xe000
	s_nop 0
	global_load_lds_dwordx4 v[158:159], off
	s_waitcnt vmcnt(8)
	s_waitcnt lgkmcnt(0)
	s_barrier
	s_setprio 1
	s_waitcnt lgkmcnt(0)
	v_mfma_f32_16x16x32_bf16 v[124:127], v[138:141], v[200:203], 0
	v_mfma_f32_16x16x32_bf16 v[120:123], v[150:153], v[200:203], 0
	v_mfma_f32_16x16x32_bf16 v[108:111], v[138:141], v[218:221], 0
	v_mfma_f32_16x16x32_bf16 v[104:107], v[150:153], v[218:221], 0
	v_mfma_f32_16x16x32_bf16 v[92:95], v[138:141], v[226:229], 0
	v_mfma_f32_16x16x32_bf16 v[88:91], v[150:153], v[226:229], 0
	v_mfma_f32_16x16x32_bf16 v[76:79], v[138:141], v[234:237], 0
	v_mfma_f32_16x16x32_bf16 v[72:75], v[150:153], v[234:237], 0
	v_mfma_f32_16x16x32_bf16 v[124:127], v[142:145], v[214:217], v[124:127]
	v_mfma_f32_16x16x32_bf16 v[120:123], v[154:157], v[214:217], v[120:123]
	v_mfma_f32_16x16x32_bf16 v[108:111], v[142:145], v[222:225], v[108:111]
	v_mfma_f32_16x16x32_bf16 v[104:107], v[154:157], v[222:225], v[104:107]
	v_mfma_f32_16x16x32_bf16 v[92:95], v[142:145], v[230:233], v[92:95]
	v_mfma_f32_16x16x32_bf16 v[88:91], v[154:157], v[230:233], v[88:91]
	v_mfma_f32_16x16x32_bf16 v[76:79], v[142:145], v[238:241], v[76:79]
	v_mfma_f32_16x16x32_bf16 v[72:75], v[154:157], v[238:241], v[72:75]
	v_mfma_f32_16x16x32_bf16 v[116:119], v[184:187], v[200:203], 0
	v_mfma_f32_16x16x32_bf16 v[112:115], v[192:195], v[200:203], 0
	v_mfma_f32_16x16x32_bf16 v[100:103], v[184:187], v[218:221], 0
	v_mfma_f32_16x16x32_bf16 v[96:99], v[192:195], v[218:221], 0
	v_mfma_f32_16x16x32_bf16 v[84:87], v[184:187], v[226:229], 0
	v_mfma_f32_16x16x32_bf16 v[80:83], v[192:195], v[226:229], 0
	v_mfma_f32_16x16x32_bf16 v[68:71], v[184:187], v[234:237], 0
	v_mfma_f32_16x16x32_bf16 v[64:67], v[192:195], v[234:237], 0
	v_mfma_f32_16x16x32_bf16 v[116:119], v[188:191], v[214:217], v[116:119]
	v_mfma_f32_16x16x32_bf16 v[112:115], v[196:199], v[214:217], v[112:115]
	v_mfma_f32_16x16x32_bf16 v[100:103], v[188:191], v[222:225], v[100:103]
	v_mfma_f32_16x16x32_bf16 v[96:99], v[196:199], v[222:225], v[96:99]
	v_mfma_f32_16x16x32_bf16 v[84:87], v[188:191], v[230:233], v[84:87]
	v_mfma_f32_16x16x32_bf16 v[80:83], v[196:199], v[230:233], v[80:83]
	v_mfma_f32_16x16x32_bf16 v[68:71], v[188:191], v[238:241], v[68:71]
	v_mfma_f32_16x16x32_bf16 v[64:67], v[196:199], v[238:241], v[64:67]
	s_setprio 0
	s_barrier
	s_add_i32 s58, s58, s22
	v_lshl_add_u64 v[158:159], s[48:49], 0, v[160:161]
	s_mov_b32 m0, s58
	ds_read_b128 v[200:203], v149 offset:16384
	ds_read_b128 v[214:217], v149 offset:17408
	ds_read_b128 v[218:221], v149 offset:18432
	ds_read_b128 v[222:225], v149 offset:19456
	ds_read_b128 v[226:229], v149 offset:20480
	ds_read_b128 v[230:233], v149 offset:21504
	ds_read_b128 v[234:237], v149 offset:22528
	ds_read_b128 v[238:241], v149 offset:23552
	global_load_lds_dwordx4 v[158:159], off
	s_add_i32 m0, s58, 0x2000
	s_add_u32 s58, s48, 0x200000
	v_lshl_add_u64 v[162:163], s[48:49], 0, v[132:133]
	s_addc_u32 s59, s49, 0
	s_add_i32 s60, s60, s22
	global_load_lds_dwordx4 v[162:163], off
	v_lshl_add_u64 v[242:243], s[58:59], 0, v[160:161]
	s_mov_b32 m0, s60
	v_lshl_add_u64 v[244:245], s[50:51], 0, v[130:131]
	global_load_lds_dwordx4 v[242:243], off
	v_lshl_add_u64 v[242:243], s[58:59], 0, v[132:133]
	s_add_i32 m0, s60, 0x2000
	s_nop 0
	global_load_lds_dwordx4 v[242:243], off
	v_lshl_add_u64 v[242:243], s[50:51], 0, v[128:129]
	s_mov_b32 m0, s23
	s_nop 0
	global_load_lds_dwordx4 v[242:243], off
	s_mov_b32 m0, s28
	s_nop 0
	global_load_lds_dwordx4 v[244:245], off
	s_waitcnt vmcnt(8)
	s_waitcnt lgkmcnt(0)
	s_barrier
; #define PG8_STAGE(bufoff, gbase, voff) do { _Pragma("unroll") for (int _i = 0; _i < 2; ++_i) \
;         __builtin_amdgcn_global_load_lds((const unsigned*)((const char*)(gbase) + (voff)[_i]), (PG8_LAS unsigned*)(lds + (bufoff) + ldsw + _i * 8192), 16, 0, 0); } while (0)
; #define PG8_WAIT_V(n) asm volatile("s_waitcnt vmcnt(" #n ")" ::: "memory")
; #define PG8_WAIT_L(n) asm volatile("s_waitcnt lgkmcnt(" #n ")" ::: "memory")
; #define PG8_BAR __builtin_amdgcn_s_barrier()
; #define PG8_SCHED __builtin_amdgcn_sched_barrier(0)
; template <class Epi, class Sched, bool ALIGN_EPI = false, bool SP2 = false, bool F8 = false>
; __device__ __forceinline__ void gemm_phase(PG8_LAS unsigned char* lds, const Gemm g, const Sched& S, const Epi& E) {
;     ...
;             PG8_WAIT_V(8); PG8_WAIT_L(0); PG8_BAR; PG8_MMA(1, 0, At, B0); PG8_MMA(1, 1, At, B1); PG8_BAR; PG8_SCHED;
;             PG8_LDB(B0, 1, 0); PG8_LDB(B1, 1, 1); PG8_SCHED; PG8_LDA(At, 1, 0); PG8_STAGE(PG8_SA(0, 1), a2 + hstep, voffA);
;             PG8_WAIT_V(8); PG8_WAIT_L(0); PG8_BAR; PG8_MMA(0, 0, At, B0); PG8_MMA(0, 1, At, B1); PG8_BAR; PG8_SCHED;
	s_setprio 1
	s_waitcnt lgkmcnt(0)
	v_mfma_f32_16x16x32_bf16 v[60:63], v[138:141], v[200:203], 0
	v_mfma_f32_16x16x32_bf16 v[56:59], v[150:153], v[200:203], 0
	v_mfma_f32_16x16x32_bf16 v[44:47], v[138:141], v[218:221], 0
	v_mfma_f32_16x16x32_bf16 v[40:43], v[150:153], v[218:221], 0
	v_mfma_f32_16x16x32_bf16 v[28:31], v[138:141], v[226:229], 0
	v_mfma_f32_16x16x32_bf16 v[24:27], v[150:153], v[226:229], 0
	v_mfma_f32_16x16x32_bf16 v[12:15], v[138:141], v[234:237], 0
	v_mfma_f32_16x16x32_bf16 v[8:11], v[150:153], v[234:237], 0
	v_mfma_f32_16x16x32_bf16 v[60:63], v[142:145], v[214:217], v[60:63]
	v_mfma_f32_16x16x32_bf16 v[56:59], v[154:157], v[214:217], v[56:59]
	v_mfma_f32_16x16x32_bf16 v[44:47], v[142:145], v[222:225], v[44:47]
	v_mfma_f32_16x16x32_bf16 v[40:43], v[154:157], v[222:225], v[40:43]
	v_mfma_f32_16x16x32_bf16 v[28:31], v[142:145], v[230:233], v[28:31]
	v_mfma_f32_16x16x32_bf16 v[24:27], v[154:157], v[230:233], v[24:27]
	v_mfma_f32_16x16x32_bf16 v[12:15], v[142:145], v[238:241], v[12:15]
	v_mfma_f32_16x16x32_bf16 v[8:11], v[154:157], v[238:241], v[8:11]
	v_mfma_f32_16x16x32_bf16 v[52:55], v[184:187], v[200:203], 0
	v_mfma_f32_16x16x32_bf16 v[48:51], v[192:195], v[200:203], 0
	v_mfma_f32_16x16x32_bf16 v[36:39], v[184:187], v[218:221], 0
	v_mfma_f32_16x16x32_bf16 v[32:35], v[192:195], v[218:221], 0
	v_mfma_f32_16x16x32_bf16 v[20:23], v[184:187], v[226:229], 0
	v_mfma_f32_16x16x32_bf16 v[16:19], v[192:195], v[226:229], 0
	v_mfma_f32_16x16x32_bf16 v[4:7], v[184:187], v[234:237], 0
	v_mfma_f32_16x16x32_bf16 v[0:3], v[192:195], v[234:237], 0
	v_mfma_f32_16x16x32_bf16 v[52:55], v[188:191], v[214:217], v[52:55]
	v_mfma_f32_16x16x32_bf16 v[48:51], v[196:199], v[214:217], v[48:51]
	v_mfma_f32_16x16x32_bf16 v[36:39], v[188:191], v[222:225], v[36:39]
	v_mfma_f32_16x16x32_bf16 v[32:35], v[196:199], v[222:225], v[32:35]
	v_mfma_f32_16x16x32_bf16 v[20:23], v[188:191], v[230:233], v[20:23]
	v_mfma_f32_16x16x32_bf16 v[16:19], v[196:199], v[230:233], v[16:19]
	v_mfma_f32_16x16x32_bf16 v[4:7], v[188:191], v[238:241], v[4:7]
	v_mfma_f32_16x16x32_bf16 v[0:3], v[196:199], v[238:241], v[0:3]
	s_setprio 0
	s_barrier
	s_add_i32 s58, 0, 0x18000
	s_add_i32 s59, 0, 0x1c000
	v_add_u32_e32 v154, s58, v147
	v_add_u32_e32 v196, s59, v147
	ds_read_b128 v[138:141], v154
	ds_read_b128 v[142:145], v154 offset:1024
	ds_read_b128 v[150:153], v154 offset:2048
	ds_read_b128 v[154:157], v154 offset:3072
	ds_read_b128 v[184:187], v196
	ds_read_b128 v[188:191], v196 offset:1024
	ds_read_b128 v[192:195], v196 offset:2048
	ds_read_b128 v[196:199], v196 offset:3072
	s_add_u32 s50, s50, 0x200000
	s_addc_u32 s51, s51, 0
	s_mov_b32 m0, s29
	v_lshl_add_u64 v[246:247], s[50:51], 0, v[128:129]
	ds_read_b128 v[200:203], v149 offset:32768
	ds_read_b128 v[214:217], v149 offset:33792
	ds_read_b128 v[218:221], v149 offset:34816
	ds_read_b128 v[222:225], v149 offset:35840
	ds_read_b128 v[226:229], v149 offset:36864
	ds_read_b128 v[230:233], v149 offset:37888
	ds_read_b128 v[234:237], v149 offset:38912
	ds_read_b128 v[238:241], v149 offset:39936
	global_load_lds_dwordx4 v[246:247], off
	v_lshl_add_u64 v[246:247], s[50:51], 0, v[130:131]
	s_mov_b32 m0, s34
	s_nop 0
	global_load_lds_dwordx4 v[246:247], off
	s_waitcnt vmcnt(8)
	s_waitcnt lgkmcnt(0)
	s_barrier
	s_setprio 1
	s_waitcnt lgkmcnt(0)
	v_mfma_f32_16x16x32_bf16 v[124:127], v[138:141], v[200:203], v[124:127]
	v_mfma_f32_16x16x32_bf16 v[120:123], v[150:153], v[200:203], v[120:123]
	v_mfma_f32_16x16x32_bf16 v[108:111], v[138:141], v[218:221], v[108:111]
	v_mfma_f32_16x16x32_bf16 v[104:107], v[150:153], v[218:221], v[104:107]
	v_mfma_f32_16x16x32_bf16 v[92:95], v[138:141], v[226:229], v[92:95]
	v_mfma_f32_16x16x32_bf16 v[88:91], v[150:153], v[226:229], v[88:91]
	v_mfma_f32_16x16x32_bf16 v[76:79], v[138:141], v[234:237], v[76:79]
	v_mfma_f32_16x16x32_bf16 v[72:75], v[150:153], v[234:237], v[72:75]
	v_mfma_f32_16x16x32_bf16 v[124:127], v[142:145], v[214:217], v[124:127]
	v_mfma_f32_16x16x32_bf16 v[120:123], v[154:157], v[214:217], v[120:123]
	v_mfma_f32_16x16x32_bf16 v[108:111], v[142:145], v[222:225], v[108:111]
	v_mfma_f32_16x16x32_bf16 v[104:107], v[154:157], v[222:225], v[104:107]
	v_mfma_f32_16x16x32_bf16 v[92:95], v[142:145], v[230:233], v[92:95]
	v_mfma_f32_16x16x32_bf16 v[88:91], v[154:157], v[230:233], v[88:91]
	v_mfma_f32_16x16x32_bf16 v[76:79], v[142:145], v[238:241], v[76:79]
	v_mfma_f32_16x16x32_bf16 v[72:75], v[154:157], v[238:241], v[72:75]
	v_mfma_f32_16x16x32_bf16 v[116:119], v[184:187], v[200:203], v[116:119]
	v_mfma_f32_16x16x32_bf16 v[112:115], v[192:195], v[200:203], v[112:115]
	v_mfma_f32_16x16x32_bf16 v[100:103], v[184:187], v[218:221], v[100:103]
	v_mfma_f32_16x16x32_bf16 v[96:99], v[192:195], v[218:221], v[96:99]
	v_mfma_f32_16x16x32_bf16 v[84:87], v[184:187], v[226:229], v[84:87]
	v_mfma_f32_16x16x32_bf16 v[80:83], v[192:195], v[226:229], v[80:83]
	v_mfma_f32_16x16x32_bf16 v[68:71], v[184:187], v[234:237], v[68:71]
	v_mfma_f32_16x16x32_bf16 v[64:67], v[192:195], v[234:237], v[64:67]
	v_mfma_f32_16x16x32_bf16 v[116:119], v[188:191], v[214:217], v[116:119]
	v_mfma_f32_16x16x32_bf16 v[112:115], v[196:199], v[214:217], v[112:115]
	v_mfma_f32_16x16x32_bf16 v[100:103], v[188:191], v[222:225], v[100:103]
	v_mfma_f32_16x16x32_bf16 v[96:99], v[196:199], v[222:225], v[96:99]
	v_mfma_f32_16x16x32_bf16 v[84:87], v[188:191], v[230:233], v[84:87]
	v_mfma_f32_16x16x32_bf16 v[80:83], v[196:199], v[230:233], v[80:83]
	v_mfma_f32_16x16x32_bf16 v[68:71], v[188:191], v[238:241], v[68:71]
	v_mfma_f32_16x16x32_bf16 v[64:67], v[196:199], v[238:241], v[64:67]
	s_setprio 0
	s_barrier
; #define PG8_STAGE(bufoff, gbase, voff) do { _Pragma("unroll") for (int _i = 0; _i < 2; ++_i) \
;         __builtin_amdgcn_global_load_lds((const unsigned*)((const char*)(gbase) + (voff)[_i]), (PG8_LAS unsigned*)(lds + (bufoff) + ldsw + _i * 8192), 16, 0, 0); } while (0)
; #define PG8_WAIT_V(n) asm volatile("s_waitcnt vmcnt(" #n ")" ::: "memory")
; #define PG8_WAIT_L(n) asm volatile("s_waitcnt lgkmcnt(" #n ")" ::: "memory")
; #define PG8_BAR __builtin_amdgcn_s_barrier()
; #define PG8_SCHED __builtin_amdgcn_sched_barrier(0)
; template <class Epi, class Sched, bool ALIGN_EPI = false, bool SP2 = false, bool F8 = false>
; __device__ __forceinline__ void gemm_phase(PG8_LAS unsigned char* lds, const Gemm g, const Sched& S, const Epi& E) {
;     ...
;         for (int t = 0; t < nt; t += 2) {
;             const bool last = (t == nt - 2);
;             const char* a1 = cA + (size_t)(t + 1) * kstep;
;             const char* a2 = last ? nA : cA + (size_t)(t + 2) * kstep; const char* b2 = last ? nB : cB + (size_t)(t + 2) * kstep;
;             const char* a3 = a2 + kstep; const char* b3 = b2 + kstep;
;             if (last && has_next) S.a_ready(nxt);
;             if constexpr (SP2) {
;             PG8_LDB(B0, 0, 0); PG8_LDB(B1, 0, 1); PG8_SCHED; PG8_LDA(At, 0, 0); PG8_STAGE(PG8_SA(1, 1), a1 + hstep, voffA);
;             PG8_WAIT_V(8); PG8_WAIT_L(0); PG8_BAR; PG8_MMA(0, 0, At, B0); PG8_MMA(0, 1, At, B1); PG8_BAR; PG8_SCHED;
;             PG8_LDA(At, 0, 1); PG8_STAGE(PG8_SB(0, 0), b2, voffB); PG8_STAGE(PG8_SB(0, 1), b2 + hstep, voffB); PG8_STAGE(PG8_SA(0, 0), a2, voffA);
;             PG8_WAIT_V(8); PG8_WAIT_L(0); PG8_BAR; PG8_MMA(1, 0, At, B0); PG8_MMA(1, 1, At, B1); PG8_BAR; PG8_SCHED;
;             PG8_LDB(B0, 1, 0); PG8_LDB(B1, 1, 1); PG8_SCHED; PG8_LDA(At, 1, 0); PG8_STAGE(PG8_SA(0, 1), a2 + hstep, voffA);
;             PG8_WAIT_V(8); PG8_WAIT_L(0); PG8_BAR; PG8_MMA(0, 0, At, B0); PG8_MMA(0, 1, At, B1); PG8_BAR; PG8_SCHED;
;             PG8_LDA(At, 1, 1); PG8_STAGE(PG8_SB(1, 0), b3, voffB); PG8_STAGE(PG8_SB(1, 1), b3 + hstep, voffB); PG8_STAGE(PG8_SA(1, 0), a3, voffA);
;             PG8_WAIT_V(8); PG8_WAIT_L(0); PG8_BAR; PG8_MMA(1, 0, At, B0); PG8_MMA(1, 1, At, B1); PG8_BAR; PG8_SCHED;
	s_add_i32 s50, s58, s22
	v_lshl_add_u64 v[158:159], v[158:159], 0, s[14:15]
	s_mov_b32 m0, s50
	ds_read_b128 v[200:203], v149 offset:49152
	ds_read_b128 v[214:217], v149 offset:50176
	ds_read_b128 v[218:221], v149 offset:51200
	ds_read_b128 v[222:225], v149 offset:52224
	ds_read_b128 v[226:229], v149 offset:53248
	ds_read_b128 v[230:233], v149 offset:54272
	ds_read_b128 v[234:237], v149 offset:55296
	ds_read_b128 v[238:241], v149 offset:56320
	global_load_lds_dwordx4 v[158:159], off
	s_add_i32 m0, s50, 0x2000
	s_add_u32 s48, s48, 0x200080
	v_lshl_add_u64 v[158:159], v[162:163], 0, s[14:15]
	s_addc_u32 s49, s49, 0
	s_add_i32 s50, s59, s22
	global_load_lds_dwordx4 v[158:159], off
	v_lshl_add_u64 v[158:159], s[48:49], 0, v[160:161]
	s_mov_b32 m0, s50
	s_nop 0
	global_load_lds_dwordx4 v[158:159], off
	v_lshl_add_u64 v[158:159], s[48:49], 0, v[132:133]
	s_add_i32 m0, s50, 0x2000
	s_nop 0
	global_load_lds_dwordx4 v[158:159], off
	v_lshl_add_u64 v[158:159], v[242:243], 0, s[14:15]
	s_mov_b32 m0, s8
	s_nop 0
	global_load_lds_dwordx4 v[158:159], off
	v_lshl_add_u64 v[158:159], v[244:245], 0, s[14:15]
	s_mov_b32 m0, s9
	s_nop 0
	global_load_lds_dwordx4 v[158:159], off
	s_waitcnt vmcnt(8)
	s_waitcnt lgkmcnt(0)
	s_barrier
	s_setprio 1
	s_waitcnt lgkmcnt(0)
	v_mfma_f32_16x16x32_bf16 v[60:63], v[138:141], v[200:203], v[60:63]
	v_mfma_f32_16x16x32_bf16 v[56:59], v[150:153], v[200:203], v[56:59]
	v_mfma_f32_16x16x32_bf16 v[44:47], v[138:141], v[218:221], v[44:47]
	v_mfma_f32_16x16x32_bf16 v[40:43], v[150:153], v[218:221], v[40:43]
	v_mfma_f32_16x16x32_bf16 v[28:31], v[138:141], v[226:229], v[28:31]
	v_mfma_f32_16x16x32_bf16 v[24:27], v[150:153], v[226:229], v[24:27]
	v_mfma_f32_16x16x32_bf16 v[12:15], v[138:141], v[234:237], v[12:15]
	v_mfma_f32_16x16x32_bf16 v[8:11], v[150:153], v[234:237], v[8:11]
	v_mfma_f32_16x16x32_bf16 v[60:63], v[142:145], v[214:217], v[60:63]
	v_mfma_f32_16x16x32_bf16 v[56:59], v[154:157], v[214:217], v[56:59]
	v_mfma_f32_16x16x32_bf16 v[44:47], v[142:145], v[222:225], v[44:47]
	v_mfma_f32_16x16x32_bf16 v[40:43], v[154:157], v[222:225], v[40:43]
	v_mfma_f32_16x16x32_bf16 v[28:31], v[142:145], v[230:233], v[28:31]
	v_mfma_f32_16x16x32_bf16 v[24:27], v[154:157], v[230:233], v[24:27]
	v_mfma_f32_16x16x32_bf16 v[12:15], v[142:145], v[238:241], v[12:15]
	v_mfma_f32_16x16x32_bf16 v[8:11], v[154:157], v[238:241], v[8:11]
	v_mfma_f32_16x16x32_bf16 v[52:55], v[184:187], v[200:203], v[52:55]
	v_mfma_f32_16x16x32_bf16 v[48:51], v[192:195], v[200:203], v[48:51]
	v_mfma_f32_16x16x32_bf16 v[36:39], v[184:187], v[218:221], v[36:39]
	v_mfma_f32_16x16x32_bf16 v[32:35], v[192:195], v[218:221], v[32:35]
	v_mfma_f32_16x16x32_bf16 v[20:23], v[184:187], v[226:229], v[20:23]
	v_mfma_f32_16x16x32_bf16 v[16:19], v[192:195], v[226:229], v[16:19]
	v_mfma_f32_16x16x32_bf16 v[4:7], v[184:187], v[234:237], v[4:7]
	v_mfma_f32_16x16x32_bf16 v[0:3], v[192:195], v[234:237], v[0:3]
	v_mfma_f32_16x16x32_bf16 v[52:55], v[188:191], v[214:217], v[52:55]
	v_mfma_f32_16x16x32_bf16 v[48:51], v[196:199], v[214:217], v[48:51]
	v_mfma_f32_16x16x32_bf16 v[36:39], v[188:191], v[222:225], v[36:39]
	v_mfma_f32_16x16x32_bf16 v[32:35], v[196:199], v[222:225], v[32:35]
	v_mfma_f32_16x16x32_bf16 v[20:23], v[188:191], v[230:233], v[20:23]
	v_mfma_f32_16x16x32_bf16 v[16:19], v[196:199], v[230:233], v[16:19]
	v_mfma_f32_16x16x32_bf16 v[4:7], v[188:191], v[238:241], v[4:7]
	v_mfma_f32_16x16x32_bf16 v[0:3], v[196:199], v[238:241], v[0:3]
	s_setprio 0
	s_barrier
	s_add_i32 s56, s56, 2
	s_add_u32 s46, s46, 0x100
	s_addc_u32 s47, s47, 0
	s_add_u32 s54, s54, 0x100
	s_addc_u32 s55, s55, 0
	s_cmpk_gt_u32 s56, 0x7d
	s_cbranch_scc0 .LBB0_1148
	s_branch .Lgk_after_1148
.LBB0_1148:
	s_add_u32 s48, s46, 0xffe00080
	s_addc_u32 s49, s47, -1
	s_add_i32 s58, 0, 0x10000
	s_cmpk_eq_i32 s56, 0x7c
	s_cselect_b32 s51, s37, s49
	s_cselect_b32 s50, s52, s48
	s_cselect_b32 s49, s17, s55
	s_cselect_b32 s48, s53, s54
	s_add_i32 s60, 0, 0x14000
	v_add_u32_e32 v154, s58, v147
	v_add_u32_e32 v158, s60, v147
	ds_read_b128 v[138:141], v154
	ds_read_b128 v[142:145], v154 offset:1024
	ds_read_b128 v[150:153], v154 offset:2048
	ds_read_b128 v[154:157], v154 offset:3072
	ds_read_b128 v[184:187], v158
	ds_read_b128 v[188:191], v158 offset:1024
	ds_read_b128 v[192:195], v158 offset:2048
	ds_read_b128 v[196:199], v158 offset:3072
	v_lshl_add_u64 v[158:159], s[46:47], 0, v[134:135]
	s_add_i32 m0, s23, 0xc000
	ds_read_b128 v[200:203], v149
	ds_read_b128 v[214:217], v149 offset:1024
	ds_read_b128 v[218:221], v149 offset:2048
	ds_read_b128 v[222:225], v149 offset:3072
	ds_read_b128 v[226:229], v149 offset:4096
	ds_read_b128 v[230:233], v149 offset:5120
	ds_read_b128 v[234:237], v149 offset:6144
	ds_read_b128 v[238:241], v149 offset:7168
	global_load_lds_dwordx4 v[158:159], off
	v_lshl_add_u64 v[158:159], s[46:47], 0, v[136:137]
	s_add_i32 m0, s23, 0xe000
	s_nop 0
	global_load_lds_dwordx4 v[158:159], off
	s_waitcnt vmcnt(8)
	s_waitcnt lgkmcnt(0)
	s_barrier
; #define PG8_STAGE(bufoff, gbase, voff) do { _Pragma("unroll") for (int _i = 0; _i < 2; ++_i) \
;         __builtin_amdgcn_global_load_lds((const unsigned*)((const char*)(gbase) + (voff)[_i]), (PG8_LAS unsigned*)(lds + (bufoff) + ldsw + _i * 8192), 16, 0, 0); } while (0)
; #define PG8_WAIT_V(n) asm volatile("s_waitcnt vmcnt(" #n ")" ::: "memory")
; #define PG8_WAIT_L(n) asm volatile("s_waitcnt lgkmcnt(" #n ")" ::: "memory")
; #define PG8_BAR __builtin_amdgcn_s_barrier()
; #define PG8_SCHED __builtin_amdgcn_sched_barrier(0)
; template <class Epi, class Sched, bool ALIGN_EPI = false, bool SP2 = false, bool F8 = false>
; __device__ __forceinline__ void gemm_phase(PG8_LAS unsigned char* lds, const Gemm g, const Sched& S, const Epi& E) {
;     ...
;             PG8_LDB(B0, 0, 0); PG8_LDB(B1, 0, 1); PG8_SCHED; PG8_LDA(At, 0, 0); PG8_STAGE(PG8_SA(1, 1), a1 + hstep, voffA);
;             PG8_WAIT_V(8); PG8_WAIT_L(0); PG8_BAR; PG8_MMA(0, 0, At, B0); PG8_MMA(0, 1, At, B1); PG8_BAR; PG8_SCHED;
;             PG8_LDA(At, 0, 1); PG8_STAGE(PG8_SB(0, 0), b2, voffB); PG8_STAGE(PG8_SB(0, 1), b2 + hstep, voffB); PG8_STAGE(PG8_SA(0, 0), a2, voffA);
;             PG8_WAIT_V(8); PG8_WAIT_L(0); PG8_BAR; PG8_MMA(1, 0, At, B0); PG8_MMA(1, 1, At, B1); PG8_BAR; PG8_SCHED;
	s_setprio 1
	s_waitcnt lgkmcnt(0)
	v_mfma_f32_16x16x32_bf16 v[124:127], v[138:141], v[200:203], v[124:127]
	v_mfma_f32_16x16x32_bf16 v[120:123], v[150:153], v[200:203], v[120:123]
	v_mfma_f32_16x16x32_bf16 v[108:111], v[138:141], v[218:221], v[108:111]
	v_mfma_f32_16x16x32_bf16 v[104:107], v[150:153], v[218:221], v[104:107]
	v_mfma_f32_16x16x32_bf16 v[92:95], v[138:141], v[226:229], v[92:95]
	v_mfma_f32_16x16x32_bf16 v[88:91], v[150:153], v[226:229], v[88:91]
	v_mfma_f32_16x16x32_bf16 v[76:79], v[138:141], v[234:237], v[76:79]
	v_mfma_f32_16x16x32_bf16 v[72:75], v[150:153], v[234:237], v[72:75]
	v_mfma_f32_16x16x32_bf16 v[124:127], v[142:145], v[214:217], v[124:127]
	v_mfma_f32_16x16x32_bf16 v[120:123], v[154:157], v[214:217], v[120:123]
	v_mfma_f32_16x16x32_bf16 v[108:111], v[142:145], v[222:225], v[108:111]
	v_mfma_f32_16x16x32_bf16 v[104:107], v[154:157], v[222:225], v[104:107]
	v_mfma_f32_16x16x32_bf16 v[92:95], v[142:145], v[230:233], v[92:95]
	v_mfma_f32_16x16x32_bf16 v[88:91], v[154:157], v[230:233], v[88:91]
	v_mfma_f32_16x16x32_bf16 v[76:79], v[142:145], v[238:241], v[76:79]
	v_mfma_f32_16x16x32_bf16 v[72:75], v[154:157], v[238:241], v[72:75]
	v_mfma_f32_16x16x32_bf16 v[116:119], v[184:187], v[200:203], v[116:119]
	v_mfma_f32_16x16x32_bf16 v[112:115], v[192:195], v[200:203], v[112:115]
	v_mfma_f32_16x16x32_bf16 v[100:103], v[184:187], v[218:221], v[100:103]
	v_mfma_f32_16x16x32_bf16 v[96:99], v[192:195], v[218:221], v[96:99]
	v_mfma_f32_16x16x32_bf16 v[84:87], v[184:187], v[226:229], v[84:87]
	v_mfma_f32_16x16x32_bf16 v[80:83], v[192:195], v[226:229], v[80:83]
	v_mfma_f32_16x16x32_bf16 v[68:71], v[184:187], v[234:237], v[68:71]
	v_mfma_f32_16x16x32_bf16 v[64:67], v[192:195], v[234:237], v[64:67]
	v_mfma_f32_16x16x32_bf16 v[116:119], v[188:191], v[214:217], v[116:119]
	v_mfma_f32_16x16x32_bf16 v[112:115], v[196:199], v[214:217], v[112:115]
	v_mfma_f32_16x16x32_bf16 v[100:103], v[188:191], v[222:225], v[100:103]
	v_mfma_f32_16x16x32_bf16 v[96:99], v[196:199], v[222:225], v[96:99]
	v_mfma_f32_16x16x32_bf16 v[84:87], v[188:191], v[230:233], v[84:87]
	v_mfma_f32_16x16x32_bf16 v[80:83], v[196:199], v[230:233], v[80:83]
	v_mfma_f32_16x16x32_bf16 v[68:71], v[188:191], v[238:241], v[68:71]
	v_mfma_f32_16x16x32_bf16 v[64:67], v[196:199], v[238:241], v[64:67]
	s_setprio 0
	s_barrier
	s_add_i32 s58, s58, s22
	v_lshl_add_u64 v[158:159], s[48:49], 0, v[160:161]
	s_mov_b32 m0, s58
	ds_read_b128 v[200:203], v149 offset:16384
	ds_read_b128 v[214:217], v149 offset:17408
	ds_read_b128 v[218:221], v149 offset:18432
	ds_read_b128 v[222:225], v149 offset:19456
	ds_read_b128 v[226:229], v149 offset:20480
	ds_read_b128 v[230:233], v149 offset:21504
	ds_read_b128 v[234:237], v149 offset:22528
	ds_read_b128 v[238:241], v149 offset:23552
	global_load_lds_dwordx4 v[158:159], off
	s_add_i32 m0, s58, 0x2000
	s_add_u32 s58, s48, 0x200000
	v_lshl_add_u64 v[162:163], s[48:49], 0, v[132:133]
	s_addc_u32 s59, s49, 0
	s_add_i32 s60, s60, s22
	global_load_lds_dwordx4 v[162:163], off
	v_lshl_add_u64 v[242:243], s[58:59], 0, v[160:161]
	s_mov_b32 m0, s60
	v_lshl_add_u64 v[244:245], s[50:51], 0, v[130:131]
	global_load_lds_dwordx4 v[242:243], off
	v_lshl_add_u64 v[242:243], s[58:59], 0, v[132:133]
	s_add_i32 m0, s60, 0x2000
	s_nop 0
	global_load_lds_dwordx4 v[242:243], off
	v_lshl_add_u64 v[242:243], s[50:51], 0, v[128:129]
	s_mov_b32 m0, s23
	s_nop 0
	global_load_lds_dwordx4 v[242:243], off
	s_mov_b32 m0, s28
	s_nop 0
	global_load_lds_dwordx4 v[244:245], off
	s_waitcnt vmcnt(8)
	s_waitcnt lgkmcnt(0)
	s_barrier
	s_setprio 1
	s_waitcnt lgkmcnt(0)
	v_mfma_f32_16x16x32_bf16 v[60:63], v[138:141], v[200:203], v[60:63]
	v_mfma_f32_16x16x32_bf16 v[56:59], v[150:153], v[200:203], v[56:59]
	v_mfma_f32_16x16x32_bf16 v[44:47], v[138:141], v[218:221], v[44:47]
	v_mfma_f32_16x16x32_bf16 v[40:43], v[150:153], v[218:221], v[40:43]
	v_mfma_f32_16x16x32_bf16 v[28:31], v[138:141], v[226:229], v[28:31]
	v_mfma_f32_16x16x32_bf16 v[24:27], v[150:153], v[226:229], v[24:27]
	v_mfma_f32_16x16x32_bf16 v[12:15], v[138:141], v[234:237], v[12:15]
	v_mfma_f32_16x16x32_bf16 v[8:11], v[150:153], v[234:237], v[8:11]
	v_mfma_f32_16x16x32_bf16 v[60:63], v[142:145], v[214:217], v[60:63]
	v_mfma_f32_16x16x32_bf16 v[56:59], v[154:157], v[214:217], v[56:59]
	v_mfma_f32_16x16x32_bf16 v[44:47], v[142:145], v[222:225], v[44:47]
	v_mfma_f32_16x16x32_bf16 v[40:43], v[154:157], v[222:225], v[40:43]
	v_mfma_f32_16x16x32_bf16 v[28:31], v[142:145], v[230:233], v[28:31]
	v_mfma_f32_16x16x32_bf16 v[24:27], v[154:157], v[230:233], v[24:27]
	v_mfma_f32_16x16x32_bf16 v[12:15], v[142:145], v[238:241], v[12:15]
	v_mfma_f32_16x16x32_bf16 v[8:11], v[154:157], v[238:241], v[8:11]
	v_mfma_f32_16x16x32_bf16 v[52:55], v[184:187], v[200:203], v[52:55]
	v_mfma_f32_16x16x32_bf16 v[48:51], v[192:195], v[200:203], v[48:51]
	v_mfma_f32_16x16x32_bf16 v[36:39], v[184:187], v[218:221], v[36:39]
	v_mfma_f32_16x16x32_bf16 v[32:35], v[192:195], v[218:221], v[32:35]
	v_mfma_f32_16x16x32_bf16 v[20:23], v[184:187], v[226:229], v[20:23]
	v_mfma_f32_16x16x32_bf16 v[16:19], v[192:195], v[226:229], v[16:19]
	v_mfma_f32_16x16x32_bf16 v[4:7], v[184:187], v[234:237], v[4:7]
	v_mfma_f32_16x16x32_bf16 v[0:3], v[192:195], v[234:237], v[0:3]
	v_mfma_f32_16x16x32_bf16 v[52:55], v[188:191], v[214:217], v[52:55]
	v_mfma_f32_16x16x32_bf16 v[48:51], v[196:199], v[214:217], v[48:51]
	v_mfma_f32_16x16x32_bf16 v[36:39], v[188:191], v[222:225], v[36:39]
	v_mfma_f32_16x16x32_bf16 v[32:35], v[196:199], v[222:225], v[32:35]
	v_mfma_f32_16x16x32_bf16 v[20:23], v[188:191], v[230:233], v[20:23]
	v_mfma_f32_16x16x32_bf16 v[16:19], v[196:199], v[230:233], v[16:19]
	v_mfma_f32_16x16x32_bf16 v[4:7], v[188:191], v[238:241], v[4:7]
	v_mfma_f32_16x16x32_bf16 v[0:3], v[196:199], v[238:241], v[0:3]
	s_setprio 0
	s_barrier
; #define PG8_STAGE(bufoff, gbase, voff) do { _Pragma("unroll") for (int _i = 0; _i < 2; ++_i) \
;         __builtin_amdgcn_global_load_lds((const unsigned*)((const char*)(gbase) + (voff)[_i]), (PG8_LAS unsigned*)(lds + (bufoff) + ldsw + _i * 8192), 16, 0, 0); } while (0)
; #define PG8_WAIT_V(n) asm volatile("s_waitcnt vmcnt(" #n ")" ::: "memory")
; #define PG8_WAIT_L(n) asm volatile("s_waitcnt lgkmcnt(" #n ")" ::: "memory")
; #define PG8_BAR __builtin_amdgcn_s_barrier()
; #define PG8_SCHED __builtin_amdgcn_sched_barrier(0)
; template <class Epi, class Sched, bool ALIGN_EPI = false, bool SP2 = false, bool F8 = false>
; __device__ __forceinline__ void gemm_phase(PG8_LAS unsigned char* lds, const Gemm g, const Sched& S, const Epi& E) {
;     ...
;             PG8_LDB(B0, 1, 0); PG8_LDB(B1, 1, 1); PG8_SCHED; PG8_LDA(At, 1, 0); PG8_STAGE(PG8_SA(0, 1), a2 + hstep, voffA);
;             PG8_WAIT_V(8); PG8_WAIT_L(0); PG8_BAR; PG8_MMA(0, 0, At, B0); PG8_MMA(0, 1, At, B1); PG8_BAR; PG8_SCHED;
	s_add_i32 s58, 0, 0x18000
	s_add_i32 s59, 0, 0x1c000
	v_add_u32_e32 v154, s58, v147
	v_add_u32_e32 v196, s59, v147
	ds_read_b128 v[138:141], v154
	ds_read_b128 v[142:145], v154 offset:1024
	ds_read_b128 v[150:153], v154 offset:2048
	ds_read_b128 v[154:157], v154 offset:3072
	ds_read_b128 v[184:187], v196
	ds_read_b128 v[188:191], v196 offset:1024
	ds_read_b128 v[192:195], v196 offset:2048
	ds_read_b128 v[196:199], v196 offset:3072
	s_add_u32 s50, s50, 0x200000
	s_addc_u32 s51, s51, 0
	s_mov_b32 m0, s29
	v_lshl_add_u64 v[246:247], s[50:51], 0, v[128:129]
	ds_read_b128 v[200:203], v149 offset:32768
	ds_read_b128 v[214:217], v149 offset:33792
	ds_read_b128 v[218:221], v149 offset:34816
	ds_read_b128 v[222:225], v149 offset:35840
	ds_read_b128 v[226:229], v149 offset:36864
	ds_read_b128 v[230:233], v149 offset:37888
	ds_read_b128 v[234:237], v149 offset:38912
	ds_read_b128 v[238:241], v149 offset:39936
	global_load_lds_dwordx4 v[246:247], off
	v_lshl_add_u64 v[246:247], s[50:51], 0, v[130:131]
	s_mov_b32 m0, s34
	s_nop 0
	global_load_lds_dwordx4 v[246:247], off
	s_waitcnt vmcnt(8)
	s_waitcnt lgkmcnt(0)
	s_barrier
	s_setprio 1
	s_waitcnt lgkmcnt(0)
	v_mfma_f32_16x16x32_bf16 v[124:127], v[138:141], v[200:203], v[124:127]
	v_mfma_f32_16x16x32_bf16 v[120:123], v[150:153], v[200:203], v[120:123]
	v_mfma_f32_16x16x32_bf16 v[108:111], v[138:141], v[218:221], v[108:111]
	v_mfma_f32_16x16x32_bf16 v[104:107], v[150:153], v[218:221], v[104:107]
	v_mfma_f32_16x16x32_bf16 v[92:95], v[138:141], v[226:229], v[92:95]
	v_mfma_f32_16x16x32_bf16 v[88:91], v[150:153], v[226:229], v[88:91]
	v_mfma_f32_16x16x32_bf16 v[76:79], v[138:141], v[234:237], v[76:79]
	v_mfma_f32_16x16x32_bf16 v[72:75], v[150:153], v[234:237], v[72:75]
	v_mfma_f32_16x16x32_bf16 v[124:127], v[142:145], v[214:217], v[124:127]
	v_mfma_f32_16x16x32_bf16 v[120:123], v[154:157], v[214:217], v[120:123]
	v_mfma_f32_16x16x32_bf16 v[108:111], v[142:145], v[222:225], v[108:111]
	v_mfma_f32_16x16x32_bf16 v[104:107], v[154:157], v[222:225], v[104:107]
	v_mfma_f32_16x16x32_bf16 v[92:95], v[142:145], v[230:233], v[92:95]
	v_mfma_f32_16x16x32_bf16 v[88:91], v[154:157], v[230:233], v[88:91]
	v_mfma_f32_16x16x32_bf16 v[76:79], v[142:145], v[238:241], v[76:79]
	v_mfma_f32_16x16x32_bf16 v[72:75], v[154:157], v[238:241], v[72:75]
	v_mfma_f32_16x16x32_bf16 v[116:119], v[184:187], v[200:203], v[116:119]
	v_mfma_f32_16x16x32_bf16 v[112:115], v[192:195], v[200:203], v[112:115]
	v_mfma_f32_16x16x32_bf16 v[100:103], v[184:187], v[218:221], v[100:103]
	v_mfma_f32_16x16x32_bf16 v[96:99], v[192:195], v[218:221], v[96:99]
	v_mfma_f32_16x16x32_bf16 v[84:87], v[184:187], v[226:229], v[84:87]
	v_mfma_f32_16x16x32_bf16 v[80:83], v[192:195], v[226:229], v[80:83]
	v_mfma_f32_16x16x32_bf16 v[68:71], v[184:187], v[234:237], v[68:71]
	v_mfma_f32_16x16x32_bf16 v[64:67], v[192:195], v[234:237], v[64:67]
	v_mfma_f32_16x16x32_bf16 v[116:119], v[188:191], v[214:217], v[116:119]
	v_mfma_f32_16x16x32_bf16 v[112:115], v[196:199], v[214:217], v[112:115]
	v_mfma_f32_16x16x32_bf16 v[100:103], v[188:191], v[222:225], v[100:103]
	v_mfma_f32_16x16x32_bf16 v[96:99], v[196:199], v[222:225], v[96:99]
	v_mfma_f32_16x16x32_bf16 v[84:87], v[188:191], v[230:233], v[84:87]
	v_mfma_f32_16x16x32_bf16 v[80:83], v[196:199], v[230:233], v[80:83]
	v_mfma_f32_16x16x32_bf16 v[68:71], v[188:191], v[238:241], v[68:71]
	v_mfma_f32_16x16x32_bf16 v[64:67], v[196:199], v[238:241], v[64:67]
	s_setprio 0
	s_barrier
; #define PG8_STAGE(bufoff, gbase, voff) do { _Pragma("unroll") for (int _i = 0; _i < 2; ++_i) \
;         __builtin_amdgcn_global_load_lds((const unsigned*)((const char*)(gbase) + (voff)[_i]), (PG8_LAS unsigned*)(lds + (bufoff) + ldsw + _i * 8192), 16, 0, 0); } while (0)
; #define PG8_WAIT_V(n) asm volatile("s_waitcnt vmcnt(" #n ")" ::: "memory")
; #define PG8_WAIT_L(n) asm volatile("s_waitcnt lgkmcnt(" #n ")" ::: "memory")
; #define PG8_BAR __builtin_amdgcn_s_barrier()
; #define PG8_SCHED __builtin_amdgcn_sched_barrier(0)
; template <class Epi, class Sched, bool ALIGN_EPI = false, bool SP2 = false, bool F8 = false>
; __device__ __forceinline__ void gemm_phase(PG8_LAS unsigned char* lds, const Gemm g, const Sched& S, const Epi& E) {
;     ...
;         for (int t = 0; t < nt; t += 2) {
;     ...
;             PG8_LDA(At, 1, 1); PG8_STAGE(PG8_SB(1, 0), b3, voffB); PG8_STAGE(PG8_SB(1, 1), b3 + hstep, voffB); PG8_STAGE(PG8_SA(1, 0), a3, voffA);
;             PG8_WAIT_V(8); PG8_WAIT_L(0); PG8_BAR; PG8_MMA(1, 0, At, B0); PG8_MMA(1, 1, At, B1); PG8_BAR; PG8_SCHED;
	s_add_i32 s50, s58, s22
	v_lshl_add_u64 v[158:159], v[158:159], 0, s[14:15]
	s_mov_b32 m0, s50
	ds_read_b128 v[200:203], v149 offset:49152
	ds_read_b128 v[214:217], v149 offset:50176
	ds_read_b128 v[218:221], v149 offset:51200
	ds_read_b128 v[222:225], v149 offset:52224
	ds_read_b128 v[226:229], v149 offset:53248
	ds_read_b128 v[230:233], v149 offset:54272
	ds_read_b128 v[234:237], v149 offset:55296
	ds_read_b128 v[238:241], v149 offset:56320
	global_load_lds_dwordx4 v[158:159], off
	s_add_i32 m0, s50, 0x2000
	s_add_u32 s48, s48, 0x200080
	v_lshl_add_u64 v[158:159], v[162:163], 0, s[14:15]
	s_addc_u32 s49, s49, 0
	s_add_i32 s50, s59, s22
	global_load_lds_dwordx4 v[158:159], off
	v_lshl_add_u64 v[158:159], s[48:49], 0, v[160:161]
	s_mov_b32 m0, s50
	s_nop 0
	global_load_lds_dwordx4 v[158:159], off
	v_lshl_add_u64 v[158:159], s[48:49], 0, v[132:133]
	s_add_i32 m0, s50, 0x2000
	s_nop 0
	global_load_lds_dwordx4 v[158:159], off
	v_lshl_add_u64 v[158:159], v[242:243], 0, s[14:15]
	s_mov_b32 m0, s8
	s_nop 0
	global_load_lds_dwordx4 v[158:159], off
	v_lshl_add_u64 v[158:159], v[244:245], 0, s[14:15]
	s_mov_b32 m0, s9
	s_nop 0
	global_load_lds_dwordx4 v[158:159], off
	s_waitcnt vmcnt(8)
	s_waitcnt lgkmcnt(0)
	s_barrier
	s_setprio 1
	s_waitcnt lgkmcnt(0)
	v_mfma_f32_16x16x32_bf16 v[60:63], v[138:141], v[200:203], v[60:63]
	v_mfma_f32_16x16x32_bf16 v[56:59], v[150:153], v[200:203], v[56:59]
	v_mfma_f32_16x16x32_bf16 v[44:47], v[138:141], v[218:221], v[44:47]
	v_mfma_f32_16x16x32_bf16 v[40:43], v[150:153], v[218:221], v[40:43]
	v_mfma_f32_16x16x32_bf16 v[28:31], v[138:141], v[226:229], v[28:31]
	v_mfma_f32_16x16x32_bf16 v[24:27], v[150:153], v[226:229], v[24:27]
	v_mfma_f32_16x16x32_bf16 v[12:15], v[138:141], v[234:237], v[12:15]
	v_mfma_f32_16x16x32_bf16 v[8:11], v[150:153], v[234:237], v[8:11]
	v_mfma_f32_16x16x32_bf16 v[60:63], v[142:145], v[214:217], v[60:63]
	v_mfma_f32_16x16x32_bf16 v[56:59], v[154:157], v[214:217], v[56:59]
	v_mfma_f32_16x16x32_bf16 v[44:47], v[142:145], v[222:225], v[44:47]
	v_mfma_f32_16x16x32_bf16 v[40:43], v[154:157], v[222:225], v[40:43]
	v_mfma_f32_16x16x32_bf16 v[28:31], v[142:145], v[230:233], v[28:31]
	v_mfma_f32_16x16x32_bf16 v[24:27], v[154:157], v[230:233], v[24:27]
	v_mfma_f32_16x16x32_bf16 v[12:15], v[142:145], v[238:241], v[12:15]
	v_mfma_f32_16x16x32_bf16 v[8:11], v[154:157], v[238:241], v[8:11]
	v_mfma_f32_16x16x32_bf16 v[52:55], v[184:187], v[200:203], v[52:55]
	v_mfma_f32_16x16x32_bf16 v[48:51], v[192:195], v[200:203], v[48:51]
	v_mfma_f32_16x16x32_bf16 v[36:39], v[184:187], v[218:221], v[36:39]
	v_mfma_f32_16x16x32_bf16 v[32:35], v[192:195], v[218:221], v[32:35]
	v_mfma_f32_16x16x32_bf16 v[20:23], v[184:187], v[226:229], v[20:23]
	v_mfma_f32_16x16x32_bf16 v[16:19], v[192:195], v[226:229], v[16:19]
	v_mfma_f32_16x16x32_bf16 v[4:7], v[184:187], v[234:237], v[4:7]
	v_mfma_f32_16x16x32_bf16 v[0:3], v[192:195], v[234:237], v[0:3]
	v_mfma_f32_16x16x32_bf16 v[52:55], v[188:191], v[214:217], v[52:55]
	v_mfma_f32_16x16x32_bf16 v[48:51], v[196:199], v[214:217], v[48:51]
	v_mfma_f32_16x16x32_bf16 v[36:39], v[188:191], v[222:225], v[36:39]
	v_mfma_f32_16x16x32_bf16 v[32:35], v[196:199], v[222:225], v[32:35]
	v_mfma_f32_16x16x32_bf16 v[20:23], v[188:191], v[230:233], v[20:23]
	v_mfma_f32_16x16x32_bf16 v[16:19], v[196:199], v[230:233], v[16:19]
	v_mfma_f32_16x16x32_bf16 v[4:7], v[188:191], v[238:241], v[4:7]
	v_mfma_f32_16x16x32_bf16 v[0:3], v[196:199], v[238:241], v[0:3]
	s_setprio 0
	s_barrier
	s_add_i32 s56, s56, 2
	s_add_u32 s46, s46, 0x100
	s_addc_u32 s47, s47, 0
	s_add_u32 s54, s54, 0x100
	s_addc_u32 s55, s55, 0
	s_cmpk_gt_u32 s56, 0x7d
	s_cbranch_scc0 .LBB0_1148
